# GEMM units: accumulator zero-fill removed (first MFMA of each accumulator takes C=0 via peeled phases 1-4) + saddr DMA + half-tile round
# speedup vs baseline: 1.0188x; 1.0043x over previous
; #define PG8_STAGE(bufoff, gbase, voff) do { _Pragma("unroll") for (int _i = 0; _i < 2; ++_i) \
;         __builtin_amdgcn_global_load_lds((const unsigned*)((const char*)(gbase) + (voff)[_i]), (PG8_LAS unsigned*)(lds + (bufoff) + ldsw + _i * 8192), 16, 0, 0); } while (0)
; #define PG8_LDA(dst, b, h) do { _Pragma("unroll") for (int m = 0; m < 4; ++m) _Pragma("unroll") for (int k = 0; k < 2; ++k) dst[m][k] = *(const PG8_LAS bf16x8*)(lds + PG8_SA(b, h) + aoff + m * 2048 + k * 1024); } while (0)
; #define PG8_LDB(dst, b, h) do { _Pragma("unroll") for (int n = 0; n < 2; ++n) _Pragma("unroll") for (int k = 0; k < 2; ++k) dst[n][k] = *(const PG8_LAS bf16x8*)(lds + PG8_SB(b, h) + boff + n * 2048 + k * 1024); } while (0)
; #define PG8_WAIT_V(n) asm volatile("s_waitcnt vmcnt(" #n ")" ::: "memory")
; #define PG8_WAIT_L(n) asm volatile("s_waitcnt lgkmcnt(" #n ")" ::: "memory")
; #define PG8_BAR __builtin_amdgcn_s_barrier()
; template <class Epi, class Sched, bool STAMP = false>
; __device__ __forceinline__ void gemm_phase(PG8_LAS unsigned char* lds, const Gemm g, const Sched& S, const Epi& E, unsigned long long* stamps) {
;     ...
;     for (;;) {
;         const bool has_next = S.next(ui + 1, nxt);
;         const char* nA = has_next ? (const char*)g.A + (size_t)nxt.pm * tstep : cA; const char* nB = has_next ? (const char*)g.Bt + (size_t)nxt.pn * tstep : cB;
;         for (int t = 0; t < nt; t += 2) {
;             const bool last = (t == nt - 2);
;             const char* a1 = cA + (size_t)(t + 1) * kstep;
;             const char* a2 = last ? nA : cA + (size_t)(t + 2) * kstep; const char* b2 = last ? nB : cB + (size_t)(t + 2) * kstep;
;             const char* a3 = a2 + kstep; const char* b3 = b2 + kstep;
;             if (last && has_next) S.a_ready(nxt);
;             PG8_LDB(B0, 0, 0); PG8_SCHED; PG8_LDA(At, 0, 0); PG8_STAGE(PG8_SA(1, 1), a1 + hstep, voffA);
;             PG8_WAIT_L(8); PG8_BAR; PG8_WAIT_L(0); PG8_MMA(0, 0, At, B0); PG8_BAR; PG8_SCHED;
;             PG8_LDB(B1, 0, 1); PG8_STAGE(PG8_SB(0, 0), b2, voffB);
;             PG8_BAR; PG8_WAIT_L(0); PG8_MMA(0, 1, At, B1); PG8_BAR;
;             PG8_LDA(At, 0, 1); PG8_STAGE(PG8_SA(0, 0), a2, voffA);
;             PG8_BAR; PG8_WAIT_L(0); PG8_MMA(1, 0, At, B0); PG8_BAR; PG8_SCHED;
;             PG8_STAGE(PG8_SB(0, 1), b2 + hstep, voffB);
;             PG8_WAIT_V(6); PG8_BAR; PG8_MMA(1, 1, At, B1); PG8_BAR;
.LBB0_62:
	s_add_u32 s75, s16, 0x100
	s_addc_u32 s76, s17, 0
	s_mov_b32 s77, -2
	s_cmp_eq_u32 s59, s99
	s_cbranch_scc1 .Lgu1_half_loop_z
	ds_read_b128 v[140:143], v148
	ds_read_b128 v[166:169], v149
	ds_read_b128 v[170:173], v150
	ds_read_b128 v[174:177], v151
	s_add_u32 s16, s14, 0x100
	s_addc_u32 s17, s15, 0
	s_cmp_eq_u32 s77, 12
	s_cselect_b32 s29, s5, s17
	s_cselect_b32 s28, s4, s16
	s_cselect_b32 s19, s1, s76
	s_cselect_b32 s18, s0, s75
	s_mov_b32 m0, s68
	ds_read_b128 v[178:181], v146
	ds_read_b128 v[182:185], v146 offset:1024
	ds_read_b128 v[186:189], v146 offset:2048
	ds_read_b128 v[190:193], v146 offset:3072
	ds_read_b128 v[194:197], v146 offset:4096
	ds_read_b128 v[198:201], v146 offset:5120
	ds_read_b128 v[202:205], v146 offset:6144
	ds_read_b128 v[206:209], v146 offset:7168
	global_load_lds_dwordx4 v132, s[14:15]
	s_mov_b32 m0, s69
	s_nop 0
	global_load_lds_dwordx4 v134, s[14:15]
	s_waitcnt lgkmcnt(8)
	s_barrier
	s_waitcnt lgkmcnt(0)
	s_setprio 1
	s_waitcnt lgkmcnt(0)
	v_mfma_f32_16x16x32_bf16 v[124:127], v[140:143], v[178:181], 0
	v_mfma_f32_16x16x32_bf16 v[120:123], v[170:173], v[178:181], 0
	v_mfma_f32_16x16x32_bf16 v[108:111], v[140:143], v[186:189], 0
	v_mfma_f32_16x16x32_bf16 v[104:107], v[170:173], v[186:189], 0
	v_mfma_f32_16x16x32_bf16 v[92:95], v[140:143], v[194:197], 0
	v_mfma_f32_16x16x32_bf16 v[88:91], v[170:173], v[194:197], 0
	v_mfma_f32_16x16x32_bf16 v[76:79], v[140:143], v[202:205], 0
	v_mfma_f32_16x16x32_bf16 v[72:75], v[170:173], v[202:205], 0
	v_mfma_f32_16x16x32_bf16 v[124:127], v[166:169], v[182:185], v[124:127]
	v_mfma_f32_16x16x32_bf16 v[120:123], v[174:177], v[182:185], v[120:123]
	v_mfma_f32_16x16x32_bf16 v[108:111], v[166:169], v[190:193], v[108:111]
	v_mfma_f32_16x16x32_bf16 v[104:107], v[174:177], v[190:193], v[104:107]
	v_mfma_f32_16x16x32_bf16 v[92:95], v[166:169], v[198:201], v[92:95]
	v_mfma_f32_16x16x32_bf16 v[88:91], v[174:177], v[198:201], v[88:91]
	v_mfma_f32_16x16x32_bf16 v[76:79], v[166:169], v[206:209], v[76:79]
	v_mfma_f32_16x16x32_bf16 v[72:75], v[174:177], v[206:209], v[72:75]
	s_setprio 0
	s_barrier
	s_mov_b32 m0, s52
	ds_read_b128 v[210:213], v152
	ds_read_b128 v[214:217], v153
	ds_read_b128 v[218:221], v154
	ds_read_b128 v[222:225], v155
	global_load_lds_dwordx4 v130, s[18:19]
	s_mov_b32 m0, s53
	s_nop 0
	global_load_lds_dwordx4 v128, s[18:19]
	s_barrier
	s_waitcnt lgkmcnt(0)
	s_setprio 1
	s_waitcnt lgkmcnt(0)
	v_mfma_f32_16x16x32_bf16 v[116:119], v[210:213], v[178:181], 0
	v_mfma_f32_16x16x32_bf16 v[112:115], v[218:221], v[178:181], 0
	v_mfma_f32_16x16x32_bf16 v[100:103], v[210:213], v[186:189], 0
	v_mfma_f32_16x16x32_bf16 v[96:99], v[218:221], v[186:189], 0
	v_mfma_f32_16x16x32_bf16 v[84:87], v[210:213], v[194:197], 0
	v_mfma_f32_16x16x32_bf16 v[80:83], v[218:221], v[194:197], 0
	v_mfma_f32_16x16x32_bf16 v[68:71], v[210:213], v[202:205], 0
	v_mfma_f32_16x16x32_bf16 v[64:67], v[218:221], v[202:205], 0
	v_mfma_f32_16x16x32_bf16 v[116:119], v[214:217], v[182:185], v[116:119]
	v_mfma_f32_16x16x32_bf16 v[112:115], v[222:225], v[182:185], v[112:115]
	v_mfma_f32_16x16x32_bf16 v[100:103], v[214:217], v[190:193], v[100:103]
	v_mfma_f32_16x16x32_bf16 v[96:99], v[222:225], v[190:193], v[96:99]
	v_mfma_f32_16x16x32_bf16 v[84:87], v[214:217], v[198:201], v[84:87]
	v_mfma_f32_16x16x32_bf16 v[80:83], v[222:225], v[198:201], v[80:83]
	v_mfma_f32_16x16x32_bf16 v[68:71], v[214:217], v[206:209], v[68:71]
	v_mfma_f32_16x16x32_bf16 v[64:67], v[222:225], v[206:209], v[64:67]
	s_setprio 0
	s_mov_b32 m0, s33
	s_barrier
	ds_read_b128 v[178:181], v146 offset:16384
	ds_read_b128 v[182:185], v146 offset:17408
	ds_read_b128 v[186:189], v146 offset:18432
	ds_read_b128 v[190:193], v146 offset:19456
	ds_read_b128 v[194:197], v146 offset:20480
	ds_read_b128 v[198:201], v146 offset:21504
	ds_read_b128 v[202:205], v146 offset:22528
	ds_read_b128 v[206:209], v146 offset:23552
	global_load_lds_dwordx4 v130, s[28:29]
	s_mov_b32 m0, s54
	s_nop 0
	global_load_lds_dwordx4 v128, s[28:29]
	s_barrier
	s_waitcnt lgkmcnt(0)
	s_setprio 1
	s_waitcnt lgkmcnt(0)
	v_mfma_f32_16x16x32_bf16 v[60:63], v[140:143], v[178:181], 0
	v_mfma_f32_16x16x32_bf16 v[56:59], v[170:173], v[178:181], 0
	v_mfma_f32_16x16x32_bf16 v[44:47], v[140:143], v[186:189], 0
	v_mfma_f32_16x16x32_bf16 v[40:43], v[170:173], v[186:189], 0
	v_mfma_f32_16x16x32_bf16 v[28:31], v[140:143], v[194:197], 0
	v_mfma_f32_16x16x32_bf16 v[24:27], v[170:173], v[194:197], 0
	v_mfma_f32_16x16x32_bf16 v[12:15], v[140:143], v[202:205], 0
	v_mfma_f32_16x16x32_bf16 v[8:11], v[170:173], v[202:205], 0
	v_mfma_f32_16x16x32_bf16 v[60:63], v[166:169], v[182:185], v[60:63]
	v_mfma_f32_16x16x32_bf16 v[56:59], v[174:177], v[182:185], v[56:59]
	v_mfma_f32_16x16x32_bf16 v[44:47], v[166:169], v[190:193], v[44:47]
	v_mfma_f32_16x16x32_bf16 v[40:43], v[174:177], v[190:193], v[40:43]
	v_mfma_f32_16x16x32_bf16 v[28:31], v[166:169], v[198:201], v[28:31]
	v_mfma_f32_16x16x32_bf16 v[24:27], v[174:177], v[198:201], v[24:27]
	v_mfma_f32_16x16x32_bf16 v[12:15], v[166:169], v[206:209], v[12:15]
	v_mfma_f32_16x16x32_bf16 v[8:11], v[174:177], v[206:209], v[8:11]
	s_setprio 0
	s_barrier
	s_add_u32 s14, s18, 0x44000
	s_addc_u32 s15, s19, 0
	s_mov_b32 m0, s55
	s_nop 0
	global_load_lds_dwordx4 v130, s[14:15]
	s_mov_b32 m0, s56
	s_nop 0
	global_load_lds_dwordx4 v128, s[14:15]
	s_waitcnt vmcnt(6)
	s_barrier
	s_setprio 1
	v_mfma_f32_16x16x32_bf16 v[52:55], v[210:213], v[178:181], 0
	v_mfma_f32_16x16x32_bf16 v[48:51], v[218:221], v[178:181], 0
	v_mfma_f32_16x16x32_bf16 v[36:39], v[210:213], v[186:189], 0
	v_mfma_f32_16x16x32_bf16 v[32:35], v[218:221], v[186:189], 0
	v_mfma_f32_16x16x32_bf16 v[20:23], v[210:213], v[194:197], 0
	v_mfma_f32_16x16x32_bf16 v[16:19], v[218:221], v[194:197], 0
	v_mfma_f32_16x16x32_bf16 v[4:7], v[210:213], v[202:205], 0
	v_mfma_f32_16x16x32_bf16 v[0:3], v[218:221], v[202:205], 0
	v_mfma_f32_16x16x32_bf16 v[52:55], v[214:217], v[182:185], v[52:55]
	v_mfma_f32_16x16x32_bf16 v[48:51], v[222:225], v[182:185], v[48:51]
	v_mfma_f32_16x16x32_bf16 v[36:39], v[214:217], v[190:193], v[36:39]
	v_mfma_f32_16x16x32_bf16 v[32:35], v[222:225], v[190:193], v[32:35]
	v_mfma_f32_16x16x32_bf16 v[20:23], v[214:217], v[198:201], v[20:23]
	v_mfma_f32_16x16x32_bf16 v[16:19], v[222:225], v[198:201], v[16:19]
	v_mfma_f32_16x16x32_bf16 v[4:7], v[214:217], v[206:209], v[4:7]
	v_mfma_f32_16x16x32_bf16 v[0:3], v[222:225], v[206:209], v[0:3]
	s_setprio 0
	s_barrier
	s_branch .Lzp1_mid

; #define PG8_STAGE(bufoff, gbase, voff) do { _Pragma("unroll") for (int _i = 0; _i < 2; ++_i) \
;         __builtin_amdgcn_global_load_lds((const unsigned*)((const char*)(gbase) + (voff)[_i]), (PG8_LAS unsigned*)(lds + (bufoff) + ldsw + _i * 8192), 16, 0, 0); } while (0)
; #define PG8_LDA(dst, b, h) do { _Pragma("unroll") for (int m = 0; m < 4; ++m) _Pragma("unroll") for (int k = 0; k < 2; ++k) dst[m][k] = *(const PG8_LAS bf16x8*)(lds + PG8_SA(b, h) + aoff + m * 2048 + k * 1024); } while (0)
; #define PG8_LDB(dst, b, h) do { _Pragma("unroll") for (int n = 0; n < 2; ++n) _Pragma("unroll") for (int k = 0; k < 2; ++k) dst[n][k] = *(const PG8_LAS bf16x8*)(lds + PG8_SB(b, h) + boff + n * 2048 + k * 1024); } while (0)
; #define PG8_MMA(ai, bj, At, Bt) do { __builtin_amdgcn_s_setprio(1); _Pragma("unroll") for (int m = 0; m < 4; ++m) _Pragma("unroll") for (int n = 0; n < 2; ++n) _Pragma("unroll") for (int k = 0; k < 2; ++k) \
;         acc[ai][bj][m][n] = __builtin_amdgcn_mfma_f32_16x16x32_bf16(Bt[n][k], At[m][k], acc[ai][bj][m][n], 0, 0, 0); __builtin_amdgcn_s_setprio(0); } while (0)
; #define PG8_WAIT_V(n) asm volatile("s_waitcnt vmcnt(" #n ")" ::: "memory")
; #define PG8_WAIT_L(n) asm volatile("s_waitcnt lgkmcnt(" #n ")" ::: "memory")
; #define PG8_BAR __builtin_amdgcn_s_barrier()
; #define PG8_SCHED __builtin_amdgcn_sched_barrier(0)
; template <class Epi, class Sched, bool STAMP = false>
; __device__ __forceinline__ void gemm_phase(PG8_LAS unsigned char* lds, const Gemm g, const Sched& S, const Epi& E, unsigned long long* stamps) {
;     ...
;             PG8_LDB(B0, 1, 0); PG8_SCHED; PG8_LDA(At, 1, 0); PG8_STAGE(PG8_SA(0, 1), a2 + hstep, voffA);
;             PG8_WAIT_L(8); PG8_BAR; PG8_WAIT_L(0); PG8_MMA(0, 0, At, B0); PG8_BAR; PG8_SCHED;
;             PG8_LDB(B1, 1, 1); PG8_STAGE(PG8_SB(1, 0), b3, voffB);
;             PG8_BAR; PG8_WAIT_L(0); PG8_MMA(0, 1, At, B1); PG8_BAR;
;             PG8_LDA(At, 1, 1); PG8_STAGE(PG8_SA(1, 0), a3, voffA);
;             PG8_BAR; PG8_WAIT_L(0); PG8_MMA(1, 0, At, B0); PG8_BAR; PG8_SCHED;
;             PG8_STAGE(PG8_SB(1, 1), b3 + hstep, voffB);
;             PG8_WAIT_V(6); PG8_BAR; PG8_MMA(1, 1, At, B1); PG8_BAR;
.Lzp1_mid:
	ds_read_b128 v[140:143], v156
	ds_read_b128 v[166:169], v157
	ds_read_b128 v[170:173], v159
	ds_read_b128 v[174:177], v160
	s_add_u32 s14, s28, 0x44000
	s_addc_u32 s15, s29, 0
	s_mov_b32 m0, s57
	ds_read_b128 v[178:181], v146 offset:32768
	ds_read_b128 v[182:185], v146 offset:33792
	ds_read_b128 v[186:189], v146 offset:34816
	ds_read_b128 v[190:193], v146 offset:35840
	ds_read_b128 v[194:197], v146 offset:36864
	ds_read_b128 v[198:201], v146 offset:37888
	ds_read_b128 v[202:205], v146 offset:38912
	ds_read_b128 v[206:209], v146 offset:39936
	global_load_lds_dwordx4 v130, s[14:15]
	s_mov_b32 m0, s58
	s_nop 0
	global_load_lds_dwordx4 v128, s[14:15]
	s_waitcnt lgkmcnt(8)
	s_barrier
	s_waitcnt lgkmcnt(0)
	s_setprio 1
	s_waitcnt lgkmcnt(0)
	v_mfma_f32_16x16x32_bf16 v[124:127], v[140:143], v[178:181], v[124:127]
	v_mfma_f32_16x16x32_bf16 v[120:123], v[170:173], v[178:181], v[120:123]
	v_mfma_f32_16x16x32_bf16 v[108:111], v[140:143], v[186:189], v[108:111]
	v_mfma_f32_16x16x32_bf16 v[104:107], v[170:173], v[186:189], v[104:107]
	v_mfma_f32_16x16x32_bf16 v[92:95], v[140:143], v[194:197], v[92:95]
	v_mfma_f32_16x16x32_bf16 v[88:91], v[170:173], v[194:197], v[88:91]
	v_mfma_f32_16x16x32_bf16 v[76:79], v[140:143], v[202:205], v[76:79]
	v_mfma_f32_16x16x32_bf16 v[72:75], v[170:173], v[202:205], v[72:75]
	v_mfma_f32_16x16x32_bf16 v[124:127], v[166:169], v[182:185], v[124:127]
	v_mfma_f32_16x16x32_bf16 v[120:123], v[174:177], v[182:185], v[120:123]
	v_mfma_f32_16x16x32_bf16 v[108:111], v[166:169], v[190:193], v[108:111]
	v_mfma_f32_16x16x32_bf16 v[104:107], v[174:177], v[190:193], v[104:107]
	v_mfma_f32_16x16x32_bf16 v[92:95], v[166:169], v[198:201], v[92:95]
	v_mfma_f32_16x16x32_bf16 v[88:91], v[174:177], v[198:201], v[88:91]
	v_mfma_f32_16x16x32_bf16 v[76:79], v[166:169], v[206:209], v[76:79]
	v_mfma_f32_16x16x32_bf16 v[72:75], v[174:177], v[206:209], v[72:75]
	s_setprio 0
	s_barrier
	s_mov_b32 m0, s61
	ds_read_b128 v[210:213], v161
	ds_read_b128 v[214:217], v162
	ds_read_b128 v[218:221], v163
	ds_read_b128 v[222:225], v164
	s_add_u32 s100, s18, 0x80
	s_addc_u32 s101, s19, 0
	global_load_lds_dwordx4 v130, s[100:101]
	s_mov_b32 m0, s62
	s_nop 0
	global_load_lds_dwordx4 v128, s[100:101]
	s_barrier
	s_waitcnt lgkmcnt(0)
	s_setprio 1
	s_waitcnt lgkmcnt(0)
	v_mfma_f32_16x16x32_bf16 v[116:119], v[210:213], v[178:181], v[116:119]
	v_mfma_f32_16x16x32_bf16 v[112:115], v[218:221], v[178:181], v[112:115]
	v_mfma_f32_16x16x32_bf16 v[100:103], v[210:213], v[186:189], v[100:103]
	v_mfma_f32_16x16x32_bf16 v[96:99], v[218:221], v[186:189], v[96:99]
	v_mfma_f32_16x16x32_bf16 v[84:87], v[210:213], v[194:197], v[84:87]
	v_mfma_f32_16x16x32_bf16 v[80:83], v[218:221], v[194:197], v[80:83]
	v_mfma_f32_16x16x32_bf16 v[68:71], v[210:213], v[202:205], v[68:71]
	v_mfma_f32_16x16x32_bf16 v[64:67], v[218:221], v[202:205], v[64:67]
	v_mfma_f32_16x16x32_bf16 v[116:119], v[214:217], v[182:185], v[116:119]
	v_mfma_f32_16x16x32_bf16 v[112:115], v[222:225], v[182:185], v[112:115]
	v_mfma_f32_16x16x32_bf16 v[100:103], v[214:217], v[190:193], v[100:103]
	v_mfma_f32_16x16x32_bf16 v[96:99], v[222:225], v[190:193], v[96:99]
	v_mfma_f32_16x16x32_bf16 v[84:87], v[214:217], v[198:201], v[84:87]
	v_mfma_f32_16x16x32_bf16 v[80:83], v[222:225], v[198:201], v[80:83]
	v_mfma_f32_16x16x32_bf16 v[68:71], v[214:217], v[206:209], v[68:71]
	v_mfma_f32_16x16x32_bf16 v[64:67], v[222:225], v[206:209], v[64:67]
	s_setprio 0
	s_mov_b32 m0, s63
	s_barrier
	ds_read_b128 v[178:181], v146 offset:49152
	ds_read_b128 v[182:185], v146 offset:50176
	ds_read_b128 v[186:189], v146 offset:51200
	ds_read_b128 v[190:193], v146 offset:52224
	ds_read_b128 v[194:197], v146 offset:53248
	ds_read_b128 v[198:201], v146 offset:54272
	ds_read_b128 v[202:205], v146 offset:55296
	ds_read_b128 v[206:209], v146 offset:56320
	s_add_u32 s100, s28, 0x80
	s_addc_u32 s101, s29, 0
	global_load_lds_dwordx4 v130, s[100:101]
	s_mov_b32 m0, s64
	s_nop 0
	global_load_lds_dwordx4 v128, s[100:101]
	s_barrier
	s_waitcnt lgkmcnt(0)
	s_setprio 1
	s_waitcnt lgkmcnt(0)
	v_mfma_f32_16x16x32_bf16 v[60:63], v[140:143], v[178:181], v[60:63]
	v_mfma_f32_16x16x32_bf16 v[56:59], v[170:173], v[178:181], v[56:59]
	v_mfma_f32_16x16x32_bf16 v[44:47], v[140:143], v[186:189], v[44:47]
	v_mfma_f32_16x16x32_bf16 v[40:43], v[170:173], v[186:189], v[40:43]
	v_mfma_f32_16x16x32_bf16 v[28:31], v[140:143], v[194:197], v[28:31]
	v_mfma_f32_16x16x32_bf16 v[24:27], v[170:173], v[194:197], v[24:27]
	v_mfma_f32_16x16x32_bf16 v[12:15], v[140:143], v[202:205], v[12:15]
	v_mfma_f32_16x16x32_bf16 v[8:11], v[170:173], v[202:205], v[8:11]
	v_mfma_f32_16x16x32_bf16 v[60:63], v[166:169], v[182:185], v[60:63]
	v_mfma_f32_16x16x32_bf16 v[56:59], v[174:177], v[182:185], v[56:59]
	v_mfma_f32_16x16x32_bf16 v[44:47], v[166:169], v[190:193], v[44:47]
	v_mfma_f32_16x16x32_bf16 v[40:43], v[174:177], v[190:193], v[40:43]
	v_mfma_f32_16x16x32_bf16 v[28:31], v[166:169], v[198:201], v[28:31]
	v_mfma_f32_16x16x32_bf16 v[24:27], v[174:177], v[198:201], v[24:27]
	v_mfma_f32_16x16x32_bf16 v[12:15], v[166:169], v[206:209], v[12:15]
	v_mfma_f32_16x16x32_bf16 v[8:11], v[174:177], v[206:209], v[8:11]
	s_setprio 0
	s_barrier
	s_add_u32 s14, s18, 0x44080
	s_addc_u32 s15, s19, 0
	s_mov_b32 m0, s65
	s_nop 0
	global_load_lds_dwordx4 v130, s[14:15]
	s_mov_b32 m0, s66
	s_nop 0
	global_load_lds_dwordx4 v128, s[14:15]
	s_waitcnt vmcnt(6)
	s_barrier
; DI float ex2(float x) { return __builtin_amdgcn_exp2f(x); }
; #define PG8_STAMP() do { if (STAMP && wid == 0 && nts < 64) { const unsigned long long _c = 0ull; \
;         ts_lo = (lane == nts) ? (int)(unsigned)_c : ts_lo; ts_hi = (lane == nts) ? (int)(unsigned)(_c >> 32) : ts_hi; ++nts; } } while (0)
; #define PG8_MMA(ai, bj, At, Bt) do { __builtin_amdgcn_s_setprio(1); _Pragma("unroll") for (int m = 0; m < 4; ++m) _Pragma("unroll") for (int n = 0; n < 2; ++n) _Pragma("unroll") for (int k = 0; k < 2; ++k) \
;         acc[ai][bj][m][n] = __builtin_amdgcn_mfma_f32_16x16x32_bf16(Bt[n][k], At[m][k], acc[ai][bj][m][n], 0, 0, 0); __builtin_amdgcn_s_setprio(0); } while (0)
; #define PG8_WAIT_V(n) asm volatile("s_waitcnt vmcnt(" #n ")" ::: "memory")
; #define PG8_BAR __builtin_amdgcn_s_barrier()
;     DI void operator()(const f32x4 (&acc)[2][2][4][2], const Unit& u, int wr, int wc, int fr, int fq) const {
;         const int row0 = u.pm * BM + wr * 64 + fr, hcol0 = ((u.pn * BM + wc * 32) >> 1) + 4 * fq;
; #pragma unroll
;         for (int ai = 0; ai < 2; ++ai)
; #pragma unroll
;             for (int m = 0; m < 4; ++m) { u16* rowp = O + (size_t)(row0 + ai * HALF + m * 16) * ldc + hcol0;
; #pragma unroll
;                 for (int bj = 0; bj < 2; ++bj) { const f32x4 g = acc[ai][bj][m][0], up = acc[ai][bj][m][1]; float r[4];
; #pragma unroll
;                     for (int j = 0; j < 4; ++j) r[j] = g[j] * up[j] * __builtin_amdgcn_rcpf(1.f + ex2(-LOG2E * g[j]));
;                     uint2 w = {pack2(r[0], r[1]), pack2(r[2], r[3])}; *(uint2*)(rowp + bj * (HALF / 2)) = w; } }
; template <class Epi, class Sched, bool STAMP = false>
; __device__ __forceinline__ void gemm_phase(PG8_LAS unsigned char* lds, const Gemm g, const Sched& S, const Epi& E, unsigned long long* stamps) {
;     ...
;             PG8_WAIT_V(6); PG8_BAR; PG8_MMA(1, 1, At, B1); PG8_BAR;
;         }
;         PG8_STAMP();
;         if constexpr (!Epi::AFTER_DRAIN) { E(acc, cur, wr, wc, fr, fq); S.done(cur); }
	s_setprio 1
	v_mfma_f32_16x16x32_bf16 v[52:55], v[210:213], v[178:181], v[52:55]
	v_mfma_f32_16x16x32_bf16 v[48:51], v[218:221], v[178:181], v[48:51]
	v_mfma_f32_16x16x32_bf16 v[36:39], v[210:213], v[186:189], v[36:39]
	v_mfma_f32_16x16x32_bf16 v[32:35], v[218:221], v[186:189], v[32:35]
	v_mfma_f32_16x16x32_bf16 v[20:23], v[210:213], v[194:197], v[20:23]
	v_mfma_f32_16x16x32_bf16 v[16:19], v[218:221], v[194:197], v[16:19]
	v_mfma_f32_16x16x32_bf16 v[4:7], v[210:213], v[202:205], v[4:7]
	v_mfma_f32_16x16x32_bf16 v[0:3], v[218:221], v[202:205], v[0:3]
	v_mfma_f32_16x16x32_bf16 v[52:55], v[214:217], v[182:185], v[52:55]
	v_mfma_f32_16x16x32_bf16 v[48:51], v[222:225], v[182:185], v[48:51]
	v_mfma_f32_16x16x32_bf16 v[36:39], v[214:217], v[190:193], v[36:39]
	v_mfma_f32_16x16x32_bf16 v[32:35], v[222:225], v[190:193], v[32:35]
	v_mfma_f32_16x16x32_bf16 v[20:23], v[214:217], v[198:201], v[20:23]
	v_mfma_f32_16x16x32_bf16 v[16:19], v[222:225], v[198:201], v[16:19]
	v_mfma_f32_16x16x32_bf16 v[4:7], v[214:217], v[206:209], v[4:7]
	v_mfma_f32_16x16x32_bf16 v[0:3], v[222:225], v[206:209], v[0:3]
	s_setprio 0
	s_add_i32 s77, s77, 2
	s_add_u32 s75, s75, 0x100
	s_addc_u32 s76, s76, 0
	s_cmp_gt_u32 s77, 13
	s_mov_b64 s[14:15], s[16:17]
	s_barrier
	s_cbranch_scc0 .LBB0_63
	v_mul_f32_e32 v168, 0xbfb8aa3b, v124
	v_mul_f32_e32 v169, 0xbfb8aa3b, v125
	v_mul_f32_e32 v170, 0xbfb8aa3b, v126
	v_mul_f32_e32 v171, 0xbfb8aa3b, v127
	v_exp_f32_e32 v168, v168
	v_exp_f32_e32 v169, v169
	v_exp_f32_e32 v170, v170
	v_exp_f32_e32 v171, v171
	v_add_f32_e32 v168, 1.0, v168
	v_add_f32_e32 v169, 1.0, v169
	v_add_f32_e32 v170, 1.0, v170
	v_add_f32_e32 v171, 1.0, v171
	v_rcp_f32_e32 v168, v168
	v_rcp_f32_e32 v169, v169
	v_rcp_f32_e32 v170, v170
	v_rcp_f32_e32 v171, v171
	s_lshl_b32 s10, s74, 8
	v_pk_mul_f32 v[122:123], v[126:127], v[122:123]
	v_pk_mul_f32 v[120:121], v[124:125], v[120:121]
	s_or_b32 s10, s10, s60
	v_pk_mul_f32 v[120:121], v[120:121], v[168:169]
	v_pk_mul_f32 v[122:123], v[122:123], v[170:171]
	s_ashr_i32 s10, s10, 1
	v_cvt_pk_bf16_f32 v120, v120, v121
	v_cvt_pk_bf16_f32 v121, v122, v123
	v_mul_f32_e32 v122, 0xbfb8aa3b, v116
	v_mul_f32_e32 v123, 0xbfb8aa3b, v117
	v_or_b32_e32 v140, s10, v147
	v_exp_f32_e32 v122, v122
	v_exp_f32_e32 v123, v123
	v_lshl_add_u32 v165, s73, 8, v145
	v_ashrrev_i32_e32 v141, 31, v140
	v_mov_b64_e32 v[142:143], s[12:13]
	v_mad_i64_i32 v[166:167], s[14:15], v165, s70, v[142:143]
	v_lshlrev_b64 v[140:141], 1, v[140:141]
	v_lshl_add_u64 v[166:167], v[166:167], 0, v[140:141]
	global_store_dwordx2 v[166:167], v[120:121], off
	v_add_f32_e32 v120, 1.0, v122
	v_add_f32_e32 v121, 1.0, v123
	v_mul_f32_e32 v122, 0xbfb8aa3b, v118
	v_mul_f32_e32 v123, 0xbfb8aa3b, v119
	v_exp_f32_e32 v122, v122
	v_exp_f32_e32 v123, v123
	v_rcp_f32_e32 v120, v120
	v_rcp_f32_e32 v121, v121
	v_add_f32_e32 v122, 1.0, v122
	v_add_f32_e32 v123, 1.0, v123
	v_rcp_f32_e32 v122, v122
	v_rcp_f32_e32 v123, v123
	v_pk_mul_f32 v[114:115], v[118:119], v[114:115]
	v_pk_mul_f32 v[112:113], v[116:117], v[112:113]
	v_mul_f32_e32 v116, 0xbfb8aa3b, v110
	v_pk_mul_f32 v[112:113], v[112:113], v[120:121]
	v_pk_mul_f32 v[114:115], v[114:115], v[122:123]
	v_cvt_pk_bf16_f32 v112, v112, v113
	v_cvt_pk_bf16_f32 v113, v114, v115
	v_mul_f32_e32 v114, 0xbfb8aa3b, v108
	v_mul_f32_e32 v115, 0xbfb8aa3b, v109
	v_mul_f32_e32 v117, 0xbfb8aa3b, v111
	v_exp_f32_e32 v114, v114
	v_exp_f32_e32 v115, v115
	v_exp_f32_e32 v116, v116
	v_exp_f32_e32 v117, v117
	v_add_f32_e32 v114, 1.0, v114
	v_add_f32_e32 v115, 1.0, v115
	v_add_f32_e32 v116, 1.0, v116
	v_add_f32_e32 v117, 1.0, v117
	v_rcp_f32_e32 v114, v114
	v_rcp_f32_e32 v115, v115
	v_rcp_f32_e32 v116, v116
	v_rcp_f32_e32 v117, v117
	v_pk_mul_f32 v[106:107], v[110:111], v[106:107]
	v_pk_mul_f32 v[104:105], v[108:109], v[104:105]
	global_store_dwordx2 v[166:167], v[112:113], off offset:128
	v_pk_mul_f32 v[104:105], v[104:105], v[114:115]
	v_pk_mul_f32 v[106:107], v[106:107], v[116:117]
	v_cvt_pk_bf16_f32 v104, v104, v105
	v_cvt_pk_bf16_f32 v105, v106, v107
	v_mul_f32_e32 v106, 0xbfb8aa3b, v100
	v_mul_f32_e32 v107, 0xbfb8aa3b, v101
	v_exp_f32_e32 v106, v106
	v_exp_f32_e32 v107, v107
	v_or_b32_e32 v112, 16, v165
	v_mad_i64_i32 v[112:113], s[14:15], v112, s70, v[142:143]
	v_lshl_add_u64 v[112:113], v[112:113], 0, v[140:141]
	global_store_dwordx2 v[112:113], v[104:105], off
	v_add_f32_e32 v104, 1.0, v106
	v_add_f32_e32 v105, 1.0, v107
	v_mul_f32_e32 v106, 0xbfb8aa3b, v102
	v_mul_f32_e32 v107, 0xbfb8aa3b, v103
	v_exp_f32_e32 v106, v106
	v_exp_f32_e32 v107, v107
	v_rcp_f32_e32 v104, v104
	v_rcp_f32_e32 v105, v105
	v_add_f32_e32 v106, 1.0, v106
	v_add_f32_e32 v107, 1.0, v107
	v_rcp_f32_e32 v106, v106
	v_rcp_f32_e32 v107, v107
	v_pk_mul_f32 v[98:99], v[102:103], v[98:99]
	v_pk_mul_f32 v[96:97], v[100:101], v[96:97]
	v_mul_f32_e32 v100, 0xbfb8aa3b, v94
	v_pk_mul_f32 v[96:97], v[96:97], v[104:105]
	v_pk_mul_f32 v[98:99], v[98:99], v[106:107]
	v_cvt_pk_bf16_f32 v96, v96, v97
	v_cvt_pk_bf16_f32 v97, v98, v99
	v_mul_f32_e32 v98, 0xbfb8aa3b, v92
	v_mul_f32_e32 v99, 0xbfb8aa3b, v93
	v_mul_f32_e32 v101, 0xbfb8aa3b, v95
	v_exp_f32_e32 v98, v98
	v_exp_f32_e32 v99, v99
	v_exp_f32_e32 v100, v100
	v_exp_f32_e32 v101, v101
	v_add_f32_e32 v98, 1.0, v98
	v_add_f32_e32 v99, 1.0, v99
	v_add_f32_e32 v100, 1.0, v100
	v_add_f32_e32 v101, 1.0, v101
	v_rcp_f32_e32 v98, v98
	v_rcp_f32_e32 v99, v99
	v_rcp_f32_e32 v100, v100
	v_rcp_f32_e32 v101, v101
	v_pk_mul_f32 v[90:91], v[94:95], v[90:91]
	v_pk_mul_f32 v[88:89], v[92:93], v[88:89]
	global_store_dwordx2 v[112:113], v[96:97], off offset:128
	v_pk_mul_f32 v[88:89], v[88:89], v[98:99]
	v_pk_mul_f32 v[90:91], v[90:91], v[100:101]
; DI float ex2(float x) { return __builtin_amdgcn_exp2f(x); }
;     DI void operator()(const f32x4 (&acc)[2][2][4][2], const Unit& u, int wr, int wc, int fr, int fq) const {
;         const int row0 = u.pm * BM + wr * 64 + fr, hcol0 = ((u.pn * BM + wc * 32) >> 1) + 4 * fq;
; #pragma unroll
;         for (int ai = 0; ai < 2; ++ai)
; #pragma unroll
;             for (int m = 0; m < 4; ++m) { u16* rowp = O + (size_t)(row0 + ai * HALF + m * 16) * ldc + hcol0;
; #pragma unroll
;                 for (int bj = 0; bj < 2; ++bj) { const f32x4 g = acc[ai][bj][m][0], up = acc[ai][bj][m][1]; float r[4];
; #pragma unroll
;                     for (int j = 0; j < 4; ++j) r[j] = g[j] * up[j] * __builtin_amdgcn_rcpf(1.f + ex2(-LOG2E * g[j]));
;                     uint2 w = {pack2(r[0], r[1]), pack2(r[2], r[3])}; *(uint2*)(rowp + bj * (HALF / 2)) = w; } }
	v_cvt_pk_bf16_f32 v88, v88, v89
	v_cvt_pk_bf16_f32 v89, v90, v91
	v_mul_f32_e32 v90, 0xbfb8aa3b, v84
	v_mul_f32_e32 v91, 0xbfb8aa3b, v85
	v_exp_f32_e32 v90, v90
	v_exp_f32_e32 v91, v91
	v_or_b32_e32 v96, 32, v165
	v_mad_i64_i32 v[96:97], s[14:15], v96, s70, v[142:143]
	v_lshl_add_u64 v[96:97], v[96:97], 0, v[140:141]
	global_store_dwordx2 v[96:97], v[88:89], off
	v_add_f32_e32 v88, 1.0, v90
	v_add_f32_e32 v89, 1.0, v91
	v_mul_f32_e32 v90, 0xbfb8aa3b, v86
	v_mul_f32_e32 v91, 0xbfb8aa3b, v87
	v_exp_f32_e32 v90, v90
	v_exp_f32_e32 v91, v91
	v_rcp_f32_e32 v88, v88
	v_rcp_f32_e32 v89, v89
	v_add_f32_e32 v90, 1.0, v90
	v_add_f32_e32 v91, 1.0, v91
	v_rcp_f32_e32 v90, v90
	v_rcp_f32_e32 v91, v91
	v_pk_mul_f32 v[82:83], v[86:87], v[82:83]
	v_pk_mul_f32 v[80:81], v[84:85], v[80:81]
	v_mul_f32_e32 v84, 0xbfb8aa3b, v78
	v_pk_mul_f32 v[80:81], v[80:81], v[88:89]
	v_pk_mul_f32 v[82:83], v[82:83], v[90:91]
	v_cvt_pk_bf16_f32 v80, v80, v81
	v_cvt_pk_bf16_f32 v81, v82, v83
	v_mul_f32_e32 v82, 0xbfb8aa3b, v76
	v_mul_f32_e32 v83, 0xbfb8aa3b, v77
	v_mul_f32_e32 v85, 0xbfb8aa3b, v79
	v_exp_f32_e32 v82, v82
	v_exp_f32_e32 v83, v83
	v_exp_f32_e32 v84, v84
	v_exp_f32_e32 v85, v85
	v_add_f32_e32 v82, 1.0, v82
	v_add_f32_e32 v83, 1.0, v83
	v_add_f32_e32 v84, 1.0, v84
	v_add_f32_e32 v85, 1.0, v85
	v_rcp_f32_e32 v82, v82
	v_rcp_f32_e32 v83, v83
	v_rcp_f32_e32 v84, v84
	v_rcp_f32_e32 v85, v85
	v_pk_mul_f32 v[74:75], v[78:79], v[74:75]
	v_pk_mul_f32 v[72:73], v[76:77], v[72:73]
	global_store_dwordx2 v[96:97], v[80:81], off offset:128
	v_pk_mul_f32 v[72:73], v[72:73], v[82:83]
	v_pk_mul_f32 v[74:75], v[74:75], v[84:85]
	v_cvt_pk_bf16_f32 v72, v72, v73
	v_cvt_pk_bf16_f32 v73, v74, v75
	v_mul_f32_e32 v74, 0xbfb8aa3b, v68
	v_mul_f32_e32 v75, 0xbfb8aa3b, v69
	v_exp_f32_e32 v74, v74
	v_exp_f32_e32 v75, v75
	v_or_b32_e32 v80, 48, v165
	v_mad_i64_i32 v[80:81], s[14:15], v80, s70, v[142:143]
	v_lshl_add_u64 v[80:81], v[80:81], 0, v[140:141]
	global_store_dwordx2 v[80:81], v[72:73], off
	v_add_f32_e32 v72, 1.0, v74
	v_add_f32_e32 v73, 1.0, v75
	v_mul_f32_e32 v74, 0xbfb8aa3b, v70
	v_mul_f32_e32 v75, 0xbfb8aa3b, v71
	v_exp_f32_e32 v74, v74
	v_exp_f32_e32 v75, v75
	v_rcp_f32_e32 v72, v72
	v_rcp_f32_e32 v73, v73
	v_add_f32_e32 v74, 1.0, v74
	v_add_f32_e32 v75, 1.0, v75
	v_rcp_f32_e32 v74, v74
	v_rcp_f32_e32 v75, v75
	v_pk_mul_f32 v[66:67], v[70:71], v[66:67]
	v_pk_mul_f32 v[64:65], v[68:69], v[64:65]
	v_mul_f32_e32 v68, 0xbfb8aa3b, v62
	v_pk_mul_f32 v[64:65], v[64:65], v[72:73]
	v_pk_mul_f32 v[66:67], v[66:67], v[74:75]
	v_cvt_pk_bf16_f32 v64, v64, v65
	v_cvt_pk_bf16_f32 v65, v66, v67
	v_mul_f32_e32 v66, 0xbfb8aa3b, v60
	v_mul_f32_e32 v67, 0xbfb8aa3b, v61
	v_mul_f32_e32 v69, 0xbfb8aa3b, v63
	v_exp_f32_e32 v66, v66
	v_exp_f32_e32 v67, v67
	v_exp_f32_e32 v68, v68
	v_exp_f32_e32 v69, v69
	v_add_f32_e32 v66, 1.0, v66
	v_add_f32_e32 v67, 1.0, v67
	v_add_f32_e32 v68, 1.0, v68
	v_add_f32_e32 v69, 1.0, v69
	v_rcp_f32_e32 v66, v66
	v_rcp_f32_e32 v67, v67
	v_rcp_f32_e32 v68, v68
	v_rcp_f32_e32 v69, v69
	v_pk_mul_f32 v[58:59], v[62:63], v[58:59]
	v_pk_mul_f32 v[56:57], v[60:61], v[56:57]
	global_store_dwordx2 v[80:81], v[64:65], off offset:128
	v_pk_mul_f32 v[56:57], v[56:57], v[66:67]
	v_pk_mul_f32 v[58:59], v[58:59], v[68:69]
	v_cvt_pk_bf16_f32 v56, v56, v57
	v_cvt_pk_bf16_f32 v57, v58, v59
	v_mul_f32_e32 v58, 0xbfb8aa3b, v52
	v_mul_f32_e32 v59, 0xbfb8aa3b, v53
	v_exp_f32_e32 v58, v58
	v_exp_f32_e32 v59, v59
	v_add_u32_e32 v64, 0x80, v165
	v_mad_i64_i32 v[64:65], s[14:15], v64, s70, v[142:143]
	v_lshl_add_u64 v[64:65], v[64:65], 0, v[140:141]
	global_store_dwordx2 v[64:65], v[56:57], off
	v_add_f32_e32 v56, 1.0, v58
	v_add_f32_e32 v57, 1.0, v59
	v_mul_f32_e32 v58, 0xbfb8aa3b, v54
	v_mul_f32_e32 v59, 0xbfb8aa3b, v55
	v_exp_f32_e32 v58, v58
	v_exp_f32_e32 v59, v59
	v_rcp_f32_e32 v56, v56
	v_rcp_f32_e32 v57, v57
	v_add_f32_e32 v58, 1.0, v58
	v_add_f32_e32 v59, 1.0, v59
	v_rcp_f32_e32 v58, v58
	v_rcp_f32_e32 v59, v59
	v_pk_mul_f32 v[50:51], v[54:55], v[50:51]
	v_pk_mul_f32 v[48:49], v[52:53], v[48:49]
	v_mul_f32_e32 v52, 0xbfb8aa3b, v46
	v_pk_mul_f32 v[48:49], v[48:49], v[56:57]
	v_pk_mul_f32 v[50:51], v[50:51], v[58:59]
	v_cvt_pk_bf16_f32 v48, v48, v49
	v_cvt_pk_bf16_f32 v49, v50, v51
	v_mul_f32_e32 v50, 0xbfb8aa3b, v44
	v_mul_f32_e32 v51, 0xbfb8aa3b, v45
	v_mul_f32_e32 v53, 0xbfb8aa3b, v47
	v_exp_f32_e32 v50, v50
	v_exp_f32_e32 v51, v51
	v_exp_f32_e32 v52, v52
	v_exp_f32_e32 v53, v53
	v_add_f32_e32 v50, 1.0, v50
	v_add_f32_e32 v51, 1.0, v51
	v_add_f32_e32 v52, 1.0, v52
	v_add_f32_e32 v53, 1.0, v53
	v_rcp_f32_e32 v50, v50
	v_rcp_f32_e32 v51, v51
	v_rcp_f32_e32 v52, v52
	v_rcp_f32_e32 v53, v53
	v_pk_mul_f32 v[42:43], v[46:47], v[42:43]
	v_pk_mul_f32 v[40:41], v[44:45], v[40:41]
	global_store_dwordx2 v[64:65], v[48:49], off offset:128
	v_pk_mul_f32 v[40:41], v[40:41], v[50:51]
	v_pk_mul_f32 v[42:43], v[42:43], v[52:53]
	v_cvt_pk_bf16_f32 v40, v40, v41
	v_cvt_pk_bf16_f32 v41, v42, v43
	v_mul_f32_e32 v42, 0xbfb8aa3b, v36
	v_mul_f32_e32 v43, 0xbfb8aa3b, v37
	v_exp_f32_e32 v42, v42
	v_exp_f32_e32 v43, v43
	v_add_u32_e32 v48, 0x90, v165
	v_mad_i64_i32 v[48:49], s[14:15], v48, s70, v[142:143]
	v_lshl_add_u64 v[48:49], v[48:49], 0, v[140:141]
	global_store_dwordx2 v[48:49], v[40:41], off
	v_add_f32_e32 v40, 1.0, v42
	v_add_f32_e32 v41, 1.0, v43
	v_mul_f32_e32 v42, 0xbfb8aa3b, v38
	v_mul_f32_e32 v43, 0xbfb8aa3b, v39
	v_exp_f32_e32 v42, v42
	v_exp_f32_e32 v43, v43
	v_rcp_f32_e32 v40, v40
	v_rcp_f32_e32 v41, v41
	v_add_f32_e32 v42, 1.0, v42
	v_add_f32_e32 v43, 1.0, v43
	v_rcp_f32_e32 v42, v42
	v_rcp_f32_e32 v43, v43
	v_pk_mul_f32 v[34:35], v[38:39], v[34:35]
	v_pk_mul_f32 v[32:33], v[36:37], v[32:33]
; DI float ex2(float x) { return __builtin_amdgcn_exp2f(x); }
;     DI void operator()(const f32x4 (&acc)[2][2][4][2], const Unit& u, int wr, int wc, int fr, int fq) const {
;         const int row0 = u.pm * BM + wr * 64 + fr, hcol0 = ((u.pn * BM + wc * 32) >> 1) + 4 * fq;
; #pragma unroll
;         for (int ai = 0; ai < 2; ++ai)
; #pragma unroll
;             for (int m = 0; m < 4; ++m) { u16* rowp = O + (size_t)(row0 + ai * HALF + m * 16) * ldc + hcol0;
; #pragma unroll
;                 for (int bj = 0; bj < 2; ++bj) { const f32x4 g = acc[ai][bj][m][0], up = acc[ai][bj][m][1]; float r[4];
; #pragma unroll
;                     for (int j = 0; j < 4; ++j) r[j] = g[j] * up[j] * __builtin_amdgcn_rcpf(1.f + ex2(-LOG2E * g[j]));
;                     uint2 w = {pack2(r[0], r[1]), pack2(r[2], r[3])}; *(uint2*)(rowp + bj * (HALF / 2)) = w; } }
; template <class Epi, class Sched, bool STAMP = false>
; __device__ __forceinline__ void gemm_phase(PG8_LAS unsigned char* lds, const Gemm g, const Sched& S, const Epi& E, unsigned long long* stamps) {
;     ...
; #pragma unroll
;         for (int a = 0; a < 2; ++a)
; #pragma unroll
;             for (int b = 0; b < 2; ++b)
; #pragma unroll
;                 for (int m = 0; m < 4; ++m)
; #pragma unroll
;                     for (int n = 0; n < 2; ++n) acc[a][b][m][n] = (f32x4){0.f, 0.f, 0.f, 0.f};
	v_mul_f32_e32 v36, 0xbfb8aa3b, v30
	v_pk_mul_f32 v[32:33], v[32:33], v[40:41]
	v_pk_mul_f32 v[34:35], v[34:35], v[42:43]
	v_cvt_pk_bf16_f32 v32, v32, v33
	v_cvt_pk_bf16_f32 v33, v34, v35
	v_mul_f32_e32 v34, 0xbfb8aa3b, v28
	v_mul_f32_e32 v35, 0xbfb8aa3b, v29
	v_mul_f32_e32 v37, 0xbfb8aa3b, v31
	v_exp_f32_e32 v34, v34
	v_exp_f32_e32 v35, v35
	v_exp_f32_e32 v36, v36
	v_exp_f32_e32 v37, v37
	v_add_f32_e32 v34, 1.0, v34
	v_add_f32_e32 v35, 1.0, v35
	v_add_f32_e32 v36, 1.0, v36
	v_add_f32_e32 v37, 1.0, v37
	v_rcp_f32_e32 v34, v34
	v_rcp_f32_e32 v35, v35
	v_rcp_f32_e32 v36, v36
	v_rcp_f32_e32 v37, v37
	v_pk_mul_f32 v[26:27], v[30:31], v[26:27]
	v_pk_mul_f32 v[24:25], v[28:29], v[24:25]
	global_store_dwordx2 v[48:49], v[32:33], off offset:128
	v_pk_mul_f32 v[24:25], v[24:25], v[34:35]
	v_pk_mul_f32 v[26:27], v[26:27], v[36:37]
	v_cvt_pk_bf16_f32 v24, v24, v25
	v_cvt_pk_bf16_f32 v25, v26, v27
	v_mul_f32_e32 v26, 0xbfb8aa3b, v20
	v_mul_f32_e32 v27, 0xbfb8aa3b, v21
	v_exp_f32_e32 v26, v26
	v_exp_f32_e32 v27, v27
	v_add_u32_e32 v32, 0xa0, v165
	v_mad_i64_i32 v[32:33], s[14:15], v32, s70, v[142:143]
	v_lshl_add_u64 v[32:33], v[32:33], 0, v[140:141]
	global_store_dwordx2 v[32:33], v[24:25], off
	v_add_f32_e32 v24, 1.0, v26
	v_add_f32_e32 v25, 1.0, v27
	v_mul_f32_e32 v26, 0xbfb8aa3b, v22
	v_mul_f32_e32 v27, 0xbfb8aa3b, v23
	v_exp_f32_e32 v26, v26
	v_exp_f32_e32 v27, v27
	v_rcp_f32_e32 v24, v24
	v_rcp_f32_e32 v25, v25
	v_add_f32_e32 v26, 1.0, v26
	v_add_f32_e32 v27, 1.0, v27
	v_rcp_f32_e32 v26, v26
	v_rcp_f32_e32 v27, v27
	v_pk_mul_f32 v[18:19], v[22:23], v[18:19]
	v_pk_mul_f32 v[16:17], v[20:21], v[16:17]
	v_mul_f32_e32 v20, 0xbfb8aa3b, v14
	v_pk_mul_f32 v[16:17], v[16:17], v[24:25]
	v_pk_mul_f32 v[18:19], v[18:19], v[26:27]
	v_cvt_pk_bf16_f32 v16, v16, v17
	v_cvt_pk_bf16_f32 v17, v18, v19
	v_mul_f32_e32 v18, 0xbfb8aa3b, v12
	v_mul_f32_e32 v19, 0xbfb8aa3b, v13
	v_mul_f32_e32 v21, 0xbfb8aa3b, v15
	v_exp_f32_e32 v18, v18
	v_exp_f32_e32 v19, v19
	v_exp_f32_e32 v20, v20
	v_exp_f32_e32 v21, v21
	v_add_f32_e32 v18, 1.0, v18
	v_add_f32_e32 v19, 1.0, v19
	v_add_f32_e32 v20, 1.0, v20
	v_add_f32_e32 v21, 1.0, v21
	v_rcp_f32_e32 v18, v18
	v_rcp_f32_e32 v19, v19
	v_rcp_f32_e32 v20, v20
	v_rcp_f32_e32 v21, v21
	v_pk_mul_f32 v[10:11], v[14:15], v[10:11]
	v_pk_mul_f32 v[8:9], v[12:13], v[8:9]
	global_store_dwordx2 v[32:33], v[16:17], off offset:128
	v_pk_mul_f32 v[8:9], v[8:9], v[18:19]
	v_pk_mul_f32 v[10:11], v[10:11], v[20:21]
	v_cvt_pk_bf16_f32 v8, v8, v9
	v_cvt_pk_bf16_f32 v9, v10, v11
	v_mul_f32_e32 v10, 0xbfb8aa3b, v4
	v_mul_f32_e32 v11, 0xbfb8aa3b, v5
	v_exp_f32_e32 v10, v10
	v_exp_f32_e32 v11, v11
	v_add_u32_e32 v16, 0xb0, v165
	v_mad_i64_i32 v[16:17], s[14:15], v16, s70, v[142:143]
	v_lshl_add_u64 v[16:17], v[16:17], 0, v[140:141]
	global_store_dwordx2 v[16:17], v[8:9], off
	v_add_f32_e32 v8, 1.0, v10
	v_add_f32_e32 v9, 1.0, v11
	v_mul_f32_e32 v10, 0xbfb8aa3b, v6
	v_mul_f32_e32 v11, 0xbfb8aa3b, v7
	v_exp_f32_e32 v10, v10
	v_exp_f32_e32 v11, v11
	v_rcp_f32_e32 v8, v8
	v_rcp_f32_e32 v9, v9
	v_add_f32_e32 v10, 1.0, v10
	v_add_f32_e32 v11, 1.0, v11
	v_rcp_f32_e32 v10, v10
	v_rcp_f32_e32 v11, v11
	v_pk_mul_f32 v[2:3], v[6:7], v[2:3]
	v_pk_mul_f32 v[0:1], v[4:5], v[0:1]
	s_and_b64 vcc, exec, s[2:3]
	v_pk_mul_f32 v[0:1], v[0:1], v[8:9]
	v_pk_mul_f32 v[2:3], v[2:3], v[10:11]
	v_cvt_pk_bf16_f32 v0, v0, v1
	v_cvt_pk_bf16_f32 v1, v2, v3
	s_mov_b32 s74, s71
	s_mov_b32 s73, s72
	s_mov_b64 s[16:17], s[0:1]
	s_mov_b64 s[14:15], s[4:5]
	global_store_dwordx2 v[16:17], v[0:1], off offset:128
	s_cbranch_vccz .LBB0_56
	s_branch .Lgu1_done
.Lgu1_half_loop_z:
	v_mov_b32_e32 v0, 0
	v_mov_b32_e32 v1, v0
	v_mov_b32_e32 v2, v0
	v_mov_b32_e32 v3, v0
	v_mov_b32_e32 v4, v0
	v_mov_b32_e32 v5, v0
	v_mov_b32_e32 v6, v0
	v_mov_b32_e32 v7, v0
	v_mov_b32_e32 v16, v0
	v_mov_b32_e32 v17, v0
	v_mov_b32_e32 v18, v0
	v_mov_b32_e32 v19, v0
	v_mov_b32_e32 v20, v0
	v_mov_b32_e32 v21, v0
	v_mov_b32_e32 v22, v0
	v_mov_b32_e32 v23, v0
	v_mov_b32_e32 v32, v0
	v_mov_b32_e32 v33, v0
	v_mov_b32_e32 v34, v0
	v_mov_b32_e32 v35, v0
	v_mov_b32_e32 v36, v0
	v_mov_b32_e32 v37, v0
	v_mov_b32_e32 v38, v0
	v_mov_b32_e32 v39, v0
	v_mov_b32_e32 v48, v0
	v_mov_b32_e32 v49, v0
	v_mov_b32_e32 v50, v0
	v_mov_b32_e32 v51, v0
	v_mov_b32_e32 v52, v0
	v_mov_b32_e32 v53, v0
	v_mov_b32_e32 v54, v0
	v_mov_b32_e32 v55, v0
	v_mov_b32_e32 v8, v0
	v_mov_b32_e32 v9, v0
	v_mov_b32_e32 v10, v0
	v_mov_b32_e32 v11, v0
	v_mov_b32_e32 v12, v0
	v_mov_b32_e32 v13, v0
	v_mov_b32_e32 v14, v0
	v_mov_b32_e32 v15, v0
	v_mov_b32_e32 v24, v0
	v_mov_b32_e32 v25, v0
	v_mov_b32_e32 v26, v0
	v_mov_b32_e32 v27, v0
	v_mov_b32_e32 v28, v0
	v_mov_b32_e32 v29, v0
	v_mov_b32_e32 v30, v0
	v_mov_b32_e32 v31, v0
	v_mov_b32_e32 v40, v0
	v_mov_b32_e32 v41, v0
	v_mov_b32_e32 v42, v0
	v_mov_b32_e32 v43, v0
	v_mov_b32_e32 v44, v0
	v_mov_b32_e32 v45, v0
	v_mov_b32_e32 v46, v0
	v_mov_b32_e32 v47, v0
	v_mov_b32_e32 v56, v0
	v_mov_b32_e32 v57, v0
	v_mov_b32_e32 v58, v0
	v_mov_b32_e32 v59, v0
	v_mov_b32_e32 v60, v0
	v_mov_b32_e32 v61, v0
	v_mov_b32_e32 v62, v0
	v_mov_b32_e32 v63, v0
	v_mov_b32_e32 v64, v0
	v_mov_b32_e32 v65, v0
	v_mov_b32_e32 v66, v0
	v_mov_b32_e32 v67, v0
	v_mov_b32_e32 v68, v0
	v_mov_b32_e32 v69, v0
	v_mov_b32_e32 v70, v0
	v_mov_b32_e32 v71, v0
	v_mov_b32_e32 v80, v0
	v_mov_b32_e32 v81, v0
	v_mov_b32_e32 v82, v0
	v_mov_b32_e32 v83, v0
	v_mov_b32_e32 v84, v0
	v_mov_b32_e32 v85, v0
	v_mov_b32_e32 v86, v0
	v_mov_b32_e32 v87, v0
	v_mov_b32_e32 v96, v0
	v_mov_b32_e32 v97, v0
	v_mov_b32_e32 v98, v0
	v_mov_b32_e32 v99, v0
	v_mov_b32_e32 v100, v0
	v_mov_b32_e32 v101, v0
	v_mov_b32_e32 v102, v0
	v_mov_b32_e32 v103, v0
	v_mov_b32_e32 v112, v0
	v_mov_b32_e32 v113, v0
	v_mov_b32_e32 v114, v0
	v_mov_b32_e32 v115, v0
	v_mov_b32_e32 v116, v0
	v_mov_b32_e32 v117, v0
	v_mov_b32_e32 v118, v0
	v_mov_b32_e32 v119, v0
	v_mov_b32_e32 v72, v0
	v_mov_b32_e32 v73, v0
	v_mov_b32_e32 v74, v0
	v_mov_b32_e32 v75, v0
	v_mov_b32_e32 v76, v0
	v_mov_b32_e32 v77, v0
	v_mov_b32_e32 v78, v0
	v_mov_b32_e32 v79, v0
	v_mov_b32_e32 v88, v0
	v_mov_b32_e32 v89, v0
	v_mov_b32_e32 v90, v0
	v_mov_b32_e32 v91, v0
	v_mov_b32_e32 v92, v0
	v_mov_b32_e32 v93, v0
	v_mov_b32_e32 v94, v0
	v_mov_b32_e32 v95, v0
	v_mov_b32_e32 v104, v0
	v_mov_b32_e32 v105, v0
	v_mov_b32_e32 v106, v0
	v_mov_b32_e32 v107, v0
	v_mov_b32_e32 v108, v0
	v_mov_b32_e32 v109, v0
	v_mov_b32_e32 v110, v0
	v_mov_b32_e32 v111, v0
	v_mov_b32_e32 v120, v0
	v_mov_b32_e32 v121, v0
	v_mov_b32_e32 v122, v0
	v_mov_b32_e32 v123, v0
	v_mov_b32_e32 v124, v0
	v_mov_b32_e32 v125, v0
	v_mov_b32_e32 v126, v0
	v_mov_b32_e32 v127, v0

; #define PG8_STAGE(bufoff, gbase, voff) do { _Pragma("unroll") for (int _i = 0; _i < 2; ++_i) \
;         __builtin_amdgcn_global_load_lds((const unsigned*)((const char*)(gbase) + (voff)[_i]), (PG8_LAS unsigned*)(lds + (bufoff) + ldsw + _i * 8192), 16, 0, 0); } while (0)
; #define PG8_LDA(dst, b, h) do { _Pragma("unroll") for (int m = 0; m < 4; ++m) _Pragma("unroll") for (int k = 0; k < 2; ++k) dst[m][k] = *(const PG8_LAS bf16x8*)(lds + PG8_SA(b, h) + aoff + m * 2048 + k * 1024); } while (0)
; #define PG8_LDB(dst, b, h) do { _Pragma("unroll") for (int n = 0; n < 2; ++n) _Pragma("unroll") for (int k = 0; k < 2; ++k) dst[n][k] = *(const PG8_LAS bf16x8*)(lds + PG8_SB(b, h) + boff + n * 2048 + k * 1024); } while (0)
; #define PG8_WAIT_V(n) asm volatile("s_waitcnt vmcnt(" #n ")" ::: "memory")
; #define PG8_WAIT_L(n) asm volatile("s_waitcnt lgkmcnt(" #n ")" ::: "memory")
; #define PG8_BAR __builtin_amdgcn_s_barrier()
; template <class Epi, class Sched, bool STAMP = false>
; __device__ __forceinline__ void gemm_phase(PG8_LAS unsigned char* lds, const Gemm g, const Sched& S, const Epi& E, unsigned long long* stamps) {
;     ...
;     for (;;) {
;         const bool has_next = S.next(ui + 1, nxt);
;         const char* nA = has_next ? (const char*)g.A + (size_t)nxt.pm * tstep : cA; const char* nB = has_next ? (const char*)g.Bt + (size_t)nxt.pn * tstep : cB;
;         for (int t = 0; t < nt; t += 2) {
;             const bool last = (t == nt - 2);
;             const char* a1 = cA + (size_t)(t + 1) * kstep;
;             const char* a2 = last ? nA : cA + (size_t)(t + 2) * kstep; const char* b2 = last ? nB : cB + (size_t)(t + 2) * kstep;
;             const char* a3 = a2 + kstep; const char* b3 = b2 + kstep;
;             if (last && has_next) S.a_ready(nxt);
;             PG8_LDB(B0, 0, 0); PG8_SCHED; PG8_LDA(At, 0, 0); PG8_STAGE(PG8_SA(1, 1), a1 + hstep, voffA);
;             PG8_WAIT_L(8); PG8_BAR; PG8_WAIT_L(0); PG8_MMA(0, 0, At, B0); PG8_BAR; PG8_SCHED;
;             PG8_LDB(B1, 0, 1); PG8_STAGE(PG8_SB(0, 0), b2, voffB);
;             PG8_BAR; PG8_WAIT_L(0); PG8_MMA(0, 1, At, B1); PG8_BAR;
;             PG8_LDA(At, 0, 1); PG8_STAGE(PG8_SA(0, 0), a2, voffA);
;             PG8_BAR; PG8_WAIT_L(0); PG8_MMA(1, 0, At, B0); PG8_BAR; PG8_SCHED;
;             PG8_STAGE(PG8_SB(0, 1), b2 + hstep, voffB);
;             PG8_WAIT_V(6); PG8_BAR; PG8_MMA(1, 1, At, B1); PG8_BAR;
.LBB0_96:
	s_add_u32 s88, s52, 0x100
	s_addc_u32 s89, s53, 0
	s_mov_b32 s90, -2
	ds_read_b128 v[166:169], v148
	ds_read_b128 v[170:173], v149
	ds_read_b128 v[174:177], v150
	ds_read_b128 v[178:181], v151
	s_add_u32 s52, s34, 0x100
	s_addc_u32 s53, s35, 0
	s_cmp_eq_u32 s90, 40
	s_cselect_b32 s57, s5, s53
	s_cselect_b32 s56, s4, s52
	s_cselect_b32 s55, s1, s89
	s_cselect_b32 s54, s0, s88
	s_mov_b32 m0, s76
	ds_read_b128 v[182:185], v146
	ds_read_b128 v[186:189], v146 offset:1024
	ds_read_b128 v[190:193], v146 offset:2048
	ds_read_b128 v[194:197], v146 offset:3072
	ds_read_b128 v[198:201], v146 offset:4096
	ds_read_b128 v[202:205], v146 offset:5120
	ds_read_b128 v[206:209], v146 offset:6144
	ds_read_b128 v[210:213], v146 offset:7168
	global_load_lds_dwordx4 v136, s[34:35]
	s_mov_b32 m0, s77
	s_nop 0
	global_load_lds_dwordx4 v138, s[34:35]
	s_waitcnt lgkmcnt(8)
	s_barrier
	s_waitcnt lgkmcnt(0)
	s_setprio 1
	s_waitcnt lgkmcnt(0)
	v_mfma_f32_16x16x32_bf16 v[124:127], v[166:169], v[182:185], 0
	v_mfma_f32_16x16x32_bf16 v[120:123], v[174:177], v[182:185], 0
	v_mfma_f32_16x16x32_bf16 v[116:119], v[166:169], v[190:193], 0
	v_mfma_f32_16x16x32_bf16 v[112:115], v[174:177], v[190:193], 0
	v_mfma_f32_16x16x32_bf16 v[100:103], v[166:169], v[198:201], 0
	v_mfma_f32_16x16x32_bf16 v[96:99], v[174:177], v[198:201], 0
	v_mfma_f32_16x16x32_bf16 v[84:87], v[166:169], v[206:209], 0
	v_mfma_f32_16x16x32_bf16 v[80:83], v[174:177], v[206:209], 0
	v_mfma_f32_16x16x32_bf16 v[124:127], v[170:173], v[186:189], v[124:127]
	v_mfma_f32_16x16x32_bf16 v[120:123], v[178:181], v[186:189], v[120:123]
	v_mfma_f32_16x16x32_bf16 v[116:119], v[170:173], v[194:197], v[116:119]
	v_mfma_f32_16x16x32_bf16 v[112:115], v[178:181], v[194:197], v[112:115]
	v_mfma_f32_16x16x32_bf16 v[100:103], v[170:173], v[202:205], v[100:103]
	v_mfma_f32_16x16x32_bf16 v[96:99], v[178:181], v[202:205], v[96:99]
	v_mfma_f32_16x16x32_bf16 v[84:87], v[170:173], v[210:213], v[84:87]
	v_mfma_f32_16x16x32_bf16 v[80:83], v[178:181], v[210:213], v[80:83]
	s_setprio 0
	s_barrier
	s_mov_b32 m0, s61
	ds_read_b128 v[214:217], v152
	ds_read_b128 v[218:221], v153
	ds_read_b128 v[222:225], v154
	ds_read_b128 v[226:229], v155
	global_load_lds_dwordx4 v130, s[54:55]
	s_mov_b32 m0, s62
	s_nop 0
	global_load_lds_dwordx4 v134, s[54:55]
	s_barrier
	s_waitcnt lgkmcnt(0)
	s_setprio 1
	s_waitcnt lgkmcnt(0)
	v_mfma_f32_16x16x32_bf16 v[108:111], v[214:217], v[182:185], 0
	v_mfma_f32_16x16x32_bf16 v[104:107], v[222:225], v[182:185], 0
	v_mfma_f32_16x16x32_bf16 v[92:95], v[214:217], v[190:193], 0
	v_mfma_f32_16x16x32_bf16 v[88:91], v[222:225], v[190:193], 0
	v_mfma_f32_16x16x32_bf16 v[76:79], v[214:217], v[198:201], 0
	v_mfma_f32_16x16x32_bf16 v[72:75], v[222:225], v[198:201], 0
	v_mfma_f32_16x16x32_bf16 v[68:71], v[214:217], v[206:209], 0
	v_mfma_f32_16x16x32_bf16 v[64:67], v[222:225], v[206:209], 0
	v_mfma_f32_16x16x32_bf16 v[108:111], v[218:221], v[186:189], v[108:111]
	v_mfma_f32_16x16x32_bf16 v[104:107], v[226:229], v[186:189], v[104:107]
	v_mfma_f32_16x16x32_bf16 v[92:95], v[218:221], v[194:197], v[92:95]
	v_mfma_f32_16x16x32_bf16 v[88:91], v[226:229], v[194:197], v[88:91]
	v_mfma_f32_16x16x32_bf16 v[76:79], v[218:221], v[202:205], v[76:79]
	v_mfma_f32_16x16x32_bf16 v[72:75], v[226:229], v[202:205], v[72:75]
	v_mfma_f32_16x16x32_bf16 v[68:71], v[218:221], v[210:213], v[68:71]
	v_mfma_f32_16x16x32_bf16 v[64:67], v[226:229], v[210:213], v[64:67]
	s_setprio 0
	s_mov_b32 m0, s60
	s_barrier
	ds_read_b128 v[182:185], v146 offset:16384
	ds_read_b128 v[186:189], v146 offset:17408
	ds_read_b128 v[190:193], v146 offset:18432
	ds_read_b128 v[194:197], v146 offset:19456
	ds_read_b128 v[198:201], v146 offset:20480
	ds_read_b128 v[202:205], v146 offset:21504
	ds_read_b128 v[206:209], v146 offset:22528
	ds_read_b128 v[210:213], v146 offset:23552
	global_load_lds_dwordx4 v128, s[56:57]
	s_mov_b32 m0, s63
	s_nop 0
	global_load_lds_dwordx4 v132, s[56:57]
	s_barrier
	s_waitcnt lgkmcnt(0)
	s_setprio 1
	s_waitcnt lgkmcnt(0)
	v_mfma_f32_16x16x32_bf16 v[60:63], v[166:169], v[182:185], 0
	v_mfma_f32_16x16x32_bf16 v[56:59], v[174:177], v[182:185], 0
	v_mfma_f32_16x16x32_bf16 v[52:55], v[166:169], v[190:193], 0
	v_mfma_f32_16x16x32_bf16 v[48:51], v[174:177], v[190:193], 0
	v_mfma_f32_16x16x32_bf16 v[36:39], v[166:169], v[198:201], 0
	v_mfma_f32_16x16x32_bf16 v[32:35], v[174:177], v[198:201], 0
	v_mfma_f32_16x16x32_bf16 v[20:23], v[166:169], v[206:209], 0
	v_mfma_f32_16x16x32_bf16 v[16:19], v[174:177], v[206:209], 0
	v_mfma_f32_16x16x32_bf16 v[60:63], v[170:173], v[186:189], v[60:63]
	v_mfma_f32_16x16x32_bf16 v[56:59], v[178:181], v[186:189], v[56:59]
	v_mfma_f32_16x16x32_bf16 v[52:55], v[170:173], v[194:197], v[52:55]
	v_mfma_f32_16x16x32_bf16 v[48:51], v[178:181], v[194:197], v[48:51]
	v_mfma_f32_16x16x32_bf16 v[36:39], v[170:173], v[202:205], v[36:39]
	v_mfma_f32_16x16x32_bf16 v[32:35], v[178:181], v[202:205], v[32:35]
	v_mfma_f32_16x16x32_bf16 v[20:23], v[170:173], v[210:213], v[20:23]
	v_mfma_f32_16x16x32_bf16 v[16:19], v[178:181], v[210:213], v[16:19]
	s_setprio 0
	s_barrier
	s_add_u32 s34, s54, 0xb4000
	s_addc_u32 s35, s55, 0
	s_mov_b32 m0, s64
	s_nop 0
	global_load_lds_dwordx4 v130, s[34:35]
	s_mov_b32 m0, s65
	s_nop 0
	global_load_lds_dwordx4 v134, s[34:35]
	s_waitcnt vmcnt(6)
	s_barrier
	s_setprio 1
	v_mfma_f32_16x16x32_bf16 v[44:47], v[214:217], v[182:185], 0
	v_mfma_f32_16x16x32_bf16 v[40:43], v[222:225], v[182:185], 0
	v_mfma_f32_16x16x32_bf16 v[28:31], v[214:217], v[190:193], 0
	v_mfma_f32_16x16x32_bf16 v[24:27], v[222:225], v[190:193], 0
	v_mfma_f32_16x16x32_bf16 v[12:15], v[214:217], v[198:201], 0
	v_mfma_f32_16x16x32_bf16 v[8:11], v[222:225], v[198:201], 0
	v_mfma_f32_16x16x32_bf16 v[4:7], v[214:217], v[206:209], 0
	v_mfma_f32_16x16x32_bf16 v[0:3], v[222:225], v[206:209], 0
	v_mfma_f32_16x16x32_bf16 v[44:47], v[218:221], v[186:189], v[44:47]
	v_mfma_f32_16x16x32_bf16 v[40:43], v[226:229], v[186:189], v[40:43]
	v_mfma_f32_16x16x32_bf16 v[28:31], v[218:221], v[194:197], v[28:31]
	v_mfma_f32_16x16x32_bf16 v[24:27], v[226:229], v[194:197], v[24:27]
	v_mfma_f32_16x16x32_bf16 v[12:15], v[218:221], v[202:205], v[12:15]
	v_mfma_f32_16x16x32_bf16 v[8:11], v[226:229], v[202:205], v[8:11]
	v_mfma_f32_16x16x32_bf16 v[4:7], v[218:221], v[210:213], v[4:7]
	v_mfma_f32_16x16x32_bf16 v[0:3], v[226:229], v[210:213], v[0:3]
	s_setprio 0
	s_barrier
	s_branch .Lzp2_mid

; #define PG8_STAGE(bufoff, gbase, voff) do { _Pragma("unroll") for (int _i = 0; _i < 2; ++_i) \
;         __builtin_amdgcn_global_load_lds((const unsigned*)((const char*)(gbase) + (voff)[_i]), (PG8_LAS unsigned*)(lds + (bufoff) + ldsw + _i * 8192), 16, 0, 0); } while (0)
; #define PG8_LDA(dst, b, h) do { _Pragma("unroll") for (int m = 0; m < 4; ++m) _Pragma("unroll") for (int k = 0; k < 2; ++k) dst[m][k] = *(const PG8_LAS bf16x8*)(lds + PG8_SA(b, h) + aoff + m * 2048 + k * 1024); } while (0)
; #define PG8_LDB(dst, b, h) do { _Pragma("unroll") for (int n = 0; n < 2; ++n) _Pragma("unroll") for (int k = 0; k < 2; ++k) dst[n][k] = *(const PG8_LAS bf16x8*)(lds + PG8_SB(b, h) + boff + n * 2048 + k * 1024); } while (0)
; #define PG8_MMA(ai, bj, At, Bt) do { __builtin_amdgcn_s_setprio(1); _Pragma("unroll") for (int m = 0; m < 4; ++m) _Pragma("unroll") for (int n = 0; n < 2; ++n) _Pragma("unroll") for (int k = 0; k < 2; ++k) \
;         acc[ai][bj][m][n] = __builtin_amdgcn_mfma_f32_16x16x32_bf16(Bt[n][k], At[m][k], acc[ai][bj][m][n], 0, 0, 0); __builtin_amdgcn_s_setprio(0); } while (0)
; #define PG8_WAIT_V(n) asm volatile("s_waitcnt vmcnt(" #n ")" ::: "memory")
; #define PG8_WAIT_L(n) asm volatile("s_waitcnt lgkmcnt(" #n ")" ::: "memory")
; #define PG8_BAR __builtin_amdgcn_s_barrier()
; #define PG8_SCHED __builtin_amdgcn_sched_barrier(0)
; template <class Epi, class Sched, bool STAMP = false>
; __device__ __forceinline__ void gemm_phase(PG8_LAS unsigned char* lds, const Gemm g, const Sched& S, const Epi& E, unsigned long long* stamps) {
;     ...
;             PG8_LDB(B0, 1, 0); PG8_SCHED; PG8_LDA(At, 1, 0); PG8_STAGE(PG8_SA(0, 1), a2 + hstep, voffA);
;             PG8_WAIT_L(8); PG8_BAR; PG8_WAIT_L(0); PG8_MMA(0, 0, At, B0); PG8_BAR; PG8_SCHED;
;             PG8_LDB(B1, 1, 1); PG8_STAGE(PG8_SB(1, 0), b3, voffB);
;             PG8_BAR; PG8_WAIT_L(0); PG8_MMA(0, 1, At, B1); PG8_BAR;
;             PG8_LDA(At, 1, 1); PG8_STAGE(PG8_SA(1, 0), a3, voffA);
;             PG8_BAR; PG8_WAIT_L(0); PG8_MMA(1, 0, At, B0); PG8_BAR; PG8_SCHED;
;             PG8_STAGE(PG8_SB(1, 1), b3 + hstep, voffB);
;             PG8_WAIT_V(6); PG8_BAR; PG8_MMA(1, 1, At, B1); PG8_BAR;
.Lzp2_mid:
	ds_read_b128 v[166:169], v156
	ds_read_b128 v[170:173], v157
	ds_read_b128 v[174:177], v159
	ds_read_b128 v[178:181], v160
	s_add_u32 s34, s56, 0xb4000
	s_addc_u32 s35, s57, 0
	s_mov_b32 m0, s66
	ds_read_b128 v[182:185], v146 offset:32768
	ds_read_b128 v[186:189], v146 offset:33792
	ds_read_b128 v[190:193], v146 offset:34816
	ds_read_b128 v[194:197], v146 offset:35840
	ds_read_b128 v[198:201], v146 offset:36864
	ds_read_b128 v[202:205], v146 offset:37888
	ds_read_b128 v[206:209], v146 offset:38912
	ds_read_b128 v[210:213], v146 offset:39936
	global_load_lds_dwordx4 v128, s[34:35]
	s_mov_b32 m0, s67
	s_nop 0
	global_load_lds_dwordx4 v132, s[34:35]
	s_waitcnt lgkmcnt(8)
	s_barrier
	s_waitcnt lgkmcnt(0)
	s_setprio 1
	s_waitcnt lgkmcnt(0)
	v_mfma_f32_16x16x32_bf16 v[124:127], v[166:169], v[182:185], v[124:127]
	v_mfma_f32_16x16x32_bf16 v[120:123], v[174:177], v[182:185], v[120:123]
	v_mfma_f32_16x16x32_bf16 v[116:119], v[166:169], v[190:193], v[116:119]
	v_mfma_f32_16x16x32_bf16 v[112:115], v[174:177], v[190:193], v[112:115]
	v_mfma_f32_16x16x32_bf16 v[100:103], v[166:169], v[198:201], v[100:103]
	v_mfma_f32_16x16x32_bf16 v[96:99], v[174:177], v[198:201], v[96:99]
	v_mfma_f32_16x16x32_bf16 v[84:87], v[166:169], v[206:209], v[84:87]
	v_mfma_f32_16x16x32_bf16 v[80:83], v[174:177], v[206:209], v[80:83]
	v_mfma_f32_16x16x32_bf16 v[124:127], v[170:173], v[186:189], v[124:127]
	v_mfma_f32_16x16x32_bf16 v[120:123], v[178:181], v[186:189], v[120:123]
	v_mfma_f32_16x16x32_bf16 v[116:119], v[170:173], v[194:197], v[116:119]
	v_mfma_f32_16x16x32_bf16 v[112:115], v[178:181], v[194:197], v[112:115]
	v_mfma_f32_16x16x32_bf16 v[100:103], v[170:173], v[202:205], v[100:103]
	v_mfma_f32_16x16x32_bf16 v[96:99], v[178:181], v[202:205], v[96:99]
	v_mfma_f32_16x16x32_bf16 v[84:87], v[170:173], v[210:213], v[84:87]
	v_mfma_f32_16x16x32_bf16 v[80:83], v[178:181], v[210:213], v[80:83]
	s_setprio 0
	s_barrier
	s_mov_b32 m0, s68
	ds_read_b128 v[214:217], v161
	ds_read_b128 v[218:221], v162
	ds_read_b128 v[222:225], v163
	ds_read_b128 v[226:229], v164
	s_add_u32 s100, s54, 0x80
	s_addc_u32 s101, s55, 0
	global_load_lds_dwordx4 v130, s[100:101]
	s_mov_b32 m0, s69
	s_nop 0
	global_load_lds_dwordx4 v134, s[100:101]
	s_barrier
	s_waitcnt lgkmcnt(0)
	s_setprio 1
	s_waitcnt lgkmcnt(0)
	v_mfma_f32_16x16x32_bf16 v[108:111], v[214:217], v[182:185], v[108:111]
	v_mfma_f32_16x16x32_bf16 v[104:107], v[222:225], v[182:185], v[104:107]
	v_mfma_f32_16x16x32_bf16 v[92:95], v[214:217], v[190:193], v[92:95]
	v_mfma_f32_16x16x32_bf16 v[88:91], v[222:225], v[190:193], v[88:91]
	v_mfma_f32_16x16x32_bf16 v[76:79], v[214:217], v[198:201], v[76:79]
	v_mfma_f32_16x16x32_bf16 v[72:75], v[222:225], v[198:201], v[72:75]
	v_mfma_f32_16x16x32_bf16 v[68:71], v[214:217], v[206:209], v[68:71]
	v_mfma_f32_16x16x32_bf16 v[64:67], v[222:225], v[206:209], v[64:67]
	v_mfma_f32_16x16x32_bf16 v[108:111], v[218:221], v[186:189], v[108:111]
	v_mfma_f32_16x16x32_bf16 v[104:107], v[226:229], v[186:189], v[104:107]
	v_mfma_f32_16x16x32_bf16 v[92:95], v[218:221], v[194:197], v[92:95]
	v_mfma_f32_16x16x32_bf16 v[88:91], v[226:229], v[194:197], v[88:91]
	v_mfma_f32_16x16x32_bf16 v[76:79], v[218:221], v[202:205], v[76:79]
	v_mfma_f32_16x16x32_bf16 v[72:75], v[226:229], v[202:205], v[72:75]
	v_mfma_f32_16x16x32_bf16 v[68:71], v[218:221], v[210:213], v[68:71]
	v_mfma_f32_16x16x32_bf16 v[64:67], v[226:229], v[210:213], v[64:67]
	s_setprio 0
	s_mov_b32 m0, s70
	s_barrier
	ds_read_b128 v[182:185], v146 offset:49152
	ds_read_b128 v[186:189], v146 offset:50176
	ds_read_b128 v[190:193], v146 offset:51200
	ds_read_b128 v[194:197], v146 offset:52224
	ds_read_b128 v[198:201], v146 offset:53248
	ds_read_b128 v[202:205], v146 offset:54272
	ds_read_b128 v[206:209], v146 offset:55296
	ds_read_b128 v[210:213], v146 offset:56320
	s_add_u32 s100, s56, 0x80
	s_addc_u32 s101, s57, 0
	global_load_lds_dwordx4 v128, s[100:101]
	s_mov_b32 m0, s71
	s_nop 0
	global_load_lds_dwordx4 v132, s[100:101]
	s_barrier
	s_waitcnt lgkmcnt(0)
	s_setprio 1
	s_waitcnt lgkmcnt(0)
	v_mfma_f32_16x16x32_bf16 v[60:63], v[166:169], v[182:185], v[60:63]
	v_mfma_f32_16x16x32_bf16 v[56:59], v[174:177], v[182:185], v[56:59]
	v_mfma_f32_16x16x32_bf16 v[52:55], v[166:169], v[190:193], v[52:55]
	v_mfma_f32_16x16x32_bf16 v[48:51], v[174:177], v[190:193], v[48:51]
	v_mfma_f32_16x16x32_bf16 v[36:39], v[166:169], v[198:201], v[36:39]
	v_mfma_f32_16x16x32_bf16 v[32:35], v[174:177], v[198:201], v[32:35]
	v_mfma_f32_16x16x32_bf16 v[20:23], v[166:169], v[206:209], v[20:23]
	v_mfma_f32_16x16x32_bf16 v[16:19], v[174:177], v[206:209], v[16:19]
	v_mfma_f32_16x16x32_bf16 v[60:63], v[170:173], v[186:189], v[60:63]
	v_mfma_f32_16x16x32_bf16 v[56:59], v[178:181], v[186:189], v[56:59]
	v_mfma_f32_16x16x32_bf16 v[52:55], v[170:173], v[194:197], v[52:55]
	v_mfma_f32_16x16x32_bf16 v[48:51], v[178:181], v[194:197], v[48:51]
	v_mfma_f32_16x16x32_bf16 v[36:39], v[170:173], v[202:205], v[36:39]
	v_mfma_f32_16x16x32_bf16 v[32:35], v[178:181], v[202:205], v[32:35]
	v_mfma_f32_16x16x32_bf16 v[20:23], v[170:173], v[210:213], v[20:23]
	v_mfma_f32_16x16x32_bf16 v[16:19], v[178:181], v[210:213], v[16:19]
	s_setprio 0
	s_barrier
	s_add_u32 s34, s54, 0xb4080
	s_addc_u32 s35, s55, 0
	s_mov_b32 m0, s72
	s_nop 0
	global_load_lds_dwordx4 v130, s[34:35]
	s_mov_b32 m0, s73
	s_nop 0
	global_load_lds_dwordx4 v134, s[34:35]
	s_waitcnt vmcnt(6)
	s_barrier
; #define PG8_STAMP() do { if (STAMP && wid == 0 && nts < 64) { const unsigned long long _c = 0ull; \
;         ts_lo = (lane == nts) ? (int)(unsigned)_c : ts_lo; ts_hi = (lane == nts) ? (int)(unsigned)(_c >> 32) : ts_hi; ++nts; } } while (0)
; #define PG8_MMA(ai, bj, At, Bt) do { __builtin_amdgcn_s_setprio(1); _Pragma("unroll") for (int m = 0; m < 4; ++m) _Pragma("unroll") for (int n = 0; n < 2; ++n) _Pragma("unroll") for (int k = 0; k < 2; ++k) \
;         acc[ai][bj][m][n] = __builtin_amdgcn_mfma_f32_16x16x32_bf16(Bt[n][k], At[m][k], acc[ai][bj][m][n], 0, 0, 0); __builtin_amdgcn_s_setprio(0); } while (0)
; #define PG8_WAIT_V(n) asm volatile("s_waitcnt vmcnt(" #n ")" ::: "memory")
; #define PG8_BAR __builtin_amdgcn_s_barrier()
;     DI void operator()(const f32x4 (&acc)[2][2][4][2], const Unit& u, int wr, int wc, int fr, int fq) const {
;         const int row0 = u.pm * BM + wr * 64 + fr, col0 = u.pn * BM + wc * 32 + 8 * fq;
; #pragma unroll
;         for (int ai = 0; ai < 2; ++ai)
; #pragma unroll
;             for (int m = 0; m < 4; ++m) { u16* rowp = O + (size_t)(row0 + ai * HALF + m * 16) * ldc + col0;
; #pragma unroll
;                 for (int bj = 0; bj < 2; ++bj) { const f32x4 v0 = acc[ai][bj][m][0], v1 = acc[ai][bj][m][1];
;                     uint4 w = {pack2(v0[0], v0[1]), pack2(v0[2], v0[3]), pack2(v1[0], v1[1]), pack2(v1[2], v1[3])}; *(uint4*)(rowp + bj * HALF) = w; } }
; template <class Epi, class Sched, bool STAMP = false>
; __device__ __forceinline__ void gemm_phase(PG8_LAS unsigned char* lds, const Gemm g, const Sched& S, const Epi& E, unsigned long long* stamps) {
;     ...
;             PG8_WAIT_V(6); PG8_BAR; PG8_MMA(1, 1, At, B1); PG8_BAR;
;         }
;         PG8_STAMP();
;         if constexpr (!Epi::AFTER_DRAIN) { E(acc, cur, wr, wc, fr, fq); S.done(cur); }
;         PG8_STAMP();
;         if (!has_next) break;
	s_setprio 1
	v_mfma_f32_16x16x32_bf16 v[44:47], v[214:217], v[182:185], v[44:47]
	v_mfma_f32_16x16x32_bf16 v[40:43], v[222:225], v[182:185], v[40:43]
	v_mfma_f32_16x16x32_bf16 v[28:31], v[214:217], v[190:193], v[28:31]
	v_mfma_f32_16x16x32_bf16 v[24:27], v[222:225], v[190:193], v[24:27]
	v_mfma_f32_16x16x32_bf16 v[12:15], v[214:217], v[198:201], v[12:15]
	v_mfma_f32_16x16x32_bf16 v[8:11], v[222:225], v[198:201], v[8:11]
	v_mfma_f32_16x16x32_bf16 v[4:7], v[214:217], v[206:209], v[4:7]
	v_mfma_f32_16x16x32_bf16 v[0:3], v[222:225], v[206:209], v[0:3]
	v_mfma_f32_16x16x32_bf16 v[44:47], v[218:221], v[186:189], v[44:47]
	v_mfma_f32_16x16x32_bf16 v[40:43], v[226:229], v[186:189], v[40:43]
	v_mfma_f32_16x16x32_bf16 v[28:31], v[218:221], v[194:197], v[28:31]
	v_mfma_f32_16x16x32_bf16 v[24:27], v[226:229], v[194:197], v[24:27]
	v_mfma_f32_16x16x32_bf16 v[12:15], v[218:221], v[202:205], v[12:15]
	v_mfma_f32_16x16x32_bf16 v[8:11], v[226:229], v[202:205], v[8:11]
	v_mfma_f32_16x16x32_bf16 v[4:7], v[218:221], v[210:213], v[4:7]
	v_mfma_f32_16x16x32_bf16 v[0:3], v[226:229], v[210:213], v[0:3]
	s_setprio 0
	s_add_i32 s90, s90, 2
	s_add_u32 s88, s88, 0x100
	s_addc_u32 s89, s89, 0
	s_cmp_gt_u32 s90, 41
	s_mov_b64 s[34:35], s[52:53]
	s_barrier
	s_cbranch_scc0 .LBB0_97
	v_lshl_add_u32 v166, s84, 8, v145
	v_lshl_or_b32 v168, s87, 8, v147
	v_ashrrev_i32_e32 v167, 31, v166
	v_ashrrev_i32_e32 v169, 31, v168
	v_lshlrev_b64 v[170:171], 11, v[166:167]
	v_lshl_add_u64 v[170:171], s[14:15], 0, v[170:171]
	v_lshlrev_b64 v[168:169], 1, v[168:169]
	v_lshl_add_u64 v[170:171], v[170:171], 0, v[168:169]
	v_cvt_pk_bf16_f32 v60, v60, v61
	v_cvt_pk_bf16_f32 v61, v62, v63
	v_cvt_pk_bf16_f32 v62, v56, v57
	v_add_co_u32_e32 v56, vcc, s78, v170
	v_cvt_pk_bf16_f32 v68, v68, v69
	v_cvt_pk_bf16_f32 v69, v70, v71
	v_cvt_pk_bf16_f32 v70, v64, v65
	v_lshl_add_u64 v[64:65], v[170:171], 0, s[16:17]
	v_addc_co_u32_e32 v57, vcc, 0, v171, vcc
	v_cvt_pk_bf16_f32 v44, v44, v45
	v_cvt_pk_bf16_f32 v45, v46, v47
	v_cvt_pk_bf16_f32 v46, v40, v41
	v_cvt_pk_bf16_f32 v47, v42, v43
	v_cvt_pk_bf16_f32 v108, v108, v109
	v_cvt_pk_bf16_f32 v109, v110, v111
	v_cvt_pk_bf16_f32 v110, v104, v105
	v_or_b32_e32 v104, 16, v166
	global_store_dwordx4 v[64:65], v[44:47], off offset:256
	v_ashrrev_i32_e32 v105, 31, v104
	v_cvt_pk_bf16_f32 v92, v92, v93
	v_add_co_u32_e32 v46, vcc, s79, v170
	v_cvt_pk_bf16_f32 v93, v94, v95
	v_cvt_pk_bf16_f32 v94, v88, v89
	v_or_b32_e32 v88, 32, v166
	v_lshl_add_u64 v[44:45], v[170:171], 0, s[18:19]
	v_addc_co_u32_e32 v47, vcc, 0, v171, vcc
	v_cvt_pk_bf16_f32 v28, v28, v29
	v_cvt_pk_bf16_f32 v29, v30, v31
	v_cvt_pk_bf16_f32 v30, v24, v25
	v_cvt_pk_bf16_f32 v31, v26, v27
	v_lshlrev_b64 v[104:105], 11, v[104:105]
	v_ashrrev_i32_e32 v89, 31, v88
	v_cvt_pk_bf16_f32 v76, v76, v77
	v_cvt_pk_bf16_f32 v77, v78, v79
	v_cvt_pk_bf16_f32 v78, v72, v73
	v_or_b32_e32 v72, 48, v166
	global_store_dwordx4 v[44:45], v[28:31], off offset:256
	v_cvt_pk_bf16_f32 v111, v106, v107
	v_lshl_add_u64 v[104:105], s[14:15], 0, v[104:105]
	v_add_co_u32_e32 v30, vcc, s82, v170
	v_lshlrev_b64 v[88:89], 11, v[88:89]
	v_ashrrev_i32_e32 v73, 31, v72
	v_lshl_add_u64 v[28:29], v[170:171], 0, s[28:29]
	v_addc_co_u32_e32 v31, vcc, 0, v171, vcc
	v_cvt_pk_bf16_f32 v12, v12, v13
	v_cvt_pk_bf16_f32 v13, v14, v15
	v_cvt_pk_bf16_f32 v14, v8, v9
	v_cvt_pk_bf16_f32 v15, v10, v11
	global_store_dwordx4 v[170:171], v[108:111], off offset:256
	v_cvt_pk_bf16_f32 v95, v90, v91
	v_lshl_add_u64 v[88:89], s[14:15], 0, v[88:89]
	v_lshl_add_u64 v[108:109], v[104:105], 0, v[168:169]
	v_lshlrev_b64 v[72:73], 11, v[72:73]
	global_store_dwordx4 v[28:29], v[12:15], off offset:256
	global_store_dwordx4 v[108:109], v[92:95], off offset:256
	v_cvt_pk_bf16_f32 v79, v74, v75
	v_add_co_u32_e32 v14, vcc, s83, v170
	v_lshl_add_u64 v[92:93], v[88:89], 0, v[168:169]
	v_lshl_add_u64 v[72:73], s[14:15], 0, v[72:73]
	v_addc_co_u32_e32 v15, vcc, 0, v171, vcc
	v_cvt_pk_bf16_f32 v124, v124, v125
	v_cvt_pk_bf16_f32 v125, v126, v127
	v_cvt_pk_bf16_f32 v126, v120, v121
	v_cvt_pk_bf16_f32 v127, v122, v123
	v_cvt_pk_bf16_f32 v104, v116, v117
	v_cvt_pk_bf16_f32 v105, v118, v119
	v_cvt_pk_bf16_f32 v106, v112, v113
	v_cvt_pk_bf16_f32 v107, v114, v115
	v_cvt_pk_bf16_f32 v88, v100, v101
	v_cvt_pk_bf16_f32 v89, v102, v103
	v_cvt_pk_bf16_f32 v90, v96, v97
	v_cvt_pk_bf16_f32 v91, v98, v99
	global_store_dwordx4 v[92:93], v[76:79], off offset:256
	v_cvt_pk_bf16_f32 v74, v80, v81
	v_cvt_pk_bf16_f32 v75, v82, v83
	v_lshl_add_u64 v[76:77], v[72:73], 0, v[168:169]
	v_cvt_pk_bf16_f32 v72, v84, v85
	v_cvt_pk_bf16_f32 v73, v86, v87
	v_cvt_pk_bf16_f32 v71, v66, v67
	v_cvt_pk_bf16_f32 v63, v58, v59
	v_cvt_pk_bf16_f32 v40, v52, v53
	v_cvt_pk_bf16_f32 v41, v54, v55
	v_cvt_pk_bf16_f32 v42, v48, v49
	v_cvt_pk_bf16_f32 v43, v50, v51
	v_cvt_pk_bf16_f32 v24, v36, v37
	v_cvt_pk_bf16_f32 v25, v38, v39
	v_cvt_pk_bf16_f32 v26, v32, v33
	v_cvt_pk_bf16_f32 v27, v34, v35
	v_lshl_add_u64 v[12:13], v[170:171], 0, s[30:31]
	v_cvt_pk_bf16_f32 v8, v20, v21
	v_cvt_pk_bf16_f32 v9, v22, v23
	v_cvt_pk_bf16_f32 v10, v16, v17
	v_cvt_pk_bf16_f32 v11, v18, v19
	v_cvt_pk_bf16_f32 v4, v4, v5
	v_cvt_pk_bf16_f32 v5, v6, v7
	v_cvt_pk_bf16_f32 v6, v0, v1
	v_cvt_pk_bf16_f32 v7, v2, v3
	s_and_b64 vcc, exec, s[2:3]
	s_mov_b32 s87, s85
	s_mov_b32 s84, s86
	s_mov_b64 s[52:53], s[0:1]
	s_mov_b64 s[34:35], s[4:5]
	global_store_dwordx4 v[170:171], v[124:127], off
	global_store_dwordx4 v[108:109], v[104:107], off
	global_store_dwordx4 v[92:93], v[88:91], off
	global_store_dwordx4 v[76:77], v[72:75], off
	global_store_dwordx4 v[76:77], v[68:71], off offset:256
	global_store_dwordx4 v[56:57], v[60:63], off
	global_store_dwordx4 v[46:47], v[40:43], off
	global_store_dwordx4 v[30:31], v[24:27], off
	global_store_dwordx4 v[14:15], v[8:11], off
	global_store_dwordx4 v[12:13], v[4:7], off offset:256
	s_cbranch_vccz .LBB0_86
	s_waitcnt vmcnt(0)
	s_cmpk_gt_u32 s58, 0xff
	s_cbranch_scc1 .LBB0_101
	s_barrier

; #define PG8_STAGE(bufoff, gbase, voff) do { _Pragma("unroll") for (int _i = 0; _i < 2; ++_i) \
;         __builtin_amdgcn_global_load_lds((const unsigned*)((const char*)(gbase) + (voff)[_i]), (PG8_LAS unsigned*)(lds + (bufoff) + ldsw + _i * 8192), 16, 0, 0); } while (0)
; #define PG8_LDA(dst, b, h) do { _Pragma("unroll") for (int m = 0; m < 4; ++m) _Pragma("unroll") for (int k = 0; k < 2; ++k) dst[m][k] = *(const PG8_LAS bf16x8*)(lds + PG8_SA(b, h) + aoff + m * 2048 + k * 1024); } while (0)
; #define PG8_LDB(dst, b, h) do { _Pragma("unroll") for (int n = 0; n < 2; ++n) _Pragma("unroll") for (int k = 0; k < 2; ++k) dst[n][k] = *(const PG8_LAS bf16x8*)(lds + PG8_SB(b, h) + boff + n * 2048 + k * 1024); } while (0)
; #define PG8_WAIT_V(n) asm volatile("s_waitcnt vmcnt(" #n ")" ::: "memory")
; #define PG8_WAIT_L(n) asm volatile("s_waitcnt lgkmcnt(" #n ")" ::: "memory")
; #define PG8_BAR __builtin_amdgcn_s_barrier()
; template <class Epi, class Sched, bool STAMP = false>
; __device__ __forceinline__ void gemm_phase(PG8_LAS unsigned char* lds, const Gemm g, const Sched& S, const Epi& E, unsigned long long* stamps) {
;     ...
;     for (;;) {
;         const bool has_next = S.next(ui + 1, nxt);
;         const char* nA = has_next ? (const char*)g.A + (size_t)nxt.pm * tstep : cA; const char* nB = has_next ? (const char*)g.Bt + (size_t)nxt.pn * tstep : cB;
;         for (int t = 0; t < nt; t += 2) {
;             const bool last = (t == nt - 2);
;             const char* a1 = cA + (size_t)(t + 1) * kstep;
;             const char* a2 = last ? nA : cA + (size_t)(t + 2) * kstep; const char* b2 = last ? nB : cB + (size_t)(t + 2) * kstep;
;             const char* a3 = a2 + kstep; const char* b3 = b2 + kstep;
;             if (last && has_next) S.a_ready(nxt);
;             PG8_LDB(B0, 0, 0); PG8_SCHED; PG8_LDA(At, 0, 0); PG8_STAGE(PG8_SA(1, 1), a1 + hstep, voffA);
;             PG8_WAIT_L(8); PG8_BAR; PG8_WAIT_L(0); PG8_MMA(0, 0, At, B0); PG8_BAR; PG8_SCHED;
;             PG8_LDB(B1, 0, 1); PG8_STAGE(PG8_SB(0, 0), b2, voffB);
;             PG8_BAR; PG8_WAIT_L(0); PG8_MMA(0, 1, At, B1); PG8_BAR;
;             PG8_LDA(At, 0, 1); PG8_STAGE(PG8_SA(0, 0), a2, voffA);
;             PG8_BAR; PG8_WAIT_L(0); PG8_MMA(1, 0, At, B0); PG8_BAR; PG8_SCHED;
;             PG8_STAGE(PG8_SB(0, 1), b2 + hstep, voffB);
;             PG8_WAIT_V(6); PG8_BAR; PG8_MMA(1, 1, At, B1); PG8_BAR;
.LBB0_137:
	s_add_u32 s83, s34, 0x100
	s_addc_u32 s84, s35, 0
	s_mov_b32 s85, -2
	s_waitcnt lgkmcnt(0)
	ds_read_b128 v[166:169], v148
	ds_read_b128 v[170:173], v149
	ds_read_b128 v[174:177], v150
	ds_read_b128 v[178:181], v151
	s_add_u32 s34, s28, 0x100
	s_addc_u32 s35, s29, 0
	s_cmp_eq_u32 s85, 12
	s_cselect_b32 s53, s7, s35
	s_cselect_b32 s52, s6, s34
	s_cselect_b32 s37, s1, s84
	s_cselect_b32 s36, s0, s83
	s_mov_b32 m0, s74
	ds_read_b128 v[182:185], v146
	ds_read_b128 v[186:189], v146 offset:1024
	ds_read_b128 v[190:193], v146 offset:2048
	ds_read_b128 v[194:197], v146 offset:3072
	ds_read_b128 v[198:201], v146 offset:4096
	ds_read_b128 v[202:205], v146 offset:5120
	ds_read_b128 v[206:209], v146 offset:6144
	ds_read_b128 v[210:213], v146 offset:7168
	global_load_lds_dwordx4 v136, s[28:29]
	s_mov_b32 m0, s75
	s_nop 0
	global_load_lds_dwordx4 v138, s[28:29]
	s_waitcnt lgkmcnt(8)
	s_barrier
	s_waitcnt lgkmcnt(0)
	s_setprio 1
	s_waitcnt lgkmcnt(0)
	v_mfma_f32_16x16x32_bf16 v[124:127], v[166:169], v[182:185], 0
	v_mfma_f32_16x16x32_bf16 v[120:123], v[174:177], v[182:185], 0
	v_mfma_f32_16x16x32_bf16 v[116:119], v[166:169], v[190:193], 0
	v_mfma_f32_16x16x32_bf16 v[112:115], v[174:177], v[190:193], 0
	v_mfma_f32_16x16x32_bf16 v[108:111], v[166:169], v[198:201], 0
	v_mfma_f32_16x16x32_bf16 v[104:107], v[174:177], v[198:201], 0
	v_mfma_f32_16x16x32_bf16 v[100:103], v[166:169], v[206:209], 0
	v_mfma_f32_16x16x32_bf16 v[96:99], v[174:177], v[206:209], 0
	v_mfma_f32_16x16x32_bf16 v[124:127], v[170:173], v[186:189], v[124:127]
	v_mfma_f32_16x16x32_bf16 v[120:123], v[178:181], v[186:189], v[120:123]
	v_mfma_f32_16x16x32_bf16 v[116:119], v[170:173], v[194:197], v[116:119]
	v_mfma_f32_16x16x32_bf16 v[112:115], v[178:181], v[194:197], v[112:115]
	v_mfma_f32_16x16x32_bf16 v[108:111], v[170:173], v[202:205], v[108:111]
	v_mfma_f32_16x16x32_bf16 v[104:107], v[178:181], v[202:205], v[104:107]
	v_mfma_f32_16x16x32_bf16 v[100:103], v[170:173], v[210:213], v[100:103]
	v_mfma_f32_16x16x32_bf16 v[96:99], v[178:181], v[210:213], v[96:99]
	s_setprio 0
	s_barrier
	s_mov_b32 m0, s58
	ds_read_b128 v[214:217], v152
	ds_read_b128 v[218:221], v153
	ds_read_b128 v[222:225], v154
	ds_read_b128 v[226:229], v155
	global_load_lds_dwordx4 v132, s[36:37]
	s_mov_b32 m0, s59
	s_nop 0
	global_load_lds_dwordx4 v128, s[36:37]
	s_barrier
	s_waitcnt lgkmcnt(0)
	s_setprio 1
	s_waitcnt lgkmcnt(0)
	v_mfma_f32_16x16x32_bf16 v[60:63], v[214:217], v[182:185], 0
	v_mfma_f32_16x16x32_bf16 v[56:59], v[222:225], v[182:185], 0
	v_mfma_f32_16x16x32_bf16 v[52:55], v[214:217], v[190:193], 0
	v_mfma_f32_16x16x32_bf16 v[48:51], v[222:225], v[190:193], 0
	v_mfma_f32_16x16x32_bf16 v[44:47], v[214:217], v[198:201], 0
	v_mfma_f32_16x16x32_bf16 v[40:43], v[222:225], v[198:201], 0
	v_mfma_f32_16x16x32_bf16 v[36:39], v[214:217], v[206:209], 0
	v_mfma_f32_16x16x32_bf16 v[32:35], v[222:225], v[206:209], 0
	v_mfma_f32_16x16x32_bf16 v[60:63], v[218:221], v[186:189], v[60:63]
	v_mfma_f32_16x16x32_bf16 v[56:59], v[226:229], v[186:189], v[56:59]
	v_mfma_f32_16x16x32_bf16 v[52:55], v[218:221], v[194:197], v[52:55]
	v_mfma_f32_16x16x32_bf16 v[48:51], v[226:229], v[194:197], v[48:51]
	v_mfma_f32_16x16x32_bf16 v[44:47], v[218:221], v[202:205], v[44:47]
	v_mfma_f32_16x16x32_bf16 v[40:43], v[226:229], v[202:205], v[40:43]
	v_mfma_f32_16x16x32_bf16 v[36:39], v[218:221], v[210:213], v[36:39]
	v_mfma_f32_16x16x32_bf16 v[32:35], v[226:229], v[210:213], v[32:35]
	s_setprio 0
	s_mov_b32 m0, s55
	s_barrier
	ds_read_b128 v[182:185], v146 offset:16384
	ds_read_b128 v[186:189], v146 offset:17408
	ds_read_b128 v[190:193], v146 offset:18432
	ds_read_b128 v[194:197], v146 offset:19456
	ds_read_b128 v[198:201], v146 offset:20480
	ds_read_b128 v[202:205], v146 offset:21504
	ds_read_b128 v[206:209], v146 offset:22528
	ds_read_b128 v[210:213], v146 offset:23552
	global_load_lds_dwordx4 v134, s[52:53]
	s_mov_b32 m0, s60
	s_nop 0
	global_load_lds_dwordx4 v130, s[52:53]
	s_barrier
	s_waitcnt lgkmcnt(0)
	s_setprio 1
	s_waitcnt lgkmcnt(0)
	v_mfma_f32_16x16x32_bf16 v[92:95], v[166:169], v[182:185], 0
	v_mfma_f32_16x16x32_bf16 v[88:91], v[174:177], v[182:185], 0
	v_mfma_f32_16x16x32_bf16 v[84:87], v[166:169], v[190:193], 0
	v_mfma_f32_16x16x32_bf16 v[80:83], v[174:177], v[190:193], 0
	v_mfma_f32_16x16x32_bf16 v[76:79], v[166:169], v[198:201], 0
	v_mfma_f32_16x16x32_bf16 v[72:75], v[174:177], v[198:201], 0
	v_mfma_f32_16x16x32_bf16 v[68:71], v[166:169], v[206:209], 0
	v_mfma_f32_16x16x32_bf16 v[64:67], v[174:177], v[206:209], 0
	v_mfma_f32_16x16x32_bf16 v[92:95], v[170:173], v[186:189], v[92:95]
	v_mfma_f32_16x16x32_bf16 v[88:91], v[178:181], v[186:189], v[88:91]
	v_mfma_f32_16x16x32_bf16 v[84:87], v[170:173], v[194:197], v[84:87]
	v_mfma_f32_16x16x32_bf16 v[80:83], v[178:181], v[194:197], v[80:83]
	v_mfma_f32_16x16x32_bf16 v[76:79], v[170:173], v[202:205], v[76:79]
	v_mfma_f32_16x16x32_bf16 v[72:75], v[178:181], v[202:205], v[72:75]
	v_mfma_f32_16x16x32_bf16 v[68:71], v[170:173], v[210:213], v[68:71]
	v_mfma_f32_16x16x32_bf16 v[64:67], v[178:181], v[210:213], v[64:67]
	s_setprio 0
	s_barrier
	s_add_u32 s28, s36, 0x44000
	s_addc_u32 s29, s37, 0
	s_mov_b32 m0, s61
	s_nop 0
	global_load_lds_dwordx4 v132, s[28:29]
	s_mov_b32 m0, s62
	s_nop 0
	global_load_lds_dwordx4 v128, s[28:29]
	s_waitcnt vmcnt(6)
	s_barrier
	s_setprio 1
	v_mfma_f32_16x16x32_bf16 v[28:31], v[214:217], v[182:185], 0
	v_mfma_f32_16x16x32_bf16 v[24:27], v[222:225], v[182:185], 0
	v_mfma_f32_16x16x32_bf16 v[20:23], v[214:217], v[190:193], 0
	v_mfma_f32_16x16x32_bf16 v[16:19], v[222:225], v[190:193], 0
	v_mfma_f32_16x16x32_bf16 v[12:15], v[214:217], v[198:201], 0
	v_mfma_f32_16x16x32_bf16 v[8:11], v[222:225], v[198:201], 0
	v_mfma_f32_16x16x32_bf16 v[4:7], v[214:217], v[206:209], 0
	v_mfma_f32_16x16x32_bf16 v[0:3], v[222:225], v[206:209], 0
	v_mfma_f32_16x16x32_bf16 v[28:31], v[218:221], v[186:189], v[28:31]
	v_mfma_f32_16x16x32_bf16 v[24:27], v[226:229], v[186:189], v[24:27]
	v_mfma_f32_16x16x32_bf16 v[20:23], v[218:221], v[194:197], v[20:23]
	v_mfma_f32_16x16x32_bf16 v[16:19], v[226:229], v[194:197], v[16:19]
	v_mfma_f32_16x16x32_bf16 v[12:15], v[218:221], v[202:205], v[12:15]
	v_mfma_f32_16x16x32_bf16 v[8:11], v[226:229], v[202:205], v[8:11]
	v_mfma_f32_16x16x32_bf16 v[4:7], v[218:221], v[210:213], v[4:7]
	v_mfma_f32_16x16x32_bf16 v[0:3], v[226:229], v[210:213], v[0:3]
	s_setprio 0
	s_barrier
	s_branch .Lzp3_mid

; #define PG8_STAGE(bufoff, gbase, voff) do { _Pragma("unroll") for (int _i = 0; _i < 2; ++_i) \
;         __builtin_amdgcn_global_load_lds((const unsigned*)((const char*)(gbase) + (voff)[_i]), (PG8_LAS unsigned*)(lds + (bufoff) + ldsw + _i * 8192), 16, 0, 0); } while (0)
; #define PG8_LDA(dst, b, h) do { _Pragma("unroll") for (int m = 0; m < 4; ++m) _Pragma("unroll") for (int k = 0; k < 2; ++k) dst[m][k] = *(const PG8_LAS bf16x8*)(lds + PG8_SA(b, h) + aoff + m * 2048 + k * 1024); } while (0)
; #define PG8_LDB(dst, b, h) do { _Pragma("unroll") for (int n = 0; n < 2; ++n) _Pragma("unroll") for (int k = 0; k < 2; ++k) dst[n][k] = *(const PG8_LAS bf16x8*)(lds + PG8_SB(b, h) + boff + n * 2048 + k * 1024); } while (0)
; #define PG8_MMA(ai, bj, At, Bt) do { __builtin_amdgcn_s_setprio(1); _Pragma("unroll") for (int m = 0; m < 4; ++m) _Pragma("unroll") for (int n = 0; n < 2; ++n) _Pragma("unroll") for (int k = 0; k < 2; ++k) \
;         acc[ai][bj][m][n] = __builtin_amdgcn_mfma_f32_16x16x32_bf16(Bt[n][k], At[m][k], acc[ai][bj][m][n], 0, 0, 0); __builtin_amdgcn_s_setprio(0); } while (0)
; #define PG8_WAIT_V(n) asm volatile("s_waitcnt vmcnt(" #n ")" ::: "memory")
; #define PG8_WAIT_L(n) asm volatile("s_waitcnt lgkmcnt(" #n ")" ::: "memory")
; #define PG8_BAR __builtin_amdgcn_s_barrier()
; #define PG8_SCHED __builtin_amdgcn_sched_barrier(0)
; template <class Epi, class Sched, bool STAMP = false>
; __device__ __forceinline__ void gemm_phase(PG8_LAS unsigned char* lds, const Gemm g, const Sched& S, const Epi& E, unsigned long long* stamps) {
;     ...
;             PG8_LDB(B0, 1, 0); PG8_SCHED; PG8_LDA(At, 1, 0); PG8_STAGE(PG8_SA(0, 1), a2 + hstep, voffA);
;             PG8_WAIT_L(8); PG8_BAR; PG8_WAIT_L(0); PG8_MMA(0, 0, At, B0); PG8_BAR; PG8_SCHED;
;             PG8_LDB(B1, 1, 1); PG8_STAGE(PG8_SB(1, 0), b3, voffB);
;             PG8_BAR; PG8_WAIT_L(0); PG8_MMA(0, 1, At, B1); PG8_BAR;
;             PG8_LDA(At, 1, 1); PG8_STAGE(PG8_SA(1, 0), a3, voffA);
;             PG8_BAR; PG8_WAIT_L(0); PG8_MMA(1, 0, At, B0); PG8_BAR; PG8_SCHED;
;             PG8_STAGE(PG8_SB(1, 1), b3 + hstep, voffB);
;             PG8_WAIT_V(6); PG8_BAR; PG8_MMA(1, 1, At, B1); PG8_BAR;
.Lzp3_mid:
	ds_read_b128 v[166:169], v156
	ds_read_b128 v[170:173], v157
	ds_read_b128 v[174:177], v159
	ds_read_b128 v[178:181], v160
	s_add_u32 s28, s52, 0x44000
	s_addc_u32 s29, s53, 0
	s_mov_b32 m0, s63
	ds_read_b128 v[182:185], v146 offset:32768
	ds_read_b128 v[186:189], v146 offset:33792
	ds_read_b128 v[190:193], v146 offset:34816
	ds_read_b128 v[194:197], v146 offset:35840
	ds_read_b128 v[198:201], v146 offset:36864
	ds_read_b128 v[202:205], v146 offset:37888
	ds_read_b128 v[206:209], v146 offset:38912
	ds_read_b128 v[210:213], v146 offset:39936
	global_load_lds_dwordx4 v134, s[28:29]
	s_mov_b32 m0, s64
	s_nop 0
	global_load_lds_dwordx4 v130, s[28:29]
	s_waitcnt lgkmcnt(8)
	s_barrier
	s_waitcnt lgkmcnt(0)
	s_setprio 1
	s_waitcnt lgkmcnt(0)
	v_mfma_f32_16x16x32_bf16 v[124:127], v[166:169], v[182:185], v[124:127]
	v_mfma_f32_16x16x32_bf16 v[120:123], v[174:177], v[182:185], v[120:123]
	v_mfma_f32_16x16x32_bf16 v[116:119], v[166:169], v[190:193], v[116:119]
	v_mfma_f32_16x16x32_bf16 v[112:115], v[174:177], v[190:193], v[112:115]
	v_mfma_f32_16x16x32_bf16 v[108:111], v[166:169], v[198:201], v[108:111]
	v_mfma_f32_16x16x32_bf16 v[104:107], v[174:177], v[198:201], v[104:107]
	v_mfma_f32_16x16x32_bf16 v[100:103], v[166:169], v[206:209], v[100:103]
	v_mfma_f32_16x16x32_bf16 v[96:99], v[174:177], v[206:209], v[96:99]
	v_mfma_f32_16x16x32_bf16 v[124:127], v[170:173], v[186:189], v[124:127]
	v_mfma_f32_16x16x32_bf16 v[120:123], v[178:181], v[186:189], v[120:123]
	v_mfma_f32_16x16x32_bf16 v[116:119], v[170:173], v[194:197], v[116:119]
	v_mfma_f32_16x16x32_bf16 v[112:115], v[178:181], v[194:197], v[112:115]
	v_mfma_f32_16x16x32_bf16 v[108:111], v[170:173], v[202:205], v[108:111]
	v_mfma_f32_16x16x32_bf16 v[104:107], v[178:181], v[202:205], v[104:107]
	v_mfma_f32_16x16x32_bf16 v[100:103], v[170:173], v[210:213], v[100:103]
	v_mfma_f32_16x16x32_bf16 v[96:99], v[178:181], v[210:213], v[96:99]
	s_setprio 0
	s_barrier
	s_mov_b32 m0, s67
	ds_read_b128 v[214:217], v161
	ds_read_b128 v[218:221], v162
	ds_read_b128 v[222:225], v163
	ds_read_b128 v[226:229], v164
	s_add_u32 s100, s36, 0x80
	s_addc_u32 s101, s37, 0
	global_load_lds_dwordx4 v132, s[100:101]
	s_mov_b32 m0, s68
	s_nop 0
	global_load_lds_dwordx4 v128, s[100:101]
	s_barrier
	s_waitcnt lgkmcnt(0)
	s_setprio 1
	s_waitcnt lgkmcnt(0)
	v_mfma_f32_16x16x32_bf16 v[60:63], v[214:217], v[182:185], v[60:63]
	v_mfma_f32_16x16x32_bf16 v[56:59], v[222:225], v[182:185], v[56:59]
	v_mfma_f32_16x16x32_bf16 v[52:55], v[214:217], v[190:193], v[52:55]
	v_mfma_f32_16x16x32_bf16 v[48:51], v[222:225], v[190:193], v[48:51]
	v_mfma_f32_16x16x32_bf16 v[44:47], v[214:217], v[198:201], v[44:47]
	v_mfma_f32_16x16x32_bf16 v[40:43], v[222:225], v[198:201], v[40:43]
	v_mfma_f32_16x16x32_bf16 v[36:39], v[214:217], v[206:209], v[36:39]
	v_mfma_f32_16x16x32_bf16 v[32:35], v[222:225], v[206:209], v[32:35]
	v_mfma_f32_16x16x32_bf16 v[60:63], v[218:221], v[186:189], v[60:63]
	v_mfma_f32_16x16x32_bf16 v[56:59], v[226:229], v[186:189], v[56:59]
	v_mfma_f32_16x16x32_bf16 v[52:55], v[218:221], v[194:197], v[52:55]
	v_mfma_f32_16x16x32_bf16 v[48:51], v[226:229], v[194:197], v[48:51]
	v_mfma_f32_16x16x32_bf16 v[44:47], v[218:221], v[202:205], v[44:47]
	v_mfma_f32_16x16x32_bf16 v[40:43], v[226:229], v[202:205], v[40:43]
	v_mfma_f32_16x16x32_bf16 v[36:39], v[218:221], v[210:213], v[36:39]
	v_mfma_f32_16x16x32_bf16 v[32:35], v[226:229], v[210:213], v[32:35]
	s_setprio 0
	s_mov_b32 m0, s69
	s_barrier
	ds_read_b128 v[182:185], v146 offset:49152
	ds_read_b128 v[186:189], v146 offset:50176
	ds_read_b128 v[190:193], v146 offset:51200
	ds_read_b128 v[194:197], v146 offset:52224
	ds_read_b128 v[198:201], v146 offset:53248
	ds_read_b128 v[202:205], v146 offset:54272
	ds_read_b128 v[206:209], v146 offset:55296
	ds_read_b128 v[210:213], v146 offset:56320
	s_add_u32 s100, s52, 0x80
	s_addc_u32 s101, s53, 0
	global_load_lds_dwordx4 v134, s[100:101]
	s_mov_b32 m0, s70
	s_nop 0
	global_load_lds_dwordx4 v130, s[100:101]
	s_barrier
	s_waitcnt lgkmcnt(0)
	s_setprio 1
	s_waitcnt lgkmcnt(0)
	v_mfma_f32_16x16x32_bf16 v[92:95], v[166:169], v[182:185], v[92:95]
	v_mfma_f32_16x16x32_bf16 v[88:91], v[174:177], v[182:185], v[88:91]
	v_mfma_f32_16x16x32_bf16 v[84:87], v[166:169], v[190:193], v[84:87]
	v_mfma_f32_16x16x32_bf16 v[80:83], v[174:177], v[190:193], v[80:83]
	v_mfma_f32_16x16x32_bf16 v[76:79], v[166:169], v[198:201], v[76:79]
	v_mfma_f32_16x16x32_bf16 v[72:75], v[174:177], v[198:201], v[72:75]
	v_mfma_f32_16x16x32_bf16 v[68:71], v[166:169], v[206:209], v[68:71]
	v_mfma_f32_16x16x32_bf16 v[64:67], v[174:177], v[206:209], v[64:67]
	v_mfma_f32_16x16x32_bf16 v[92:95], v[170:173], v[186:189], v[92:95]
	v_mfma_f32_16x16x32_bf16 v[88:91], v[178:181], v[186:189], v[88:91]
	v_mfma_f32_16x16x32_bf16 v[84:87], v[170:173], v[194:197], v[84:87]
	v_mfma_f32_16x16x32_bf16 v[80:83], v[178:181], v[194:197], v[80:83]
	v_mfma_f32_16x16x32_bf16 v[76:79], v[170:173], v[202:205], v[76:79]
	v_mfma_f32_16x16x32_bf16 v[72:75], v[178:181], v[202:205], v[72:75]
	v_mfma_f32_16x16x32_bf16 v[68:71], v[170:173], v[210:213], v[68:71]
	v_mfma_f32_16x16x32_bf16 v[64:67], v[178:181], v[210:213], v[64:67]
	s_setprio 0
	s_barrier
	s_add_u32 s28, s36, 0x44080
	s_addc_u32 s29, s37, 0
	s_mov_b32 m0, s71
	s_nop 0
	global_load_lds_dwordx4 v132, s[28:29]
	s_mov_b32 m0, s72
	s_nop 0
	global_load_lds_dwordx4 v128, s[28:29]
	s_waitcnt vmcnt(6)
	s_barrier
; #define PG8_STAMP() do { if (STAMP && wid == 0 && nts < 64) { const unsigned long long _c = 0ull; \
;         ts_lo = (lane == nts) ? (int)(unsigned)_c : ts_lo; ts_hi = (lane == nts) ? (int)(unsigned)(_c >> 32) : ts_hi; ++nts; } } while (0)
; #define PG8_MMA(ai, bj, At, Bt) do { __builtin_amdgcn_s_setprio(1); _Pragma("unroll") for (int m = 0; m < 4; ++m) _Pragma("unroll") for (int n = 0; n < 2; ++n) _Pragma("unroll") for (int k = 0; k < 2; ++k) \
;         acc[ai][bj][m][n] = __builtin_amdgcn_mfma_f32_16x16x32_bf16(Bt[n][k], At[m][k], acc[ai][bj][m][n], 0, 0, 0); __builtin_amdgcn_s_setprio(0); } while (0)
; #define PG8_WAIT_V(n) asm volatile("s_waitcnt vmcnt(" #n ")" ::: "memory")
; #define PG8_BAR __builtin_amdgcn_s_barrier()
;     DI void operator()(const f32x4 (&acc)[2][2][4][2], const Unit& u, int wr, int wc, int fr, int fq) const {
;         const int row0 = u.pm * BM + wr * 64 + fr, col0 = u.pn * BM + wc * 32 + 8 * fq;
; #pragma unroll
;         for (int ai = 0; ai < 2; ++ai)
; #pragma unroll
;             for (int m = 0; m < 4; ++m) { u16* rowp = O + (size_t)(row0 + ai * HALF + m * 16) * ldc + col0;
; #pragma unroll
;                 for (int bj = 0; bj < 2; ++bj) { const f32x4 v0 = acc[ai][bj][m][0], v1 = acc[ai][bj][m][1];
;                     uint4 w = {pack2(v0[0], v0[1]), pack2(v0[2], v0[3]), pack2(v1[0], v1[1]), pack2(v1[2], v1[3])}; *(uint4*)(rowp + bj * HALF) = w; } }
;         if (kmaxp) {
; #pragma unroll
;             for (int bj = 0; bj < 2; ++bj) {
;                 const int cb = u.pn * BM + bj * HALF + wc * 32;
;                 const bool isA = (cb >= 384 && cb < 768), isB = (cb >= 1408 && cb < 1664);
; template <class Epi, class Sched, bool STAMP = false>
; __device__ __forceinline__ void gemm_phase(PG8_LAS unsigned char* lds, const Gemm g, const Sched& S, const Epi& E, unsigned long long* stamps) {
;     ...
;             PG8_WAIT_V(6); PG8_BAR; PG8_MMA(1, 1, At, B1); PG8_BAR;
;         }
;         PG8_STAMP();
;         if constexpr (!Epi::AFTER_DRAIN) { E(acc, cur, wr, wc, fr, fq); S.done(cur); }
	s_setprio 1
	v_mfma_f32_16x16x32_bf16 v[28:31], v[214:217], v[182:185], v[28:31]
	v_mfma_f32_16x16x32_bf16 v[24:27], v[222:225], v[182:185], v[24:27]
	v_mfma_f32_16x16x32_bf16 v[20:23], v[214:217], v[190:193], v[20:23]
	v_mfma_f32_16x16x32_bf16 v[16:19], v[222:225], v[190:193], v[16:19]
	v_mfma_f32_16x16x32_bf16 v[12:15], v[214:217], v[198:201], v[12:15]
	v_mfma_f32_16x16x32_bf16 v[8:11], v[222:225], v[198:201], v[8:11]
	v_mfma_f32_16x16x32_bf16 v[4:7], v[214:217], v[206:209], v[4:7]
	v_mfma_f32_16x16x32_bf16 v[0:3], v[222:225], v[206:209], v[0:3]
	v_mfma_f32_16x16x32_bf16 v[28:31], v[218:221], v[186:189], v[28:31]
	v_mfma_f32_16x16x32_bf16 v[24:27], v[226:229], v[186:189], v[24:27]
	v_mfma_f32_16x16x32_bf16 v[20:23], v[218:221], v[194:197], v[20:23]
	v_mfma_f32_16x16x32_bf16 v[16:19], v[226:229], v[194:197], v[16:19]
	v_mfma_f32_16x16x32_bf16 v[12:15], v[218:221], v[202:205], v[12:15]
	v_mfma_f32_16x16x32_bf16 v[8:11], v[226:229], v[202:205], v[8:11]
	v_mfma_f32_16x16x32_bf16 v[4:7], v[218:221], v[210:213], v[4:7]
	v_mfma_f32_16x16x32_bf16 v[0:3], v[226:229], v[210:213], v[0:3]
	s_setprio 0
	s_add_i32 s85, s85, 2
	s_add_u32 s83, s83, 0x100
	s_addc_u32 s84, s84, 0
	s_cmp_gt_u32 s85, 13
	s_mov_b64 s[28:29], s[34:35]
	s_barrier
	s_cbranch_scc0 .LBB0_138
	s_lshl_b32 s52, s79, 8
	v_or_b32_e32 v166, s52, v147
	v_lshl_add_u32 v176, s82, 8, v145
	v_ashrrev_i32_e32 v167, 31, v166
	v_mov_b64_e32 v[170:171], s[12:13]
	v_mad_i64_i32 v[168:169], s[28:29], v176, s76, v[170:171]
	v_lshlrev_b64 v[172:173], 1, v[166:167]
	v_lshl_add_u64 v[174:175], v[168:169], 0, v[172:173]
	v_cvt_pk_bf16_f32 v166, v124, v125
	v_cvt_pk_bf16_f32 v167, v126, v127
	v_cvt_pk_bf16_f32 v168, v120, v121
	v_cvt_pk_bf16_f32 v169, v122, v123
	global_store_dwordx4 v[174:175], v[166:169], off
	s_or_b32 s10, s52, s66
	s_nop 0
	v_cvt_pk_bf16_f32 v166, v60, v61
	v_cvt_pk_bf16_f32 v167, v62, v63
	v_cvt_pk_bf16_f32 v168, v56, v57
	v_cvt_pk_bf16_f32 v169, v58, v59
	global_store_dwordx4 v[174:175], v[166:169], off offset:256
	s_nop 1
	v_or_b32_e32 v166, 16, v176
	v_mad_i64_i32 v[166:167], s[28:29], v166, s76, v[170:171]
	v_lshl_add_u64 v[174:175], v[166:167], 0, v[172:173]
	v_cvt_pk_bf16_f32 v166, v116, v117
	v_cvt_pk_bf16_f32 v167, v118, v119
	v_cvt_pk_bf16_f32 v168, v112, v113
	v_cvt_pk_bf16_f32 v169, v114, v115
	global_store_dwordx4 v[174:175], v[166:169], off
	s_nop 1
	v_cvt_pk_bf16_f32 v166, v52, v53
	v_cvt_pk_bf16_f32 v167, v54, v55
	v_cvt_pk_bf16_f32 v168, v48, v49
	v_cvt_pk_bf16_f32 v169, v50, v51
	global_store_dwordx4 v[174:175], v[166:169], off offset:256
	s_nop 1
	v_or_b32_e32 v166, 32, v176
	v_mad_i64_i32 v[166:167], s[28:29], v166, s76, v[170:171]
	v_lshl_add_u64 v[174:175], v[166:167], 0, v[172:173]
	v_cvt_pk_bf16_f32 v166, v108, v109
	v_cvt_pk_bf16_f32 v167, v110, v111
	v_cvt_pk_bf16_f32 v168, v104, v105
	v_cvt_pk_bf16_f32 v169, v106, v107
	global_store_dwordx4 v[174:175], v[166:169], off
	s_nop 1
	v_cvt_pk_bf16_f32 v166, v44, v45
	v_cvt_pk_bf16_f32 v167, v46, v47
	v_cvt_pk_bf16_f32 v168, v40, v41
	v_cvt_pk_bf16_f32 v169, v42, v43
	global_store_dwordx4 v[174:175], v[166:169], off offset:256
	s_nop 1
	v_or_b32_e32 v166, 48, v176
	v_mad_i64_i32 v[166:167], s[28:29], v166, s76, v[170:171]
	v_lshl_add_u64 v[174:175], v[166:167], 0, v[172:173]
	v_cvt_pk_bf16_f32 v166, v100, v101
	v_cvt_pk_bf16_f32 v167, v102, v103
	v_cvt_pk_bf16_f32 v168, v96, v97
	v_cvt_pk_bf16_f32 v169, v98, v99
	global_store_dwordx4 v[174:175], v[166:169], off
	s_nop 1
	v_cvt_pk_bf16_f32 v166, v36, v37
	v_cvt_pk_bf16_f32 v167, v38, v39
	v_cvt_pk_bf16_f32 v168, v32, v33
	v_cvt_pk_bf16_f32 v169, v34, v35
	global_store_dwordx4 v[174:175], v[166:169], off offset:256
	s_nop 1
	v_add_u32_e32 v166, 0x80, v176
	v_mad_i64_i32 v[166:167], s[28:29], v166, s76, v[170:171]
	v_lshl_add_u64 v[174:175], v[166:167], 0, v[172:173]
	v_cvt_pk_bf16_f32 v166, v92, v93
	v_cvt_pk_bf16_f32 v167, v94, v95
	v_cvt_pk_bf16_f32 v168, v88, v89
	v_cvt_pk_bf16_f32 v169, v90, v91
	global_store_dwordx4 v[174:175], v[166:169], off
	s_nop 1
	v_cvt_pk_bf16_f32 v166, v28, v29
	v_cvt_pk_bf16_f32 v167, v30, v31
	v_cvt_pk_bf16_f32 v168, v24, v25
	v_cvt_pk_bf16_f32 v169, v26, v27
	global_store_dwordx4 v[174:175], v[166:169], off offset:256
	s_nop 1
	v_add_u32_e32 v166, 0x90, v176
	v_mad_i64_i32 v[166:167], s[28:29], v166, s76, v[170:171]
	v_lshl_add_u64 v[174:175], v[166:167], 0, v[172:173]
	v_cvt_pk_bf16_f32 v166, v84, v85
	v_cvt_pk_bf16_f32 v167, v86, v87
	v_cvt_pk_bf16_f32 v168, v80, v81
	v_cvt_pk_bf16_f32 v169, v82, v83
	global_store_dwordx4 v[174:175], v[166:169], off
	s_nop 1
	v_cvt_pk_bf16_f32 v166, v20, v21
	v_cvt_pk_bf16_f32 v167, v22, v23
	v_cvt_pk_bf16_f32 v168, v16, v17
	v_cvt_pk_bf16_f32 v169, v18, v19
	global_store_dwordx4 v[174:175], v[166:169], off offset:256
	s_nop 1
	v_add_u32_e32 v166, 0xa0, v176
	v_mad_i64_i32 v[166:167], s[28:29], v166, s76, v[170:171]
	v_lshl_add_u64 v[174:175], v[166:167], 0, v[172:173]
	v_cvt_pk_bf16_f32 v166, v76, v77
	v_cvt_pk_bf16_f32 v167, v78, v79
	v_cvt_pk_bf16_f32 v168, v72, v73
	v_cvt_pk_bf16_f32 v169, v74, v75
	global_store_dwordx4 v[174:175], v[166:169], off
	s_nop 1
	v_cvt_pk_bf16_f32 v166, v12, v13
	v_cvt_pk_bf16_f32 v167, v14, v15
	v_cvt_pk_bf16_f32 v168, v8, v9
	v_cvt_pk_bf16_f32 v169, v10, v11
	global_store_dwordx4 v[174:175], v[166:169], off offset:256
	s_nop 1
	v_add_u32_e32 v166, 0xb0, v176
	v_mad_i64_i32 v[166:167], s[28:29], v166, s76, v[170:171]
	s_add_i32 s28, s52, 0xfffffe80
	s_cmpk_gt_u32 s28, 0x17f
	s_cselect_b64 s[28:29], -1, 0
	s_add_i32 s34, s52, 0xfffffa80
	s_cmpk_gt_u32 s34, 0xff
	s_cselect_b64 s[34:35], -1, 0
	v_lshl_add_u64 v[170:171], v[166:167], 0, v[172:173]
	v_cvt_pk_bf16_f32 v166, v68, v69
	v_cvt_pk_bf16_f32 v167, v70, v71
	v_cvt_pk_bf16_f32 v168, v64, v65
	v_cvt_pk_bf16_f32 v169, v66, v67
	s_and_b64 s[34:35], s[28:29], s[34:35]
	global_store_dwordx4 v[170:171], v[166:169], off
	s_and_b64 vcc, exec, s[34:35]
	s_nop 0
	v_cvt_pk_bf16_f32 v166, v4, v5
	v_cvt_pk_bf16_f32 v167, v6, v7
	v_cvt_pk_bf16_f32 v168, v0, v1
	v_cvt_pk_bf16_f32 v169, v2, v3
	global_store_dwordx4 v[170:171], v[166:169], off offset:256
	s_cbranch_vccnz .LBB0_150
;     DI void operator()(const f32x4 (&acc)[2][2][4][2], const Unit& u, int wr, int wc, int fr, int fq) const {
;     ...
;         if (kmaxp) {
; #pragma unroll
;             for (int bj = 0; bj < 2; ++bj) {
;                 const int cb = u.pn * BM + bj * HALF + wc * 32;
;                 const bool isA = (cb >= 384 && cb < 768), isB = (cb >= 1408 && cb < 1664);
;                 if (isA || isB) {
;                     float mx = 0.f;
; #pragma unroll
;                     for (int ai = 0; ai < 2; ++ai)
; #pragma unroll
;                         for (int m = 0; m < 4; ++m) {
;                             const f32x4 a = acc[ai][bj][m][0], b = acc[ai][bj][m][1];
;                             float s0 = a[0] * a[0] + a[1] * a[1] + a[2] * a[2] + a[3] * a[3] + b[0] * b[0] + b[1] * b[1] + b[2] * b[2] + b[3] * b[3];
;                             s0 += __shfl_xor(s0, 16);
;                             s0 += __shfl_xor(s0, 32);
;                             mx = fmaxf(mx, s0);
;                         }
; #pragma unroll
;                     for (int o = 1; o <= 8; o <<= 1) mx = fmaxf(mx, __shfl_xor(mx, o));
;                     if ((threadIdx.x & 63) == 0) atomicMax((unsigned*)kmaxp + (isA ? ((cb - 384) >> 5) : (12 + ((cb - 1408) >> 5))), __float_as_uint(mx));
	v_mul_f32_e32 v125, v125, v125
	v_mul_f32_e32 v117, v117, v117
	v_fmac_f32_e32 v125, v124, v124
	v_fmac_f32_e32 v117, v116, v116
	v_mul_f32_e32 v109, v109, v109
	v_mul_f32_e32 v101, v101, v101
	v_fmac_f32_e32 v125, v126, v126
	v_fmac_f32_e32 v117, v118, v118
	v_fmac_f32_e32 v109, v108, v108
	v_fmac_f32_e32 v101, v100, v100
	v_and_b32_e32 v167, 64, v165
	v_fmac_f32_e32 v125, v127, v127
	v_fmac_f32_e32 v117, v119, v119
	v_fmac_f32_e32 v109, v110, v110
	v_fmac_f32_e32 v101, v102, v102
	v_xor_b32_e32 v166, 16, v165
	v_add_u32_e32 v167, 64, v167
	v_fmac_f32_e32 v125, v120, v120
	v_fmac_f32_e32 v117, v112, v112
	v_fmac_f32_e32 v109, v111, v111
	v_fmac_f32_e32 v101, v103, v103
	v_cmp_lt_i32_e32 vcc, v166, v167
	v_fmac_f32_e32 v125, v121, v121
	v_fmac_f32_e32 v117, v113, v113
	v_fmac_f32_e32 v109, v104, v104
	v_fmac_f32_e32 v101, v96, v96
	v_cndmask_b32_e32 v166, v165, v166, vcc
	v_fmac_f32_e32 v125, v122, v122
	v_fmac_f32_e32 v117, v114, v114
	v_fmac_f32_e32 v109, v105, v105
	v_fmac_f32_e32 v101, v97, v97
	v_lshlrev_b32_e32 v166, 2, v166
	v_fmac_f32_e32 v125, v123, v123
	v_fmac_f32_e32 v117, v115, v115
	v_fmac_f32_e32 v109, v106, v106
	v_fmac_f32_e32 v101, v98, v98
	v_mul_f32_e32 v93, v93, v93
	v_mul_f32_e32 v85, v85, v85
	ds_bpermute_b32 v120, v166, v125
	ds_bpermute_b32 v112, v166, v117
	v_fmac_f32_e32 v109, v107, v107
	v_fmac_f32_e32 v101, v99, v99
	v_fmac_f32_e32 v93, v92, v92
	v_fmac_f32_e32 v85, v84, v84
	v_mul_f32_e32 v77, v77, v77
	v_mul_f32_e32 v69, v69, v69
	ds_bpermute_b32 v104, v166, v109
	ds_bpermute_b32 v96, v166, v101
	v_fmac_f32_e32 v93, v94, v94
	v_fmac_f32_e32 v85, v86, v86
	v_fmac_f32_e32 v77, v76, v76
	v_fmac_f32_e32 v69, v68, v68
	v_xor_b32_e32 v168, 32, v165
	v_fmac_f32_e32 v93, v95, v95
	v_fmac_f32_e32 v85, v87, v87
	v_fmac_f32_e32 v77, v78, v78
	v_fmac_f32_e32 v69, v70, v70
	v_cmp_lt_i32_e32 vcc, v168, v167
	v_fmac_f32_e32 v93, v88, v88
	v_fmac_f32_e32 v85, v80, v80
	v_fmac_f32_e32 v77, v79, v79
	v_fmac_f32_e32 v69, v71, v71
	v_cndmask_b32_e32 v113, v165, v168, vcc
	v_fmac_f32_e32 v93, v89, v89
	v_fmac_f32_e32 v85, v81, v81
	v_fmac_f32_e32 v77, v72, v72
	v_fmac_f32_e32 v69, v64, v64
	v_lshlrev_b32_e32 v113, 2, v113
	s_waitcnt lgkmcnt(0)
	v_add_f32_e32 v114, v125, v120
	v_add_f32_e32 v112, v117, v112
	v_fmac_f32_e32 v93, v90, v90
	v_fmac_f32_e32 v85, v82, v82
	v_fmac_f32_e32 v77, v73, v73
	v_fmac_f32_e32 v69, v65, v65
	ds_bpermute_b32 v115, v113, v114
	ds_bpermute_b32 v116, v113, v112
	v_add_f32_e32 v99, v109, v104
	v_add_f32_e32 v96, v101, v96
	v_fmac_f32_e32 v93, v91, v91
	v_fmac_f32_e32 v85, v83, v83
	v_fmac_f32_e32 v77, v74, v74
	v_fmac_f32_e32 v69, v66, v66
	ds_bpermute_b32 v100, v113, v99
	ds_bpermute_b32 v101, v113, v96
	ds_bpermute_b32 v88, v166, v93
	ds_bpermute_b32 v80, v166, v85
	v_fmac_f32_e32 v77, v75, v75
	v_fmac_f32_e32 v69, v67, v67
	ds_bpermute_b32 v72, v166, v77
	ds_bpermute_b32 v64, v166, v69
	s_waitcnt lgkmcnt(0)
	v_add_f32_e32 v97, v114, v115
	v_add_f32_e32 v98, v112, v116
	v_max3_f32 v89, v97, 0, v98
	v_add_f32_e32 v90, v99, v100
	v_add_f32_e32 v91, v96, v101
	v_add_f32_e32 v88, v93, v88
	v_add_f32_e32 v65, v85, v80
	v_max3_f32 v89, v89, v90, v91
	ds_bpermute_b32 v90, v113, v88
	ds_bpermute_b32 v66, v113, v65
	v_add_f32_e32 v67, v77, v72
	v_add_f32_e32 v64, v69, v64
	ds_bpermute_b32 v68, v113, v67
	ds_bpermute_b32 v69, v113, v64
	s_waitcnt lgkmcnt(0)
	v_add_f32_e32 v70, v88, v90
	v_add_f32_e32 v65, v65, v66
	v_max3_f32 v65, v89, v70, v65
	v_add_f32_e32 v66, v67, v68
	v_add_f32_e32 v64, v64, v69
	v_max3_f32 v64, v65, v66, v64
	v_xor_b32_e32 v65, 1, v165
	v_cmp_lt_i32_e32 vcc, v65, v167
	s_nop 1
	v_cndmask_b32_e32 v65, v165, v65, vcc
	v_lshlrev_b32_e32 v65, 2, v65
	ds_bpermute_b32 v65, v65, v64
	s_waitcnt lgkmcnt(0)
	v_max_f32_e32 v65, v65, v65
	v_max_f32_e32 v64, v64, v65
	v_xor_b32_e32 v65, 2, v165
	v_cmp_lt_i32_e32 vcc, v65, v167
	s_nop 1
	v_cndmask_b32_e32 v65, v165, v65, vcc
	v_lshlrev_b32_e32 v65, 2, v65
	ds_bpermute_b32 v65, v65, v64
	s_waitcnt lgkmcnt(0)
	v_max_f32_e32 v65, v65, v65
	v_max_f32_e32 v64, v64, v65
	v_xor_b32_e32 v65, 4, v165
	v_cmp_lt_i32_e32 vcc, v65, v167
	s_nop 1
	v_cndmask_b32_e32 v65, v165, v65, vcc
	v_lshlrev_b32_e32 v65, 2, v65
	ds_bpermute_b32 v65, v65, v64
	s_waitcnt lgkmcnt(0)
	v_max_f32_e32 v65, v65, v65
	v_max_f32_e32 v64, v64, v65
	v_xor_b32_e32 v65, 8, v165
	v_cmp_lt_i32_e32 vcc, v65, v167
	s_nop 1
	v_cndmask_b32_e32 v65, v165, v65, vcc
	v_lshlrev_b32_e32 v65, 2, v65
	ds_bpermute_b32 v65, v65, v64
	s_and_saveexec_b64 s[34:35], s[2:3]
	s_cbranch_execz .LBB0_149
	s_mov_b64 s[36:37], -1
	s_and_b64 vcc, exec, s[28:29]
	s_cbranch_vccz .LBB0_143
	s_add_i32 s28, s10, 0xfffffa80
	s_ashr_i32 s28, s28, 5
	s_add_i32 s28, s28, 12
	s_mov_b64 s[36:37], 0

; #define PG8_STAGE(bufoff, gbase, voff) do { _Pragma("unroll") for (int _i = 0; _i < 2; ++_i) \
;         __builtin_amdgcn_global_load_lds((const unsigned*)((const char*)(gbase) + (voff)[_i]), (PG8_LAS unsigned*)(lds + (bufoff) + ldsw + _i * 8192), 16, 0, 0); } while (0)
; #define PG8_LDA(dst, b, h) do { _Pragma("unroll") for (int m = 0; m < 4; ++m) _Pragma("unroll") for (int k = 0; k < 2; ++k) dst[m][k] = *(const PG8_LAS bf16x8*)(lds + PG8_SA(b, h) + aoff + m * 2048 + k * 1024); } while (0)
; #define PG8_LDB(dst, b, h) do { _Pragma("unroll") for (int n = 0; n < 2; ++n) _Pragma("unroll") for (int k = 0; k < 2; ++k) dst[n][k] = *(const PG8_LAS bf16x8*)(lds + PG8_SB(b, h) + boff + n * 2048 + k * 1024); } while (0)
; #define PG8_WAIT_V(n) asm volatile("s_waitcnt vmcnt(" #n ")" ::: "memory")
; #define PG8_WAIT_L(n) asm volatile("s_waitcnt lgkmcnt(" #n ")" ::: "memory")
; #define PG8_BAR __builtin_amdgcn_s_barrier()
; template <class Epi, class Sched, bool STAMP = false>
; __device__ __forceinline__ void gemm_phase(PG8_LAS unsigned char* lds, const Gemm g, const Sched& S, const Epi& E, unsigned long long* stamps) {
;     ...
;     for (;;) {
;         const bool has_next = S.next(ui + 1, nxt);
;         const char* nA = has_next ? (const char*)g.A + (size_t)nxt.pm * tstep : cA; const char* nB = has_next ? (const char*)g.Bt + (size_t)nxt.pn * tstep : cB;
;         for (int t = 0; t < nt; t += 2) {
;             const bool last = (t == nt - 2);
;             const char* a1 = cA + (size_t)(t + 1) * kstep;
;             const char* a2 = last ? nA : cA + (size_t)(t + 2) * kstep; const char* b2 = last ? nB : cB + (size_t)(t + 2) * kstep;
;             const char* a3 = a2 + kstep; const char* b3 = b2 + kstep;
;             if (last && has_next) S.a_ready(nxt);
;             PG8_LDB(B0, 0, 0); PG8_SCHED; PG8_LDA(At, 0, 0); PG8_STAGE(PG8_SA(1, 1), a1 + hstep, voffA);
;             PG8_WAIT_L(8); PG8_BAR; PG8_WAIT_L(0); PG8_MMA(0, 0, At, B0); PG8_BAR; PG8_SCHED;
;             PG8_LDB(B1, 0, 1); PG8_STAGE(PG8_SB(0, 0), b2, voffB);
;             PG8_BAR; PG8_WAIT_L(0); PG8_MMA(0, 1, At, B1); PG8_BAR;
;             PG8_LDA(At, 0, 1); PG8_STAGE(PG8_SA(0, 0), a2, voffA);
;             PG8_BAR; PG8_WAIT_L(0); PG8_MMA(1, 0, At, B0); PG8_BAR; PG8_SCHED;
;             PG8_STAGE(PG8_SB(0, 1), b2 + hstep, voffB);
;             PG8_WAIT_V(6); PG8_BAR; PG8_MMA(1, 1, At, B1); PG8_BAR;
.LBB0_311:
	s_add_u32 s94, s58, 0x100
	s_addc_u32 s95, s59, 0
	s_mov_b32 s96, -2
	ds_read_b128 v[170:173], v147
	ds_read_b128 v[174:177], v148
	ds_read_b128 v[178:181], v149
	ds_read_b128 v[182:185], v150
	s_add_u32 s58, s56, 0x100
	s_addc_u32 s59, s57, 0
	s_cmp_eq_u32 s96, 12
	s_cselect_b32 s63, s5, s59
	s_cselect_b32 s62, s4, s58
	s_cselect_b32 s61, s1, s95
	s_cselect_b32 s60, s0, s94
	s_mov_b32 m0, s84
	ds_read_b128 v[186:189], v145
	ds_read_b128 v[190:193], v145 offset:1024
	ds_read_b128 v[194:197], v145 offset:2048
	ds_read_b128 v[198:201], v145 offset:3072
	ds_read_b128 v[202:205], v145 offset:4096
	ds_read_b128 v[206:209], v145 offset:5120
	ds_read_b128 v[210:213], v145 offset:6144
	ds_read_b128 v[214:217], v145 offset:7168
	global_load_lds_dwordx4 v136, s[56:57]
	s_mov_b32 m0, s85
	s_nop 0
	global_load_lds_dwordx4 v138, s[56:57]
	s_waitcnt lgkmcnt(8)
	s_barrier
	s_waitcnt lgkmcnt(0)
	s_setprio 1
	s_waitcnt lgkmcnt(0)
	v_mfma_f32_16x16x32_bf16 v[124:127], v[170:173], v[186:189], 0
	v_mfma_f32_16x16x32_bf16 v[120:123], v[178:181], v[186:189], 0
	v_mfma_f32_16x16x32_bf16 v[116:119], v[170:173], v[194:197], 0
	v_mfma_f32_16x16x32_bf16 v[112:115], v[178:181], v[194:197], 0
	v_mfma_f32_16x16x32_bf16 v[100:103], v[170:173], v[202:205], 0
	v_mfma_f32_16x16x32_bf16 v[96:99], v[178:181], v[202:205], 0
	v_mfma_f32_16x16x32_bf16 v[84:87], v[170:173], v[210:213], 0
	v_mfma_f32_16x16x32_bf16 v[80:83], v[178:181], v[210:213], 0
	v_mfma_f32_16x16x32_bf16 v[124:127], v[174:177], v[190:193], v[124:127]
	v_mfma_f32_16x16x32_bf16 v[120:123], v[182:185], v[190:193], v[120:123]
	v_mfma_f32_16x16x32_bf16 v[116:119], v[174:177], v[198:201], v[116:119]
	v_mfma_f32_16x16x32_bf16 v[112:115], v[182:185], v[198:201], v[112:115]
	v_mfma_f32_16x16x32_bf16 v[100:103], v[174:177], v[206:209], v[100:103]
	v_mfma_f32_16x16x32_bf16 v[96:99], v[182:185], v[206:209], v[96:99]
	v_mfma_f32_16x16x32_bf16 v[84:87], v[174:177], v[214:217], v[84:87]
	v_mfma_f32_16x16x32_bf16 v[80:83], v[182:185], v[214:217], v[80:83]
	s_setprio 0
	s_barrier
	s_mov_b32 m0, s67
	ds_read_b128 v[218:221], v151
	ds_read_b128 v[222:225], v152
	ds_read_b128 v[226:229], v153
	ds_read_b128 v[230:233], v154
	global_load_lds_dwordx4 v130, s[60:61]
	s_mov_b32 m0, s68
	s_nop 0
	global_load_lds_dwordx4 v134, s[60:61]
	s_barrier
	s_waitcnt lgkmcnt(0)
	s_setprio 1
	s_waitcnt lgkmcnt(0)
	v_mfma_f32_16x16x32_bf16 v[108:111], v[218:221], v[186:189], 0
	v_mfma_f32_16x16x32_bf16 v[104:107], v[226:229], v[186:189], 0
	v_mfma_f32_16x16x32_bf16 v[92:95], v[218:221], v[194:197], 0
	v_mfma_f32_16x16x32_bf16 v[88:91], v[226:229], v[194:197], 0
	v_mfma_f32_16x16x32_bf16 v[76:79], v[218:221], v[202:205], 0
	v_mfma_f32_16x16x32_bf16 v[72:75], v[226:229], v[202:205], 0
	v_mfma_f32_16x16x32_bf16 v[68:71], v[218:221], v[210:213], 0
	v_mfma_f32_16x16x32_bf16 v[64:67], v[226:229], v[210:213], 0
	v_mfma_f32_16x16x32_bf16 v[108:111], v[222:225], v[190:193], v[108:111]
	v_mfma_f32_16x16x32_bf16 v[104:107], v[230:233], v[190:193], v[104:107]
	v_mfma_f32_16x16x32_bf16 v[92:95], v[222:225], v[198:201], v[92:95]
	v_mfma_f32_16x16x32_bf16 v[88:91], v[230:233], v[198:201], v[88:91]
	v_mfma_f32_16x16x32_bf16 v[76:79], v[222:225], v[206:209], v[76:79]
	v_mfma_f32_16x16x32_bf16 v[72:75], v[230:233], v[206:209], v[72:75]
	v_mfma_f32_16x16x32_bf16 v[68:71], v[222:225], v[214:217], v[68:71]
	v_mfma_f32_16x16x32_bf16 v[64:67], v[230:233], v[214:217], v[64:67]
	s_setprio 0
	s_mov_b32 m0, s66
	s_barrier
	ds_read_b128 v[186:189], v145 offset:16384
	ds_read_b128 v[190:193], v145 offset:17408
	ds_read_b128 v[194:197], v145 offset:18432
	ds_read_b128 v[198:201], v145 offset:19456
	ds_read_b128 v[202:205], v145 offset:20480
	ds_read_b128 v[206:209], v145 offset:21504
	ds_read_b128 v[210:213], v145 offset:22528
	ds_read_b128 v[214:217], v145 offset:23552
	global_load_lds_dwordx4 v128, s[62:63]
	s_mov_b32 m0, s69
	s_nop 0
	global_load_lds_dwordx4 v132, s[62:63]
	s_barrier
	s_waitcnt lgkmcnt(0)
	s_setprio 1
	s_waitcnt lgkmcnt(0)
	v_mfma_f32_16x16x32_bf16 v[60:63], v[170:173], v[186:189], 0
	v_mfma_f32_16x16x32_bf16 v[56:59], v[178:181], v[186:189], 0
	v_mfma_f32_16x16x32_bf16 v[52:55], v[170:173], v[194:197], 0
	v_mfma_f32_16x16x32_bf16 v[48:51], v[178:181], v[194:197], 0
	v_mfma_f32_16x16x32_bf16 v[36:39], v[170:173], v[202:205], 0
	v_mfma_f32_16x16x32_bf16 v[32:35], v[178:181], v[202:205], 0
	v_mfma_f32_16x16x32_bf16 v[20:23], v[170:173], v[210:213], 0
	v_mfma_f32_16x16x32_bf16 v[16:19], v[178:181], v[210:213], 0
	v_mfma_f32_16x16x32_bf16 v[60:63], v[174:177], v[190:193], v[60:63]
	v_mfma_f32_16x16x32_bf16 v[56:59], v[182:185], v[190:193], v[56:59]
	v_mfma_f32_16x16x32_bf16 v[52:55], v[174:177], v[198:201], v[52:55]
	v_mfma_f32_16x16x32_bf16 v[48:51], v[182:185], v[198:201], v[48:51]
	v_mfma_f32_16x16x32_bf16 v[36:39], v[174:177], v[206:209], v[36:39]
	v_mfma_f32_16x16x32_bf16 v[32:35], v[182:185], v[206:209], v[32:35]
	v_mfma_f32_16x16x32_bf16 v[20:23], v[174:177], v[214:217], v[20:23]
	v_mfma_f32_16x16x32_bf16 v[16:19], v[182:185], v[214:217], v[16:19]
	s_setprio 0
	s_barrier
	s_add_u32 s56, s60, 0x44000
	s_addc_u32 s57, s61, 0
	s_mov_b32 m0, s70
	s_nop 0
	global_load_lds_dwordx4 v130, s[56:57]
	s_mov_b32 m0, s71
	s_nop 0
	global_load_lds_dwordx4 v134, s[56:57]
	s_waitcnt vmcnt(6)
	s_barrier
	s_setprio 1
	v_mfma_f32_16x16x32_bf16 v[44:47], v[218:221], v[186:189], 0
	v_mfma_f32_16x16x32_bf16 v[40:43], v[226:229], v[186:189], 0
	v_mfma_f32_16x16x32_bf16 v[28:31], v[218:221], v[194:197], 0
	v_mfma_f32_16x16x32_bf16 v[24:27], v[226:229], v[194:197], 0
	v_mfma_f32_16x16x32_bf16 v[12:15], v[218:221], v[202:205], 0
	v_mfma_f32_16x16x32_bf16 v[8:11], v[226:229], v[202:205], 0
	v_mfma_f32_16x16x32_bf16 v[4:7], v[218:221], v[210:213], 0
	v_mfma_f32_16x16x32_bf16 v[0:3], v[226:229], v[210:213], 0
	v_mfma_f32_16x16x32_bf16 v[44:47], v[222:225], v[190:193], v[44:47]
	v_mfma_f32_16x16x32_bf16 v[40:43], v[230:233], v[190:193], v[40:43]
	v_mfma_f32_16x16x32_bf16 v[28:31], v[222:225], v[198:201], v[28:31]
	v_mfma_f32_16x16x32_bf16 v[24:27], v[230:233], v[198:201], v[24:27]
	v_mfma_f32_16x16x32_bf16 v[12:15], v[222:225], v[206:209], v[12:15]
	v_mfma_f32_16x16x32_bf16 v[8:11], v[230:233], v[206:209], v[8:11]
	v_mfma_f32_16x16x32_bf16 v[4:7], v[222:225], v[214:217], v[4:7]
	v_mfma_f32_16x16x32_bf16 v[0:3], v[230:233], v[214:217], v[0:3]
	s_setprio 0
	s_barrier
	s_branch .Lzp4_mid

; #define PG8_STAGE(bufoff, gbase, voff) do { _Pragma("unroll") for (int _i = 0; _i < 2; ++_i) \
;         __builtin_amdgcn_global_load_lds((const unsigned*)((const char*)(gbase) + (voff)[_i]), (PG8_LAS unsigned*)(lds + (bufoff) + ldsw + _i * 8192), 16, 0, 0); } while (0)
; #define PG8_LDA(dst, b, h) do { _Pragma("unroll") for (int m = 0; m < 4; ++m) _Pragma("unroll") for (int k = 0; k < 2; ++k) dst[m][k] = *(const PG8_LAS bf16x8*)(lds + PG8_SA(b, h) + aoff + m * 2048 + k * 1024); } while (0)
; #define PG8_LDB(dst, b, h) do { _Pragma("unroll") for (int n = 0; n < 2; ++n) _Pragma("unroll") for (int k = 0; k < 2; ++k) dst[n][k] = *(const PG8_LAS bf16x8*)(lds + PG8_SB(b, h) + boff + n * 2048 + k * 1024); } while (0)
; #define PG8_MMA(ai, bj, At, Bt) do { __builtin_amdgcn_s_setprio(1); _Pragma("unroll") for (int m = 0; m < 4; ++m) _Pragma("unroll") for (int n = 0; n < 2; ++n) _Pragma("unroll") for (int k = 0; k < 2; ++k) \
;         acc[ai][bj][m][n] = __builtin_amdgcn_mfma_f32_16x16x32_bf16(Bt[n][k], At[m][k], acc[ai][bj][m][n], 0, 0, 0); __builtin_amdgcn_s_setprio(0); } while (0)
; #define PG8_WAIT_V(n) asm volatile("s_waitcnt vmcnt(" #n ")" ::: "memory")
; #define PG8_WAIT_L(n) asm volatile("s_waitcnt lgkmcnt(" #n ")" ::: "memory")
; #define PG8_BAR __builtin_amdgcn_s_barrier()
; #define PG8_SCHED __builtin_amdgcn_sched_barrier(0)
; template <class Epi, class Sched, bool STAMP = false>
; __device__ __forceinline__ void gemm_phase(PG8_LAS unsigned char* lds, const Gemm g, const Sched& S, const Epi& E, unsigned long long* stamps) {
;     ...
;             PG8_LDB(B0, 1, 0); PG8_SCHED; PG8_LDA(At, 1, 0); PG8_STAGE(PG8_SA(0, 1), a2 + hstep, voffA);
;             PG8_WAIT_L(8); PG8_BAR; PG8_WAIT_L(0); PG8_MMA(0, 0, At, B0); PG8_BAR; PG8_SCHED;
;             PG8_LDB(B1, 1, 1); PG8_STAGE(PG8_SB(1, 0), b3, voffB);
;             PG8_BAR; PG8_WAIT_L(0); PG8_MMA(0, 1, At, B1); PG8_BAR;
;             PG8_LDA(At, 1, 1); PG8_STAGE(PG8_SA(1, 0), a3, voffA);
;             PG8_BAR; PG8_WAIT_L(0); PG8_MMA(1, 0, At, B0); PG8_BAR; PG8_SCHED;
;             PG8_STAGE(PG8_SB(1, 1), b3 + hstep, voffB);
;             PG8_WAIT_V(6); PG8_BAR; PG8_MMA(1, 1, At, B1); PG8_BAR;
.Lzp4_mid:
	ds_read_b128 v[170:173], v155
	ds_read_b128 v[174:177], v156
	ds_read_b128 v[178:181], v157
	ds_read_b128 v[182:185], v165
	s_add_u32 s56, s62, 0x44000
	s_addc_u32 s57, s63, 0
	s_mov_b32 m0, s72
	ds_read_b128 v[186:189], v145 offset:32768
	ds_read_b128 v[190:193], v145 offset:33792
	ds_read_b128 v[194:197], v145 offset:34816
	ds_read_b128 v[198:201], v145 offset:35840
	ds_read_b128 v[202:205], v145 offset:36864
	ds_read_b128 v[206:209], v145 offset:37888
	ds_read_b128 v[210:213], v145 offset:38912
	ds_read_b128 v[214:217], v145 offset:39936
	global_load_lds_dwordx4 v128, s[56:57]
	s_mov_b32 m0, s73
	s_nop 0
	global_load_lds_dwordx4 v132, s[56:57]
	s_waitcnt lgkmcnt(8)
	s_barrier
	s_waitcnt lgkmcnt(0)
	s_setprio 1
	s_waitcnt lgkmcnt(0)
	v_mfma_f32_16x16x32_bf16 v[124:127], v[170:173], v[186:189], v[124:127]
	v_mfma_f32_16x16x32_bf16 v[120:123], v[178:181], v[186:189], v[120:123]
	v_mfma_f32_16x16x32_bf16 v[116:119], v[170:173], v[194:197], v[116:119]
	v_mfma_f32_16x16x32_bf16 v[112:115], v[178:181], v[194:197], v[112:115]
	v_mfma_f32_16x16x32_bf16 v[100:103], v[170:173], v[202:205], v[100:103]
	v_mfma_f32_16x16x32_bf16 v[96:99], v[178:181], v[202:205], v[96:99]
	v_mfma_f32_16x16x32_bf16 v[84:87], v[170:173], v[210:213], v[84:87]
	v_mfma_f32_16x16x32_bf16 v[80:83], v[178:181], v[210:213], v[80:83]
	v_mfma_f32_16x16x32_bf16 v[124:127], v[174:177], v[190:193], v[124:127]
	v_mfma_f32_16x16x32_bf16 v[120:123], v[182:185], v[190:193], v[120:123]
	v_mfma_f32_16x16x32_bf16 v[116:119], v[174:177], v[198:201], v[116:119]
	v_mfma_f32_16x16x32_bf16 v[112:115], v[182:185], v[198:201], v[112:115]
	v_mfma_f32_16x16x32_bf16 v[100:103], v[174:177], v[206:209], v[100:103]
	v_mfma_f32_16x16x32_bf16 v[96:99], v[182:185], v[206:209], v[96:99]
	v_mfma_f32_16x16x32_bf16 v[84:87], v[174:177], v[214:217], v[84:87]
	v_mfma_f32_16x16x32_bf16 v[80:83], v[182:185], v[214:217], v[80:83]
	s_setprio 0
	s_barrier
	s_mov_b32 m0, s74
	ds_read_b128 v[218:221], v166
	ds_read_b128 v[222:225], v167
	ds_read_b128 v[226:229], v168
	ds_read_b128 v[230:233], v169
	s_add_u32 s100, s60, 0x80
	s_addc_u32 s101, s61, 0
	global_load_lds_dwordx4 v130, s[100:101]
	s_mov_b32 m0, s75
	s_nop 0
	global_load_lds_dwordx4 v134, s[100:101]
	s_barrier
	s_waitcnt lgkmcnt(0)
	s_setprio 1
	s_waitcnt lgkmcnt(0)
	v_mfma_f32_16x16x32_bf16 v[108:111], v[218:221], v[186:189], v[108:111]
	v_mfma_f32_16x16x32_bf16 v[104:107], v[226:229], v[186:189], v[104:107]
	v_mfma_f32_16x16x32_bf16 v[92:95], v[218:221], v[194:197], v[92:95]
	v_mfma_f32_16x16x32_bf16 v[88:91], v[226:229], v[194:197], v[88:91]
	v_mfma_f32_16x16x32_bf16 v[76:79], v[218:221], v[202:205], v[76:79]
	v_mfma_f32_16x16x32_bf16 v[72:75], v[226:229], v[202:205], v[72:75]
	v_mfma_f32_16x16x32_bf16 v[68:71], v[218:221], v[210:213], v[68:71]
	v_mfma_f32_16x16x32_bf16 v[64:67], v[226:229], v[210:213], v[64:67]
	v_mfma_f32_16x16x32_bf16 v[108:111], v[222:225], v[190:193], v[108:111]
	v_mfma_f32_16x16x32_bf16 v[104:107], v[230:233], v[190:193], v[104:107]
	v_mfma_f32_16x16x32_bf16 v[92:95], v[222:225], v[198:201], v[92:95]
	v_mfma_f32_16x16x32_bf16 v[88:91], v[230:233], v[198:201], v[88:91]
	v_mfma_f32_16x16x32_bf16 v[76:79], v[222:225], v[206:209], v[76:79]
	v_mfma_f32_16x16x32_bf16 v[72:75], v[230:233], v[206:209], v[72:75]
	v_mfma_f32_16x16x32_bf16 v[68:71], v[222:225], v[214:217], v[68:71]
	v_mfma_f32_16x16x32_bf16 v[64:67], v[230:233], v[214:217], v[64:67]
	s_setprio 0
	s_mov_b32 m0, s76
	s_barrier
	ds_read_b128 v[186:189], v145 offset:49152
	ds_read_b128 v[190:193], v145 offset:50176
	ds_read_b128 v[194:197], v145 offset:51200
	ds_read_b128 v[198:201], v145 offset:52224
	ds_read_b128 v[202:205], v145 offset:53248
	ds_read_b128 v[206:209], v145 offset:54272
	ds_read_b128 v[210:213], v145 offset:55296
	ds_read_b128 v[214:217], v145 offset:56320
	s_add_u32 s100, s62, 0x80
	s_addc_u32 s101, s63, 0
	global_load_lds_dwordx4 v128, s[100:101]
	s_mov_b32 m0, s77
	s_nop 0
	global_load_lds_dwordx4 v132, s[100:101]
	s_barrier
	s_waitcnt lgkmcnt(0)
	s_setprio 1
	s_waitcnt lgkmcnt(0)
	v_mfma_f32_16x16x32_bf16 v[60:63], v[170:173], v[186:189], v[60:63]
	v_mfma_f32_16x16x32_bf16 v[56:59], v[178:181], v[186:189], v[56:59]
	v_mfma_f32_16x16x32_bf16 v[52:55], v[170:173], v[194:197], v[52:55]
	v_mfma_f32_16x16x32_bf16 v[48:51], v[178:181], v[194:197], v[48:51]
	v_mfma_f32_16x16x32_bf16 v[36:39], v[170:173], v[202:205], v[36:39]
	v_mfma_f32_16x16x32_bf16 v[32:35], v[178:181], v[202:205], v[32:35]
	v_mfma_f32_16x16x32_bf16 v[20:23], v[170:173], v[210:213], v[20:23]
	v_mfma_f32_16x16x32_bf16 v[16:19], v[178:181], v[210:213], v[16:19]
	v_mfma_f32_16x16x32_bf16 v[60:63], v[174:177], v[190:193], v[60:63]
	v_mfma_f32_16x16x32_bf16 v[56:59], v[182:185], v[190:193], v[56:59]
	v_mfma_f32_16x16x32_bf16 v[52:55], v[174:177], v[198:201], v[52:55]
	v_mfma_f32_16x16x32_bf16 v[48:51], v[182:185], v[198:201], v[48:51]
	v_mfma_f32_16x16x32_bf16 v[36:39], v[174:177], v[206:209], v[36:39]
	v_mfma_f32_16x16x32_bf16 v[32:35], v[182:185], v[206:209], v[32:35]
	v_mfma_f32_16x16x32_bf16 v[20:23], v[174:177], v[214:217], v[20:23]
	v_mfma_f32_16x16x32_bf16 v[16:19], v[182:185], v[214:217], v[16:19]
	s_setprio 0
	s_barrier
	s_add_u32 s56, s60, 0x44080
	s_addc_u32 s57, s61, 0
	s_mov_b32 m0, s78
	s_nop 0
	global_load_lds_dwordx4 v130, s[56:57]
	s_mov_b32 m0, s79
	s_nop 0
	global_load_lds_dwordx4 v134, s[56:57]
	s_waitcnt vmcnt(6)
	s_barrier
; #define PG8_STAMP() do { if (STAMP && wid == 0 && nts < 64) { const unsigned long long _c = 0ull; \
;         ts_lo = (lane == nts) ? (int)(unsigned)_c : ts_lo; ts_hi = (lane == nts) ? (int)(unsigned)(_c >> 32) : ts_hi; ++nts; } } while (0)
; #define PG8_MMA(ai, bj, At, Bt) do { __builtin_amdgcn_s_setprio(1); _Pragma("unroll") for (int m = 0; m < 4; ++m) _Pragma("unroll") for (int n = 0; n < 2; ++n) _Pragma("unroll") for (int k = 0; k < 2; ++k) \
;         acc[ai][bj][m][n] = __builtin_amdgcn_mfma_f32_16x16x32_bf16(Bt[n][k], At[m][k], acc[ai][bj][m][n], 0, 0, 0); __builtin_amdgcn_s_setprio(0); } while (0)
; #define PG8_WAIT_V(n) asm volatile("s_waitcnt vmcnt(" #n ")" ::: "memory")
; #define PG8_BAR __builtin_amdgcn_s_barrier()
;     DI void operator()(const f32x4 (&acc)[2][2][4][2], const Unit& u, int wr, int wc, int fr, int fq) const {
;         const int row0 = u.pm * BM + wr * 64 + fr, col0 = u.pn * BM + wc * 32 + 8 * fq;
; #pragma unroll
;         for (int ai = 0; ai < 2; ++ai)
; #pragma unroll
;             for (int m = 0; m < 4; ++m) { u16* rowp = O + (size_t)(row0 + ai * HALF + m * 16) * ldc + col0;
; #pragma unroll
;                 for (int bj = 0; bj < 2; ++bj) { const f32x4 v0 = acc[ai][bj][m][0], v1 = acc[ai][bj][m][1];
;                     uint4 w = {pack2(v0[0], v0[1]), pack2(v0[2], v0[3]), pack2(v1[0], v1[1]), pack2(v1[2], v1[3])}; *(uint4*)(rowp + bj * HALF) = w; } }
; template <class Epi, class Sched, bool STAMP = false>
; __device__ __forceinline__ void gemm_phase(PG8_LAS unsigned char* lds, const Gemm g, const Sched& S, const Epi& E, unsigned long long* stamps) {
;     ...
;             PG8_WAIT_V(6); PG8_BAR; PG8_MMA(1, 1, At, B1); PG8_BAR;
;         }
;         PG8_STAMP();
;         if constexpr (!Epi::AFTER_DRAIN) { E(acc, cur, wr, wc, fr, fq); S.done(cur); }
;         PG8_STAMP();
;         if (!has_next) break;
	s_setprio 1
	v_mfma_f32_16x16x32_bf16 v[44:47], v[218:221], v[186:189], v[44:47]
	v_mfma_f32_16x16x32_bf16 v[40:43], v[226:229], v[186:189], v[40:43]
	v_mfma_f32_16x16x32_bf16 v[28:31], v[218:221], v[194:197], v[28:31]
	v_mfma_f32_16x16x32_bf16 v[24:27], v[226:229], v[194:197], v[24:27]
	v_mfma_f32_16x16x32_bf16 v[12:15], v[218:221], v[202:205], v[12:15]
	v_mfma_f32_16x16x32_bf16 v[8:11], v[226:229], v[202:205], v[8:11]
	v_mfma_f32_16x16x32_bf16 v[4:7], v[218:221], v[210:213], v[4:7]
	v_mfma_f32_16x16x32_bf16 v[0:3], v[226:229], v[210:213], v[0:3]
	v_mfma_f32_16x16x32_bf16 v[44:47], v[222:225], v[190:193], v[44:47]
	v_mfma_f32_16x16x32_bf16 v[40:43], v[230:233], v[190:193], v[40:43]
	v_mfma_f32_16x16x32_bf16 v[28:31], v[222:225], v[198:201], v[28:31]
	v_mfma_f32_16x16x32_bf16 v[24:27], v[230:233], v[198:201], v[24:27]
	v_mfma_f32_16x16x32_bf16 v[12:15], v[222:225], v[206:209], v[12:15]
	v_mfma_f32_16x16x32_bf16 v[8:11], v[230:233], v[206:209], v[8:11]
	v_mfma_f32_16x16x32_bf16 v[4:7], v[222:225], v[214:217], v[4:7]
	v_mfma_f32_16x16x32_bf16 v[0:3], v[230:233], v[214:217], v[0:3]
	s_setprio 0
	s_add_i32 s96, s96, 2
	s_add_u32 s94, s94, 0x100
	s_addc_u32 s95, s95, 0
	s_cmp_gt_u32 s96, 13
	s_mov_b64 s[56:57], s[58:59]
	s_barrier
	s_cbranch_scc0 .LBB0_312
	v_lshl_add_u32 v170, s90, 8, v144
	v_lshl_or_b32 v172, s93, 8, v146
	v_ashrrev_i32_e32 v171, 31, v170
	v_ashrrev_i32_e32 v173, 31, v172
	v_lshlrev_b64 v[174:175], 11, v[170:171]
	v_lshl_add_u64 v[174:175], s[14:15], 0, v[174:175]
	v_lshlrev_b64 v[172:173], 1, v[172:173]
	v_lshl_add_u64 v[174:175], v[174:175], 0, v[172:173]
	v_cvt_pk_bf16_f32 v60, v60, v61
	v_cvt_pk_bf16_f32 v61, v62, v63
	v_cvt_pk_bf16_f32 v62, v56, v57
	v_add_co_u32_e32 v56, vcc, s86, v174
	v_cvt_pk_bf16_f32 v68, v68, v69
	v_cvt_pk_bf16_f32 v69, v70, v71
	v_cvt_pk_bf16_f32 v70, v64, v65
	v_lshl_add_u64 v[64:65], v[174:175], 0, s[34:35]
	v_addc_co_u32_e32 v57, vcc, 0, v175, vcc
	v_cvt_pk_bf16_f32 v44, v44, v45
	v_cvt_pk_bf16_f32 v45, v46, v47
	v_cvt_pk_bf16_f32 v46, v40, v41
	v_cvt_pk_bf16_f32 v47, v42, v43
	v_cvt_pk_bf16_f32 v108, v108, v109
	v_cvt_pk_bf16_f32 v109, v110, v111
	v_cvt_pk_bf16_f32 v110, v104, v105
	v_or_b32_e32 v104, 16, v170
	global_store_dwordx4 v[64:65], v[44:47], off offset:256
	v_ashrrev_i32_e32 v105, 31, v104
	v_cvt_pk_bf16_f32 v92, v92, v93
	v_add_co_u32_e32 v46, vcc, s87, v174
	v_cvt_pk_bf16_f32 v93, v94, v95
	v_cvt_pk_bf16_f32 v94, v88, v89
	v_or_b32_e32 v88, 32, v170
	v_lshl_add_u64 v[44:45], v[174:175], 0, s[36:37]
	v_addc_co_u32_e32 v47, vcc, 0, v175, vcc
	v_cvt_pk_bf16_f32 v28, v28, v29
	v_cvt_pk_bf16_f32 v29, v30, v31
	v_cvt_pk_bf16_f32 v30, v24, v25
	v_cvt_pk_bf16_f32 v31, v26, v27
	v_lshlrev_b64 v[104:105], 11, v[104:105]
	v_ashrrev_i32_e32 v89, 31, v88
	v_cvt_pk_bf16_f32 v76, v76, v77
	v_cvt_pk_bf16_f32 v77, v78, v79
	v_cvt_pk_bf16_f32 v78, v72, v73
	v_or_b32_e32 v72, 48, v170
	global_store_dwordx4 v[44:45], v[28:31], off offset:256
	v_cvt_pk_bf16_f32 v111, v106, v107
	v_lshl_add_u64 v[104:105], s[14:15], 0, v[104:105]
	v_add_co_u32_e32 v30, vcc, s88, v174
	v_lshlrev_b64 v[88:89], 11, v[88:89]
	v_ashrrev_i32_e32 v73, 31, v72
	v_lshl_add_u64 v[28:29], v[174:175], 0, s[52:53]
	v_addc_co_u32_e32 v31, vcc, 0, v175, vcc
	v_cvt_pk_bf16_f32 v12, v12, v13
	v_cvt_pk_bf16_f32 v13, v14, v15
	v_cvt_pk_bf16_f32 v14, v8, v9
	v_cvt_pk_bf16_f32 v15, v10, v11
	global_store_dwordx4 v[174:175], v[108:111], off offset:256
	v_cvt_pk_bf16_f32 v95, v90, v91
	v_lshl_add_u64 v[88:89], s[14:15], 0, v[88:89]
	v_lshl_add_u64 v[108:109], v[104:105], 0, v[172:173]
	v_lshlrev_b64 v[72:73], 11, v[72:73]
	global_store_dwordx4 v[28:29], v[12:15], off offset:256
	global_store_dwordx4 v[108:109], v[92:95], off offset:256
	v_cvt_pk_bf16_f32 v79, v74, v75
	v_add_co_u32_e32 v14, vcc, s89, v174
	v_lshl_add_u64 v[92:93], v[88:89], 0, v[172:173]
	v_lshl_add_u64 v[72:73], s[14:15], 0, v[72:73]
	v_addc_co_u32_e32 v15, vcc, 0, v175, vcc
	v_cvt_pk_bf16_f32 v124, v124, v125
	v_cvt_pk_bf16_f32 v125, v126, v127
	v_cvt_pk_bf16_f32 v126, v120, v121
	v_cvt_pk_bf16_f32 v127, v122, v123
	v_cvt_pk_bf16_f32 v104, v116, v117
	v_cvt_pk_bf16_f32 v105, v118, v119
	v_cvt_pk_bf16_f32 v106, v112, v113
	v_cvt_pk_bf16_f32 v107, v114, v115
	v_cvt_pk_bf16_f32 v88, v100, v101
	v_cvt_pk_bf16_f32 v89, v102, v103
	v_cvt_pk_bf16_f32 v90, v96, v97
	v_cvt_pk_bf16_f32 v91, v98, v99
	global_store_dwordx4 v[92:93], v[76:79], off offset:256
	v_cvt_pk_bf16_f32 v74, v80, v81
	v_cvt_pk_bf16_f32 v75, v82, v83
	v_lshl_add_u64 v[76:77], v[72:73], 0, v[172:173]
	v_cvt_pk_bf16_f32 v72, v84, v85
	v_cvt_pk_bf16_f32 v73, v86, v87
	v_cvt_pk_bf16_f32 v71, v66, v67
	v_cvt_pk_bf16_f32 v63, v58, v59
	v_cvt_pk_bf16_f32 v40, v52, v53
	v_cvt_pk_bf16_f32 v41, v54, v55
	v_cvt_pk_bf16_f32 v42, v48, v49
	v_cvt_pk_bf16_f32 v43, v50, v51
	v_cvt_pk_bf16_f32 v24, v36, v37
	v_cvt_pk_bf16_f32 v25, v38, v39
	v_cvt_pk_bf16_f32 v26, v32, v33
	v_cvt_pk_bf16_f32 v27, v34, v35
	v_lshl_add_u64 v[12:13], v[174:175], 0, s[54:55]
	v_cvt_pk_bf16_f32 v8, v20, v21
	v_cvt_pk_bf16_f32 v9, v22, v23
	v_cvt_pk_bf16_f32 v10, v16, v17
	v_cvt_pk_bf16_f32 v11, v18, v19
	v_cvt_pk_bf16_f32 v4, v4, v5
	v_cvt_pk_bf16_f32 v5, v6, v7
	v_cvt_pk_bf16_f32 v6, v0, v1
	v_cvt_pk_bf16_f32 v7, v2, v3
	s_and_b64 vcc, exec, s[2:3]
	s_mov_b32 s93, s91
	s_mov_b32 s90, s92
	s_mov_b64 s[58:59], s[0:1]
	s_mov_b64 s[56:57], s[4:5]
	global_store_dwordx4 v[174:175], v[124:127], off
	global_store_dwordx4 v[108:109], v[104:107], off
	global_store_dwordx4 v[92:93], v[88:91], off
	global_store_dwordx4 v[76:77], v[72:75], off
	global_store_dwordx4 v[76:77], v[68:71], off offset:256
	global_store_dwordx4 v[56:57], v[60:63], off
	global_store_dwordx4 v[46:47], v[40:43], off
	global_store_dwordx4 v[30:31], v[24:27], off
	global_store_dwordx4 v[14:15], v[8:11], off
	global_store_dwordx4 v[12:13], v[4:7], off offset:256
	s_cbranch_vccz .LBB0_301
	s_waitcnt vmcnt(0)
	s_cmpk_gt_u32 s64, 0xff
	s_cbranch_scc1 .LBB0_316
	s_barrier

; #define PG8_STAGE(bufoff, gbase, voff) do { _Pragma("unroll") for (int _i = 0; _i < 2; ++_i) \
;         __builtin_amdgcn_global_load_lds((const unsigned*)((const char*)(gbase) + (voff)[_i]), (PG8_LAS unsigned*)(lds + (bufoff) + ldsw + _i * 8192), 16, 0, 0); } while (0)
; #define PG8_LDA(dst, b, h) do { _Pragma("unroll") for (int m = 0; m < 4; ++m) _Pragma("unroll") for (int k = 0; k < 2; ++k) dst[m][k] = *(const PG8_LAS bf16x8*)(lds + PG8_SA(b, h) + aoff + m * 2048 + k * 1024); } while (0)
; #define PG8_LDB(dst, b, h) do { _Pragma("unroll") for (int n = 0; n < 2; ++n) _Pragma("unroll") for (int k = 0; k < 2; ++k) dst[n][k] = *(const PG8_LAS bf16x8*)(lds + PG8_SB(b, h) + boff + n * 2048 + k * 1024); } while (0)
; #define PG8_WAIT_V(n) asm volatile("s_waitcnt vmcnt(" #n ")" ::: "memory")
; #define PG8_WAIT_L(n) asm volatile("s_waitcnt lgkmcnt(" #n ")" ::: "memory")
; #define PG8_BAR __builtin_amdgcn_s_barrier()
; template <class Epi, class Sched, bool STAMP = false>
; __device__ __forceinline__ void gemm_phase(PG8_LAS unsigned char* lds, const Gemm g, const Sched& S, const Epi& E, unsigned long long* stamps) {
;     ...
;     for (;;) {
;         const bool has_next = S.next(ui + 1, nxt);
;         const char* nA = has_next ? (const char*)g.A + (size_t)nxt.pm * tstep : cA; const char* nB = has_next ? (const char*)g.Bt + (size_t)nxt.pn * tstep : cB;
;         for (int t = 0; t < nt; t += 2) {
;             const bool last = (t == nt - 2);
;             const char* a1 = cA + (size_t)(t + 1) * kstep;
;             const char* a2 = last ? nA : cA + (size_t)(t + 2) * kstep; const char* b2 = last ? nB : cB + (size_t)(t + 2) * kstep;
;             const char* a3 = a2 + kstep; const char* b3 = b2 + kstep;
;             if (last && has_next) S.a_ready(nxt);
;             PG8_LDB(B0, 0, 0); PG8_SCHED; PG8_LDA(At, 0, 0); PG8_STAGE(PG8_SA(1, 1), a1 + hstep, voffA);
;             PG8_WAIT_L(8); PG8_BAR; PG8_WAIT_L(0); PG8_MMA(0, 0, At, B0); PG8_BAR; PG8_SCHED;
;             PG8_LDB(B1, 0, 1); PG8_STAGE(PG8_SB(0, 0), b2, voffB);
;             PG8_BAR; PG8_WAIT_L(0); PG8_MMA(0, 1, At, B1); PG8_BAR;
;             PG8_LDA(At, 0, 1); PG8_STAGE(PG8_SA(0, 0), a2, voffA);
;             PG8_BAR; PG8_WAIT_L(0); PG8_MMA(1, 0, At, B0); PG8_BAR; PG8_SCHED;
;             PG8_STAGE(PG8_SB(0, 1), b2 + hstep, voffB);
;             PG8_WAIT_V(6); PG8_BAR; PG8_MMA(1, 1, At, B1); PG8_BAR;
.LBB0_350:
	s_add_u32 s87, s36, 0x100
	s_addc_u32 s88, s37, 0
	s_mov_b32 s89, -2
	s_cmp_eq_u32 s68, s99
	s_cbranch_scc1 .Lgu2_half_loop_z
	ds_read_b128 v[140:143], v147
	ds_read_b128 v[170:173], v148
	ds_read_b128 v[174:177], v149
	ds_read_b128 v[178:181], v150
	s_add_u32 s36, s34, 0x100
	s_addc_u32 s37, s35, 0
	s_cmp_eq_u32 s89, 12
	s_cselect_b32 s55, s5, s37
	s_cselect_b32 s54, s4, s36
	s_cselect_b32 s53, s1, s88
	s_cselect_b32 s52, s0, s87
	s_mov_b32 m0, s78
	ds_read_b128 v[182:185], v145
	ds_read_b128 v[186:189], v145 offset:1024
	ds_read_b128 v[190:193], v145 offset:2048
	ds_read_b128 v[194:197], v145 offset:3072
	ds_read_b128 v[198:201], v145 offset:4096
	ds_read_b128 v[202:205], v145 offset:5120
	ds_read_b128 v[206:209], v145 offset:6144
	ds_read_b128 v[210:213], v145 offset:7168
	global_load_lds_dwordx4 v132, s[34:35]
	s_mov_b32 m0, s79
	s_nop 0
	global_load_lds_dwordx4 v134, s[34:35]
	s_waitcnt lgkmcnt(8)
	s_barrier
	s_waitcnt lgkmcnt(0)
	s_setprio 1
	s_waitcnt lgkmcnt(0)
	v_mfma_f32_16x16x32_bf16 v[124:127], v[140:143], v[182:185], 0
	v_mfma_f32_16x16x32_bf16 v[120:123], v[174:177], v[182:185], 0
	v_mfma_f32_16x16x32_bf16 v[108:111], v[140:143], v[190:193], 0
	v_mfma_f32_16x16x32_bf16 v[104:107], v[174:177], v[190:193], 0
	v_mfma_f32_16x16x32_bf16 v[92:95], v[140:143], v[198:201], 0
	v_mfma_f32_16x16x32_bf16 v[88:91], v[174:177], v[198:201], 0
	v_mfma_f32_16x16x32_bf16 v[76:79], v[140:143], v[206:209], 0
	v_mfma_f32_16x16x32_bf16 v[72:75], v[174:177], v[206:209], 0
	v_mfma_f32_16x16x32_bf16 v[124:127], v[170:173], v[186:189], v[124:127]
	v_mfma_f32_16x16x32_bf16 v[120:123], v[178:181], v[186:189], v[120:123]
	v_mfma_f32_16x16x32_bf16 v[108:111], v[170:173], v[194:197], v[108:111]
	v_mfma_f32_16x16x32_bf16 v[104:107], v[178:181], v[194:197], v[104:107]
	v_mfma_f32_16x16x32_bf16 v[92:95], v[170:173], v[202:205], v[92:95]
	v_mfma_f32_16x16x32_bf16 v[88:91], v[178:181], v[202:205], v[88:91]
	v_mfma_f32_16x16x32_bf16 v[76:79], v[170:173], v[210:213], v[76:79]
	v_mfma_f32_16x16x32_bf16 v[72:75], v[178:181], v[210:213], v[72:75]
	s_setprio 0
	s_barrier
	s_mov_b32 m0, s61
	ds_read_b128 v[214:217], v151
	ds_read_b128 v[218:221], v152
	ds_read_b128 v[222:225], v153
	ds_read_b128 v[226:229], v154
	global_load_lds_dwordx4 v130, s[52:53]
	s_mov_b32 m0, s62
	s_nop 0
	global_load_lds_dwordx4 v128, s[52:53]
	s_barrier
	s_waitcnt lgkmcnt(0)
	s_setprio 1
	s_waitcnt lgkmcnt(0)
	v_mfma_f32_16x16x32_bf16 v[116:119], v[214:217], v[182:185], 0
	v_mfma_f32_16x16x32_bf16 v[112:115], v[222:225], v[182:185], 0
	v_mfma_f32_16x16x32_bf16 v[100:103], v[214:217], v[190:193], 0
	v_mfma_f32_16x16x32_bf16 v[96:99], v[222:225], v[190:193], 0
	v_mfma_f32_16x16x32_bf16 v[84:87], v[214:217], v[198:201], 0
	v_mfma_f32_16x16x32_bf16 v[80:83], v[222:225], v[198:201], 0
	v_mfma_f32_16x16x32_bf16 v[68:71], v[214:217], v[206:209], 0
	v_mfma_f32_16x16x32_bf16 v[64:67], v[222:225], v[206:209], 0
	v_mfma_f32_16x16x32_bf16 v[116:119], v[218:221], v[186:189], v[116:119]
	v_mfma_f32_16x16x32_bf16 v[112:115], v[226:229], v[186:189], v[112:115]
	v_mfma_f32_16x16x32_bf16 v[100:103], v[218:221], v[194:197], v[100:103]
	v_mfma_f32_16x16x32_bf16 v[96:99], v[226:229], v[194:197], v[96:99]
	v_mfma_f32_16x16x32_bf16 v[84:87], v[218:221], v[202:205], v[84:87]
	v_mfma_f32_16x16x32_bf16 v[80:83], v[226:229], v[202:205], v[80:83]
	v_mfma_f32_16x16x32_bf16 v[68:71], v[218:221], v[210:213], v[68:71]
	v_mfma_f32_16x16x32_bf16 v[64:67], v[226:229], v[210:213], v[64:67]
	s_setprio 0
	s_mov_b32 m0, s58
	s_barrier
	ds_read_b128 v[182:185], v145 offset:16384
	ds_read_b128 v[186:189], v145 offset:17408
	ds_read_b128 v[190:193], v145 offset:18432
	ds_read_b128 v[194:197], v145 offset:19456
	ds_read_b128 v[198:201], v145 offset:20480
	ds_read_b128 v[202:205], v145 offset:21504
	ds_read_b128 v[206:209], v145 offset:22528
	ds_read_b128 v[210:213], v145 offset:23552
	global_load_lds_dwordx4 v130, s[54:55]
	s_mov_b32 m0, s63
	s_nop 0
	global_load_lds_dwordx4 v128, s[54:55]
	s_barrier
	s_waitcnt lgkmcnt(0)
	s_setprio 1
	s_waitcnt lgkmcnt(0)
	v_mfma_f32_16x16x32_bf16 v[60:63], v[140:143], v[182:185], 0
	v_mfma_f32_16x16x32_bf16 v[56:59], v[174:177], v[182:185], 0
	v_mfma_f32_16x16x32_bf16 v[44:47], v[140:143], v[190:193], 0
	v_mfma_f32_16x16x32_bf16 v[40:43], v[174:177], v[190:193], 0
	v_mfma_f32_16x16x32_bf16 v[28:31], v[140:143], v[198:201], 0
	v_mfma_f32_16x16x32_bf16 v[24:27], v[174:177], v[198:201], 0
	v_mfma_f32_16x16x32_bf16 v[12:15], v[140:143], v[206:209], 0
	v_mfma_f32_16x16x32_bf16 v[8:11], v[174:177], v[206:209], 0
	v_mfma_f32_16x16x32_bf16 v[60:63], v[170:173], v[186:189], v[60:63]
	v_mfma_f32_16x16x32_bf16 v[56:59], v[178:181], v[186:189], v[56:59]
	v_mfma_f32_16x16x32_bf16 v[44:47], v[170:173], v[194:197], v[44:47]
	v_mfma_f32_16x16x32_bf16 v[40:43], v[178:181], v[194:197], v[40:43]
	v_mfma_f32_16x16x32_bf16 v[28:31], v[170:173], v[202:205], v[28:31]
	v_mfma_f32_16x16x32_bf16 v[24:27], v[178:181], v[202:205], v[24:27]
	v_mfma_f32_16x16x32_bf16 v[12:15], v[170:173], v[210:213], v[12:15]
	v_mfma_f32_16x16x32_bf16 v[8:11], v[178:181], v[210:213], v[8:11]
	s_setprio 0
	s_barrier
	s_add_u32 s34, s52, 0x44000
	s_addc_u32 s35, s53, 0
	s_mov_b32 m0, s64
	s_nop 0
	global_load_lds_dwordx4 v130, s[34:35]
	s_mov_b32 m0, s65
	s_nop 0
	global_load_lds_dwordx4 v128, s[34:35]
	s_waitcnt vmcnt(6)
	s_barrier
	s_setprio 1
	v_mfma_f32_16x16x32_bf16 v[52:55], v[214:217], v[182:185], 0
	v_mfma_f32_16x16x32_bf16 v[48:51], v[222:225], v[182:185], 0
	v_mfma_f32_16x16x32_bf16 v[36:39], v[214:217], v[190:193], 0
	v_mfma_f32_16x16x32_bf16 v[32:35], v[222:225], v[190:193], 0
	v_mfma_f32_16x16x32_bf16 v[20:23], v[214:217], v[198:201], 0
	v_mfma_f32_16x16x32_bf16 v[16:19], v[222:225], v[198:201], 0
	v_mfma_f32_16x16x32_bf16 v[4:7], v[214:217], v[206:209], 0
	v_mfma_f32_16x16x32_bf16 v[0:3], v[222:225], v[206:209], 0
	v_mfma_f32_16x16x32_bf16 v[52:55], v[218:221], v[186:189], v[52:55]
	v_mfma_f32_16x16x32_bf16 v[48:51], v[226:229], v[186:189], v[48:51]
	v_mfma_f32_16x16x32_bf16 v[36:39], v[218:221], v[194:197], v[36:39]
	v_mfma_f32_16x16x32_bf16 v[32:35], v[226:229], v[194:197], v[32:35]
	v_mfma_f32_16x16x32_bf16 v[20:23], v[218:221], v[202:205], v[20:23]
	v_mfma_f32_16x16x32_bf16 v[16:19], v[226:229], v[202:205], v[16:19]
	v_mfma_f32_16x16x32_bf16 v[4:7], v[218:221], v[210:213], v[4:7]
	v_mfma_f32_16x16x32_bf16 v[0:3], v[226:229], v[210:213], v[0:3]
	s_setprio 0
	s_barrier
	s_branch .Lzp5_mid

; #define PG8_STAGE(bufoff, gbase, voff) do { _Pragma("unroll") for (int _i = 0; _i < 2; ++_i) \
;         __builtin_amdgcn_global_load_lds((const unsigned*)((const char*)(gbase) + (voff)[_i]), (PG8_LAS unsigned*)(lds + (bufoff) + ldsw + _i * 8192), 16, 0, 0); } while (0)
; #define PG8_LDA(dst, b, h) do { _Pragma("unroll") for (int m = 0; m < 4; ++m) _Pragma("unroll") for (int k = 0; k < 2; ++k) dst[m][k] = *(const PG8_LAS bf16x8*)(lds + PG8_SA(b, h) + aoff + m * 2048 + k * 1024); } while (0)
; #define PG8_LDB(dst, b, h) do { _Pragma("unroll") for (int n = 0; n < 2; ++n) _Pragma("unroll") for (int k = 0; k < 2; ++k) dst[n][k] = *(const PG8_LAS bf16x8*)(lds + PG8_SB(b, h) + boff + n * 2048 + k * 1024); } while (0)
; #define PG8_MMA(ai, bj, At, Bt) do { __builtin_amdgcn_s_setprio(1); _Pragma("unroll") for (int m = 0; m < 4; ++m) _Pragma("unroll") for (int n = 0; n < 2; ++n) _Pragma("unroll") for (int k = 0; k < 2; ++k) \
;         acc[ai][bj][m][n] = __builtin_amdgcn_mfma_f32_16x16x32_bf16(Bt[n][k], At[m][k], acc[ai][bj][m][n], 0, 0, 0); __builtin_amdgcn_s_setprio(0); } while (0)
; #define PG8_WAIT_V(n) asm volatile("s_waitcnt vmcnt(" #n ")" ::: "memory")
; #define PG8_WAIT_L(n) asm volatile("s_waitcnt lgkmcnt(" #n ")" ::: "memory")
; #define PG8_BAR __builtin_amdgcn_s_barrier()
; #define PG8_SCHED __builtin_amdgcn_sched_barrier(0)
; template <class Epi, class Sched, bool STAMP = false>
; __device__ __forceinline__ void gemm_phase(PG8_LAS unsigned char* lds, const Gemm g, const Sched& S, const Epi& E, unsigned long long* stamps) {
;     ...
;             PG8_LDB(B0, 1, 0); PG8_SCHED; PG8_LDA(At, 1, 0); PG8_STAGE(PG8_SA(0, 1), a2 + hstep, voffA);
;             PG8_WAIT_L(8); PG8_BAR; PG8_WAIT_L(0); PG8_MMA(0, 0, At, B0); PG8_BAR; PG8_SCHED;
;             PG8_LDB(B1, 1, 1); PG8_STAGE(PG8_SB(1, 0), b3, voffB);
;             PG8_BAR; PG8_WAIT_L(0); PG8_MMA(0, 1, At, B1); PG8_BAR;
;             PG8_LDA(At, 1, 1); PG8_STAGE(PG8_SA(1, 0), a3, voffA);
;             PG8_BAR; PG8_WAIT_L(0); PG8_MMA(1, 0, At, B0); PG8_BAR; PG8_SCHED;
;             PG8_STAGE(PG8_SB(1, 1), b3 + hstep, voffB);
;             PG8_WAIT_V(6); PG8_BAR; PG8_MMA(1, 1, At, B1); PG8_BAR;
.Lzp5_mid:
	ds_read_b128 v[140:143], v155
	ds_read_b128 v[170:173], v156
	ds_read_b128 v[174:177], v157
	ds_read_b128 v[178:181], v165
	s_add_u32 s34, s54, 0x44000
	s_addc_u32 s35, s55, 0
	s_mov_b32 m0, s66
	ds_read_b128 v[182:185], v145 offset:32768
	ds_read_b128 v[186:189], v145 offset:33792
	ds_read_b128 v[190:193], v145 offset:34816
	ds_read_b128 v[194:197], v145 offset:35840
	ds_read_b128 v[198:201], v145 offset:36864
	ds_read_b128 v[202:205], v145 offset:37888
	ds_read_b128 v[206:209], v145 offset:38912
	ds_read_b128 v[210:213], v145 offset:39936
	global_load_lds_dwordx4 v130, s[34:35]
	s_mov_b32 m0, s67
	s_nop 0
	global_load_lds_dwordx4 v128, s[34:35]
	s_waitcnt lgkmcnt(8)
	s_barrier
	s_waitcnt lgkmcnt(0)
	s_setprio 1
	s_waitcnt lgkmcnt(0)
	v_mfma_f32_16x16x32_bf16 v[124:127], v[140:143], v[182:185], v[124:127]
	v_mfma_f32_16x16x32_bf16 v[120:123], v[174:177], v[182:185], v[120:123]
	v_mfma_f32_16x16x32_bf16 v[108:111], v[140:143], v[190:193], v[108:111]
	v_mfma_f32_16x16x32_bf16 v[104:107], v[174:177], v[190:193], v[104:107]
	v_mfma_f32_16x16x32_bf16 v[92:95], v[140:143], v[198:201], v[92:95]
	v_mfma_f32_16x16x32_bf16 v[88:91], v[174:177], v[198:201], v[88:91]
	v_mfma_f32_16x16x32_bf16 v[76:79], v[140:143], v[206:209], v[76:79]
	v_mfma_f32_16x16x32_bf16 v[72:75], v[174:177], v[206:209], v[72:75]
	v_mfma_f32_16x16x32_bf16 v[124:127], v[170:173], v[186:189], v[124:127]
	v_mfma_f32_16x16x32_bf16 v[120:123], v[178:181], v[186:189], v[120:123]
	v_mfma_f32_16x16x32_bf16 v[108:111], v[170:173], v[194:197], v[108:111]
	v_mfma_f32_16x16x32_bf16 v[104:107], v[178:181], v[194:197], v[104:107]
	v_mfma_f32_16x16x32_bf16 v[92:95], v[170:173], v[202:205], v[92:95]
	v_mfma_f32_16x16x32_bf16 v[88:91], v[178:181], v[202:205], v[88:91]
	v_mfma_f32_16x16x32_bf16 v[76:79], v[170:173], v[210:213], v[76:79]
	v_mfma_f32_16x16x32_bf16 v[72:75], v[178:181], v[210:213], v[72:75]
	s_setprio 0
	s_barrier
	s_mov_b32 m0, s70
	ds_read_b128 v[214:217], v166
	ds_read_b128 v[218:221], v167
	ds_read_b128 v[222:225], v168
	ds_read_b128 v[226:229], v169
	s_add_u32 s100, s52, 0x80
	s_addc_u32 s101, s53, 0
	global_load_lds_dwordx4 v130, s[100:101]
	s_mov_b32 m0, s71
	s_nop 0
	global_load_lds_dwordx4 v128, s[100:101]
	s_barrier
	s_waitcnt lgkmcnt(0)
	s_setprio 1
	s_waitcnt lgkmcnt(0)
	v_mfma_f32_16x16x32_bf16 v[116:119], v[214:217], v[182:185], v[116:119]
	v_mfma_f32_16x16x32_bf16 v[112:115], v[222:225], v[182:185], v[112:115]
	v_mfma_f32_16x16x32_bf16 v[100:103], v[214:217], v[190:193], v[100:103]
	v_mfma_f32_16x16x32_bf16 v[96:99], v[222:225], v[190:193], v[96:99]
	v_mfma_f32_16x16x32_bf16 v[84:87], v[214:217], v[198:201], v[84:87]
	v_mfma_f32_16x16x32_bf16 v[80:83], v[222:225], v[198:201], v[80:83]
	v_mfma_f32_16x16x32_bf16 v[68:71], v[214:217], v[206:209], v[68:71]
	v_mfma_f32_16x16x32_bf16 v[64:67], v[222:225], v[206:209], v[64:67]
	v_mfma_f32_16x16x32_bf16 v[116:119], v[218:221], v[186:189], v[116:119]
	v_mfma_f32_16x16x32_bf16 v[112:115], v[226:229], v[186:189], v[112:115]
	v_mfma_f32_16x16x32_bf16 v[100:103], v[218:221], v[194:197], v[100:103]
	v_mfma_f32_16x16x32_bf16 v[96:99], v[226:229], v[194:197], v[96:99]
	v_mfma_f32_16x16x32_bf16 v[84:87], v[218:221], v[202:205], v[84:87]
	v_mfma_f32_16x16x32_bf16 v[80:83], v[226:229], v[202:205], v[80:83]
	v_mfma_f32_16x16x32_bf16 v[68:71], v[218:221], v[210:213], v[68:71]
	v_mfma_f32_16x16x32_bf16 v[64:67], v[226:229], v[210:213], v[64:67]
	s_setprio 0
	s_mov_b32 m0, s73
	s_barrier
	ds_read_b128 v[182:185], v145 offset:49152
	ds_read_b128 v[186:189], v145 offset:50176
	ds_read_b128 v[190:193], v145 offset:51200
	ds_read_b128 v[194:197], v145 offset:52224
	ds_read_b128 v[198:201], v145 offset:53248
	ds_read_b128 v[202:205], v145 offset:54272
	ds_read_b128 v[206:209], v145 offset:55296
	ds_read_b128 v[210:213], v145 offset:56320
	s_add_u32 s100, s54, 0x80
	s_addc_u32 s101, s55, 0
	global_load_lds_dwordx4 v130, s[100:101]
	s_mov_b32 m0, s74
	s_nop 0
	global_load_lds_dwordx4 v128, s[100:101]
	s_barrier
	s_waitcnt lgkmcnt(0)
	s_setprio 1
	s_waitcnt lgkmcnt(0)
	v_mfma_f32_16x16x32_bf16 v[60:63], v[140:143], v[182:185], v[60:63]
	v_mfma_f32_16x16x32_bf16 v[56:59], v[174:177], v[182:185], v[56:59]
	v_mfma_f32_16x16x32_bf16 v[44:47], v[140:143], v[190:193], v[44:47]
	v_mfma_f32_16x16x32_bf16 v[40:43], v[174:177], v[190:193], v[40:43]
	v_mfma_f32_16x16x32_bf16 v[28:31], v[140:143], v[198:201], v[28:31]
	v_mfma_f32_16x16x32_bf16 v[24:27], v[174:177], v[198:201], v[24:27]
	v_mfma_f32_16x16x32_bf16 v[12:15], v[140:143], v[206:209], v[12:15]
	v_mfma_f32_16x16x32_bf16 v[8:11], v[174:177], v[206:209], v[8:11]
	v_mfma_f32_16x16x32_bf16 v[60:63], v[170:173], v[186:189], v[60:63]
	v_mfma_f32_16x16x32_bf16 v[56:59], v[178:181], v[186:189], v[56:59]
	v_mfma_f32_16x16x32_bf16 v[44:47], v[170:173], v[194:197], v[44:47]
	v_mfma_f32_16x16x32_bf16 v[40:43], v[178:181], v[194:197], v[40:43]
	v_mfma_f32_16x16x32_bf16 v[28:31], v[170:173], v[202:205], v[28:31]
	v_mfma_f32_16x16x32_bf16 v[24:27], v[178:181], v[202:205], v[24:27]
	v_mfma_f32_16x16x32_bf16 v[12:15], v[170:173], v[210:213], v[12:15]
	v_mfma_f32_16x16x32_bf16 v[8:11], v[178:181], v[210:213], v[8:11]
	s_setprio 0
	s_barrier
	s_add_u32 s34, s52, 0x44080
	s_addc_u32 s35, s53, 0
	s_mov_b32 m0, s75
	s_nop 0
	global_load_lds_dwordx4 v130, s[34:35]
	s_mov_b32 m0, s76
	s_nop 0
	global_load_lds_dwordx4 v128, s[34:35]
	s_waitcnt vmcnt(6)
	s_barrier
; DI float ex2(float x) { return __builtin_amdgcn_exp2f(x); }
; #define PG8_STAMP() do { if (STAMP && wid == 0 && nts < 64) { const unsigned long long _c = 0ull; \
;         ts_lo = (lane == nts) ? (int)(unsigned)_c : ts_lo; ts_hi = (lane == nts) ? (int)(unsigned)(_c >> 32) : ts_hi; ++nts; } } while (0)
; #define PG8_MMA(ai, bj, At, Bt) do { __builtin_amdgcn_s_setprio(1); _Pragma("unroll") for (int m = 0; m < 4; ++m) _Pragma("unroll") for (int n = 0; n < 2; ++n) _Pragma("unroll") for (int k = 0; k < 2; ++k) \
;         acc[ai][bj][m][n] = __builtin_amdgcn_mfma_f32_16x16x32_bf16(Bt[n][k], At[m][k], acc[ai][bj][m][n], 0, 0, 0); __builtin_amdgcn_s_setprio(0); } while (0)
; #define PG8_WAIT_V(n) asm volatile("s_waitcnt vmcnt(" #n ")" ::: "memory")
; #define PG8_BAR __builtin_amdgcn_s_barrier()
;     DI void operator()(const f32x4 (&acc)[2][2][4][2], const Unit& u, int wr, int wc, int fr, int fq) const {
;         const int row0 = u.pm * BM + wr * 64 + fr, hcol0 = ((u.pn * BM + wc * 32) >> 1) + 4 * fq;
; #pragma unroll
;         for (int ai = 0; ai < 2; ++ai)
; #pragma unroll
;             for (int m = 0; m < 4; ++m) { u16* rowp = O + (size_t)(row0 + ai * HALF + m * 16) * ldc + hcol0;
; #pragma unroll
;                 for (int bj = 0; bj < 2; ++bj) { const f32x4 g = acc[ai][bj][m][0], up = acc[ai][bj][m][1]; float r[4];
; #pragma unroll
;                     for (int j = 0; j < 4; ++j) r[j] = g[j] * up[j] * __builtin_amdgcn_rcpf(1.f + ex2(-LOG2E * g[j]));
;                     uint2 w = {pack2(r[0], r[1]), pack2(r[2], r[3])}; *(uint2*)(rowp + bj * (HALF / 2)) = w; } }
; template <class Epi, class Sched, bool STAMP = false>
; __device__ __forceinline__ void gemm_phase(PG8_LAS unsigned char* lds, const Gemm g, const Sched& S, const Epi& E, unsigned long long* stamps) {
;     ...
;             PG8_WAIT_V(6); PG8_BAR; PG8_MMA(1, 1, At, B1); PG8_BAR;
;         }
;         PG8_STAMP();
;         if constexpr (!Epi::AFTER_DRAIN) { E(acc, cur, wr, wc, fr, fq); S.done(cur); }
	s_setprio 1
	v_mfma_f32_16x16x32_bf16 v[52:55], v[214:217], v[182:185], v[52:55]
	v_mfma_f32_16x16x32_bf16 v[48:51], v[222:225], v[182:185], v[48:51]
	v_mfma_f32_16x16x32_bf16 v[36:39], v[214:217], v[190:193], v[36:39]
	v_mfma_f32_16x16x32_bf16 v[32:35], v[222:225], v[190:193], v[32:35]
	v_mfma_f32_16x16x32_bf16 v[20:23], v[214:217], v[198:201], v[20:23]
	v_mfma_f32_16x16x32_bf16 v[16:19], v[222:225], v[198:201], v[16:19]
	v_mfma_f32_16x16x32_bf16 v[4:7], v[214:217], v[206:209], v[4:7]
	v_mfma_f32_16x16x32_bf16 v[0:3], v[222:225], v[206:209], v[0:3]
	v_mfma_f32_16x16x32_bf16 v[52:55], v[218:221], v[186:189], v[52:55]
	v_mfma_f32_16x16x32_bf16 v[48:51], v[226:229], v[186:189], v[48:51]
	v_mfma_f32_16x16x32_bf16 v[36:39], v[218:221], v[194:197], v[36:39]
	v_mfma_f32_16x16x32_bf16 v[32:35], v[226:229], v[194:197], v[32:35]
	v_mfma_f32_16x16x32_bf16 v[20:23], v[218:221], v[202:205], v[20:23]
	v_mfma_f32_16x16x32_bf16 v[16:19], v[226:229], v[202:205], v[16:19]
	v_mfma_f32_16x16x32_bf16 v[4:7], v[218:221], v[210:213], v[4:7]
	v_mfma_f32_16x16x32_bf16 v[0:3], v[226:229], v[210:213], v[0:3]
	s_setprio 0
	s_add_i32 s89, s89, 2
	s_add_u32 s87, s87, 0x100
	s_addc_u32 s88, s88, 0
	s_cmp_gt_u32 s89, 13
	s_mov_b64 s[34:35], s[36:37]
	s_barrier
	s_cbranch_scc0 .LBB0_351
	v_mul_f32_e32 v171, 0xbfb8aa3b, v124
	v_exp_f32_e32 v171, v171
	v_mul_f32_e32 v174, 0xbfb8aa3b, v125
	v_exp_f32_e32 v175, v174
	s_lshl_b32 s10, s86, 8
	v_add_f32_e32 v171, 1.0, v171
	v_rcp_f32_e32 v174, v171
	v_add_f32_e32 v171, 1.0, v175
	v_mul_f32_e32 v175, 0xbfb8aa3b, v126
	v_exp_f32_e32 v176, v175
	v_mul_f32_e32 v175, 0xbfb8aa3b, v127
	v_exp_f32_e32 v177, v175
	v_rcp_f32_e32 v175, v171
	v_add_f32_e32 v171, 1.0, v176
	v_rcp_f32_e32 v176, v171
	v_add_f32_e32 v171, 1.0, v177
	v_rcp_f32_e32 v177, v171
	v_pk_mul_f32 v[122:123], v[126:127], v[122:123]
	v_pk_mul_f32 v[120:121], v[124:125], v[120:121]
	s_or_b32 s10, s10, s69
	v_pk_mul_f32 v[120:121], v[120:121], v[174:175]
	v_pk_mul_f32 v[122:123], v[122:123], v[176:177]
	s_ashr_i32 s10, s10, 1
	v_cvt_pk_bf16_f32 v120, v120, v121
	v_cvt_pk_bf16_f32 v121, v122, v123
	v_mul_f32_e32 v122, 0xbfb8aa3b, v116
	v_mul_f32_e32 v123, 0xbfb8aa3b, v117
	v_or_b32_e32 v140, s10, v146
	v_exp_f32_e32 v122, v122
	v_exp_f32_e32 v123, v123
	v_lshl_add_u32 v170, s85, 8, v144
	v_ashrrev_i32_e32 v141, 31, v140
	v_mov_b64_e32 v[142:143], s[12:13]
	v_mad_i64_i32 v[172:173], s[34:35], v170, s82, v[142:143]
	v_lshlrev_b64 v[140:141], 1, v[140:141]
	v_lshl_add_u64 v[172:173], v[172:173], 0, v[140:141]
	global_store_dwordx2 v[172:173], v[120:121], off
	v_add_f32_e32 v120, 1.0, v122
	v_add_f32_e32 v121, 1.0, v123
	v_mul_f32_e32 v122, 0xbfb8aa3b, v118
	v_mul_f32_e32 v123, 0xbfb8aa3b, v119
	v_exp_f32_e32 v122, v122
	v_exp_f32_e32 v123, v123
	v_rcp_f32_e32 v120, v120
	v_rcp_f32_e32 v121, v121
	v_add_f32_e32 v122, 1.0, v122
	v_add_f32_e32 v123, 1.0, v123
	v_rcp_f32_e32 v122, v122
	v_rcp_f32_e32 v123, v123
	v_pk_mul_f32 v[114:115], v[118:119], v[114:115]
	v_pk_mul_f32 v[112:113], v[116:117], v[112:113]
	v_mul_f32_e32 v116, 0xbfb8aa3b, v110
	v_pk_mul_f32 v[112:113], v[112:113], v[120:121]
	v_pk_mul_f32 v[114:115], v[114:115], v[122:123]
	v_cvt_pk_bf16_f32 v112, v112, v113
	v_cvt_pk_bf16_f32 v113, v114, v115
	v_mul_f32_e32 v114, 0xbfb8aa3b, v108
	v_mul_f32_e32 v115, 0xbfb8aa3b, v109
	v_mul_f32_e32 v117, 0xbfb8aa3b, v111
	v_exp_f32_e32 v114, v114
	v_exp_f32_e32 v115, v115
	v_exp_f32_e32 v116, v116
	v_exp_f32_e32 v117, v117
	v_add_f32_e32 v114, 1.0, v114
	v_add_f32_e32 v115, 1.0, v115
	v_add_f32_e32 v116, 1.0, v116
	v_add_f32_e32 v117, 1.0, v117
	v_rcp_f32_e32 v114, v114
	v_rcp_f32_e32 v115, v115
	v_rcp_f32_e32 v116, v116
	v_rcp_f32_e32 v117, v117
	v_pk_mul_f32 v[106:107], v[110:111], v[106:107]
	v_pk_mul_f32 v[104:105], v[108:109], v[104:105]
	global_store_dwordx2 v[172:173], v[112:113], off offset:128
	v_pk_mul_f32 v[104:105], v[104:105], v[114:115]
	v_pk_mul_f32 v[106:107], v[106:107], v[116:117]
	v_cvt_pk_bf16_f32 v104, v104, v105
	v_cvt_pk_bf16_f32 v105, v106, v107
	v_mul_f32_e32 v106, 0xbfb8aa3b, v100
	v_mul_f32_e32 v107, 0xbfb8aa3b, v101
	v_exp_f32_e32 v106, v106
	v_exp_f32_e32 v107, v107
	v_or_b32_e32 v112, 16, v170
	v_mad_i64_i32 v[112:113], s[34:35], v112, s82, v[142:143]
	v_lshl_add_u64 v[112:113], v[112:113], 0, v[140:141]
	global_store_dwordx2 v[112:113], v[104:105], off
	v_add_f32_e32 v104, 1.0, v106
	v_add_f32_e32 v105, 1.0, v107
	v_mul_f32_e32 v106, 0xbfb8aa3b, v102
	v_mul_f32_e32 v107, 0xbfb8aa3b, v103
	v_exp_f32_e32 v106, v106
	v_exp_f32_e32 v107, v107
	v_rcp_f32_e32 v104, v104
	v_rcp_f32_e32 v105, v105
	v_add_f32_e32 v106, 1.0, v106
	v_add_f32_e32 v107, 1.0, v107
	v_rcp_f32_e32 v106, v106
	v_rcp_f32_e32 v107, v107
	v_pk_mul_f32 v[98:99], v[102:103], v[98:99]
	v_pk_mul_f32 v[96:97], v[100:101], v[96:97]
	v_mul_f32_e32 v100, 0xbfb8aa3b, v94
	v_pk_mul_f32 v[96:97], v[96:97], v[104:105]
	v_pk_mul_f32 v[98:99], v[98:99], v[106:107]
	v_cvt_pk_bf16_f32 v96, v96, v97
	v_cvt_pk_bf16_f32 v97, v98, v99
	v_mul_f32_e32 v98, 0xbfb8aa3b, v92
	v_mul_f32_e32 v99, 0xbfb8aa3b, v93
	v_mul_f32_e32 v101, 0xbfb8aa3b, v95
	v_exp_f32_e32 v98, v98
	v_exp_f32_e32 v99, v99
	v_exp_f32_e32 v100, v100
	v_exp_f32_e32 v101, v101
	v_add_f32_e32 v98, 1.0, v98
	v_add_f32_e32 v99, 1.0, v99
	v_add_f32_e32 v100, 1.0, v100
	v_add_f32_e32 v101, 1.0, v101
	v_rcp_f32_e32 v98, v98
	v_rcp_f32_e32 v99, v99
	v_rcp_f32_e32 v100, v100
	v_rcp_f32_e32 v101, v101
	v_pk_mul_f32 v[90:91], v[94:95], v[90:91]
	v_pk_mul_f32 v[88:89], v[92:93], v[88:89]
	global_store_dwordx2 v[112:113], v[96:97], off offset:128
	v_pk_mul_f32 v[88:89], v[88:89], v[98:99]
	v_pk_mul_f32 v[90:91], v[90:91], v[100:101]
; DI float ex2(float x) { return __builtin_amdgcn_exp2f(x); }
;     DI void operator()(const f32x4 (&acc)[2][2][4][2], const Unit& u, int wr, int wc, int fr, int fq) const {
;         const int row0 = u.pm * BM + wr * 64 + fr, hcol0 = ((u.pn * BM + wc * 32) >> 1) + 4 * fq;
; #pragma unroll
;         for (int ai = 0; ai < 2; ++ai)
; #pragma unroll
;             for (int m = 0; m < 4; ++m) { u16* rowp = O + (size_t)(row0 + ai * HALF + m * 16) * ldc + hcol0;
; #pragma unroll
;                 for (int bj = 0; bj < 2; ++bj) { const f32x4 g = acc[ai][bj][m][0], up = acc[ai][bj][m][1]; float r[4];
; #pragma unroll
;                     for (int j = 0; j < 4; ++j) r[j] = g[j] * up[j] * __builtin_amdgcn_rcpf(1.f + ex2(-LOG2E * g[j]));
;                     uint2 w = {pack2(r[0], r[1]), pack2(r[2], r[3])}; *(uint2*)(rowp + bj * (HALF / 2)) = w; } }
	v_cvt_pk_bf16_f32 v88, v88, v89
	v_cvt_pk_bf16_f32 v89, v90, v91
	v_mul_f32_e32 v90, 0xbfb8aa3b, v84
	v_mul_f32_e32 v91, 0xbfb8aa3b, v85
	v_exp_f32_e32 v90, v90
	v_exp_f32_e32 v91, v91
	v_or_b32_e32 v96, 32, v170
	v_mad_i64_i32 v[96:97], s[34:35], v96, s82, v[142:143]
	v_lshl_add_u64 v[96:97], v[96:97], 0, v[140:141]
	global_store_dwordx2 v[96:97], v[88:89], off
	v_add_f32_e32 v88, 1.0, v90
	v_add_f32_e32 v89, 1.0, v91
	v_mul_f32_e32 v90, 0xbfb8aa3b, v86
	v_mul_f32_e32 v91, 0xbfb8aa3b, v87
	v_exp_f32_e32 v90, v90
	v_exp_f32_e32 v91, v91
	v_rcp_f32_e32 v88, v88
	v_rcp_f32_e32 v89, v89
	v_add_f32_e32 v90, 1.0, v90
	v_add_f32_e32 v91, 1.0, v91
	v_rcp_f32_e32 v90, v90
	v_rcp_f32_e32 v91, v91
	v_pk_mul_f32 v[82:83], v[86:87], v[82:83]
	v_pk_mul_f32 v[80:81], v[84:85], v[80:81]
	v_mul_f32_e32 v84, 0xbfb8aa3b, v78
	v_pk_mul_f32 v[80:81], v[80:81], v[88:89]
	v_pk_mul_f32 v[82:83], v[82:83], v[90:91]
	v_cvt_pk_bf16_f32 v80, v80, v81
	v_cvt_pk_bf16_f32 v81, v82, v83
	v_mul_f32_e32 v82, 0xbfb8aa3b, v76
	v_mul_f32_e32 v83, 0xbfb8aa3b, v77
	v_mul_f32_e32 v85, 0xbfb8aa3b, v79
	v_exp_f32_e32 v82, v82
	v_exp_f32_e32 v83, v83
	v_exp_f32_e32 v84, v84
	v_exp_f32_e32 v85, v85
	v_add_f32_e32 v82, 1.0, v82
	v_add_f32_e32 v83, 1.0, v83
	v_add_f32_e32 v84, 1.0, v84
	v_add_f32_e32 v85, 1.0, v85
	v_rcp_f32_e32 v82, v82
	v_rcp_f32_e32 v83, v83
	v_rcp_f32_e32 v84, v84
	v_rcp_f32_e32 v85, v85
	v_pk_mul_f32 v[74:75], v[78:79], v[74:75]
	v_pk_mul_f32 v[72:73], v[76:77], v[72:73]
	global_store_dwordx2 v[96:97], v[80:81], off offset:128
	v_pk_mul_f32 v[72:73], v[72:73], v[82:83]
	v_pk_mul_f32 v[74:75], v[74:75], v[84:85]
	v_cvt_pk_bf16_f32 v72, v72, v73
	v_cvt_pk_bf16_f32 v73, v74, v75
	v_mul_f32_e32 v74, 0xbfb8aa3b, v68
	v_mul_f32_e32 v75, 0xbfb8aa3b, v69
	v_exp_f32_e32 v74, v74
	v_exp_f32_e32 v75, v75
	v_or_b32_e32 v80, 48, v170
	v_mad_i64_i32 v[80:81], s[34:35], v80, s82, v[142:143]
	v_lshl_add_u64 v[80:81], v[80:81], 0, v[140:141]
	global_store_dwordx2 v[80:81], v[72:73], off
	v_add_f32_e32 v72, 1.0, v74
	v_add_f32_e32 v73, 1.0, v75
	v_mul_f32_e32 v74, 0xbfb8aa3b, v70
	v_mul_f32_e32 v75, 0xbfb8aa3b, v71
	v_exp_f32_e32 v74, v74
	v_exp_f32_e32 v75, v75
	v_rcp_f32_e32 v72, v72
	v_rcp_f32_e32 v73, v73
	v_add_f32_e32 v74, 1.0, v74
	v_add_f32_e32 v75, 1.0, v75
	v_rcp_f32_e32 v74, v74
	v_rcp_f32_e32 v75, v75
	v_pk_mul_f32 v[66:67], v[70:71], v[66:67]
	v_pk_mul_f32 v[64:65], v[68:69], v[64:65]
	v_mul_f32_e32 v68, 0xbfb8aa3b, v62
	v_pk_mul_f32 v[64:65], v[64:65], v[72:73]
	v_pk_mul_f32 v[66:67], v[66:67], v[74:75]
	v_cvt_pk_bf16_f32 v64, v64, v65
	v_cvt_pk_bf16_f32 v65, v66, v67
	v_mul_f32_e32 v66, 0xbfb8aa3b, v60
	v_mul_f32_e32 v67, 0xbfb8aa3b, v61
	v_mul_f32_e32 v69, 0xbfb8aa3b, v63
	v_exp_f32_e32 v66, v66
	v_exp_f32_e32 v67, v67
	v_exp_f32_e32 v68, v68
	v_exp_f32_e32 v69, v69
	v_add_f32_e32 v66, 1.0, v66
	v_add_f32_e32 v67, 1.0, v67
	v_add_f32_e32 v68, 1.0, v68
	v_add_f32_e32 v69, 1.0, v69
	v_rcp_f32_e32 v66, v66
	v_rcp_f32_e32 v67, v67
	v_rcp_f32_e32 v68, v68
	v_rcp_f32_e32 v69, v69
	v_pk_mul_f32 v[58:59], v[62:63], v[58:59]
	v_pk_mul_f32 v[56:57], v[60:61], v[56:57]
	global_store_dwordx2 v[80:81], v[64:65], off offset:128
	v_pk_mul_f32 v[56:57], v[56:57], v[66:67]
	v_pk_mul_f32 v[58:59], v[58:59], v[68:69]
	v_cvt_pk_bf16_f32 v56, v56, v57
	v_cvt_pk_bf16_f32 v57, v58, v59
	v_mul_f32_e32 v58, 0xbfb8aa3b, v52
	v_mul_f32_e32 v59, 0xbfb8aa3b, v53
	v_exp_f32_e32 v58, v58
	v_exp_f32_e32 v59, v59
	v_add_u32_e32 v64, 0x80, v170
	v_mad_i64_i32 v[64:65], s[34:35], v64, s82, v[142:143]
	v_lshl_add_u64 v[64:65], v[64:65], 0, v[140:141]
	global_store_dwordx2 v[64:65], v[56:57], off
	v_add_f32_e32 v56, 1.0, v58
	v_add_f32_e32 v57, 1.0, v59
	v_mul_f32_e32 v58, 0xbfb8aa3b, v54
	v_mul_f32_e32 v59, 0xbfb8aa3b, v55
	v_exp_f32_e32 v58, v58
	v_exp_f32_e32 v59, v59
	v_rcp_f32_e32 v56, v56
	v_rcp_f32_e32 v57, v57
	v_add_f32_e32 v58, 1.0, v58
	v_add_f32_e32 v59, 1.0, v59
	v_rcp_f32_e32 v58, v58
	v_rcp_f32_e32 v59, v59
	v_pk_mul_f32 v[50:51], v[54:55], v[50:51]
	v_pk_mul_f32 v[48:49], v[52:53], v[48:49]
	v_mul_f32_e32 v52, 0xbfb8aa3b, v46
	v_pk_mul_f32 v[48:49], v[48:49], v[56:57]
	v_pk_mul_f32 v[50:51], v[50:51], v[58:59]
	v_cvt_pk_bf16_f32 v48, v48, v49
	v_cvt_pk_bf16_f32 v49, v50, v51
	v_mul_f32_e32 v50, 0xbfb8aa3b, v44
	v_mul_f32_e32 v51, 0xbfb8aa3b, v45
	v_mul_f32_e32 v53, 0xbfb8aa3b, v47
	v_exp_f32_e32 v50, v50
	v_exp_f32_e32 v51, v51
	v_exp_f32_e32 v52, v52
	v_exp_f32_e32 v53, v53
	v_add_f32_e32 v50, 1.0, v50
	v_add_f32_e32 v51, 1.0, v51
	v_add_f32_e32 v52, 1.0, v52
	v_add_f32_e32 v53, 1.0, v53
	v_rcp_f32_e32 v50, v50
	v_rcp_f32_e32 v51, v51
	v_rcp_f32_e32 v52, v52
; DI float ex2(float x) { return __builtin_amdgcn_exp2f(x); }
; #define PG8_STAMP() do { if (STAMP && wid == 0 && nts < 64) { const unsigned long long _c = 0ull; \
;         ts_lo = (lane == nts) ? (int)(unsigned)_c : ts_lo; ts_hi = (lane == nts) ? (int)(unsigned)(_c >> 32) : ts_hi; ++nts; } } while (0)
;     DI void operator()(const f32x4 (&acc)[2][2][4][2], const Unit& u, int wr, int wc, int fr, int fq) const {
;         const int row0 = u.pm * BM + wr * 64 + fr, hcol0 = ((u.pn * BM + wc * 32) >> 1) + 4 * fq;
; #pragma unroll
;         for (int ai = 0; ai < 2; ++ai)
; #pragma unroll
;             for (int m = 0; m < 4; ++m) { u16* rowp = O + (size_t)(row0 + ai * HALF + m * 16) * ldc + hcol0;
; #pragma unroll
;                 for (int bj = 0; bj < 2; ++bj) { const f32x4 g = acc[ai][bj][m][0], up = acc[ai][bj][m][1]; float r[4];
; #pragma unroll
;                     for (int j = 0; j < 4; ++j) r[j] = g[j] * up[j] * __builtin_amdgcn_rcpf(1.f + ex2(-LOG2E * g[j]));
;                     uint2 w = {pack2(r[0], r[1]), pack2(r[2], r[3])}; *(uint2*)(rowp + bj * (HALF / 2)) = w; } }
; template <class Epi, class Sched, bool STAMP = false>
; __device__ __forceinline__ void gemm_phase(PG8_LAS unsigned char* lds, const Gemm g, const Sched& S, const Epi& E, unsigned long long* stamps) {
;     ...
;         PG8_STAMP();
;         if constexpr (!Epi::AFTER_DRAIN) { E(acc, cur, wr, wc, fr, fq); S.done(cur); }
;         PG8_STAMP();
;         if (!has_next) break;
	v_rcp_f32_e32 v53, v53
	v_pk_mul_f32 v[42:43], v[46:47], v[42:43]
	v_pk_mul_f32 v[40:41], v[44:45], v[40:41]
	global_store_dwordx2 v[64:65], v[48:49], off offset:128
	v_pk_mul_f32 v[40:41], v[40:41], v[50:51]
	v_pk_mul_f32 v[42:43], v[42:43], v[52:53]
	v_cvt_pk_bf16_f32 v40, v40, v41
	v_cvt_pk_bf16_f32 v41, v42, v43
	v_mul_f32_e32 v42, 0xbfb8aa3b, v36
	v_mul_f32_e32 v43, 0xbfb8aa3b, v37
	v_exp_f32_e32 v42, v42
	v_exp_f32_e32 v43, v43
	v_add_u32_e32 v48, 0x90, v170
	v_mad_i64_i32 v[48:49], s[34:35], v48, s82, v[142:143]
	v_lshl_add_u64 v[48:49], v[48:49], 0, v[140:141]
	global_store_dwordx2 v[48:49], v[40:41], off
	v_add_f32_e32 v40, 1.0, v42
	v_add_f32_e32 v41, 1.0, v43
	v_mul_f32_e32 v42, 0xbfb8aa3b, v38
	v_mul_f32_e32 v43, 0xbfb8aa3b, v39
	v_exp_f32_e32 v42, v42
	v_exp_f32_e32 v43, v43
	v_rcp_f32_e32 v40, v40
	v_rcp_f32_e32 v41, v41
	v_add_f32_e32 v42, 1.0, v42
	v_add_f32_e32 v43, 1.0, v43
	v_rcp_f32_e32 v42, v42
	v_rcp_f32_e32 v43, v43
	v_pk_mul_f32 v[34:35], v[38:39], v[34:35]
	v_pk_mul_f32 v[32:33], v[36:37], v[32:33]
	v_mul_f32_e32 v36, 0xbfb8aa3b, v30
	v_pk_mul_f32 v[32:33], v[32:33], v[40:41]
	v_pk_mul_f32 v[34:35], v[34:35], v[42:43]
	v_cvt_pk_bf16_f32 v32, v32, v33
	v_cvt_pk_bf16_f32 v33, v34, v35
	v_mul_f32_e32 v34, 0xbfb8aa3b, v28
	v_mul_f32_e32 v35, 0xbfb8aa3b, v29
	v_mul_f32_e32 v37, 0xbfb8aa3b, v31
	v_exp_f32_e32 v34, v34
	v_exp_f32_e32 v35, v35
	v_exp_f32_e32 v36, v36
	v_exp_f32_e32 v37, v37
	v_add_f32_e32 v34, 1.0, v34
	v_add_f32_e32 v35, 1.0, v35
	v_add_f32_e32 v36, 1.0, v36
	v_add_f32_e32 v37, 1.0, v37
	v_rcp_f32_e32 v34, v34
	v_rcp_f32_e32 v35, v35
	v_rcp_f32_e32 v36, v36
	v_rcp_f32_e32 v37, v37
	v_pk_mul_f32 v[26:27], v[30:31], v[26:27]
	v_pk_mul_f32 v[24:25], v[28:29], v[24:25]
	global_store_dwordx2 v[48:49], v[32:33], off offset:128
	v_pk_mul_f32 v[24:25], v[24:25], v[34:35]
	v_pk_mul_f32 v[26:27], v[26:27], v[36:37]
	v_cvt_pk_bf16_f32 v24, v24, v25
	v_cvt_pk_bf16_f32 v25, v26, v27
	v_mul_f32_e32 v26, 0xbfb8aa3b, v20
	v_mul_f32_e32 v27, 0xbfb8aa3b, v21
	v_exp_f32_e32 v26, v26
	v_exp_f32_e32 v27, v27
	v_add_u32_e32 v32, 0xa0, v170
	v_mad_i64_i32 v[32:33], s[34:35], v32, s82, v[142:143]
	v_lshl_add_u64 v[32:33], v[32:33], 0, v[140:141]
	global_store_dwordx2 v[32:33], v[24:25], off
	v_add_f32_e32 v24, 1.0, v26
	v_add_f32_e32 v25, 1.0, v27
	v_mul_f32_e32 v26, 0xbfb8aa3b, v22
	v_mul_f32_e32 v27, 0xbfb8aa3b, v23
	v_exp_f32_e32 v26, v26
	v_exp_f32_e32 v27, v27
	v_rcp_f32_e32 v24, v24
	v_rcp_f32_e32 v25, v25
	v_add_f32_e32 v26, 1.0, v26
	v_add_f32_e32 v27, 1.0, v27
	v_rcp_f32_e32 v26, v26
	v_rcp_f32_e32 v27, v27
	v_pk_mul_f32 v[18:19], v[22:23], v[18:19]
	v_pk_mul_f32 v[16:17], v[20:21], v[16:17]
	v_mul_f32_e32 v20, 0xbfb8aa3b, v14
	v_pk_mul_f32 v[16:17], v[16:17], v[24:25]
	v_pk_mul_f32 v[18:19], v[18:19], v[26:27]
	v_cvt_pk_bf16_f32 v16, v16, v17
	v_cvt_pk_bf16_f32 v17, v18, v19
	v_mul_f32_e32 v18, 0xbfb8aa3b, v12
	v_mul_f32_e32 v19, 0xbfb8aa3b, v13
	v_mul_f32_e32 v21, 0xbfb8aa3b, v15
	v_exp_f32_e32 v18, v18
	v_exp_f32_e32 v19, v19
	v_exp_f32_e32 v20, v20
	v_exp_f32_e32 v21, v21
	v_add_f32_e32 v18, 1.0, v18
	v_add_f32_e32 v19, 1.0, v19
	v_add_f32_e32 v20, 1.0, v20
	v_add_f32_e32 v21, 1.0, v21
	v_rcp_f32_e32 v18, v18
	v_rcp_f32_e32 v19, v19
	v_rcp_f32_e32 v20, v20
	v_rcp_f32_e32 v21, v21
	v_pk_mul_f32 v[10:11], v[14:15], v[10:11]
	v_pk_mul_f32 v[8:9], v[12:13], v[8:9]
	global_store_dwordx2 v[32:33], v[16:17], off offset:128
	v_pk_mul_f32 v[8:9], v[8:9], v[18:19]
	v_pk_mul_f32 v[10:11], v[10:11], v[20:21]
	v_cvt_pk_bf16_f32 v8, v8, v9
	v_cvt_pk_bf16_f32 v9, v10, v11
	v_mul_f32_e32 v10, 0xbfb8aa3b, v4
	v_mul_f32_e32 v11, 0xbfb8aa3b, v5
	v_exp_f32_e32 v10, v10
	v_exp_f32_e32 v11, v11
	v_add_u32_e32 v16, 0xb0, v170
	v_mad_i64_i32 v[16:17], s[34:35], v16, s82, v[142:143]
	v_lshl_add_u64 v[16:17], v[16:17], 0, v[140:141]
	global_store_dwordx2 v[16:17], v[8:9], off
	v_add_f32_e32 v8, 1.0, v10
	v_add_f32_e32 v9, 1.0, v11
	v_mul_f32_e32 v10, 0xbfb8aa3b, v6
	v_mul_f32_e32 v11, 0xbfb8aa3b, v7
	v_exp_f32_e32 v10, v10
	v_exp_f32_e32 v11, v11
	v_rcp_f32_e32 v8, v8
	v_rcp_f32_e32 v9, v9
	v_add_f32_e32 v10, 1.0, v10
	v_add_f32_e32 v11, 1.0, v11
	v_rcp_f32_e32 v10, v10
	v_rcp_f32_e32 v11, v11
	v_pk_mul_f32 v[2:3], v[6:7], v[2:3]
	v_pk_mul_f32 v[0:1], v[4:5], v[0:1]
	s_and_b64 vcc, exec, s[2:3]
	v_pk_mul_f32 v[0:1], v[0:1], v[8:9]
	v_pk_mul_f32 v[2:3], v[2:3], v[10:11]
	v_cvt_pk_bf16_f32 v0, v0, v1
	v_cvt_pk_bf16_f32 v1, v2, v3
	s_mov_b32 s86, s83
	s_mov_b32 s85, s84
	s_mov_b64 s[36:37], s[0:1]
	s_mov_b64 s[34:35], s[4:5]
	global_store_dwordx2 v[16:17], v[0:1], off offset:128
	s_cbranch_vccz .LBB0_344
	s_branch .Lgu2_done

; #define PG8_STAGE(bufoff, gbase, voff) do { _Pragma("unroll") for (int _i = 0; _i < 2; ++_i) \
;         __builtin_amdgcn_global_load_lds((const unsigned*)((const char*)(gbase) + (voff)[_i]), (PG8_LAS unsigned*)(lds + (bufoff) + ldsw + _i * 8192), 16, 0, 0); } while (0)
; #define PG8_LDA(dst, b, h) do { _Pragma("unroll") for (int m = 0; m < 4; ++m) _Pragma("unroll") for (int k = 0; k < 2; ++k) dst[m][k] = *(const PG8_LAS bf16x8*)(lds + PG8_SA(b, h) + aoff + m * 2048 + k * 1024); } while (0)
; #define PG8_WAIT_V(n) asm volatile("s_waitcnt vmcnt(" #n ")" ::: "memory")
; #define PG8_WAIT_L(n) asm volatile("s_waitcnt lgkmcnt(" #n ")" ::: "memory")
; template <class Epi, class Sched, bool STAMP = false>
; __device__ __forceinline__ void gemm_phase(PG8_LAS unsigned char* lds, const Gemm g, const Sched& S, const Epi& E, unsigned long long* stamps) {
;     ...
;         const bool has_next = S.next(ui + 1, nxt);
;         const char* nA = has_next ? (const char*)g.A + (size_t)nxt.pm * tstep : cA; const char* nB = has_next ? (const char*)g.Bt + (size_t)nxt.pn * tstep : cB;
;         for (int t = 0; t < nt; t += 2) {
;             const bool last = (t == nt - 2);
;             const char* a1 = cA + (size_t)(t + 1) * kstep;
;             const char* a2 = last ? nA : cA + (size_t)(t + 2) * kstep; const char* b2 = last ? nB : cB + (size_t)(t + 2) * kstep;
;             const char* a3 = a2 + kstep; const char* b3 = b2 + kstep;
;             if (last && has_next) S.a_ready(nxt);
;             PG8_LDB(B0, 0, 0); PG8_SCHED; PG8_LDA(At, 0, 0); PG8_STAGE(PG8_SA(1, 1), a1 + hstep, voffA);
;             PG8_WAIT_L(8); PG8_BAR; PG8_WAIT_L(0); PG8_MMA(0, 0, At, B0); PG8_BAR; PG8_SCHED;
;             PG8_LDB(B1, 0, 1); PG8_STAGE(PG8_SB(0, 0), b2, voffB);
;             PG8_BAR; PG8_WAIT_L(0); PG8_MMA(0, 1, At, B1); PG8_BAR;
;             PG8_LDA(At, 0, 1); PG8_STAGE(PG8_SA(0, 0), a2, voffA);
;             PG8_BAR; PG8_WAIT_L(0); PG8_MMA(1, 0, At, B0); PG8_BAR; PG8_SCHED;
;             PG8_STAGE(PG8_SB(0, 1), b2 + hstep, voffB);
;             PG8_WAIT_V(6); PG8_BAR; PG8_MMA(1, 1, At, B1); PG8_BAR;
;     ...
; #pragma unroll
;         for (int a = 0; a < 2; ++a)
; #pragma unroll
;             for (int b = 0; b < 2; ++b)
; #pragma unroll
;                 for (int m = 0; m < 4; ++m)
; #pragma unroll
;                     for (int n = 0; n < 2; ++n) acc[a][b][m][n] = (f32x4){0.f, 0.f, 0.f, 0.f};
.LBB0_384:
	s_add_u32 vcc_lo, s58, 0x100
	s_addc_u32 vcc_hi, s59, 0
	s_mov_b32 s10, -2
	ds_read_b128 v[170:173], v147
	ds_read_b128 v[174:177], v148
	ds_read_b128 v[178:181], v149
	ds_read_b128 v[182:185], v150
	s_add_u32 s58, s56, 0x100
	s_addc_u32 s59, s57, 0
	s_cmp_eq_u32 s10, 40
	s_cselect_b32 s63, s5, s59
	s_cselect_b32 s62, s4, s58
	s_cselect_b32 s61, s1, vcc_hi
	s_cselect_b32 s60, s0, vcc_lo
	s_mov_b32 m0, s88
	ds_read_b128 v[186:189], v145
	ds_read_b128 v[190:193], v145 offset:1024
	ds_read_b128 v[194:197], v145 offset:2048
	ds_read_b128 v[198:201], v145 offset:3072
	ds_read_b128 v[202:205], v145 offset:4096
	ds_read_b128 v[206:209], v145 offset:5120
	ds_read_b128 v[210:213], v145 offset:6144
	ds_read_b128 v[214:217], v145 offset:7168
	global_load_lds_dwordx4 v136, s[56:57]
	s_mov_b32 m0, s89
	s_nop 0
	global_load_lds_dwordx4 v138, s[56:57]
	s_waitcnt lgkmcnt(8)
	s_barrier
	s_waitcnt lgkmcnt(0)
	s_setprio 1
	s_waitcnt lgkmcnt(0)
	v_mfma_f32_16x16x32_bf16 v[124:127], v[170:173], v[186:189], 0
	v_mfma_f32_16x16x32_bf16 v[120:123], v[178:181], v[186:189], 0
	v_mfma_f32_16x16x32_bf16 v[116:119], v[170:173], v[194:197], 0
	v_mfma_f32_16x16x32_bf16 v[112:115], v[178:181], v[194:197], 0
	v_mfma_f32_16x16x32_bf16 v[100:103], v[170:173], v[202:205], 0
	v_mfma_f32_16x16x32_bf16 v[96:99], v[178:181], v[202:205], 0
	v_mfma_f32_16x16x32_bf16 v[84:87], v[170:173], v[210:213], 0
	v_mfma_f32_16x16x32_bf16 v[80:83], v[178:181], v[210:213], 0
	v_mfma_f32_16x16x32_bf16 v[124:127], v[174:177], v[190:193], v[124:127]
	v_mfma_f32_16x16x32_bf16 v[120:123], v[182:185], v[190:193], v[120:123]
	v_mfma_f32_16x16x32_bf16 v[116:119], v[174:177], v[198:201], v[116:119]
	v_mfma_f32_16x16x32_bf16 v[112:115], v[182:185], v[198:201], v[112:115]
	v_mfma_f32_16x16x32_bf16 v[100:103], v[174:177], v[206:209], v[100:103]
	v_mfma_f32_16x16x32_bf16 v[96:99], v[182:185], v[206:209], v[96:99]
	v_mfma_f32_16x16x32_bf16 v[84:87], v[174:177], v[214:217], v[84:87]
	v_mfma_f32_16x16x32_bf16 v[80:83], v[182:185], v[214:217], v[80:83]
	s_setprio 0
	s_barrier
	s_mov_b32 m0, s68
	ds_read_b128 v[218:221], v151
	ds_read_b128 v[222:225], v152
	ds_read_b128 v[226:229], v153
	ds_read_b128 v[230:233], v154
	global_load_lds_dwordx4 v130, s[60:61]
	s_mov_b32 m0, s69
	s_nop 0
	global_load_lds_dwordx4 v134, s[60:61]
	s_barrier
	s_waitcnt lgkmcnt(0)
	s_setprio 1
	s_waitcnt lgkmcnt(0)
	v_mfma_f32_16x16x32_bf16 v[108:111], v[218:221], v[186:189], 0
	v_mfma_f32_16x16x32_bf16 v[104:107], v[226:229], v[186:189], 0
	v_mfma_f32_16x16x32_bf16 v[92:95], v[218:221], v[194:197], 0
	v_mfma_f32_16x16x32_bf16 v[88:91], v[226:229], v[194:197], 0
	v_mfma_f32_16x16x32_bf16 v[76:79], v[218:221], v[202:205], 0
	v_mfma_f32_16x16x32_bf16 v[72:75], v[226:229], v[202:205], 0
	v_mfma_f32_16x16x32_bf16 v[68:71], v[218:221], v[210:213], 0
	v_mfma_f32_16x16x32_bf16 v[64:67], v[226:229], v[210:213], 0
	v_mfma_f32_16x16x32_bf16 v[108:111], v[222:225], v[190:193], v[108:111]
	v_mfma_f32_16x16x32_bf16 v[104:107], v[230:233], v[190:193], v[104:107]
	v_mfma_f32_16x16x32_bf16 v[92:95], v[222:225], v[198:201], v[92:95]
	v_mfma_f32_16x16x32_bf16 v[88:91], v[230:233], v[198:201], v[88:91]
	v_mfma_f32_16x16x32_bf16 v[76:79], v[222:225], v[206:209], v[76:79]
	v_mfma_f32_16x16x32_bf16 v[72:75], v[230:233], v[206:209], v[72:75]
	v_mfma_f32_16x16x32_bf16 v[68:71], v[222:225], v[214:217], v[68:71]
	v_mfma_f32_16x16x32_bf16 v[64:67], v[230:233], v[214:217], v[64:67]
	s_setprio 0
	s_mov_b32 m0, s67
	s_barrier
	ds_read_b128 v[186:189], v145 offset:16384
	ds_read_b128 v[190:193], v145 offset:17408
	ds_read_b128 v[194:197], v145 offset:18432
	ds_read_b128 v[198:201], v145 offset:19456
	ds_read_b128 v[202:205], v145 offset:20480
	ds_read_b128 v[206:209], v145 offset:21504
	ds_read_b128 v[210:213], v145 offset:22528
	ds_read_b128 v[214:217], v145 offset:23552
	global_load_lds_dwordx4 v128, s[62:63]
	s_mov_b32 m0, s70
	s_nop 0
	global_load_lds_dwordx4 v132, s[62:63]
	s_barrier
	s_waitcnt lgkmcnt(0)
	s_setprio 1
	s_waitcnt lgkmcnt(0)
	v_mfma_f32_16x16x32_bf16 v[60:63], v[170:173], v[186:189], 0
	v_mfma_f32_16x16x32_bf16 v[56:59], v[178:181], v[186:189], 0
	v_mfma_f32_16x16x32_bf16 v[52:55], v[170:173], v[194:197], 0
	v_mfma_f32_16x16x32_bf16 v[48:51], v[178:181], v[194:197], 0
	v_mfma_f32_16x16x32_bf16 v[36:39], v[170:173], v[202:205], 0
	v_mfma_f32_16x16x32_bf16 v[32:35], v[178:181], v[202:205], 0
	v_mfma_f32_16x16x32_bf16 v[20:23], v[170:173], v[210:213], 0
	v_mfma_f32_16x16x32_bf16 v[16:19], v[178:181], v[210:213], 0
	v_mfma_f32_16x16x32_bf16 v[60:63], v[174:177], v[190:193], v[60:63]
	v_mfma_f32_16x16x32_bf16 v[56:59], v[182:185], v[190:193], v[56:59]
	v_mfma_f32_16x16x32_bf16 v[52:55], v[174:177], v[198:201], v[52:55]
	v_mfma_f32_16x16x32_bf16 v[48:51], v[182:185], v[198:201], v[48:51]
	v_mfma_f32_16x16x32_bf16 v[36:39], v[174:177], v[206:209], v[36:39]
	v_mfma_f32_16x16x32_bf16 v[32:35], v[182:185], v[206:209], v[32:35]
	v_mfma_f32_16x16x32_bf16 v[20:23], v[174:177], v[214:217], v[20:23]
	v_mfma_f32_16x16x32_bf16 v[16:19], v[182:185], v[214:217], v[16:19]
	s_setprio 0
	s_barrier
	s_add_u32 s56, s60, 0xb4000
	s_addc_u32 s57, s61, 0
	s_mov_b32 m0, s71
	s_nop 0
	global_load_lds_dwordx4 v130, s[56:57]
	s_mov_b32 m0, s75
	s_nop 0
	global_load_lds_dwordx4 v134, s[56:57]
	s_waitcnt vmcnt(6)
	s_barrier
	s_setprio 1
	v_mfma_f32_16x16x32_bf16 v[44:47], v[218:221], v[186:189], 0
	v_mfma_f32_16x16x32_bf16 v[40:43], v[226:229], v[186:189], 0
	v_mfma_f32_16x16x32_bf16 v[28:31], v[218:221], v[194:197], 0
	v_mfma_f32_16x16x32_bf16 v[24:27], v[226:229], v[194:197], 0
	v_mfma_f32_16x16x32_bf16 v[12:15], v[218:221], v[202:205], 0
	v_mfma_f32_16x16x32_bf16 v[8:11], v[226:229], v[202:205], 0
	v_mfma_f32_16x16x32_bf16 v[4:7], v[218:221], v[210:213], 0
	v_mfma_f32_16x16x32_bf16 v[0:3], v[226:229], v[210:213], 0
	v_mfma_f32_16x16x32_bf16 v[44:47], v[222:225], v[190:193], v[44:47]
	v_mfma_f32_16x16x32_bf16 v[40:43], v[230:233], v[190:193], v[40:43]
	v_mfma_f32_16x16x32_bf16 v[28:31], v[222:225], v[198:201], v[28:31]
	v_mfma_f32_16x16x32_bf16 v[24:27], v[230:233], v[198:201], v[24:27]
	v_mfma_f32_16x16x32_bf16 v[12:15], v[222:225], v[206:209], v[12:15]
	v_mfma_f32_16x16x32_bf16 v[8:11], v[230:233], v[206:209], v[8:11]
	v_mfma_f32_16x16x32_bf16 v[4:7], v[222:225], v[214:217], v[4:7]
	v_mfma_f32_16x16x32_bf16 v[0:3], v[230:233], v[214:217], v[0:3]
	s_setprio 0
	s_barrier
	s_branch .Lzp6_mid

; #define PG8_STAGE(bufoff, gbase, voff) do { _Pragma("unroll") for (int _i = 0; _i < 2; ++_i) \
;         __builtin_amdgcn_global_load_lds((const unsigned*)((const char*)(gbase) + (voff)[_i]), (PG8_LAS unsigned*)(lds + (bufoff) + ldsw + _i * 8192), 16, 0, 0); } while (0)
; #define PG8_LDA(dst, b, h) do { _Pragma("unroll") for (int m = 0; m < 4; ++m) _Pragma("unroll") for (int k = 0; k < 2; ++k) dst[m][k] = *(const PG8_LAS bf16x8*)(lds + PG8_SA(b, h) + aoff + m * 2048 + k * 1024); } while (0)
; #define PG8_LDB(dst, b, h) do { _Pragma("unroll") for (int n = 0; n < 2; ++n) _Pragma("unroll") for (int k = 0; k < 2; ++k) dst[n][k] = *(const PG8_LAS bf16x8*)(lds + PG8_SB(b, h) + boff + n * 2048 + k * 1024); } while (0)
; #define PG8_MMA(ai, bj, At, Bt) do { __builtin_amdgcn_s_setprio(1); _Pragma("unroll") for (int m = 0; m < 4; ++m) _Pragma("unroll") for (int n = 0; n < 2; ++n) _Pragma("unroll") for (int k = 0; k < 2; ++k) \
;         acc[ai][bj][m][n] = __builtin_amdgcn_mfma_f32_16x16x32_bf16(Bt[n][k], At[m][k], acc[ai][bj][m][n], 0, 0, 0); __builtin_amdgcn_s_setprio(0); } while (0)
; #define PG8_WAIT_V(n) asm volatile("s_waitcnt vmcnt(" #n ")" ::: "memory")
; #define PG8_WAIT_L(n) asm volatile("s_waitcnt lgkmcnt(" #n ")" ::: "memory")
; #define PG8_BAR __builtin_amdgcn_s_barrier()
; #define PG8_SCHED __builtin_amdgcn_sched_barrier(0)
; template <class Epi, class Sched, bool STAMP = false>
; __device__ __forceinline__ void gemm_phase(PG8_LAS unsigned char* lds, const Gemm g, const Sched& S, const Epi& E, unsigned long long* stamps) {
;     ...
;             PG8_LDB(B0, 1, 0); PG8_SCHED; PG8_LDA(At, 1, 0); PG8_STAGE(PG8_SA(0, 1), a2 + hstep, voffA);
;             PG8_WAIT_L(8); PG8_BAR; PG8_WAIT_L(0); PG8_MMA(0, 0, At, B0); PG8_BAR; PG8_SCHED;
;             PG8_LDB(B1, 1, 1); PG8_STAGE(PG8_SB(1, 0), b3, voffB);
;             PG8_BAR; PG8_WAIT_L(0); PG8_MMA(0, 1, At, B1); PG8_BAR;
;             PG8_LDA(At, 1, 1); PG8_STAGE(PG8_SA(1, 0), a3, voffA);
;             PG8_BAR; PG8_WAIT_L(0); PG8_MMA(1, 0, At, B0); PG8_BAR; PG8_SCHED;
;             PG8_STAGE(PG8_SB(1, 1), b3 + hstep, voffB);
;             PG8_WAIT_V(6); PG8_BAR; PG8_MMA(1, 1, At, B1); PG8_BAR;
.Lzp6_mid:
	ds_read_b128 v[170:173], v155
	ds_read_b128 v[174:177], v156
	ds_read_b128 v[178:181], v157
	ds_read_b128 v[182:185], v165
	s_add_u32 s56, s62, 0xb4000
	s_addc_u32 s57, s63, 0
	s_mov_b32 m0, s76
	ds_read_b128 v[186:189], v145 offset:32768
	ds_read_b128 v[190:193], v145 offset:33792
	ds_read_b128 v[194:197], v145 offset:34816
	ds_read_b128 v[198:201], v145 offset:35840
	ds_read_b128 v[202:205], v145 offset:36864
	ds_read_b128 v[206:209], v145 offset:37888
	ds_read_b128 v[210:213], v145 offset:38912
	ds_read_b128 v[214:217], v145 offset:39936
	global_load_lds_dwordx4 v128, s[56:57]
	s_mov_b32 m0, s77
	s_nop 0
	global_load_lds_dwordx4 v132, s[56:57]
	s_waitcnt lgkmcnt(8)
	s_barrier
	s_waitcnt lgkmcnt(0)
	s_setprio 1
	s_waitcnt lgkmcnt(0)
	v_mfma_f32_16x16x32_bf16 v[124:127], v[170:173], v[186:189], v[124:127]
	v_mfma_f32_16x16x32_bf16 v[120:123], v[178:181], v[186:189], v[120:123]
	v_mfma_f32_16x16x32_bf16 v[116:119], v[170:173], v[194:197], v[116:119]
	v_mfma_f32_16x16x32_bf16 v[112:115], v[178:181], v[194:197], v[112:115]
	v_mfma_f32_16x16x32_bf16 v[100:103], v[170:173], v[202:205], v[100:103]
	v_mfma_f32_16x16x32_bf16 v[96:99], v[178:181], v[202:205], v[96:99]
	v_mfma_f32_16x16x32_bf16 v[84:87], v[170:173], v[210:213], v[84:87]
	v_mfma_f32_16x16x32_bf16 v[80:83], v[178:181], v[210:213], v[80:83]
	v_mfma_f32_16x16x32_bf16 v[124:127], v[174:177], v[190:193], v[124:127]
	v_mfma_f32_16x16x32_bf16 v[120:123], v[182:185], v[190:193], v[120:123]
	v_mfma_f32_16x16x32_bf16 v[116:119], v[174:177], v[198:201], v[116:119]
	v_mfma_f32_16x16x32_bf16 v[112:115], v[182:185], v[198:201], v[112:115]
	v_mfma_f32_16x16x32_bf16 v[100:103], v[174:177], v[206:209], v[100:103]
	v_mfma_f32_16x16x32_bf16 v[96:99], v[182:185], v[206:209], v[96:99]
	v_mfma_f32_16x16x32_bf16 v[84:87], v[174:177], v[214:217], v[84:87]
	v_mfma_f32_16x16x32_bf16 v[80:83], v[182:185], v[214:217], v[80:83]
	s_setprio 0
	s_barrier
	s_mov_b32 m0, s78
	ds_read_b128 v[218:221], v166
	ds_read_b128 v[222:225], v167
	ds_read_b128 v[226:229], v168
	ds_read_b128 v[230:233], v169
	s_add_u32 s100, s60, 0x80
	s_addc_u32 s101, s61, 0
	global_load_lds_dwordx4 v130, s[100:101]
	s_mov_b32 m0, s79
	s_nop 0
	global_load_lds_dwordx4 v134, s[100:101]
	s_barrier
	s_waitcnt lgkmcnt(0)
	s_setprio 1
	s_waitcnt lgkmcnt(0)
	v_mfma_f32_16x16x32_bf16 v[108:111], v[218:221], v[186:189], v[108:111]
	v_mfma_f32_16x16x32_bf16 v[104:107], v[226:229], v[186:189], v[104:107]
	v_mfma_f32_16x16x32_bf16 v[92:95], v[218:221], v[194:197], v[92:95]
	v_mfma_f32_16x16x32_bf16 v[88:91], v[226:229], v[194:197], v[88:91]
	v_mfma_f32_16x16x32_bf16 v[76:79], v[218:221], v[202:205], v[76:79]
	v_mfma_f32_16x16x32_bf16 v[72:75], v[226:229], v[202:205], v[72:75]
	v_mfma_f32_16x16x32_bf16 v[68:71], v[218:221], v[210:213], v[68:71]
	v_mfma_f32_16x16x32_bf16 v[64:67], v[226:229], v[210:213], v[64:67]
	v_mfma_f32_16x16x32_bf16 v[108:111], v[222:225], v[190:193], v[108:111]
	v_mfma_f32_16x16x32_bf16 v[104:107], v[230:233], v[190:193], v[104:107]
	v_mfma_f32_16x16x32_bf16 v[92:95], v[222:225], v[198:201], v[92:95]
	v_mfma_f32_16x16x32_bf16 v[88:91], v[230:233], v[198:201], v[88:91]
	v_mfma_f32_16x16x32_bf16 v[76:79], v[222:225], v[206:209], v[76:79]
	v_mfma_f32_16x16x32_bf16 v[72:75], v[230:233], v[206:209], v[72:75]
	v_mfma_f32_16x16x32_bf16 v[68:71], v[222:225], v[214:217], v[68:71]
	v_mfma_f32_16x16x32_bf16 v[64:67], v[230:233], v[214:217], v[64:67]
	s_setprio 0
	s_mov_b32 m0, s82
	s_barrier
	ds_read_b128 v[186:189], v145 offset:49152
	ds_read_b128 v[190:193], v145 offset:50176
	ds_read_b128 v[194:197], v145 offset:51200
	ds_read_b128 v[198:201], v145 offset:52224
	ds_read_b128 v[202:205], v145 offset:53248
	ds_read_b128 v[206:209], v145 offset:54272
	ds_read_b128 v[210:213], v145 offset:55296
	ds_read_b128 v[214:217], v145 offset:56320
	s_add_u32 s100, s62, 0x80
	s_addc_u32 s101, s63, 0
	global_load_lds_dwordx4 v128, s[100:101]
	s_mov_b32 m0, s83
	s_nop 0
	global_load_lds_dwordx4 v132, s[100:101]
	s_barrier
	s_waitcnt lgkmcnt(0)
	s_setprio 1
	s_waitcnt lgkmcnt(0)
	v_mfma_f32_16x16x32_bf16 v[60:63], v[170:173], v[186:189], v[60:63]
	v_mfma_f32_16x16x32_bf16 v[56:59], v[178:181], v[186:189], v[56:59]
	v_mfma_f32_16x16x32_bf16 v[52:55], v[170:173], v[194:197], v[52:55]
	v_mfma_f32_16x16x32_bf16 v[48:51], v[178:181], v[194:197], v[48:51]
	v_mfma_f32_16x16x32_bf16 v[36:39], v[170:173], v[202:205], v[36:39]
	v_mfma_f32_16x16x32_bf16 v[32:35], v[178:181], v[202:205], v[32:35]
	v_mfma_f32_16x16x32_bf16 v[20:23], v[170:173], v[210:213], v[20:23]
	v_mfma_f32_16x16x32_bf16 v[16:19], v[178:181], v[210:213], v[16:19]
	v_mfma_f32_16x16x32_bf16 v[60:63], v[174:177], v[190:193], v[60:63]
	v_mfma_f32_16x16x32_bf16 v[56:59], v[182:185], v[190:193], v[56:59]
	v_mfma_f32_16x16x32_bf16 v[52:55], v[174:177], v[198:201], v[52:55]
	v_mfma_f32_16x16x32_bf16 v[48:51], v[182:185], v[198:201], v[48:51]
	v_mfma_f32_16x16x32_bf16 v[36:39], v[174:177], v[206:209], v[36:39]
	v_mfma_f32_16x16x32_bf16 v[32:35], v[182:185], v[206:209], v[32:35]
	v_mfma_f32_16x16x32_bf16 v[20:23], v[174:177], v[214:217], v[20:23]
	v_mfma_f32_16x16x32_bf16 v[16:19], v[182:185], v[214:217], v[16:19]
	s_setprio 0
	s_barrier
	s_add_u32 s56, s60, 0xb4080
	s_addc_u32 s57, s61, 0
	s_mov_b32 m0, s84
	s_nop 0
	global_load_lds_dwordx4 v130, s[56:57]
	s_mov_b32 m0, s85
	s_nop 0
	global_load_lds_dwordx4 v134, s[56:57]
	s_waitcnt vmcnt(6)
	s_barrier
; #define PG8_STAMP() do { if (STAMP && wid == 0 && nts < 64) { const unsigned long long _c = 0ull; \
;         ts_lo = (lane == nts) ? (int)(unsigned)_c : ts_lo; ts_hi = (lane == nts) ? (int)(unsigned)(_c >> 32) : ts_hi; ++nts; } } while (0)
; #define PG8_MMA(ai, bj, At, Bt) do { __builtin_amdgcn_s_setprio(1); _Pragma("unroll") for (int m = 0; m < 4; ++m) _Pragma("unroll") for (int n = 0; n < 2; ++n) _Pragma("unroll") for (int k = 0; k < 2; ++k) \
;         acc[ai][bj][m][n] = __builtin_amdgcn_mfma_f32_16x16x32_bf16(Bt[n][k], At[m][k], acc[ai][bj][m][n], 0, 0, 0); __builtin_amdgcn_s_setprio(0); } while (0)
; #define PG8_WAIT_V(n) asm volatile("s_waitcnt vmcnt(" #n ")" ::: "memory")
; #define PG8_BAR __builtin_amdgcn_s_barrier()
;     DI void operator()(const f32x4 (&acc)[2][2][4][2], const Unit& u, int wr, int wc, int fr, int fq) const {
;         const int row0 = u.pm * BM + wr * 64 + fr, col0 = u.pn * BM + wc * 32 + 8 * fq;
; #pragma unroll
;         for (int ai = 0; ai < 2; ++ai)
; #pragma unroll
;             for (int m = 0; m < 4; ++m) { u16* rowp = O + (size_t)(row0 + ai * HALF + m * 16) * ldc + col0;
; #pragma unroll
;                 for (int bj = 0; bj < 2; ++bj) { const f32x4 v0 = acc[ai][bj][m][0], v1 = acc[ai][bj][m][1];
;                     uint4 w = {pack2(v0[0], v0[1]), pack2(v0[2], v0[3]), pack2(v1[0], v1[1]), pack2(v1[2], v1[3])}; *(uint4*)(rowp + bj * HALF) = w; } }
; template <class Epi, class Sched, bool STAMP = false>
; __device__ __forceinline__ void gemm_phase(PG8_LAS unsigned char* lds, const Gemm g, const Sched& S, const Epi& E, unsigned long long* stamps) {
;     ...
;             PG8_WAIT_V(6); PG8_BAR; PG8_MMA(1, 1, At, B1); PG8_BAR;
;         }
;         PG8_STAMP();
;         if constexpr (!Epi::AFTER_DRAIN) { E(acc, cur, wr, wc, fr, fq); S.done(cur); }
;         PG8_STAMP();
;         if (!has_next) break;
	s_setprio 1
	v_mfma_f32_16x16x32_bf16 v[44:47], v[218:221], v[186:189], v[44:47]
	v_mfma_f32_16x16x32_bf16 v[40:43], v[226:229], v[186:189], v[40:43]
	v_mfma_f32_16x16x32_bf16 v[28:31], v[218:221], v[194:197], v[28:31]
	v_mfma_f32_16x16x32_bf16 v[24:27], v[226:229], v[194:197], v[24:27]
	v_mfma_f32_16x16x32_bf16 v[12:15], v[218:221], v[202:205], v[12:15]
	v_mfma_f32_16x16x32_bf16 v[8:11], v[226:229], v[202:205], v[8:11]
	v_mfma_f32_16x16x32_bf16 v[4:7], v[218:221], v[210:213], v[4:7]
	v_mfma_f32_16x16x32_bf16 v[0:3], v[226:229], v[210:213], v[0:3]
	v_mfma_f32_16x16x32_bf16 v[44:47], v[222:225], v[190:193], v[44:47]
	v_mfma_f32_16x16x32_bf16 v[40:43], v[230:233], v[190:193], v[40:43]
	v_mfma_f32_16x16x32_bf16 v[28:31], v[222:225], v[198:201], v[28:31]
	v_mfma_f32_16x16x32_bf16 v[24:27], v[230:233], v[198:201], v[24:27]
	v_mfma_f32_16x16x32_bf16 v[12:15], v[222:225], v[206:209], v[12:15]
	v_mfma_f32_16x16x32_bf16 v[8:11], v[230:233], v[206:209], v[8:11]
	v_mfma_f32_16x16x32_bf16 v[4:7], v[222:225], v[214:217], v[4:7]
	v_mfma_f32_16x16x32_bf16 v[0:3], v[230:233], v[214:217], v[0:3]
	s_setprio 0
	s_add_i32 s10, s10, 2
	s_add_u32 vcc_lo, vcc_lo, 0x100
	s_addc_u32 vcc_hi, vcc_hi, 0
	s_cmp_gt_u32 s10, 41
	s_mov_b64 s[56:57], s[58:59]
	s_barrier
	s_cbranch_scc0 .LBB0_385
	v_lshl_add_u32 v170, s94, 8, v144
	v_lshl_or_b32 v172, s97, 8, v146
	v_ashrrev_i32_e32 v171, 31, v170
	v_ashrrev_i32_e32 v173, 31, v172
	v_lshlrev_b64 v[174:175], 11, v[170:171]
	v_lshl_add_u64 v[174:175], s[14:15], 0, v[174:175]
	v_lshlrev_b64 v[172:173], 1, v[172:173]
	v_lshl_add_u64 v[174:175], v[174:175], 0, v[172:173]
	v_cvt_pk_bf16_f32 v60, v60, v61
	v_cvt_pk_bf16_f32 v61, v62, v63
	v_cvt_pk_bf16_f32 v62, v56, v57
	v_add_co_u32_e32 v56, vcc, s90, v174
	v_cvt_pk_bf16_f32 v68, v68, v69
	v_cvt_pk_bf16_f32 v69, v70, v71
	v_cvt_pk_bf16_f32 v70, v64, v65
	v_lshl_add_u64 v[64:65], v[174:175], 0, s[34:35]
	v_addc_co_u32_e32 v57, vcc, 0, v175, vcc
	v_cvt_pk_bf16_f32 v44, v44, v45
	v_cvt_pk_bf16_f32 v45, v46, v47
	v_cvt_pk_bf16_f32 v46, v40, v41
	v_cvt_pk_bf16_f32 v47, v42, v43
	v_cvt_pk_bf16_f32 v108, v108, v109
	v_cvt_pk_bf16_f32 v109, v110, v111
	v_cvt_pk_bf16_f32 v110, v104, v105
	v_or_b32_e32 v104, 16, v170
	global_store_dwordx4 v[64:65], v[44:47], off offset:256
	v_ashrrev_i32_e32 v105, 31, v104
	v_cvt_pk_bf16_f32 v92, v92, v93
	v_add_co_u32_e32 v46, vcc, s91, v174
	v_cvt_pk_bf16_f32 v93, v94, v95
	v_cvt_pk_bf16_f32 v94, v88, v89
	v_or_b32_e32 v88, 32, v170
	v_lshl_add_u64 v[44:45], v[174:175], 0, s[36:37]
	v_addc_co_u32_e32 v47, vcc, 0, v175, vcc
	v_cvt_pk_bf16_f32 v28, v28, v29
	v_cvt_pk_bf16_f32 v29, v30, v31
	v_cvt_pk_bf16_f32 v30, v24, v25
	v_cvt_pk_bf16_f32 v31, v26, v27
	v_lshlrev_b64 v[104:105], 11, v[104:105]
	v_ashrrev_i32_e32 v89, 31, v88
	v_cvt_pk_bf16_f32 v76, v76, v77
	v_cvt_pk_bf16_f32 v77, v78, v79
	v_cvt_pk_bf16_f32 v78, v72, v73
	v_or_b32_e32 v72, 48, v170
	global_store_dwordx4 v[44:45], v[28:31], off offset:256
	v_cvt_pk_bf16_f32 v111, v106, v107
	v_lshl_add_u64 v[104:105], s[14:15], 0, v[104:105]
	v_add_co_u32_e32 v30, vcc, s92, v174
	v_lshlrev_b64 v[88:89], 11, v[88:89]
	v_ashrrev_i32_e32 v73, 31, v72
	v_lshl_add_u64 v[28:29], v[174:175], 0, s[52:53]
	v_addc_co_u32_e32 v31, vcc, 0, v175, vcc
	v_cvt_pk_bf16_f32 v12, v12, v13
	v_cvt_pk_bf16_f32 v13, v14, v15
	v_cvt_pk_bf16_f32 v14, v8, v9
	v_cvt_pk_bf16_f32 v15, v10, v11
	global_store_dwordx4 v[174:175], v[108:111], off offset:256
	v_cvt_pk_bf16_f32 v95, v90, v91
	v_lshl_add_u64 v[88:89], s[14:15], 0, v[88:89]
	v_lshl_add_u64 v[108:109], v[104:105], 0, v[172:173]
	v_lshlrev_b64 v[72:73], 11, v[72:73]
	global_store_dwordx4 v[28:29], v[12:15], off offset:256
	global_store_dwordx4 v[108:109], v[92:95], off offset:256
	v_cvt_pk_bf16_f32 v79, v74, v75
	v_add_co_u32_e32 v14, vcc, s93, v174
	v_lshl_add_u64 v[92:93], v[88:89], 0, v[172:173]
	v_lshl_add_u64 v[72:73], s[14:15], 0, v[72:73]
	v_addc_co_u32_e32 v15, vcc, 0, v175, vcc
	v_cvt_pk_bf16_f32 v124, v124, v125
	v_cvt_pk_bf16_f32 v125, v126, v127
	v_cvt_pk_bf16_f32 v126, v120, v121
	v_cvt_pk_bf16_f32 v127, v122, v123
	v_cvt_pk_bf16_f32 v104, v116, v117
	v_cvt_pk_bf16_f32 v105, v118, v119
	v_cvt_pk_bf16_f32 v106, v112, v113
	v_cvt_pk_bf16_f32 v107, v114, v115
	v_cvt_pk_bf16_f32 v88, v100, v101
	v_cvt_pk_bf16_f32 v89, v102, v103
	v_cvt_pk_bf16_f32 v90, v96, v97
	v_cvt_pk_bf16_f32 v91, v98, v99
	global_store_dwordx4 v[92:93], v[76:79], off offset:256
	v_cvt_pk_bf16_f32 v74, v80, v81
	v_cvt_pk_bf16_f32 v75, v82, v83
	v_lshl_add_u64 v[76:77], v[72:73], 0, v[172:173]
	v_cvt_pk_bf16_f32 v72, v84, v85
	v_cvt_pk_bf16_f32 v73, v86, v87
	v_cvt_pk_bf16_f32 v71, v66, v67
	v_cvt_pk_bf16_f32 v63, v58, v59
	v_cvt_pk_bf16_f32 v40, v52, v53
	v_cvt_pk_bf16_f32 v41, v54, v55
	v_cvt_pk_bf16_f32 v42, v48, v49
	v_cvt_pk_bf16_f32 v43, v50, v51
	v_cvt_pk_bf16_f32 v24, v36, v37
	v_cvt_pk_bf16_f32 v25, v38, v39
	v_cvt_pk_bf16_f32 v26, v32, v33
	v_cvt_pk_bf16_f32 v27, v34, v35
	v_lshl_add_u64 v[12:13], v[174:175], 0, s[54:55]
	v_cvt_pk_bf16_f32 v8, v20, v21
	v_cvt_pk_bf16_f32 v9, v22, v23
	v_cvt_pk_bf16_f32 v10, v16, v17
	v_cvt_pk_bf16_f32 v11, v18, v19
	v_cvt_pk_bf16_f32 v4, v4, v5
	v_cvt_pk_bf16_f32 v5, v6, v7
	v_cvt_pk_bf16_f32 v6, v0, v1
	v_cvt_pk_bf16_f32 v7, v2, v3
	s_and_b64 vcc, exec, s[2:3]
	s_mov_b32 s97, s95
	s_mov_b32 s94, s96
	s_mov_b64 s[58:59], s[0:1]
	s_mov_b64 s[56:57], s[4:5]
	global_store_dwordx4 v[174:175], v[124:127], off
	global_store_dwordx4 v[108:109], v[104:107], off
	global_store_dwordx4 v[92:93], v[88:91], off
	global_store_dwordx4 v[76:77], v[72:75], off
	global_store_dwordx4 v[76:77], v[68:71], off offset:256
	global_store_dwordx4 v[56:57], v[60:63], off
	global_store_dwordx4 v[46:47], v[40:43], off
	global_store_dwordx4 v[30:31], v[24:27], off
	global_store_dwordx4 v[14:15], v[8:11], off
	global_store_dwordx4 v[12:13], v[4:7], off offset:256
	s_cbranch_vccz .LBB0_374
	s_waitcnt vmcnt(0)
	s_cmpk_gt_u32 s65, 0xff
	s_cbranch_scc1 .LBB0_389
	s_barrier

; #define PG8_STAGE(bufoff, gbase, voff) do { _Pragma("unroll") for (int _i = 0; _i < 2; ++_i) \
;         __builtin_amdgcn_global_load_lds((const unsigned*)((const char*)(gbase) + (voff)[_i]), (PG8_LAS unsigned*)(lds + (bufoff) + ldsw + _i * 8192), 16, 0, 0); } while (0)
; #define PG8_LDA(dst, b, h) do { _Pragma("unroll") for (int m = 0; m < 4; ++m) _Pragma("unroll") for (int k = 0; k < 2; ++k) dst[m][k] = *(const PG8_LAS bf16x8*)(lds + PG8_SA(b, h) + aoff + m * 2048 + k * 1024); } while (0)
; #define PG8_WAIT_V(n) asm volatile("s_waitcnt vmcnt(" #n ")" ::: "memory")
; #define PG8_WAIT_L(n) asm volatile("s_waitcnt lgkmcnt(" #n ")" ::: "memory")
; template <class Epi, class Sched, bool STAMP = false>
; __device__ __forceinline__ void gemm_phase(PG8_LAS unsigned char* lds, const Gemm g, const Sched& S, const Epi& E, unsigned long long* stamps) {
;     ...
;         const bool has_next = S.next(ui + 1, nxt);
;         const char* nA = has_next ? (const char*)g.A + (size_t)nxt.pm * tstep : cA; const char* nB = has_next ? (const char*)g.Bt + (size_t)nxt.pn * tstep : cB;
;         for (int t = 0; t < nt; t += 2) {
;             const bool last = (t == nt - 2);
;             const char* a1 = cA + (size_t)(t + 1) * kstep;
;             const char* a2 = last ? nA : cA + (size_t)(t + 2) * kstep; const char* b2 = last ? nB : cB + (size_t)(t + 2) * kstep;
;             const char* a3 = a2 + kstep; const char* b3 = b2 + kstep;
;             if (last && has_next) S.a_ready(nxt);
;             PG8_LDB(B0, 0, 0); PG8_SCHED; PG8_LDA(At, 0, 0); PG8_STAGE(PG8_SA(1, 1), a1 + hstep, voffA);
;             PG8_WAIT_L(8); PG8_BAR; PG8_WAIT_L(0); PG8_MMA(0, 0, At, B0); PG8_BAR; PG8_SCHED;
;             PG8_LDB(B1, 0, 1); PG8_STAGE(PG8_SB(0, 0), b2, voffB);
;             PG8_BAR; PG8_WAIT_L(0); PG8_MMA(0, 1, At, B1); PG8_BAR;
;             PG8_LDA(At, 0, 1); PG8_STAGE(PG8_SA(0, 0), a2, voffA);
;             PG8_BAR; PG8_WAIT_L(0); PG8_MMA(1, 0, At, B0); PG8_BAR; PG8_SCHED;
;             PG8_STAGE(PG8_SB(0, 1), b2 + hstep, voffB);
;             PG8_WAIT_V(6); PG8_BAR; PG8_MMA(1, 1, At, B1); PG8_BAR;
;     ...
; #pragma unroll
;         for (int a = 0; a < 2; ++a)
; #pragma unroll
;             for (int b = 0; b < 2; ++b)
; #pragma unroll
;                 for (int m = 0; m < 4; ++m)
; #pragma unroll
;                     for (int n = 0; n < 2; ++n) acc[a][b][m][n] = (f32x4){0.f, 0.f, 0.f, 0.f};
.LBB0_438:
	s_add_u32 s77, s36, 0x100
	s_addc_u32 s78, s37, 0
	s_mov_b32 s10, -2
	s_cmp_eq_u32 s58, s99
	s_cbranch_scc1 .Lgu3_half_loop_z
	ds_read_b128 v[140:143], v147
	ds_read_b128 v[170:173], v148
	ds_read_b128 v[174:177], v149
	ds_read_b128 v[178:181], v150
	s_add_u32 s36, s34, 0x100
	s_addc_u32 s37, s35, 0
	s_cmp_eq_u32 s10, 12
	s_cselect_b32 s43, s5, s37
	s_cselect_b32 s42, s4, s36
	s_cselect_b32 s41, s1, s78
	s_cselect_b32 s40, s0, s77
	s_mov_b32 m0, s67
	ds_read_b128 v[182:185], v145
	ds_read_b128 v[186:189], v145 offset:1024
	ds_read_b128 v[190:193], v145 offset:2048
	ds_read_b128 v[194:197], v145 offset:3072
	ds_read_b128 v[198:201], v145 offset:4096
	ds_read_b128 v[202:205], v145 offset:5120
	ds_read_b128 v[206:209], v145 offset:6144
	ds_read_b128 v[210:213], v145 offset:7168
	global_load_lds_dwordx4 v132, s[34:35]
	s_mov_b32 m0, s68
	s_nop 0
	global_load_lds_dwordx4 v134, s[34:35]
	s_waitcnt lgkmcnt(8)
	s_barrier
	s_waitcnt lgkmcnt(0)
	s_setprio 1
	s_waitcnt lgkmcnt(0)
	v_mfma_f32_16x16x32_bf16 v[124:127], v[140:143], v[182:185], 0
	v_mfma_f32_16x16x32_bf16 v[120:123], v[174:177], v[182:185], 0
	v_mfma_f32_16x16x32_bf16 v[108:111], v[140:143], v[190:193], 0
	v_mfma_f32_16x16x32_bf16 v[104:107], v[174:177], v[190:193], 0
	v_mfma_f32_16x16x32_bf16 v[92:95], v[140:143], v[198:201], 0
	v_mfma_f32_16x16x32_bf16 v[88:91], v[174:177], v[198:201], 0
	v_mfma_f32_16x16x32_bf16 v[76:79], v[140:143], v[206:209], 0
	v_mfma_f32_16x16x32_bf16 v[72:75], v[174:177], v[206:209], 0
	v_mfma_f32_16x16x32_bf16 v[124:127], v[170:173], v[186:189], v[124:127]
	v_mfma_f32_16x16x32_bf16 v[120:123], v[178:181], v[186:189], v[120:123]
	v_mfma_f32_16x16x32_bf16 v[108:111], v[170:173], v[194:197], v[108:111]
	v_mfma_f32_16x16x32_bf16 v[104:107], v[178:181], v[194:197], v[104:107]
	v_mfma_f32_16x16x32_bf16 v[92:95], v[170:173], v[202:205], v[92:95]
	v_mfma_f32_16x16x32_bf16 v[88:91], v[178:181], v[202:205], v[88:91]
	v_mfma_f32_16x16x32_bf16 v[76:79], v[170:173], v[210:213], v[76:79]
	v_mfma_f32_16x16x32_bf16 v[72:75], v[178:181], v[210:213], v[72:75]
	s_setprio 0
	s_barrier
	s_mov_b32 m0, s49
	ds_read_b128 v[214:217], v151
	ds_read_b128 v[218:221], v152
	ds_read_b128 v[222:225], v153
	ds_read_b128 v[226:229], v154
	global_load_lds_dwordx4 v130, s[40:41]
	s_mov_b32 m0, s52
	s_nop 0
	global_load_lds_dwordx4 v128, s[40:41]
	s_barrier
	s_waitcnt lgkmcnt(0)
	s_setprio 1
	s_waitcnt lgkmcnt(0)
	v_mfma_f32_16x16x32_bf16 v[116:119], v[214:217], v[182:185], 0
	v_mfma_f32_16x16x32_bf16 v[112:115], v[222:225], v[182:185], 0
	v_mfma_f32_16x16x32_bf16 v[100:103], v[214:217], v[190:193], 0
	v_mfma_f32_16x16x32_bf16 v[96:99], v[222:225], v[190:193], 0
	v_mfma_f32_16x16x32_bf16 v[84:87], v[214:217], v[198:201], 0
	v_mfma_f32_16x16x32_bf16 v[80:83], v[222:225], v[198:201], 0
	v_mfma_f32_16x16x32_bf16 v[68:71], v[214:217], v[206:209], 0
	v_mfma_f32_16x16x32_bf16 v[64:67], v[222:225], v[206:209], 0
	v_mfma_f32_16x16x32_bf16 v[116:119], v[218:221], v[186:189], v[116:119]
	v_mfma_f32_16x16x32_bf16 v[112:115], v[226:229], v[186:189], v[112:115]
	v_mfma_f32_16x16x32_bf16 v[100:103], v[218:221], v[194:197], v[100:103]
	v_mfma_f32_16x16x32_bf16 v[96:99], v[226:229], v[194:197], v[96:99]
	v_mfma_f32_16x16x32_bf16 v[84:87], v[218:221], v[202:205], v[84:87]
	v_mfma_f32_16x16x32_bf16 v[80:83], v[226:229], v[202:205], v[80:83]
	v_mfma_f32_16x16x32_bf16 v[68:71], v[218:221], v[210:213], v[68:71]
	v_mfma_f32_16x16x32_bf16 v[64:67], v[226:229], v[210:213], v[64:67]
	s_setprio 0
	s_mov_b32 m0, s46
	s_barrier
	ds_read_b128 v[182:185], v145 offset:16384
	ds_read_b128 v[186:189], v145 offset:17408
	ds_read_b128 v[190:193], v145 offset:18432
	ds_read_b128 v[194:197], v145 offset:19456
	ds_read_b128 v[198:201], v145 offset:20480
	ds_read_b128 v[202:205], v145 offset:21504
	ds_read_b128 v[206:209], v145 offset:22528
	ds_read_b128 v[210:213], v145 offset:23552
	global_load_lds_dwordx4 v130, s[42:43]
	s_mov_b32 m0, s53
	s_nop 0
	global_load_lds_dwordx4 v128, s[42:43]
	s_barrier
	s_waitcnt lgkmcnt(0)
	s_setprio 1
	s_waitcnt lgkmcnt(0)
	v_mfma_f32_16x16x32_bf16 v[60:63], v[140:143], v[182:185], 0
	v_mfma_f32_16x16x32_bf16 v[56:59], v[174:177], v[182:185], 0
	v_mfma_f32_16x16x32_bf16 v[44:47], v[140:143], v[190:193], 0
	v_mfma_f32_16x16x32_bf16 v[40:43], v[174:177], v[190:193], 0
	v_mfma_f32_16x16x32_bf16 v[28:31], v[140:143], v[198:201], 0
	v_mfma_f32_16x16x32_bf16 v[24:27], v[174:177], v[198:201], 0
	v_mfma_f32_16x16x32_bf16 v[12:15], v[140:143], v[206:209], 0
	v_mfma_f32_16x16x32_bf16 v[8:11], v[174:177], v[206:209], 0
	v_mfma_f32_16x16x32_bf16 v[60:63], v[170:173], v[186:189], v[60:63]
	v_mfma_f32_16x16x32_bf16 v[56:59], v[178:181], v[186:189], v[56:59]
	v_mfma_f32_16x16x32_bf16 v[44:47], v[170:173], v[194:197], v[44:47]
	v_mfma_f32_16x16x32_bf16 v[40:43], v[178:181], v[194:197], v[40:43]
	v_mfma_f32_16x16x32_bf16 v[28:31], v[170:173], v[202:205], v[28:31]
	v_mfma_f32_16x16x32_bf16 v[24:27], v[178:181], v[202:205], v[24:27]
	v_mfma_f32_16x16x32_bf16 v[12:15], v[170:173], v[210:213], v[12:15]
	v_mfma_f32_16x16x32_bf16 v[8:11], v[178:181], v[210:213], v[8:11]
	s_setprio 0
	s_barrier
	s_add_u32 s34, s40, 0x44000
	s_addc_u32 s35, s41, 0
	s_mov_b32 m0, s54
	s_nop 0
	global_load_lds_dwordx4 v130, s[34:35]
	s_mov_b32 m0, s55
	s_nop 0
	global_load_lds_dwordx4 v128, s[34:35]
	s_waitcnt vmcnt(6)
	s_barrier
	s_setprio 1
	v_mfma_f32_16x16x32_bf16 v[52:55], v[214:217], v[182:185], 0
	v_mfma_f32_16x16x32_bf16 v[48:51], v[222:225], v[182:185], 0
	v_mfma_f32_16x16x32_bf16 v[36:39], v[214:217], v[190:193], 0
	v_mfma_f32_16x16x32_bf16 v[32:35], v[222:225], v[190:193], 0
	v_mfma_f32_16x16x32_bf16 v[20:23], v[214:217], v[198:201], 0
	v_mfma_f32_16x16x32_bf16 v[16:19], v[222:225], v[198:201], 0
	v_mfma_f32_16x16x32_bf16 v[4:7], v[214:217], v[206:209], 0
	v_mfma_f32_16x16x32_bf16 v[0:3], v[222:225], v[206:209], 0
	v_mfma_f32_16x16x32_bf16 v[52:55], v[218:221], v[186:189], v[52:55]
	v_mfma_f32_16x16x32_bf16 v[48:51], v[226:229], v[186:189], v[48:51]
	v_mfma_f32_16x16x32_bf16 v[36:39], v[218:221], v[194:197], v[36:39]
	v_mfma_f32_16x16x32_bf16 v[32:35], v[226:229], v[194:197], v[32:35]
	v_mfma_f32_16x16x32_bf16 v[20:23], v[218:221], v[202:205], v[20:23]
	v_mfma_f32_16x16x32_bf16 v[16:19], v[226:229], v[202:205], v[16:19]
	v_mfma_f32_16x16x32_bf16 v[4:7], v[218:221], v[210:213], v[4:7]
	v_mfma_f32_16x16x32_bf16 v[0:3], v[226:229], v[210:213], v[0:3]
	s_setprio 0
	s_barrier
	s_branch .Lzp7_mid

; #define PG8_STAGE(bufoff, gbase, voff) do { _Pragma("unroll") for (int _i = 0; _i < 2; ++_i) \
;         __builtin_amdgcn_global_load_lds((const unsigned*)((const char*)(gbase) + (voff)[_i]), (PG8_LAS unsigned*)(lds + (bufoff) + ldsw + _i * 8192), 16, 0, 0); } while (0)
; #define PG8_LDA(dst, b, h) do { _Pragma("unroll") for (int m = 0; m < 4; ++m) _Pragma("unroll") for (int k = 0; k < 2; ++k) dst[m][k] = *(const PG8_LAS bf16x8*)(lds + PG8_SA(b, h) + aoff + m * 2048 + k * 1024); } while (0)
; #define PG8_LDB(dst, b, h) do { _Pragma("unroll") for (int n = 0; n < 2; ++n) _Pragma("unroll") for (int k = 0; k < 2; ++k) dst[n][k] = *(const PG8_LAS bf16x8*)(lds + PG8_SB(b, h) + boff + n * 2048 + k * 1024); } while (0)
; #define PG8_MMA(ai, bj, At, Bt) do { __builtin_amdgcn_s_setprio(1); _Pragma("unroll") for (int m = 0; m < 4; ++m) _Pragma("unroll") for (int n = 0; n < 2; ++n) _Pragma("unroll") for (int k = 0; k < 2; ++k) \
;         acc[ai][bj][m][n] = __builtin_amdgcn_mfma_f32_16x16x32_bf16(Bt[n][k], At[m][k], acc[ai][bj][m][n], 0, 0, 0); __builtin_amdgcn_s_setprio(0); } while (0)
; #define PG8_WAIT_V(n) asm volatile("s_waitcnt vmcnt(" #n ")" ::: "memory")
; #define PG8_WAIT_L(n) asm volatile("s_waitcnt lgkmcnt(" #n ")" ::: "memory")
; #define PG8_BAR __builtin_amdgcn_s_barrier()
; #define PG8_SCHED __builtin_amdgcn_sched_barrier(0)
; template <class Epi, class Sched, bool STAMP = false>
; __device__ __forceinline__ void gemm_phase(PG8_LAS unsigned char* lds, const Gemm g, const Sched& S, const Epi& E, unsigned long long* stamps) {
;     ...
;             PG8_LDB(B0, 1, 0); PG8_SCHED; PG8_LDA(At, 1, 0); PG8_STAGE(PG8_SA(0, 1), a2 + hstep, voffA);
;             PG8_WAIT_L(8); PG8_BAR; PG8_WAIT_L(0); PG8_MMA(0, 0, At, B0); PG8_BAR; PG8_SCHED;
;             PG8_LDB(B1, 1, 1); PG8_STAGE(PG8_SB(1, 0), b3, voffB);
;             PG8_BAR; PG8_WAIT_L(0); PG8_MMA(0, 1, At, B1); PG8_BAR;
;             PG8_LDA(At, 1, 1); PG8_STAGE(PG8_SA(1, 0), a3, voffA);
;             PG8_BAR; PG8_WAIT_L(0); PG8_MMA(1, 0, At, B0); PG8_BAR; PG8_SCHED;
;             PG8_STAGE(PG8_SB(1, 1), b3 + hstep, voffB);
;             PG8_WAIT_V(6); PG8_BAR; PG8_MMA(1, 1, At, B1); PG8_BAR;
.Lzp7_mid:
	ds_read_b128 v[140:143], v155
	ds_read_b128 v[170:173], v156
	ds_read_b128 v[174:177], v157
	ds_read_b128 v[178:181], v165
	s_add_u32 s34, s42, 0x44000
	s_addc_u32 s35, s43, 0
	s_mov_b32 m0, s56
	ds_read_b128 v[182:185], v145 offset:32768
	ds_read_b128 v[186:189], v145 offset:33792
	ds_read_b128 v[190:193], v145 offset:34816
	ds_read_b128 v[194:197], v145 offset:35840
	ds_read_b128 v[198:201], v145 offset:36864
	ds_read_b128 v[202:205], v145 offset:37888
	ds_read_b128 v[206:209], v145 offset:38912
	ds_read_b128 v[210:213], v145 offset:39936
	global_load_lds_dwordx4 v130, s[34:35]
	s_mov_b32 m0, s57
	s_nop 0
	global_load_lds_dwordx4 v128, s[34:35]
	s_waitcnt lgkmcnt(8)
	s_barrier
	s_waitcnt lgkmcnt(0)
	s_setprio 1
	s_waitcnt lgkmcnt(0)
	v_mfma_f32_16x16x32_bf16 v[124:127], v[140:143], v[182:185], v[124:127]
	v_mfma_f32_16x16x32_bf16 v[120:123], v[174:177], v[182:185], v[120:123]
	v_mfma_f32_16x16x32_bf16 v[108:111], v[140:143], v[190:193], v[108:111]
	v_mfma_f32_16x16x32_bf16 v[104:107], v[174:177], v[190:193], v[104:107]
	v_mfma_f32_16x16x32_bf16 v[92:95], v[140:143], v[198:201], v[92:95]
	v_mfma_f32_16x16x32_bf16 v[88:91], v[174:177], v[198:201], v[88:91]
	v_mfma_f32_16x16x32_bf16 v[76:79], v[140:143], v[206:209], v[76:79]
	v_mfma_f32_16x16x32_bf16 v[72:75], v[174:177], v[206:209], v[72:75]
	v_mfma_f32_16x16x32_bf16 v[124:127], v[170:173], v[186:189], v[124:127]
	v_mfma_f32_16x16x32_bf16 v[120:123], v[178:181], v[186:189], v[120:123]
	v_mfma_f32_16x16x32_bf16 v[108:111], v[170:173], v[194:197], v[108:111]
	v_mfma_f32_16x16x32_bf16 v[104:107], v[178:181], v[194:197], v[104:107]
	v_mfma_f32_16x16x32_bf16 v[92:95], v[170:173], v[202:205], v[92:95]
	v_mfma_f32_16x16x32_bf16 v[88:91], v[178:181], v[202:205], v[88:91]
	v_mfma_f32_16x16x32_bf16 v[76:79], v[170:173], v[210:213], v[76:79]
	v_mfma_f32_16x16x32_bf16 v[72:75], v[178:181], v[210:213], v[72:75]
	s_setprio 0
	s_barrier
	s_mov_b32 m0, s60
	ds_read_b128 v[214:217], v166
	ds_read_b128 v[218:221], v167
	ds_read_b128 v[222:225], v168
	ds_read_b128 v[226:229], v169
	s_add_u32 s100, s40, 0x80
	s_addc_u32 s101, s41, 0
	global_load_lds_dwordx4 v130, s[100:101]
	s_mov_b32 m0, s61
	s_nop 0
	global_load_lds_dwordx4 v128, s[100:101]
	s_barrier
	s_waitcnt lgkmcnt(0)
	s_setprio 1
	s_waitcnt lgkmcnt(0)
	v_mfma_f32_16x16x32_bf16 v[116:119], v[214:217], v[182:185], v[116:119]
	v_mfma_f32_16x16x32_bf16 v[112:115], v[222:225], v[182:185], v[112:115]
	v_mfma_f32_16x16x32_bf16 v[100:103], v[214:217], v[190:193], v[100:103]
	v_mfma_f32_16x16x32_bf16 v[96:99], v[222:225], v[190:193], v[96:99]
	v_mfma_f32_16x16x32_bf16 v[84:87], v[214:217], v[198:201], v[84:87]
	v_mfma_f32_16x16x32_bf16 v[80:83], v[222:225], v[198:201], v[80:83]
	v_mfma_f32_16x16x32_bf16 v[68:71], v[214:217], v[206:209], v[68:71]
	v_mfma_f32_16x16x32_bf16 v[64:67], v[222:225], v[206:209], v[64:67]
	v_mfma_f32_16x16x32_bf16 v[116:119], v[218:221], v[186:189], v[116:119]
	v_mfma_f32_16x16x32_bf16 v[112:115], v[226:229], v[186:189], v[112:115]
	v_mfma_f32_16x16x32_bf16 v[100:103], v[218:221], v[194:197], v[100:103]
	v_mfma_f32_16x16x32_bf16 v[96:99], v[226:229], v[194:197], v[96:99]
	v_mfma_f32_16x16x32_bf16 v[84:87], v[218:221], v[202:205], v[84:87]
	v_mfma_f32_16x16x32_bf16 v[80:83], v[226:229], v[202:205], v[80:83]
	v_mfma_f32_16x16x32_bf16 v[68:71], v[218:221], v[210:213], v[68:71]
	v_mfma_f32_16x16x32_bf16 v[64:67], v[226:229], v[210:213], v[64:67]
	s_setprio 0
	s_mov_b32 m0, s62
	s_barrier
	ds_read_b128 v[182:185], v145 offset:49152
	ds_read_b128 v[186:189], v145 offset:50176
	ds_read_b128 v[190:193], v145 offset:51200
	ds_read_b128 v[194:197], v145 offset:52224
	ds_read_b128 v[198:201], v145 offset:53248
	ds_read_b128 v[202:205], v145 offset:54272
	ds_read_b128 v[206:209], v145 offset:55296
	ds_read_b128 v[210:213], v145 offset:56320
	s_add_u32 s100, s42, 0x80
	s_addc_u32 s101, s43, 0
	global_load_lds_dwordx4 v130, s[100:101]
	s_mov_b32 m0, s63
	s_nop 0
	global_load_lds_dwordx4 v128, s[100:101]
	s_barrier
	s_waitcnt lgkmcnt(0)
	s_setprio 1
	s_waitcnt lgkmcnt(0)
	v_mfma_f32_16x16x32_bf16 v[60:63], v[140:143], v[182:185], v[60:63]
	v_mfma_f32_16x16x32_bf16 v[56:59], v[174:177], v[182:185], v[56:59]
	v_mfma_f32_16x16x32_bf16 v[44:47], v[140:143], v[190:193], v[44:47]
	v_mfma_f32_16x16x32_bf16 v[40:43], v[174:177], v[190:193], v[40:43]
	v_mfma_f32_16x16x32_bf16 v[28:31], v[140:143], v[198:201], v[28:31]
	v_mfma_f32_16x16x32_bf16 v[24:27], v[174:177], v[198:201], v[24:27]
	v_mfma_f32_16x16x32_bf16 v[12:15], v[140:143], v[206:209], v[12:15]
	v_mfma_f32_16x16x32_bf16 v[8:11], v[174:177], v[206:209], v[8:11]
	v_mfma_f32_16x16x32_bf16 v[60:63], v[170:173], v[186:189], v[60:63]
	v_mfma_f32_16x16x32_bf16 v[56:59], v[178:181], v[186:189], v[56:59]
	v_mfma_f32_16x16x32_bf16 v[44:47], v[170:173], v[194:197], v[44:47]
	v_mfma_f32_16x16x32_bf16 v[40:43], v[178:181], v[194:197], v[40:43]
	v_mfma_f32_16x16x32_bf16 v[28:31], v[170:173], v[202:205], v[28:31]
	v_mfma_f32_16x16x32_bf16 v[24:27], v[178:181], v[202:205], v[24:27]
	v_mfma_f32_16x16x32_bf16 v[12:15], v[170:173], v[210:213], v[12:15]
	v_mfma_f32_16x16x32_bf16 v[8:11], v[178:181], v[210:213], v[8:11]
	s_setprio 0
	s_barrier
	s_add_u32 s34, s40, 0x44080
	s_addc_u32 s35, s41, 0
	s_mov_b32 m0, s64
	s_nop 0
	global_load_lds_dwordx4 v130, s[34:35]
	s_mov_b32 m0, s65
	s_nop 0
	global_load_lds_dwordx4 v128, s[34:35]
	s_waitcnt vmcnt(6)
	s_barrier
; DI float ex2(float x) { return __builtin_amdgcn_exp2f(x); }
; #define PG8_STAMP() do { if (STAMP && wid == 0 && nts < 64) { const unsigned long long _c = 0ull; \
;         ts_lo = (lane == nts) ? (int)(unsigned)_c : ts_lo; ts_hi = (lane == nts) ? (int)(unsigned)(_c >> 32) : ts_hi; ++nts; } } while (0)
; #define PG8_MMA(ai, bj, At, Bt) do { __builtin_amdgcn_s_setprio(1); _Pragma("unroll") for (int m = 0; m < 4; ++m) _Pragma("unroll") for (int n = 0; n < 2; ++n) _Pragma("unroll") for (int k = 0; k < 2; ++k) \
;         acc[ai][bj][m][n] = __builtin_amdgcn_mfma_f32_16x16x32_bf16(Bt[n][k], At[m][k], acc[ai][bj][m][n], 0, 0, 0); __builtin_amdgcn_s_setprio(0); } while (0)
; #define PG8_WAIT_V(n) asm volatile("s_waitcnt vmcnt(" #n ")" ::: "memory")
; #define PG8_BAR __builtin_amdgcn_s_barrier()
;     DI void operator()(const f32x4 (&acc)[2][2][4][2], const Unit& u, int wr, int wc, int fr, int fq) const {
;         const int row0 = u.pm * BM + wr * 64 + fr, hcol0 = ((u.pn * BM + wc * 32) >> 1) + 4 * fq;
; #pragma unroll
;         for (int ai = 0; ai < 2; ++ai)
; #pragma unroll
;             for (int m = 0; m < 4; ++m) { u16* rowp = O + (size_t)(row0 + ai * HALF + m * 16) * ldc + hcol0;
; #pragma unroll
;                 for (int bj = 0; bj < 2; ++bj) { const f32x4 g = acc[ai][bj][m][0], up = acc[ai][bj][m][1]; float r[4];
; #pragma unroll
;                     for (int j = 0; j < 4; ++j) r[j] = g[j] * up[j] * __builtin_amdgcn_rcpf(1.f + ex2(-LOG2E * g[j]));
;                     uint2 w = {pack2(r[0], r[1]), pack2(r[2], r[3])}; *(uint2*)(rowp + bj * (HALF / 2)) = w; } }
; template <class Epi, class Sched, bool STAMP = false>
; __device__ __forceinline__ void gemm_phase(PG8_LAS unsigned char* lds, const Gemm g, const Sched& S, const Epi& E, unsigned long long* stamps) {
;     ...
;             PG8_WAIT_V(6); PG8_BAR; PG8_MMA(1, 1, At, B1); PG8_BAR;
;         }
;         PG8_STAMP();
;         if constexpr (!Epi::AFTER_DRAIN) { E(acc, cur, wr, wc, fr, fq); S.done(cur); }
	s_setprio 1
	v_mfma_f32_16x16x32_bf16 v[52:55], v[214:217], v[182:185], v[52:55]
	v_mfma_f32_16x16x32_bf16 v[48:51], v[222:225], v[182:185], v[48:51]
	v_mfma_f32_16x16x32_bf16 v[36:39], v[214:217], v[190:193], v[36:39]
	v_mfma_f32_16x16x32_bf16 v[32:35], v[222:225], v[190:193], v[32:35]
	v_mfma_f32_16x16x32_bf16 v[20:23], v[214:217], v[198:201], v[20:23]
	v_mfma_f32_16x16x32_bf16 v[16:19], v[222:225], v[198:201], v[16:19]
	v_mfma_f32_16x16x32_bf16 v[4:7], v[214:217], v[206:209], v[4:7]
	v_mfma_f32_16x16x32_bf16 v[0:3], v[222:225], v[206:209], v[0:3]
	v_mfma_f32_16x16x32_bf16 v[52:55], v[218:221], v[186:189], v[52:55]
	v_mfma_f32_16x16x32_bf16 v[48:51], v[226:229], v[186:189], v[48:51]
	v_mfma_f32_16x16x32_bf16 v[36:39], v[218:221], v[194:197], v[36:39]
	v_mfma_f32_16x16x32_bf16 v[32:35], v[226:229], v[194:197], v[32:35]
	v_mfma_f32_16x16x32_bf16 v[20:23], v[218:221], v[202:205], v[20:23]
	v_mfma_f32_16x16x32_bf16 v[16:19], v[226:229], v[202:205], v[16:19]
	v_mfma_f32_16x16x32_bf16 v[4:7], v[218:221], v[210:213], v[4:7]
	v_mfma_f32_16x16x32_bf16 v[0:3], v[226:229], v[210:213], v[0:3]
	s_setprio 0
	s_add_i32 s10, s10, 2
	s_add_u32 s77, s77, 0x100
	s_addc_u32 s78, s78, 0
	s_cmp_gt_u32 s10, 13
	s_mov_b64 s[34:35], s[36:37]
	s_barrier
	s_cbranch_scc0 .LBB0_439
	v_mul_f32_e32 v171, 0xbfb8aa3b, v124
	v_exp_f32_e32 v171, v171
	v_mul_f32_e32 v174, 0xbfb8aa3b, v125
	v_exp_f32_e32 v175, v174
	s_lshl_b32 s10, s76, 8
	v_add_f32_e32 v171, 1.0, v171
	v_rcp_f32_e32 v174, v171
	v_add_f32_e32 v171, 1.0, v175
	v_mul_f32_e32 v175, 0xbfb8aa3b, v126
	v_exp_f32_e32 v176, v175
	v_mul_f32_e32 v175, 0xbfb8aa3b, v127
	v_exp_f32_e32 v177, v175
	v_rcp_f32_e32 v175, v171
	v_add_f32_e32 v171, 1.0, v176
	v_rcp_f32_e32 v176, v171
	v_add_f32_e32 v171, 1.0, v177
	v_rcp_f32_e32 v177, v171
	v_pk_mul_f32 v[122:123], v[126:127], v[122:123]
	v_pk_mul_f32 v[120:121], v[124:125], v[120:121]
	s_or_b32 s10, s10, s59
	v_pk_mul_f32 v[120:121], v[120:121], v[174:175]
	v_pk_mul_f32 v[122:123], v[122:123], v[176:177]
	s_ashr_i32 s10, s10, 1
	v_cvt_pk_bf16_f32 v120, v120, v121
	v_cvt_pk_bf16_f32 v121, v122, v123
	v_mul_f32_e32 v122, 0xbfb8aa3b, v116
	v_mul_f32_e32 v123, 0xbfb8aa3b, v117
	v_or_b32_e32 v140, s10, v146
	v_exp_f32_e32 v122, v122
	v_exp_f32_e32 v123, v123
	v_lshl_add_u32 v170, s75, 8, v144
	v_ashrrev_i32_e32 v141, 31, v140
	v_mov_b64_e32 v[142:143], s[12:13]
	v_mad_i64_i32 v[172:173], s[34:35], v170, s69, v[142:143]
	v_lshlrev_b64 v[140:141], 1, v[140:141]
	v_lshl_add_u64 v[172:173], v[172:173], 0, v[140:141]
	global_store_dwordx2 v[172:173], v[120:121], off
	v_add_f32_e32 v120, 1.0, v122
	v_add_f32_e32 v121, 1.0, v123
	v_mul_f32_e32 v122, 0xbfb8aa3b, v118
	v_mul_f32_e32 v123, 0xbfb8aa3b, v119
	v_exp_f32_e32 v122, v122
	v_exp_f32_e32 v123, v123
	v_rcp_f32_e32 v120, v120
	v_rcp_f32_e32 v121, v121
	v_add_f32_e32 v122, 1.0, v122
	v_add_f32_e32 v123, 1.0, v123
	v_rcp_f32_e32 v122, v122
	v_rcp_f32_e32 v123, v123
	v_pk_mul_f32 v[114:115], v[118:119], v[114:115]
	v_pk_mul_f32 v[112:113], v[116:117], v[112:113]
	v_mul_f32_e32 v116, 0xbfb8aa3b, v110
	v_pk_mul_f32 v[112:113], v[112:113], v[120:121]
	v_pk_mul_f32 v[114:115], v[114:115], v[122:123]
	v_cvt_pk_bf16_f32 v112, v112, v113
	v_cvt_pk_bf16_f32 v113, v114, v115
	v_mul_f32_e32 v114, 0xbfb8aa3b, v108
	v_mul_f32_e32 v115, 0xbfb8aa3b, v109
	v_mul_f32_e32 v117, 0xbfb8aa3b, v111
	v_exp_f32_e32 v114, v114
	v_exp_f32_e32 v115, v115
	v_exp_f32_e32 v116, v116
	v_exp_f32_e32 v117, v117
	v_add_f32_e32 v114, 1.0, v114
	v_add_f32_e32 v115, 1.0, v115
	v_add_f32_e32 v116, 1.0, v116
	v_add_f32_e32 v117, 1.0, v117
	v_rcp_f32_e32 v114, v114
	v_rcp_f32_e32 v115, v115
	v_rcp_f32_e32 v116, v116
	v_rcp_f32_e32 v117, v117
	v_pk_mul_f32 v[106:107], v[110:111], v[106:107]
	v_pk_mul_f32 v[104:105], v[108:109], v[104:105]
	global_store_dwordx2 v[172:173], v[112:113], off offset:128
	v_pk_mul_f32 v[104:105], v[104:105], v[114:115]
	v_pk_mul_f32 v[106:107], v[106:107], v[116:117]
	v_cvt_pk_bf16_f32 v104, v104, v105
	v_cvt_pk_bf16_f32 v105, v106, v107
	v_mul_f32_e32 v106, 0xbfb8aa3b, v100
	v_mul_f32_e32 v107, 0xbfb8aa3b, v101
	v_exp_f32_e32 v106, v106
	v_exp_f32_e32 v107, v107
	v_or_b32_e32 v112, 16, v170
	v_mad_i64_i32 v[112:113], s[34:35], v112, s69, v[142:143]
	v_lshl_add_u64 v[112:113], v[112:113], 0, v[140:141]
	global_store_dwordx2 v[112:113], v[104:105], off
	v_add_f32_e32 v104, 1.0, v106
	v_add_f32_e32 v105, 1.0, v107
	v_mul_f32_e32 v106, 0xbfb8aa3b, v102
	v_mul_f32_e32 v107, 0xbfb8aa3b, v103
	v_exp_f32_e32 v106, v106
	v_exp_f32_e32 v107, v107
	v_rcp_f32_e32 v104, v104
	v_rcp_f32_e32 v105, v105
	v_add_f32_e32 v106, 1.0, v106
	v_add_f32_e32 v107, 1.0, v107
	v_rcp_f32_e32 v106, v106
	v_rcp_f32_e32 v107, v107
	v_pk_mul_f32 v[98:99], v[102:103], v[98:99]
	v_pk_mul_f32 v[96:97], v[100:101], v[96:97]
	v_mul_f32_e32 v100, 0xbfb8aa3b, v94
	v_pk_mul_f32 v[96:97], v[96:97], v[104:105]
	v_pk_mul_f32 v[98:99], v[98:99], v[106:107]
	v_cvt_pk_bf16_f32 v96, v96, v97
	v_cvt_pk_bf16_f32 v97, v98, v99
	v_mul_f32_e32 v98, 0xbfb8aa3b, v92
	v_mul_f32_e32 v99, 0xbfb8aa3b, v93
	v_mul_f32_e32 v101, 0xbfb8aa3b, v95
	v_exp_f32_e32 v98, v98
	v_exp_f32_e32 v99, v99
	v_exp_f32_e32 v100, v100
	v_exp_f32_e32 v101, v101
	v_add_f32_e32 v98, 1.0, v98
	v_add_f32_e32 v99, 1.0, v99
	v_add_f32_e32 v100, 1.0, v100
	v_add_f32_e32 v101, 1.0, v101
	v_rcp_f32_e32 v98, v98
	v_rcp_f32_e32 v99, v99
	v_rcp_f32_e32 v100, v100
	v_rcp_f32_e32 v101, v101
	v_pk_mul_f32 v[90:91], v[94:95], v[90:91]
	v_pk_mul_f32 v[88:89], v[92:93], v[88:89]
	global_store_dwordx2 v[112:113], v[96:97], off offset:128
	v_pk_mul_f32 v[88:89], v[88:89], v[98:99]
	v_pk_mul_f32 v[90:91], v[90:91], v[100:101]
; DI float ex2(float x) { return __builtin_amdgcn_exp2f(x); }
;     DI void operator()(const f32x4 (&acc)[2][2][4][2], const Unit& u, int wr, int wc, int fr, int fq) const {
;         const int row0 = u.pm * BM + wr * 64 + fr, hcol0 = ((u.pn * BM + wc * 32) >> 1) + 4 * fq;
; #pragma unroll
;         for (int ai = 0; ai < 2; ++ai)
; #pragma unroll
;             for (int m = 0; m < 4; ++m) { u16* rowp = O + (size_t)(row0 + ai * HALF + m * 16) * ldc + hcol0;
; #pragma unroll
;                 for (int bj = 0; bj < 2; ++bj) { const f32x4 g = acc[ai][bj][m][0], up = acc[ai][bj][m][1]; float r[4];
; #pragma unroll
;                     for (int j = 0; j < 4; ++j) r[j] = g[j] * up[j] * __builtin_amdgcn_rcpf(1.f + ex2(-LOG2E * g[j]));
;                     uint2 w = {pack2(r[0], r[1]), pack2(r[2], r[3])}; *(uint2*)(rowp + bj * (HALF / 2)) = w; } }
	v_cvt_pk_bf16_f32 v88, v88, v89
	v_cvt_pk_bf16_f32 v89, v90, v91
	v_mul_f32_e32 v90, 0xbfb8aa3b, v84
	v_mul_f32_e32 v91, 0xbfb8aa3b, v85
	v_exp_f32_e32 v90, v90
	v_exp_f32_e32 v91, v91
	v_or_b32_e32 v96, 32, v170
	v_mad_i64_i32 v[96:97], s[34:35], v96, s69, v[142:143]
	v_lshl_add_u64 v[96:97], v[96:97], 0, v[140:141]
	global_store_dwordx2 v[96:97], v[88:89], off
	v_add_f32_e32 v88, 1.0, v90
	v_add_f32_e32 v89, 1.0, v91
	v_mul_f32_e32 v90, 0xbfb8aa3b, v86
	v_mul_f32_e32 v91, 0xbfb8aa3b, v87
	v_exp_f32_e32 v90, v90
	v_exp_f32_e32 v91, v91
	v_rcp_f32_e32 v88, v88
	v_rcp_f32_e32 v89, v89
	v_add_f32_e32 v90, 1.0, v90
	v_add_f32_e32 v91, 1.0, v91
	v_rcp_f32_e32 v90, v90
	v_rcp_f32_e32 v91, v91
	v_pk_mul_f32 v[82:83], v[86:87], v[82:83]
	v_pk_mul_f32 v[80:81], v[84:85], v[80:81]
	v_mul_f32_e32 v84, 0xbfb8aa3b, v78
	v_pk_mul_f32 v[80:81], v[80:81], v[88:89]
	v_pk_mul_f32 v[82:83], v[82:83], v[90:91]
	v_cvt_pk_bf16_f32 v80, v80, v81
	v_cvt_pk_bf16_f32 v81, v82, v83
	v_mul_f32_e32 v82, 0xbfb8aa3b, v76
	v_mul_f32_e32 v83, 0xbfb8aa3b, v77
	v_mul_f32_e32 v85, 0xbfb8aa3b, v79
	v_exp_f32_e32 v82, v82
	v_exp_f32_e32 v83, v83
	v_exp_f32_e32 v84, v84
	v_exp_f32_e32 v85, v85
	v_add_f32_e32 v82, 1.0, v82
	v_add_f32_e32 v83, 1.0, v83
	v_add_f32_e32 v84, 1.0, v84
	v_add_f32_e32 v85, 1.0, v85
	v_rcp_f32_e32 v82, v82
	v_rcp_f32_e32 v83, v83
	v_rcp_f32_e32 v84, v84
	v_rcp_f32_e32 v85, v85
	v_pk_mul_f32 v[74:75], v[78:79], v[74:75]
	v_pk_mul_f32 v[72:73], v[76:77], v[72:73]
	global_store_dwordx2 v[96:97], v[80:81], off offset:128
	v_pk_mul_f32 v[72:73], v[72:73], v[82:83]
	v_pk_mul_f32 v[74:75], v[74:75], v[84:85]
	v_cvt_pk_bf16_f32 v72, v72, v73
	v_cvt_pk_bf16_f32 v73, v74, v75
	v_mul_f32_e32 v74, 0xbfb8aa3b, v68
	v_mul_f32_e32 v75, 0xbfb8aa3b, v69
	v_exp_f32_e32 v74, v74
	v_exp_f32_e32 v75, v75
	v_or_b32_e32 v80, 48, v170
	v_mad_i64_i32 v[80:81], s[34:35], v80, s69, v[142:143]
	v_lshl_add_u64 v[80:81], v[80:81], 0, v[140:141]
	global_store_dwordx2 v[80:81], v[72:73], off
	v_add_f32_e32 v72, 1.0, v74
	v_add_f32_e32 v73, 1.0, v75
	v_mul_f32_e32 v74, 0xbfb8aa3b, v70
	v_mul_f32_e32 v75, 0xbfb8aa3b, v71
	v_exp_f32_e32 v74, v74
	v_exp_f32_e32 v75, v75
	v_rcp_f32_e32 v72, v72
	v_rcp_f32_e32 v73, v73
	v_add_f32_e32 v74, 1.0, v74
	v_add_f32_e32 v75, 1.0, v75
	v_rcp_f32_e32 v74, v74
	v_rcp_f32_e32 v75, v75
	v_pk_mul_f32 v[66:67], v[70:71], v[66:67]
	v_pk_mul_f32 v[64:65], v[68:69], v[64:65]
	v_mul_f32_e32 v68, 0xbfb8aa3b, v62
	v_pk_mul_f32 v[64:65], v[64:65], v[72:73]
	v_pk_mul_f32 v[66:67], v[66:67], v[74:75]
	v_cvt_pk_bf16_f32 v64, v64, v65
	v_cvt_pk_bf16_f32 v65, v66, v67
	v_mul_f32_e32 v66, 0xbfb8aa3b, v60
	v_mul_f32_e32 v67, 0xbfb8aa3b, v61
	v_mul_f32_e32 v69, 0xbfb8aa3b, v63
	v_exp_f32_e32 v66, v66
	v_exp_f32_e32 v67, v67
	v_exp_f32_e32 v68, v68
	v_exp_f32_e32 v69, v69
	v_add_f32_e32 v66, 1.0, v66
	v_add_f32_e32 v67, 1.0, v67
	v_add_f32_e32 v68, 1.0, v68
	v_add_f32_e32 v69, 1.0, v69
	v_rcp_f32_e32 v66, v66
	v_rcp_f32_e32 v67, v67
	v_rcp_f32_e32 v68, v68
	v_rcp_f32_e32 v69, v69
	v_pk_mul_f32 v[58:59], v[62:63], v[58:59]
	v_pk_mul_f32 v[56:57], v[60:61], v[56:57]
	global_store_dwordx2 v[80:81], v[64:65], off offset:128
	v_pk_mul_f32 v[56:57], v[56:57], v[66:67]
	v_pk_mul_f32 v[58:59], v[58:59], v[68:69]
	v_cvt_pk_bf16_f32 v56, v56, v57
	v_cvt_pk_bf16_f32 v57, v58, v59
	v_mul_f32_e32 v58, 0xbfb8aa3b, v52
	v_mul_f32_e32 v59, 0xbfb8aa3b, v53
	v_exp_f32_e32 v58, v58
	v_exp_f32_e32 v59, v59
	v_add_u32_e32 v64, 0x80, v170
	v_mad_i64_i32 v[64:65], s[34:35], v64, s69, v[142:143]
	v_lshl_add_u64 v[64:65], v[64:65], 0, v[140:141]
	global_store_dwordx2 v[64:65], v[56:57], off
	v_add_f32_e32 v56, 1.0, v58
	v_add_f32_e32 v57, 1.0, v59
	v_mul_f32_e32 v58, 0xbfb8aa3b, v54
	v_mul_f32_e32 v59, 0xbfb8aa3b, v55
	v_exp_f32_e32 v58, v58
	v_exp_f32_e32 v59, v59
	v_rcp_f32_e32 v56, v56
	v_rcp_f32_e32 v57, v57
	v_add_f32_e32 v58, 1.0, v58
	v_add_f32_e32 v59, 1.0, v59
	v_rcp_f32_e32 v58, v58
	v_rcp_f32_e32 v59, v59
	v_pk_mul_f32 v[50:51], v[54:55], v[50:51]
	v_pk_mul_f32 v[48:49], v[52:53], v[48:49]
	v_mul_f32_e32 v52, 0xbfb8aa3b, v46
	v_pk_mul_f32 v[48:49], v[48:49], v[56:57]
	v_pk_mul_f32 v[50:51], v[50:51], v[58:59]
	v_cvt_pk_bf16_f32 v48, v48, v49
	v_cvt_pk_bf16_f32 v49, v50, v51
	v_mul_f32_e32 v50, 0xbfb8aa3b, v44
	v_mul_f32_e32 v51, 0xbfb8aa3b, v45
	v_mul_f32_e32 v53, 0xbfb8aa3b, v47
	v_exp_f32_e32 v50, v50
	v_exp_f32_e32 v51, v51
	v_exp_f32_e32 v52, v52
	v_exp_f32_e32 v53, v53
	v_add_f32_e32 v50, 1.0, v50
	v_add_f32_e32 v51, 1.0, v51
	v_add_f32_e32 v52, 1.0, v52
	v_add_f32_e32 v53, 1.0, v53
	v_rcp_f32_e32 v50, v50
	v_rcp_f32_e32 v51, v51
	v_rcp_f32_e32 v52, v52
; DI float ex2(float x) { return __builtin_amdgcn_exp2f(x); }
;     DI void operator()(const f32x4 (&acc)[2][2][4][2], const Unit& u, int wr, int wc, int fr, int fq) const {
;         const int row0 = u.pm * BM + wr * 64 + fr, hcol0 = ((u.pn * BM + wc * 32) >> 1) + 4 * fq;
; #pragma unroll
;         for (int ai = 0; ai < 2; ++ai)
; #pragma unroll
;             for (int m = 0; m < 4; ++m) { u16* rowp = O + (size_t)(row0 + ai * HALF + m * 16) * ldc + hcol0;
; #pragma unroll
;                 for (int bj = 0; bj < 2; ++bj) { const f32x4 g = acc[ai][bj][m][0], up = acc[ai][bj][m][1]; float r[4];
; #pragma unroll
;                     for (int j = 0; j < 4; ++j) r[j] = g[j] * up[j] * __builtin_amdgcn_rcpf(1.f + ex2(-LOG2E * g[j]));
;                     uint2 w = {pack2(r[0], r[1]), pack2(r[2], r[3])}; *(uint2*)(rowp + bj * (HALF / 2)) = w; } }
; template <class Epi, class Sched, bool STAMP = false>
; __device__ __forceinline__ void gemm_phase(PG8_LAS unsigned char* lds, const Gemm g, const Sched& S, const Epi& E, unsigned long long* stamps) {
;     ...
;         if (!has_next) break;
; #pragma unroll
;         for (int a = 0; a < 2; ++a)
; #pragma unroll
;             for (int b = 0; b < 2; ++b)
; #pragma unroll
;                 for (int m = 0; m < 4; ++m)
; #pragma unroll
;                     for (int n = 0; n < 2; ++n) acc[a][b][m][n] = (f32x4){0.f, 0.f, 0.f, 0.f};
;         cur = nxt; cA = nA; cB = nB; ++ui;
	v_rcp_f32_e32 v53, v53
	v_pk_mul_f32 v[42:43], v[46:47], v[42:43]
	v_pk_mul_f32 v[40:41], v[44:45], v[40:41]
	global_store_dwordx2 v[64:65], v[48:49], off offset:128
	v_pk_mul_f32 v[40:41], v[40:41], v[50:51]
	v_pk_mul_f32 v[42:43], v[42:43], v[52:53]
	v_cvt_pk_bf16_f32 v40, v40, v41
	v_cvt_pk_bf16_f32 v41, v42, v43
	v_mul_f32_e32 v42, 0xbfb8aa3b, v36
	v_mul_f32_e32 v43, 0xbfb8aa3b, v37
	v_exp_f32_e32 v42, v42
	v_exp_f32_e32 v43, v43
	v_add_u32_e32 v48, 0x90, v170
	v_mad_i64_i32 v[48:49], s[34:35], v48, s69, v[142:143]
	v_lshl_add_u64 v[48:49], v[48:49], 0, v[140:141]
	global_store_dwordx2 v[48:49], v[40:41], off
	v_add_f32_e32 v40, 1.0, v42
	v_add_f32_e32 v41, 1.0, v43
	v_mul_f32_e32 v42, 0xbfb8aa3b, v38
	v_mul_f32_e32 v43, 0xbfb8aa3b, v39
	v_exp_f32_e32 v42, v42
	v_exp_f32_e32 v43, v43
	v_rcp_f32_e32 v40, v40
	v_rcp_f32_e32 v41, v41
	v_add_f32_e32 v42, 1.0, v42
	v_add_f32_e32 v43, 1.0, v43
	v_rcp_f32_e32 v42, v42
	v_rcp_f32_e32 v43, v43
	v_pk_mul_f32 v[34:35], v[38:39], v[34:35]
	v_pk_mul_f32 v[32:33], v[36:37], v[32:33]
	v_mul_f32_e32 v36, 0xbfb8aa3b, v30
	v_pk_mul_f32 v[32:33], v[32:33], v[40:41]
	v_pk_mul_f32 v[34:35], v[34:35], v[42:43]
	v_cvt_pk_bf16_f32 v32, v32, v33
	v_cvt_pk_bf16_f32 v33, v34, v35
	v_mul_f32_e32 v34, 0xbfb8aa3b, v28
	v_mul_f32_e32 v35, 0xbfb8aa3b, v29
	v_mul_f32_e32 v37, 0xbfb8aa3b, v31
	v_exp_f32_e32 v34, v34
	v_exp_f32_e32 v35, v35
	v_exp_f32_e32 v36, v36
	v_exp_f32_e32 v37, v37
	v_add_f32_e32 v34, 1.0, v34
	v_add_f32_e32 v35, 1.0, v35
	v_add_f32_e32 v36, 1.0, v36
	v_add_f32_e32 v37, 1.0, v37
	v_rcp_f32_e32 v34, v34
	v_rcp_f32_e32 v35, v35
	v_rcp_f32_e32 v36, v36
	v_rcp_f32_e32 v37, v37
	v_pk_mul_f32 v[26:27], v[30:31], v[26:27]
	v_pk_mul_f32 v[24:25], v[28:29], v[24:25]
	global_store_dwordx2 v[48:49], v[32:33], off offset:128
	v_pk_mul_f32 v[24:25], v[24:25], v[34:35]
	v_pk_mul_f32 v[26:27], v[26:27], v[36:37]
	v_cvt_pk_bf16_f32 v24, v24, v25
	v_cvt_pk_bf16_f32 v25, v26, v27
	v_mul_f32_e32 v26, 0xbfb8aa3b, v20
	v_mul_f32_e32 v27, 0xbfb8aa3b, v21
	v_exp_f32_e32 v26, v26
	v_exp_f32_e32 v27, v27
	v_add_u32_e32 v32, 0xa0, v170
	v_mad_i64_i32 v[32:33], s[34:35], v32, s69, v[142:143]
	v_lshl_add_u64 v[32:33], v[32:33], 0, v[140:141]
	global_store_dwordx2 v[32:33], v[24:25], off
	v_add_f32_e32 v24, 1.0, v26
	v_add_f32_e32 v25, 1.0, v27
	v_mul_f32_e32 v26, 0xbfb8aa3b, v22
	v_mul_f32_e32 v27, 0xbfb8aa3b, v23
	v_exp_f32_e32 v26, v26
	v_exp_f32_e32 v27, v27
	v_rcp_f32_e32 v24, v24
	v_rcp_f32_e32 v25, v25
	v_add_f32_e32 v26, 1.0, v26
	v_add_f32_e32 v27, 1.0, v27
	v_rcp_f32_e32 v26, v26
	v_rcp_f32_e32 v27, v27
	v_pk_mul_f32 v[18:19], v[22:23], v[18:19]
	v_pk_mul_f32 v[16:17], v[20:21], v[16:17]
	v_mul_f32_e32 v20, 0xbfb8aa3b, v14
	v_pk_mul_f32 v[16:17], v[16:17], v[24:25]
	v_pk_mul_f32 v[18:19], v[18:19], v[26:27]
	v_cvt_pk_bf16_f32 v16, v16, v17
	v_cvt_pk_bf16_f32 v17, v18, v19
	v_mul_f32_e32 v18, 0xbfb8aa3b, v12
	v_mul_f32_e32 v19, 0xbfb8aa3b, v13
	v_mul_f32_e32 v21, 0xbfb8aa3b, v15
	v_exp_f32_e32 v18, v18
	v_exp_f32_e32 v19, v19
	v_exp_f32_e32 v20, v20
	v_exp_f32_e32 v21, v21
	v_add_f32_e32 v18, 1.0, v18
	v_add_f32_e32 v19, 1.0, v19
	v_add_f32_e32 v20, 1.0, v20
	v_add_f32_e32 v21, 1.0, v21
	v_rcp_f32_e32 v18, v18
	v_rcp_f32_e32 v19, v19
	v_rcp_f32_e32 v20, v20
	v_rcp_f32_e32 v21, v21
	v_pk_mul_f32 v[10:11], v[14:15], v[10:11]
	v_pk_mul_f32 v[8:9], v[12:13], v[8:9]
	global_store_dwordx2 v[32:33], v[16:17], off offset:128
	v_pk_mul_f32 v[8:9], v[8:9], v[18:19]
	v_pk_mul_f32 v[10:11], v[10:11], v[20:21]
	v_cvt_pk_bf16_f32 v8, v8, v9
	v_cvt_pk_bf16_f32 v9, v10, v11
	v_mul_f32_e32 v10, 0xbfb8aa3b, v4
	v_mul_f32_e32 v11, 0xbfb8aa3b, v5
	v_exp_f32_e32 v10, v10
	v_exp_f32_e32 v11, v11
	v_add_u32_e32 v16, 0xb0, v170
	v_mad_i64_i32 v[16:17], s[34:35], v16, s69, v[142:143]
	v_lshl_add_u64 v[16:17], v[16:17], 0, v[140:141]
	global_store_dwordx2 v[16:17], v[8:9], off
	v_add_f32_e32 v8, 1.0, v10
	v_add_f32_e32 v9, 1.0, v11
	v_mul_f32_e32 v10, 0xbfb8aa3b, v6
	v_mul_f32_e32 v11, 0xbfb8aa3b, v7
	v_exp_f32_e32 v10, v10
	v_exp_f32_e32 v11, v11
	v_rcp_f32_e32 v8, v8
	v_rcp_f32_e32 v9, v9
	v_add_f32_e32 v10, 1.0, v10
	v_add_f32_e32 v11, 1.0, v11
	v_rcp_f32_e32 v10, v10
	v_rcp_f32_e32 v11, v11
	v_pk_mul_f32 v[2:3], v[6:7], v[2:3]
	v_pk_mul_f32 v[0:1], v[4:5], v[0:1]
	s_and_b64 vcc, exec, s[2:3]
	v_pk_mul_f32 v[0:1], v[0:1], v[8:9]
	v_pk_mul_f32 v[2:3], v[2:3], v[10:11]
	v_cvt_pk_bf16_f32 v0, v0, v1
	v_cvt_pk_bf16_f32 v1, v2, v3
	s_mov_b32 s76, s70
	s_mov_b32 s75, s71
	s_mov_b64 s[36:37], s[0:1]
	s_mov_b64 s[34:35], s[4:5]
	global_store_dwordx2 v[16:17], v[0:1], off offset:128
	s_cbranch_vccz .LBB0_432
	s_branch .Lgu3_done

; #define PG8_STAGE(bufoff, gbase, voff) do { _Pragma("unroll") for (int _i = 0; _i < 2; ++_i) \
;         __builtin_amdgcn_global_load_lds((const unsigned*)((const char*)(gbase) + (voff)[_i]), (PG8_LAS unsigned*)(lds + (bufoff) + ldsw + _i * 8192), 16, 0, 0); } while (0)
; #define PG8_LDA(dst, b, h) do { _Pragma("unroll") for (int m = 0; m < 4; ++m) _Pragma("unroll") for (int k = 0; k < 2; ++k) dst[m][k] = *(const PG8_LAS bf16x8*)(lds + PG8_SA(b, h) + aoff + m * 2048 + k * 1024); } while (0)
; #define PG8_WAIT_V(n) asm volatile("s_waitcnt vmcnt(" #n ")" ::: "memory")
; #define PG8_WAIT_L(n) asm volatile("s_waitcnt lgkmcnt(" #n ")" ::: "memory")
; template <class Epi, class Sched, bool STAMP = false>
; __device__ __forceinline__ void gemm_phase(PG8_LAS unsigned char* lds, const Gemm g, const Sched& S, const Epi& E, unsigned long long* stamps) {
;     ...
;         const bool has_next = S.next(ui + 1, nxt);
;         const char* nA = has_next ? (const char*)g.A + (size_t)nxt.pm * tstep : cA; const char* nB = has_next ? (const char*)g.Bt + (size_t)nxt.pn * tstep : cB;
;         for (int t = 0; t < nt; t += 2) {
;             const bool last = (t == nt - 2);
;             const char* a1 = cA + (size_t)(t + 1) * kstep;
;             const char* a2 = last ? nA : cA + (size_t)(t + 2) * kstep; const char* b2 = last ? nB : cB + (size_t)(t + 2) * kstep;
;             const char* a3 = a2 + kstep; const char* b3 = b2 + kstep;
;             if (last && has_next) S.a_ready(nxt);
;             PG8_LDB(B0, 0, 0); PG8_SCHED; PG8_LDA(At, 0, 0); PG8_STAGE(PG8_SA(1, 1), a1 + hstep, voffA);
;             PG8_WAIT_L(8); PG8_BAR; PG8_WAIT_L(0); PG8_MMA(0, 0, At, B0); PG8_BAR; PG8_SCHED;
;             PG8_LDB(B1, 0, 1); PG8_STAGE(PG8_SB(0, 0), b2, voffB);
;             PG8_BAR; PG8_WAIT_L(0); PG8_MMA(0, 1, At, B1); PG8_BAR;
;             PG8_LDA(At, 0, 1); PG8_STAGE(PG8_SA(0, 0), a2, voffA);
;             PG8_BAR; PG8_WAIT_L(0); PG8_MMA(1, 0, At, B0); PG8_BAR; PG8_SCHED;
;             PG8_STAGE(PG8_SB(0, 1), b2 + hstep, voffB);
;             PG8_WAIT_V(6); PG8_BAR; PG8_MMA(1, 1, At, B1); PG8_BAR;
;     ...
; #pragma unroll
;         for (int a = 0; a < 2; ++a)
; #pragma unroll
;             for (int b = 0; b < 2; ++b)
; #pragma unroll
;                 for (int m = 0; m < 4; ++m)
; #pragma unroll
;                     for (int n = 0; n < 2; ++n) acc[a][b][m][n] = (f32x4){0.f, 0.f, 0.f, 0.f};
.LBB0_472:
	s_add_u32 s88, s46, 0x100
	s_addc_u32 s89, s47, 0
	s_mov_b32 s10, -2
	ds_read_b128 v[170:173], v147
	ds_read_b128 v[174:177], v148
	ds_read_b128 v[178:181], v149
	ds_read_b128 v[182:185], v150
	s_add_u32 s46, s44, 0x100
	s_addc_u32 s47, s45, 0
	s_cmp_eq_u32 s10, 40
	s_cselect_b32 s53, s5, s47
	s_cselect_b32 s52, s4, s46
	s_cselect_b32 s49, s1, s89
	s_cselect_b32 s48, s0, s88
	s_mov_b32 m0, s76
	ds_read_b128 v[186:189], v145
	ds_read_b128 v[190:193], v145 offset:1024
	ds_read_b128 v[194:197], v145 offset:2048
	ds_read_b128 v[198:201], v145 offset:3072
	ds_read_b128 v[202:205], v145 offset:4096
	ds_read_b128 v[206:209], v145 offset:5120
	ds_read_b128 v[210:213], v145 offset:6144
	ds_read_b128 v[214:217], v145 offset:7168
	global_load_lds_dwordx4 v136, s[44:45]
	s_mov_b32 m0, s77
	s_nop 0
	global_load_lds_dwordx4 v138, s[44:45]
	s_waitcnt lgkmcnt(8)
	s_barrier
	s_waitcnt lgkmcnt(0)
	s_setprio 1
	s_waitcnt lgkmcnt(0)
	v_mfma_f32_16x16x32_bf16 v[124:127], v[170:173], v[186:189], 0
	v_mfma_f32_16x16x32_bf16 v[120:123], v[178:181], v[186:189], 0
	v_mfma_f32_16x16x32_bf16 v[116:119], v[170:173], v[194:197], 0
	v_mfma_f32_16x16x32_bf16 v[112:115], v[178:181], v[194:197], 0
	v_mfma_f32_16x16x32_bf16 v[100:103], v[170:173], v[202:205], 0
	v_mfma_f32_16x16x32_bf16 v[96:99], v[178:181], v[202:205], 0
	v_mfma_f32_16x16x32_bf16 v[84:87], v[170:173], v[210:213], 0
	v_mfma_f32_16x16x32_bf16 v[80:83], v[178:181], v[210:213], 0
	v_mfma_f32_16x16x32_bf16 v[124:127], v[174:177], v[190:193], v[124:127]
	v_mfma_f32_16x16x32_bf16 v[120:123], v[182:185], v[190:193], v[120:123]
	v_mfma_f32_16x16x32_bf16 v[116:119], v[174:177], v[198:201], v[116:119]
	v_mfma_f32_16x16x32_bf16 v[112:115], v[182:185], v[198:201], v[112:115]
	v_mfma_f32_16x16x32_bf16 v[100:103], v[174:177], v[206:209], v[100:103]
	v_mfma_f32_16x16x32_bf16 v[96:99], v[182:185], v[206:209], v[96:99]
	v_mfma_f32_16x16x32_bf16 v[84:87], v[174:177], v[214:217], v[84:87]
	v_mfma_f32_16x16x32_bf16 v[80:83], v[182:185], v[214:217], v[80:83]
	s_setprio 0
	s_barrier
	s_mov_b32 m0, s58
	ds_read_b128 v[218:221], v151
	ds_read_b128 v[222:225], v152
	ds_read_b128 v[226:229], v153
	ds_read_b128 v[230:233], v154
	global_load_lds_dwordx4 v130, s[48:49]
	s_mov_b32 m0, s59
	s_nop 0
	global_load_lds_dwordx4 v134, s[48:49]
	s_barrier
	s_waitcnt lgkmcnt(0)
	s_setprio 1
	s_waitcnt lgkmcnt(0)
	v_mfma_f32_16x16x32_bf16 v[108:111], v[218:221], v[186:189], 0
	v_mfma_f32_16x16x32_bf16 v[104:107], v[226:229], v[186:189], 0
	v_mfma_f32_16x16x32_bf16 v[92:95], v[218:221], v[194:197], 0
	v_mfma_f32_16x16x32_bf16 v[88:91], v[226:229], v[194:197], 0
	v_mfma_f32_16x16x32_bf16 v[76:79], v[218:221], v[202:205], 0
	v_mfma_f32_16x16x32_bf16 v[72:75], v[226:229], v[202:205], 0
	v_mfma_f32_16x16x32_bf16 v[68:71], v[218:221], v[210:213], 0
	v_mfma_f32_16x16x32_bf16 v[64:67], v[226:229], v[210:213], 0
	v_mfma_f32_16x16x32_bf16 v[108:111], v[222:225], v[190:193], v[108:111]
	v_mfma_f32_16x16x32_bf16 v[104:107], v[230:233], v[190:193], v[104:107]
	v_mfma_f32_16x16x32_bf16 v[92:95], v[222:225], v[198:201], v[92:95]
	v_mfma_f32_16x16x32_bf16 v[88:91], v[230:233], v[198:201], v[88:91]
	v_mfma_f32_16x16x32_bf16 v[76:79], v[222:225], v[206:209], v[76:79]
	v_mfma_f32_16x16x32_bf16 v[72:75], v[230:233], v[206:209], v[72:75]
	v_mfma_f32_16x16x32_bf16 v[68:71], v[222:225], v[214:217], v[68:71]
	v_mfma_f32_16x16x32_bf16 v[64:67], v[230:233], v[214:217], v[64:67]
	s_setprio 0
	s_mov_b32 m0, s57
	s_barrier
	ds_read_b128 v[186:189], v145 offset:16384
	ds_read_b128 v[190:193], v145 offset:17408
	ds_read_b128 v[194:197], v145 offset:18432
	ds_read_b128 v[198:201], v145 offset:19456
	ds_read_b128 v[202:205], v145 offset:20480
	ds_read_b128 v[206:209], v145 offset:21504
	ds_read_b128 v[210:213], v145 offset:22528
	ds_read_b128 v[214:217], v145 offset:23552
	global_load_lds_dwordx4 v128, s[52:53]
	s_mov_b32 m0, s60
	s_nop 0
	global_load_lds_dwordx4 v132, s[52:53]
	s_barrier
	s_waitcnt lgkmcnt(0)
	s_setprio 1
	s_waitcnt lgkmcnt(0)
	v_mfma_f32_16x16x32_bf16 v[60:63], v[170:173], v[186:189], 0
	v_mfma_f32_16x16x32_bf16 v[56:59], v[178:181], v[186:189], 0
	v_mfma_f32_16x16x32_bf16 v[52:55], v[170:173], v[194:197], 0
	v_mfma_f32_16x16x32_bf16 v[48:51], v[178:181], v[194:197], 0
	v_mfma_f32_16x16x32_bf16 v[36:39], v[170:173], v[202:205], 0
	v_mfma_f32_16x16x32_bf16 v[32:35], v[178:181], v[202:205], 0
	v_mfma_f32_16x16x32_bf16 v[20:23], v[170:173], v[210:213], 0
	v_mfma_f32_16x16x32_bf16 v[16:19], v[178:181], v[210:213], 0
	v_mfma_f32_16x16x32_bf16 v[60:63], v[174:177], v[190:193], v[60:63]
	v_mfma_f32_16x16x32_bf16 v[56:59], v[182:185], v[190:193], v[56:59]
	v_mfma_f32_16x16x32_bf16 v[52:55], v[174:177], v[198:201], v[52:55]
	v_mfma_f32_16x16x32_bf16 v[48:51], v[182:185], v[198:201], v[48:51]
	v_mfma_f32_16x16x32_bf16 v[36:39], v[174:177], v[206:209], v[36:39]
	v_mfma_f32_16x16x32_bf16 v[32:35], v[182:185], v[206:209], v[32:35]
	v_mfma_f32_16x16x32_bf16 v[20:23], v[174:177], v[214:217], v[20:23]
	v_mfma_f32_16x16x32_bf16 v[16:19], v[182:185], v[214:217], v[16:19]
	s_setprio 0
	s_barrier
	s_add_u32 s44, s48, 0xb4000
	s_addc_u32 s45, s49, 0
	s_mov_b32 m0, s61
	s_nop 0
	global_load_lds_dwordx4 v130, s[44:45]
	s_mov_b32 m0, s62
	s_nop 0
	global_load_lds_dwordx4 v134, s[44:45]
	s_waitcnt vmcnt(6)
	s_barrier
	s_setprio 1
	v_mfma_f32_16x16x32_bf16 v[44:47], v[218:221], v[186:189], 0
	v_mfma_f32_16x16x32_bf16 v[40:43], v[226:229], v[186:189], 0
	v_mfma_f32_16x16x32_bf16 v[28:31], v[218:221], v[194:197], 0
	v_mfma_f32_16x16x32_bf16 v[24:27], v[226:229], v[194:197], 0
	v_mfma_f32_16x16x32_bf16 v[12:15], v[218:221], v[202:205], 0
	v_mfma_f32_16x16x32_bf16 v[8:11], v[226:229], v[202:205], 0
	v_mfma_f32_16x16x32_bf16 v[4:7], v[218:221], v[210:213], 0
	v_mfma_f32_16x16x32_bf16 v[0:3], v[226:229], v[210:213], 0
	v_mfma_f32_16x16x32_bf16 v[44:47], v[222:225], v[190:193], v[44:47]
	v_mfma_f32_16x16x32_bf16 v[40:43], v[230:233], v[190:193], v[40:43]
	v_mfma_f32_16x16x32_bf16 v[28:31], v[222:225], v[198:201], v[28:31]
	v_mfma_f32_16x16x32_bf16 v[24:27], v[230:233], v[198:201], v[24:27]
	v_mfma_f32_16x16x32_bf16 v[12:15], v[222:225], v[206:209], v[12:15]
	v_mfma_f32_16x16x32_bf16 v[8:11], v[230:233], v[206:209], v[8:11]
	v_mfma_f32_16x16x32_bf16 v[4:7], v[222:225], v[214:217], v[4:7]
	v_mfma_f32_16x16x32_bf16 v[0:3], v[230:233], v[214:217], v[0:3]
	s_setprio 0
	s_barrier
	s_branch .Lzp8_mid

; #define PG8_STAGE(bufoff, gbase, voff) do { _Pragma("unroll") for (int _i = 0; _i < 2; ++_i) \
;         __builtin_amdgcn_global_load_lds((const unsigned*)((const char*)(gbase) + (voff)[_i]), (PG8_LAS unsigned*)(lds + (bufoff) + ldsw + _i * 8192), 16, 0, 0); } while (0)
; #define PG8_LDA(dst, b, h) do { _Pragma("unroll") for (int m = 0; m < 4; ++m) _Pragma("unroll") for (int k = 0; k < 2; ++k) dst[m][k] = *(const PG8_LAS bf16x8*)(lds + PG8_SA(b, h) + aoff + m * 2048 + k * 1024); } while (0)
; #define PG8_LDB(dst, b, h) do { _Pragma("unroll") for (int n = 0; n < 2; ++n) _Pragma("unroll") for (int k = 0; k < 2; ++k) dst[n][k] = *(const PG8_LAS bf16x8*)(lds + PG8_SB(b, h) + boff + n * 2048 + k * 1024); } while (0)
; #define PG8_MMA(ai, bj, At, Bt) do { __builtin_amdgcn_s_setprio(1); _Pragma("unroll") for (int m = 0; m < 4; ++m) _Pragma("unroll") for (int n = 0; n < 2; ++n) _Pragma("unroll") for (int k = 0; k < 2; ++k) \
;         acc[ai][bj][m][n] = __builtin_amdgcn_mfma_f32_16x16x32_bf16(Bt[n][k], At[m][k], acc[ai][bj][m][n], 0, 0, 0); __builtin_amdgcn_s_setprio(0); } while (0)
; #define PG8_WAIT_V(n) asm volatile("s_waitcnt vmcnt(" #n ")" ::: "memory")
; #define PG8_WAIT_L(n) asm volatile("s_waitcnt lgkmcnt(" #n ")" ::: "memory")
; #define PG8_BAR __builtin_amdgcn_s_barrier()
; #define PG8_SCHED __builtin_amdgcn_sched_barrier(0)
; template <class Epi, class Sched, bool STAMP = false>
; __device__ __forceinline__ void gemm_phase(PG8_LAS unsigned char* lds, const Gemm g, const Sched& S, const Epi& E, unsigned long long* stamps) {
;     ...
;             PG8_LDB(B0, 1, 0); PG8_SCHED; PG8_LDA(At, 1, 0); PG8_STAGE(PG8_SA(0, 1), a2 + hstep, voffA);
;             PG8_WAIT_L(8); PG8_BAR; PG8_WAIT_L(0); PG8_MMA(0, 0, At, B0); PG8_BAR; PG8_SCHED;
;             PG8_LDB(B1, 1, 1); PG8_STAGE(PG8_SB(1, 0), b3, voffB);
;             PG8_BAR; PG8_WAIT_L(0); PG8_MMA(0, 1, At, B1); PG8_BAR;
;             PG8_LDA(At, 1, 1); PG8_STAGE(PG8_SA(1, 0), a3, voffA);
;             PG8_BAR; PG8_WAIT_L(0); PG8_MMA(1, 0, At, B0); PG8_BAR; PG8_SCHED;
;             PG8_STAGE(PG8_SB(1, 1), b3 + hstep, voffB);
;             PG8_WAIT_V(6); PG8_BAR; PG8_MMA(1, 1, At, B1); PG8_BAR;
.Lzp8_mid:
	ds_read_b128 v[170:173], v155
	ds_read_b128 v[174:177], v156
	ds_read_b128 v[178:181], v157
	ds_read_b128 v[182:185], v165
	s_add_u32 s44, s52, 0xb4000
	s_addc_u32 s45, s53, 0
	s_mov_b32 m0, s63
	ds_read_b128 v[186:189], v145 offset:32768
	ds_read_b128 v[190:193], v145 offset:33792
	ds_read_b128 v[194:197], v145 offset:34816
	ds_read_b128 v[198:201], v145 offset:35840
	ds_read_b128 v[202:205], v145 offset:36864
	ds_read_b128 v[206:209], v145 offset:37888
	ds_read_b128 v[210:213], v145 offset:38912
	ds_read_b128 v[214:217], v145 offset:39936
	global_load_lds_dwordx4 v128, s[44:45]
	s_mov_b32 m0, s64
	s_nop 0
	global_load_lds_dwordx4 v132, s[44:45]
	s_waitcnt lgkmcnt(8)
	s_barrier
	s_waitcnt lgkmcnt(0)
	s_setprio 1
	s_waitcnt lgkmcnt(0)
	v_mfma_f32_16x16x32_bf16 v[124:127], v[170:173], v[186:189], v[124:127]
	v_mfma_f32_16x16x32_bf16 v[120:123], v[178:181], v[186:189], v[120:123]
	v_mfma_f32_16x16x32_bf16 v[116:119], v[170:173], v[194:197], v[116:119]
	v_mfma_f32_16x16x32_bf16 v[112:115], v[178:181], v[194:197], v[112:115]
	v_mfma_f32_16x16x32_bf16 v[100:103], v[170:173], v[202:205], v[100:103]
	v_mfma_f32_16x16x32_bf16 v[96:99], v[178:181], v[202:205], v[96:99]
	v_mfma_f32_16x16x32_bf16 v[84:87], v[170:173], v[210:213], v[84:87]
	v_mfma_f32_16x16x32_bf16 v[80:83], v[178:181], v[210:213], v[80:83]
	v_mfma_f32_16x16x32_bf16 v[124:127], v[174:177], v[190:193], v[124:127]
	v_mfma_f32_16x16x32_bf16 v[120:123], v[182:185], v[190:193], v[120:123]
	v_mfma_f32_16x16x32_bf16 v[116:119], v[174:177], v[198:201], v[116:119]
	v_mfma_f32_16x16x32_bf16 v[112:115], v[182:185], v[198:201], v[112:115]
	v_mfma_f32_16x16x32_bf16 v[100:103], v[174:177], v[206:209], v[100:103]
	v_mfma_f32_16x16x32_bf16 v[96:99], v[182:185], v[206:209], v[96:99]
	v_mfma_f32_16x16x32_bf16 v[84:87], v[174:177], v[214:217], v[84:87]
	v_mfma_f32_16x16x32_bf16 v[80:83], v[182:185], v[214:217], v[80:83]
	s_setprio 0
	s_barrier
	s_mov_b32 m0, s65
	ds_read_b128 v[218:221], v166
	ds_read_b128 v[222:225], v167
	ds_read_b128 v[226:229], v168
	ds_read_b128 v[230:233], v169
	s_add_u32 s100, s48, 0x80
	s_addc_u32 s101, s49, 0
	global_load_lds_dwordx4 v130, s[100:101]
	s_mov_b32 m0, s66
	s_nop 0
	global_load_lds_dwordx4 v134, s[100:101]
	s_barrier
	s_waitcnt lgkmcnt(0)
	s_setprio 1
	s_waitcnt lgkmcnt(0)
	v_mfma_f32_16x16x32_bf16 v[108:111], v[218:221], v[186:189], v[108:111]
	v_mfma_f32_16x16x32_bf16 v[104:107], v[226:229], v[186:189], v[104:107]
	v_mfma_f32_16x16x32_bf16 v[92:95], v[218:221], v[194:197], v[92:95]
	v_mfma_f32_16x16x32_bf16 v[88:91], v[226:229], v[194:197], v[88:91]
	v_mfma_f32_16x16x32_bf16 v[76:79], v[218:221], v[202:205], v[76:79]
	v_mfma_f32_16x16x32_bf16 v[72:75], v[226:229], v[202:205], v[72:75]
	v_mfma_f32_16x16x32_bf16 v[68:71], v[218:221], v[210:213], v[68:71]
	v_mfma_f32_16x16x32_bf16 v[64:67], v[226:229], v[210:213], v[64:67]
	v_mfma_f32_16x16x32_bf16 v[108:111], v[222:225], v[190:193], v[108:111]
	v_mfma_f32_16x16x32_bf16 v[104:107], v[230:233], v[190:193], v[104:107]
	v_mfma_f32_16x16x32_bf16 v[92:95], v[222:225], v[198:201], v[92:95]
	v_mfma_f32_16x16x32_bf16 v[88:91], v[230:233], v[198:201], v[88:91]
	v_mfma_f32_16x16x32_bf16 v[76:79], v[222:225], v[206:209], v[76:79]
	v_mfma_f32_16x16x32_bf16 v[72:75], v[230:233], v[206:209], v[72:75]
	v_mfma_f32_16x16x32_bf16 v[68:71], v[222:225], v[214:217], v[68:71]
	v_mfma_f32_16x16x32_bf16 v[64:67], v[230:233], v[214:217], v[64:67]
	s_setprio 0
	s_mov_b32 m0, s67
	s_barrier
	ds_read_b128 v[186:189], v145 offset:49152
	ds_read_b128 v[190:193], v145 offset:50176
	ds_read_b128 v[194:197], v145 offset:51200
	ds_read_b128 v[198:201], v145 offset:52224
	ds_read_b128 v[202:205], v145 offset:53248
	ds_read_b128 v[206:209], v145 offset:54272
	ds_read_b128 v[210:213], v145 offset:55296
	ds_read_b128 v[214:217], v145 offset:56320
	s_add_u32 s100, s52, 0x80
	s_addc_u32 s101, s53, 0
	global_load_lds_dwordx4 v128, s[100:101]
	s_mov_b32 m0, s68
	s_nop 0
	global_load_lds_dwordx4 v132, s[100:101]
	s_barrier
	s_waitcnt lgkmcnt(0)
	s_setprio 1
	s_waitcnt lgkmcnt(0)
	v_mfma_f32_16x16x32_bf16 v[60:63], v[170:173], v[186:189], v[60:63]
	v_mfma_f32_16x16x32_bf16 v[56:59], v[178:181], v[186:189], v[56:59]
	v_mfma_f32_16x16x32_bf16 v[52:55], v[170:173], v[194:197], v[52:55]
	v_mfma_f32_16x16x32_bf16 v[48:51], v[178:181], v[194:197], v[48:51]
	v_mfma_f32_16x16x32_bf16 v[36:39], v[170:173], v[202:205], v[36:39]
	v_mfma_f32_16x16x32_bf16 v[32:35], v[178:181], v[202:205], v[32:35]
	v_mfma_f32_16x16x32_bf16 v[20:23], v[170:173], v[210:213], v[20:23]
	v_mfma_f32_16x16x32_bf16 v[16:19], v[178:181], v[210:213], v[16:19]
	v_mfma_f32_16x16x32_bf16 v[60:63], v[174:177], v[190:193], v[60:63]
	v_mfma_f32_16x16x32_bf16 v[56:59], v[182:185], v[190:193], v[56:59]
	v_mfma_f32_16x16x32_bf16 v[52:55], v[174:177], v[198:201], v[52:55]
	v_mfma_f32_16x16x32_bf16 v[48:51], v[182:185], v[198:201], v[48:51]
	v_mfma_f32_16x16x32_bf16 v[36:39], v[174:177], v[206:209], v[36:39]
	v_mfma_f32_16x16x32_bf16 v[32:35], v[182:185], v[206:209], v[32:35]
	v_mfma_f32_16x16x32_bf16 v[20:23], v[174:177], v[214:217], v[20:23]
	v_mfma_f32_16x16x32_bf16 v[16:19], v[182:185], v[214:217], v[16:19]
	s_setprio 0
	s_barrier
	s_add_u32 s44, s48, 0xb4080
	s_addc_u32 s45, s49, 0
	s_mov_b32 m0, s69
	s_nop 0
	global_load_lds_dwordx4 v130, s[44:45]
	s_mov_b32 m0, s70
	s_nop 0
	global_load_lds_dwordx4 v134, s[44:45]
	s_waitcnt vmcnt(6)
	s_barrier
; #define PG8_STAMP() do { if (STAMP && wid == 0 && nts < 64) { const unsigned long long _c = 0ull; \
;         ts_lo = (lane == nts) ? (int)(unsigned)_c : ts_lo; ts_hi = (lane == nts) ? (int)(unsigned)(_c >> 32) : ts_hi; ++nts; } } while (0)
; #define PG8_MMA(ai, bj, At, Bt) do { __builtin_amdgcn_s_setprio(1); _Pragma("unroll") for (int m = 0; m < 4; ++m) _Pragma("unroll") for (int n = 0; n < 2; ++n) _Pragma("unroll") for (int k = 0; k < 2; ++k) \
;         acc[ai][bj][m][n] = __builtin_amdgcn_mfma_f32_16x16x32_bf16(Bt[n][k], At[m][k], acc[ai][bj][m][n], 0, 0, 0); __builtin_amdgcn_s_setprio(0); } while (0)
; #define PG8_WAIT_V(n) asm volatile("s_waitcnt vmcnt(" #n ")" ::: "memory")
; #define PG8_BAR __builtin_amdgcn_s_barrier()
;     DI void operator()(const f32x4 (&acc)[2][2][4][2], const Unit& u, int wr, int wc, int fr, int fq) const {
;         const int row0 = u.pm * BM + wr * 64 + fr, col0 = u.pn * BM + wc * 32 + 8 * fq;
; #pragma unroll
;         for (int ai = 0; ai < 2; ++ai)
; #pragma unroll
;             for (int m = 0; m < 4; ++m) { u16* rowp = O + (size_t)(row0 + ai * HALF + m * 16) * ldc + col0;
; #pragma unroll
;                 for (int bj = 0; bj < 2; ++bj) { const f32x4 v0 = acc[ai][bj][m][0], v1 = acc[ai][bj][m][1];
;                     uint4 w = {pack2(v0[0], v0[1]), pack2(v0[2], v0[3]), pack2(v1[0], v1[1]), pack2(v1[2], v1[3])}; *(uint4*)(rowp + bj * HALF) = w; } }
; template <class Epi, class Sched, bool STAMP = false>
; __device__ __forceinline__ void gemm_phase(PG8_LAS unsigned char* lds, const Gemm g, const Sched& S, const Epi& E, unsigned long long* stamps) {
;     ...
;             PG8_WAIT_V(6); PG8_BAR; PG8_MMA(1, 1, At, B1); PG8_BAR;
;         }
;         PG8_STAMP();
;         if constexpr (!Epi::AFTER_DRAIN) { E(acc, cur, wr, wc, fr, fq); S.done(cur); }
;         PG8_STAMP();
;         if (!has_next) break;
	s_setprio 1
	v_mfma_f32_16x16x32_bf16 v[44:47], v[218:221], v[186:189], v[44:47]
	v_mfma_f32_16x16x32_bf16 v[40:43], v[226:229], v[186:189], v[40:43]
	v_mfma_f32_16x16x32_bf16 v[28:31], v[218:221], v[194:197], v[28:31]
	v_mfma_f32_16x16x32_bf16 v[24:27], v[226:229], v[194:197], v[24:27]
	v_mfma_f32_16x16x32_bf16 v[12:15], v[218:221], v[202:205], v[12:15]
	v_mfma_f32_16x16x32_bf16 v[8:11], v[226:229], v[202:205], v[8:11]
	v_mfma_f32_16x16x32_bf16 v[4:7], v[218:221], v[210:213], v[4:7]
	v_mfma_f32_16x16x32_bf16 v[0:3], v[226:229], v[210:213], v[0:3]
	v_mfma_f32_16x16x32_bf16 v[44:47], v[222:225], v[190:193], v[44:47]
	v_mfma_f32_16x16x32_bf16 v[40:43], v[230:233], v[190:193], v[40:43]
	v_mfma_f32_16x16x32_bf16 v[28:31], v[222:225], v[198:201], v[28:31]
	v_mfma_f32_16x16x32_bf16 v[24:27], v[230:233], v[198:201], v[24:27]
	v_mfma_f32_16x16x32_bf16 v[12:15], v[222:225], v[206:209], v[12:15]
	v_mfma_f32_16x16x32_bf16 v[8:11], v[230:233], v[206:209], v[8:11]
	v_mfma_f32_16x16x32_bf16 v[4:7], v[222:225], v[214:217], v[4:7]
	v_mfma_f32_16x16x32_bf16 v[0:3], v[230:233], v[214:217], v[0:3]
	s_setprio 0
	s_add_i32 s10, s10, 2
	s_add_u32 s88, s88, 0x100
	s_addc_u32 s89, s89, 0
	s_cmp_gt_u32 s10, 41
	s_mov_b64 s[44:45], s[46:47]
	s_barrier
	s_cbranch_scc0 .LBB0_473
	v_lshl_add_u32 v170, s84, 8, v144
	v_lshl_or_b32 v172, s87, 8, v146
	v_ashrrev_i32_e32 v171, 31, v170
	v_ashrrev_i32_e32 v173, 31, v172
	v_lshlrev_b64 v[174:175], 11, v[170:171]
	v_lshl_add_u64 v[174:175], s[14:15], 0, v[174:175]
	v_lshlrev_b64 v[172:173], 1, v[172:173]
	v_lshl_add_u64 v[174:175], v[174:175], 0, v[172:173]
	v_cvt_pk_bf16_f32 v60, v60, v61
	v_cvt_pk_bf16_f32 v61, v62, v63
	v_cvt_pk_bf16_f32 v62, v56, v57
	v_add_co_u32_e32 v56, vcc, s78, v174
	v_cvt_pk_bf16_f32 v68, v68, v69
	v_cvt_pk_bf16_f32 v69, v70, v71
	v_cvt_pk_bf16_f32 v70, v64, v65
	v_lshl_add_u64 v[64:65], v[174:175], 0, s[34:35]
	v_addc_co_u32_e32 v57, vcc, 0, v175, vcc
	v_cvt_pk_bf16_f32 v44, v44, v45
	v_cvt_pk_bf16_f32 v45, v46, v47
	v_cvt_pk_bf16_f32 v46, v40, v41
	v_cvt_pk_bf16_f32 v47, v42, v43
	v_cvt_pk_bf16_f32 v108, v108, v109
	v_cvt_pk_bf16_f32 v109, v110, v111
	v_cvt_pk_bf16_f32 v110, v104, v105
	v_or_b32_e32 v104, 16, v170
	global_store_dwordx4 v[64:65], v[44:47], off offset:256
	v_ashrrev_i32_e32 v105, 31, v104
	v_cvt_pk_bf16_f32 v92, v92, v93
	v_add_co_u32_e32 v46, vcc, s79, v174
	v_cvt_pk_bf16_f32 v93, v94, v95
	v_cvt_pk_bf16_f32 v94, v88, v89
	v_or_b32_e32 v88, 32, v170
	v_lshl_add_u64 v[44:45], v[174:175], 0, s[36:37]
	v_addc_co_u32_e32 v47, vcc, 0, v175, vcc
	v_cvt_pk_bf16_f32 v28, v28, v29
	v_cvt_pk_bf16_f32 v29, v30, v31
	v_cvt_pk_bf16_f32 v30, v24, v25
	v_cvt_pk_bf16_f32 v31, v26, v27
	v_lshlrev_b64 v[104:105], 11, v[104:105]
	v_ashrrev_i32_e32 v89, 31, v88
	v_cvt_pk_bf16_f32 v76, v76, v77
	v_cvt_pk_bf16_f32 v77, v78, v79
	v_cvt_pk_bf16_f32 v78, v72, v73
	v_or_b32_e32 v72, 48, v170
	global_store_dwordx4 v[44:45], v[28:31], off offset:256
	v_cvt_pk_bf16_f32 v111, v106, v107
	v_lshl_add_u64 v[104:105], s[14:15], 0, v[104:105]
	v_add_co_u32_e32 v30, vcc, s82, v174
	v_lshlrev_b64 v[88:89], 11, v[88:89]
	v_ashrrev_i32_e32 v73, 31, v72
	v_lshl_add_u64 v[28:29], v[174:175], 0, s[40:41]
	v_addc_co_u32_e32 v31, vcc, 0, v175, vcc
	v_cvt_pk_bf16_f32 v12, v12, v13
	v_cvt_pk_bf16_f32 v13, v14, v15
	v_cvt_pk_bf16_f32 v14, v8, v9
	v_cvt_pk_bf16_f32 v15, v10, v11
	global_store_dwordx4 v[174:175], v[108:111], off offset:256
	v_cvt_pk_bf16_f32 v95, v90, v91
	v_lshl_add_u64 v[88:89], s[14:15], 0, v[88:89]
	v_lshl_add_u64 v[108:109], v[104:105], 0, v[172:173]
	v_lshlrev_b64 v[72:73], 11, v[72:73]
	global_store_dwordx4 v[28:29], v[12:15], off offset:256
	global_store_dwordx4 v[108:109], v[92:95], off offset:256
	v_cvt_pk_bf16_f32 v79, v74, v75
	v_add_co_u32_e32 v14, vcc, s83, v174
	v_lshl_add_u64 v[92:93], v[88:89], 0, v[172:173]
	v_lshl_add_u64 v[72:73], s[14:15], 0, v[72:73]
	v_addc_co_u32_e32 v15, vcc, 0, v175, vcc
	v_cvt_pk_bf16_f32 v124, v124, v125
	v_cvt_pk_bf16_f32 v125, v126, v127
	v_cvt_pk_bf16_f32 v126, v120, v121
	v_cvt_pk_bf16_f32 v127, v122, v123
	v_cvt_pk_bf16_f32 v104, v116, v117
	v_cvt_pk_bf16_f32 v105, v118, v119
	v_cvt_pk_bf16_f32 v106, v112, v113
	v_cvt_pk_bf16_f32 v107, v114, v115
	v_cvt_pk_bf16_f32 v88, v100, v101
	v_cvt_pk_bf16_f32 v89, v102, v103
	v_cvt_pk_bf16_f32 v90, v96, v97
	v_cvt_pk_bf16_f32 v91, v98, v99
	global_store_dwordx4 v[92:93], v[76:79], off offset:256
	v_cvt_pk_bf16_f32 v74, v80, v81
	v_cvt_pk_bf16_f32 v75, v82, v83
	v_lshl_add_u64 v[76:77], v[72:73], 0, v[172:173]
	v_cvt_pk_bf16_f32 v72, v84, v85
	v_cvt_pk_bf16_f32 v73, v86, v87
	v_cvt_pk_bf16_f32 v71, v66, v67
	v_cvt_pk_bf16_f32 v63, v58, v59
	v_cvt_pk_bf16_f32 v40, v52, v53
	v_cvt_pk_bf16_f32 v41, v54, v55
	v_cvt_pk_bf16_f32 v42, v48, v49
	v_cvt_pk_bf16_f32 v43, v50, v51
	v_cvt_pk_bf16_f32 v24, v36, v37
	v_cvt_pk_bf16_f32 v25, v38, v39
	v_cvt_pk_bf16_f32 v26, v32, v33
	v_cvt_pk_bf16_f32 v27, v34, v35
	v_lshl_add_u64 v[12:13], v[174:175], 0, s[42:43]
	v_cvt_pk_bf16_f32 v8, v20, v21
	v_cvt_pk_bf16_f32 v9, v22, v23
	v_cvt_pk_bf16_f32 v10, v16, v17
	v_cvt_pk_bf16_f32 v11, v18, v19
	v_cvt_pk_bf16_f32 v4, v4, v5
	v_cvt_pk_bf16_f32 v5, v6, v7
	v_cvt_pk_bf16_f32 v6, v0, v1
	v_cvt_pk_bf16_f32 v7, v2, v3
	s_and_b64 vcc, exec, s[2:3]
	s_mov_b32 s87, s85
	s_mov_b32 s84, s86
	s_mov_b64 s[46:47], s[0:1]
	s_mov_b64 s[44:45], s[4:5]
	global_store_dwordx4 v[174:175], v[124:127], off
	global_store_dwordx4 v[108:109], v[104:107], off
	global_store_dwordx4 v[92:93], v[88:91], off
	global_store_dwordx4 v[76:77], v[72:75], off
	global_store_dwordx4 v[76:77], v[68:71], off offset:256
	global_store_dwordx4 v[56:57], v[60:63], off
	global_store_dwordx4 v[46:47], v[40:43], off
	global_store_dwordx4 v[30:31], v[24:27], off
	global_store_dwordx4 v[14:15], v[8:11], off
	global_store_dwordx4 v[12:13], v[4:7], off offset:256
	s_cbranch_vccz .LBB0_462
	s_waitcnt vmcnt(0)
	s_cmpk_gt_u32 s55, 0xff
	s_cbranch_scc1 .LBB0_477
	s_barrier

; #define PG8_STAGE(bufoff, gbase, voff) do { _Pragma("unroll") for (int _i = 0; _i < 2; ++_i) \
;         __builtin_amdgcn_global_load_lds((const unsigned*)((const char*)(gbase) + (voff)[_i]), (PG8_LAS unsigned*)(lds + (bufoff) + ldsw + _i * 8192), 16, 0, 0); } while (0)
; #define PG8_LDA(dst, b, h) do { _Pragma("unroll") for (int m = 0; m < 4; ++m) _Pragma("unroll") for (int k = 0; k < 2; ++k) dst[m][k] = *(const PG8_LAS bf16x8*)(lds + PG8_SA(b, h) + aoff + m * 2048 + k * 1024); } while (0)
; #define PG8_WAIT_V(n) asm volatile("s_waitcnt vmcnt(" #n ")" ::: "memory")
; #define PG8_WAIT_L(n) asm volatile("s_waitcnt lgkmcnt(" #n ")" ::: "memory")
; template <class Epi, class Sched, bool STAMP = false>
; __device__ __forceinline__ void gemm_phase(PG8_LAS unsigned char* lds, const Gemm g, const Sched& S, const Epi& E, unsigned long long* stamps) {
;     ...
;         const bool has_next = S.next(ui + 1, nxt);
;         const char* nA = has_next ? (const char*)g.A + (size_t)nxt.pm * tstep : cA; const char* nB = has_next ? (const char*)g.Bt + (size_t)nxt.pn * tstep : cB;
;         for (int t = 0; t < nt; t += 2) {
;             const bool last = (t == nt - 2);
;             const char* a1 = cA + (size_t)(t + 1) * kstep;
;             const char* a2 = last ? nA : cA + (size_t)(t + 2) * kstep; const char* b2 = last ? nB : cB + (size_t)(t + 2) * kstep;
;             const char* a3 = a2 + kstep; const char* b3 = b2 + kstep;
;             if (last && has_next) S.a_ready(nxt);
;             PG8_LDB(B0, 0, 0); PG8_SCHED; PG8_LDA(At, 0, 0); PG8_STAGE(PG8_SA(1, 1), a1 + hstep, voffA);
;             PG8_WAIT_L(8); PG8_BAR; PG8_WAIT_L(0); PG8_MMA(0, 0, At, B0); PG8_BAR; PG8_SCHED;
;             PG8_LDB(B1, 0, 1); PG8_STAGE(PG8_SB(0, 0), b2, voffB);
;             PG8_BAR; PG8_WAIT_L(0); PG8_MMA(0, 1, At, B1); PG8_BAR;
;             PG8_LDA(At, 0, 1); PG8_STAGE(PG8_SA(0, 0), a2, voffA);
;             PG8_BAR; PG8_WAIT_L(0); PG8_MMA(1, 0, At, B0); PG8_BAR; PG8_SCHED;
;             PG8_STAGE(PG8_SB(0, 1), b2 + hstep, voffB);
;             PG8_WAIT_V(6); PG8_BAR; PG8_MMA(1, 1, At, B1); PG8_BAR;
;     ...
; #pragma unroll
;         for (int a = 0; a < 2; ++a)
; #pragma unroll
;             for (int b = 0; b < 2; ++b)
; #pragma unroll
;                 for (int m = 0; m < 4; ++m)
; #pragma unroll
;                     for (int n = 0; n < 2; ++n) acc[a][b][m][n] = (f32x4){0.f, 0.f, 0.f, 0.f};
.LBB0_513:
	s_add_u32 s81, s42, 0x100
	s_addc_u32 s82, s43, 0
	s_mov_b32 s10, -2
	s_waitcnt lgkmcnt(0)
	ds_read_b128 v[170:173], v147
	ds_read_b128 v[174:177], v148
	ds_read_b128 v[178:181], v149
	ds_read_b128 v[182:185], v150
	s_add_u32 s42, s40, 0x100
	s_addc_u32 s43, s41, 0
	s_cmp_eq_u32 s10, 12
	s_cselect_b32 s47, s7, s43
	s_cselect_b32 s46, s6, s42
	s_cselect_b32 s45, s1, s82
	s_cselect_b32 s44, s0, s81
	s_mov_b32 m0, s71
	ds_read_b128 v[186:189], v145
	ds_read_b128 v[190:193], v145 offset:1024
	ds_read_b128 v[194:197], v145 offset:2048
	ds_read_b128 v[198:201], v145 offset:3072
	ds_read_b128 v[202:205], v145 offset:4096
	ds_read_b128 v[206:209], v145 offset:5120
	ds_read_b128 v[210:213], v145 offset:6144
	ds_read_b128 v[214:217], v145 offset:7168
	global_load_lds_dwordx4 v136, s[40:41]
	s_mov_b32 m0, s75
	s_nop 0
	global_load_lds_dwordx4 v138, s[40:41]
	s_waitcnt lgkmcnt(8)
	s_barrier
	s_waitcnt lgkmcnt(0)
	s_setprio 1
	s_waitcnt lgkmcnt(0)
	v_mfma_f32_16x16x32_bf16 v[124:127], v[170:173], v[186:189], 0
	v_mfma_f32_16x16x32_bf16 v[120:123], v[178:181], v[186:189], 0
	v_mfma_f32_16x16x32_bf16 v[116:119], v[170:173], v[194:197], 0
	v_mfma_f32_16x16x32_bf16 v[112:115], v[178:181], v[194:197], 0
	v_mfma_f32_16x16x32_bf16 v[108:111], v[170:173], v[202:205], 0
	v_mfma_f32_16x16x32_bf16 v[104:107], v[178:181], v[202:205], 0
	v_mfma_f32_16x16x32_bf16 v[100:103], v[170:173], v[210:213], 0
	v_mfma_f32_16x16x32_bf16 v[96:99], v[178:181], v[210:213], 0
	v_mfma_f32_16x16x32_bf16 v[124:127], v[174:177], v[190:193], v[124:127]
	v_mfma_f32_16x16x32_bf16 v[120:123], v[182:185], v[190:193], v[120:123]
	v_mfma_f32_16x16x32_bf16 v[116:119], v[174:177], v[198:201], v[116:119]
	v_mfma_f32_16x16x32_bf16 v[112:115], v[182:185], v[198:201], v[112:115]
	v_mfma_f32_16x16x32_bf16 v[108:111], v[174:177], v[206:209], v[108:111]
	v_mfma_f32_16x16x32_bf16 v[104:107], v[182:185], v[206:209], v[104:107]
	v_mfma_f32_16x16x32_bf16 v[100:103], v[174:177], v[214:217], v[100:103]
	v_mfma_f32_16x16x32_bf16 v[96:99], v[182:185], v[214:217], v[96:99]
	s_setprio 0
	s_barrier
	s_mov_b32 m0, s55
	ds_read_b128 v[218:221], v151
	ds_read_b128 v[222:225], v152
	ds_read_b128 v[226:229], v153
	ds_read_b128 v[230:233], v154
	global_load_lds_dwordx4 v132, s[44:45]
	s_mov_b32 m0, s56
	s_nop 0
	global_load_lds_dwordx4 v128, s[44:45]
	s_barrier
	s_waitcnt lgkmcnt(0)
	s_setprio 1
	s_waitcnt lgkmcnt(0)
	v_mfma_f32_16x16x32_bf16 v[60:63], v[218:221], v[186:189], 0
	v_mfma_f32_16x16x32_bf16 v[56:59], v[226:229], v[186:189], 0
	v_mfma_f32_16x16x32_bf16 v[52:55], v[218:221], v[194:197], 0
	v_mfma_f32_16x16x32_bf16 v[48:51], v[226:229], v[194:197], 0
	v_mfma_f32_16x16x32_bf16 v[44:47], v[218:221], v[202:205], 0
	v_mfma_f32_16x16x32_bf16 v[40:43], v[226:229], v[202:205], 0
	v_mfma_f32_16x16x32_bf16 v[36:39], v[218:221], v[210:213], 0
	v_mfma_f32_16x16x32_bf16 v[32:35], v[226:229], v[210:213], 0
	v_mfma_f32_16x16x32_bf16 v[60:63], v[222:225], v[190:193], v[60:63]
	v_mfma_f32_16x16x32_bf16 v[56:59], v[230:233], v[190:193], v[56:59]
	v_mfma_f32_16x16x32_bf16 v[52:55], v[222:225], v[198:201], v[52:55]
	v_mfma_f32_16x16x32_bf16 v[48:51], v[230:233], v[198:201], v[48:51]
	v_mfma_f32_16x16x32_bf16 v[44:47], v[222:225], v[206:209], v[44:47]
	v_mfma_f32_16x16x32_bf16 v[40:43], v[230:233], v[206:209], v[40:43]
	v_mfma_f32_16x16x32_bf16 v[36:39], v[222:225], v[214:217], v[36:39]
	v_mfma_f32_16x16x32_bf16 v[32:35], v[230:233], v[214:217], v[32:35]
	s_setprio 0
	s_mov_b32 m0, s52
	s_barrier
	ds_read_b128 v[186:189], v145 offset:16384
	ds_read_b128 v[190:193], v145 offset:17408
	ds_read_b128 v[194:197], v145 offset:18432
	ds_read_b128 v[198:201], v145 offset:19456
	ds_read_b128 v[202:205], v145 offset:20480
	ds_read_b128 v[206:209], v145 offset:21504
	ds_read_b128 v[210:213], v145 offset:22528
	ds_read_b128 v[214:217], v145 offset:23552
	global_load_lds_dwordx4 v134, s[46:47]
	s_mov_b32 m0, s57
	s_nop 0
	global_load_lds_dwordx4 v130, s[46:47]
	s_barrier
	s_waitcnt lgkmcnt(0)
	s_setprio 1
	s_waitcnt lgkmcnt(0)
	v_mfma_f32_16x16x32_bf16 v[92:95], v[170:173], v[186:189], 0
	v_mfma_f32_16x16x32_bf16 v[88:91], v[178:181], v[186:189], 0
	v_mfma_f32_16x16x32_bf16 v[84:87], v[170:173], v[194:197], 0
	v_mfma_f32_16x16x32_bf16 v[80:83], v[178:181], v[194:197], 0
	v_mfma_f32_16x16x32_bf16 v[76:79], v[170:173], v[202:205], 0
	v_mfma_f32_16x16x32_bf16 v[72:75], v[178:181], v[202:205], 0
	v_mfma_f32_16x16x32_bf16 v[68:71], v[170:173], v[210:213], 0
	v_mfma_f32_16x16x32_bf16 v[64:67], v[178:181], v[210:213], 0
	v_mfma_f32_16x16x32_bf16 v[92:95], v[174:177], v[190:193], v[92:95]
	v_mfma_f32_16x16x32_bf16 v[88:91], v[182:185], v[190:193], v[88:91]
	v_mfma_f32_16x16x32_bf16 v[84:87], v[174:177], v[198:201], v[84:87]
	v_mfma_f32_16x16x32_bf16 v[80:83], v[182:185], v[198:201], v[80:83]
	v_mfma_f32_16x16x32_bf16 v[76:79], v[174:177], v[206:209], v[76:79]
	v_mfma_f32_16x16x32_bf16 v[72:75], v[182:185], v[206:209], v[72:75]
	v_mfma_f32_16x16x32_bf16 v[68:71], v[174:177], v[214:217], v[68:71]
	v_mfma_f32_16x16x32_bf16 v[64:67], v[182:185], v[214:217], v[64:67]
	s_setprio 0
	s_barrier
	s_add_u32 s40, s44, 0x44000
	s_addc_u32 s41, s45, 0
	s_mov_b32 m0, s58
	s_nop 0
	global_load_lds_dwordx4 v132, s[40:41]
	s_mov_b32 m0, s59
	s_nop 0
	global_load_lds_dwordx4 v128, s[40:41]
	s_waitcnt vmcnt(6)
	s_barrier
	s_setprio 1
	v_mfma_f32_16x16x32_bf16 v[28:31], v[218:221], v[186:189], 0
	v_mfma_f32_16x16x32_bf16 v[24:27], v[226:229], v[186:189], 0
	v_mfma_f32_16x16x32_bf16 v[20:23], v[218:221], v[194:197], 0
	v_mfma_f32_16x16x32_bf16 v[16:19], v[226:229], v[194:197], 0
	v_mfma_f32_16x16x32_bf16 v[12:15], v[218:221], v[202:205], 0
	v_mfma_f32_16x16x32_bf16 v[8:11], v[226:229], v[202:205], 0
	v_mfma_f32_16x16x32_bf16 v[4:7], v[218:221], v[210:213], 0
	v_mfma_f32_16x16x32_bf16 v[0:3], v[226:229], v[210:213], 0
	v_mfma_f32_16x16x32_bf16 v[28:31], v[222:225], v[190:193], v[28:31]
	v_mfma_f32_16x16x32_bf16 v[24:27], v[230:233], v[190:193], v[24:27]
	v_mfma_f32_16x16x32_bf16 v[20:23], v[222:225], v[198:201], v[20:23]
	v_mfma_f32_16x16x32_bf16 v[16:19], v[230:233], v[198:201], v[16:19]
	v_mfma_f32_16x16x32_bf16 v[12:15], v[222:225], v[206:209], v[12:15]
	v_mfma_f32_16x16x32_bf16 v[8:11], v[230:233], v[206:209], v[8:11]
	v_mfma_f32_16x16x32_bf16 v[4:7], v[222:225], v[214:217], v[4:7]
	v_mfma_f32_16x16x32_bf16 v[0:3], v[230:233], v[214:217], v[0:3]
	s_setprio 0
	s_barrier
	s_branch .Lzp9_mid

; #define PG8_STAGE(bufoff, gbase, voff) do { _Pragma("unroll") for (int _i = 0; _i < 2; ++_i) \
;         __builtin_amdgcn_global_load_lds((const unsigned*)((const char*)(gbase) + (voff)[_i]), (PG8_LAS unsigned*)(lds + (bufoff) + ldsw + _i * 8192), 16, 0, 0); } while (0)
; #define PG8_LDA(dst, b, h) do { _Pragma("unroll") for (int m = 0; m < 4; ++m) _Pragma("unroll") for (int k = 0; k < 2; ++k) dst[m][k] = *(const PG8_LAS bf16x8*)(lds + PG8_SA(b, h) + aoff + m * 2048 + k * 1024); } while (0)
; #define PG8_LDB(dst, b, h) do { _Pragma("unroll") for (int n = 0; n < 2; ++n) _Pragma("unroll") for (int k = 0; k < 2; ++k) dst[n][k] = *(const PG8_LAS bf16x8*)(lds + PG8_SB(b, h) + boff + n * 2048 + k * 1024); } while (0)
; #define PG8_MMA(ai, bj, At, Bt) do { __builtin_amdgcn_s_setprio(1); _Pragma("unroll") for (int m = 0; m < 4; ++m) _Pragma("unroll") for (int n = 0; n < 2; ++n) _Pragma("unroll") for (int k = 0; k < 2; ++k) \
;         acc[ai][bj][m][n] = __builtin_amdgcn_mfma_f32_16x16x32_bf16(Bt[n][k], At[m][k], acc[ai][bj][m][n], 0, 0, 0); __builtin_amdgcn_s_setprio(0); } while (0)
; #define PG8_WAIT_V(n) asm volatile("s_waitcnt vmcnt(" #n ")" ::: "memory")
; #define PG8_WAIT_L(n) asm volatile("s_waitcnt lgkmcnt(" #n ")" ::: "memory")
; #define PG8_BAR __builtin_amdgcn_s_barrier()
; #define PG8_SCHED __builtin_amdgcn_sched_barrier(0)
; template <class Epi, class Sched, bool STAMP = false>
; __device__ __forceinline__ void gemm_phase(PG8_LAS unsigned char* lds, const Gemm g, const Sched& S, const Epi& E, unsigned long long* stamps) {
;     ...
;             PG8_LDB(B0, 1, 0); PG8_SCHED; PG8_LDA(At, 1, 0); PG8_STAGE(PG8_SA(0, 1), a2 + hstep, voffA);
;             PG8_WAIT_L(8); PG8_BAR; PG8_WAIT_L(0); PG8_MMA(0, 0, At, B0); PG8_BAR; PG8_SCHED;
;             PG8_LDB(B1, 1, 1); PG8_STAGE(PG8_SB(1, 0), b3, voffB);
;             PG8_BAR; PG8_WAIT_L(0); PG8_MMA(0, 1, At, B1); PG8_BAR;
;             PG8_LDA(At, 1, 1); PG8_STAGE(PG8_SA(1, 0), a3, voffA);
;             PG8_BAR; PG8_WAIT_L(0); PG8_MMA(1, 0, At, B0); PG8_BAR; PG8_SCHED;
;             PG8_STAGE(PG8_SB(1, 1), b3 + hstep, voffB);
;             PG8_WAIT_V(6); PG8_BAR; PG8_MMA(1, 1, At, B1); PG8_BAR;
.Lzp9_mid:
	ds_read_b128 v[170:173], v155
	ds_read_b128 v[174:177], v156
	ds_read_b128 v[178:181], v157
	ds_read_b128 v[182:185], v165
	s_add_u32 s40, s46, 0x44000
	s_addc_u32 s41, s47, 0
	s_mov_b32 m0, s60
	ds_read_b128 v[186:189], v145 offset:32768
	ds_read_b128 v[190:193], v145 offset:33792
	ds_read_b128 v[194:197], v145 offset:34816
	ds_read_b128 v[198:201], v145 offset:35840
	ds_read_b128 v[202:205], v145 offset:36864
	ds_read_b128 v[206:209], v145 offset:37888
	ds_read_b128 v[210:213], v145 offset:38912
	ds_read_b128 v[214:217], v145 offset:39936
	global_load_lds_dwordx4 v134, s[40:41]
	s_mov_b32 m0, s61
	s_nop 0
	global_load_lds_dwordx4 v130, s[40:41]
	s_waitcnt lgkmcnt(8)
	s_barrier
	s_waitcnt lgkmcnt(0)
	s_setprio 1
	s_waitcnt lgkmcnt(0)
	v_mfma_f32_16x16x32_bf16 v[124:127], v[170:173], v[186:189], v[124:127]
	v_mfma_f32_16x16x32_bf16 v[120:123], v[178:181], v[186:189], v[120:123]
	v_mfma_f32_16x16x32_bf16 v[116:119], v[170:173], v[194:197], v[116:119]
	v_mfma_f32_16x16x32_bf16 v[112:115], v[178:181], v[194:197], v[112:115]
	v_mfma_f32_16x16x32_bf16 v[108:111], v[170:173], v[202:205], v[108:111]
	v_mfma_f32_16x16x32_bf16 v[104:107], v[178:181], v[202:205], v[104:107]
	v_mfma_f32_16x16x32_bf16 v[100:103], v[170:173], v[210:213], v[100:103]
	v_mfma_f32_16x16x32_bf16 v[96:99], v[178:181], v[210:213], v[96:99]
	v_mfma_f32_16x16x32_bf16 v[124:127], v[174:177], v[190:193], v[124:127]
	v_mfma_f32_16x16x32_bf16 v[120:123], v[182:185], v[190:193], v[120:123]
	v_mfma_f32_16x16x32_bf16 v[116:119], v[174:177], v[198:201], v[116:119]
	v_mfma_f32_16x16x32_bf16 v[112:115], v[182:185], v[198:201], v[112:115]
	v_mfma_f32_16x16x32_bf16 v[108:111], v[174:177], v[206:209], v[108:111]
	v_mfma_f32_16x16x32_bf16 v[104:107], v[182:185], v[206:209], v[104:107]
	v_mfma_f32_16x16x32_bf16 v[100:103], v[174:177], v[214:217], v[100:103]
	v_mfma_f32_16x16x32_bf16 v[96:99], v[182:185], v[214:217], v[96:99]
	s_setprio 0
	s_barrier
	s_mov_b32 m0, s64
	ds_read_b128 v[218:221], v166
	ds_read_b128 v[222:225], v167
	ds_read_b128 v[226:229], v168
	ds_read_b128 v[230:233], v169
	s_add_u32 s100, s44, 0x80
	s_addc_u32 s101, s45, 0
	global_load_lds_dwordx4 v132, s[100:101]
	s_mov_b32 m0, s65
	s_nop 0
	global_load_lds_dwordx4 v128, s[100:101]
	s_barrier
	s_waitcnt lgkmcnt(0)
	s_setprio 1
	s_waitcnt lgkmcnt(0)
	v_mfma_f32_16x16x32_bf16 v[60:63], v[218:221], v[186:189], v[60:63]
	v_mfma_f32_16x16x32_bf16 v[56:59], v[226:229], v[186:189], v[56:59]
	v_mfma_f32_16x16x32_bf16 v[52:55], v[218:221], v[194:197], v[52:55]
	v_mfma_f32_16x16x32_bf16 v[48:51], v[226:229], v[194:197], v[48:51]
	v_mfma_f32_16x16x32_bf16 v[44:47], v[218:221], v[202:205], v[44:47]
	v_mfma_f32_16x16x32_bf16 v[40:43], v[226:229], v[202:205], v[40:43]
	v_mfma_f32_16x16x32_bf16 v[36:39], v[218:221], v[210:213], v[36:39]
	v_mfma_f32_16x16x32_bf16 v[32:35], v[226:229], v[210:213], v[32:35]
	v_mfma_f32_16x16x32_bf16 v[60:63], v[222:225], v[190:193], v[60:63]
	v_mfma_f32_16x16x32_bf16 v[56:59], v[230:233], v[190:193], v[56:59]
	v_mfma_f32_16x16x32_bf16 v[52:55], v[222:225], v[198:201], v[52:55]
	v_mfma_f32_16x16x32_bf16 v[48:51], v[230:233], v[198:201], v[48:51]
	v_mfma_f32_16x16x32_bf16 v[44:47], v[222:225], v[206:209], v[44:47]
	v_mfma_f32_16x16x32_bf16 v[40:43], v[230:233], v[206:209], v[40:43]
	v_mfma_f32_16x16x32_bf16 v[36:39], v[222:225], v[214:217], v[36:39]
	v_mfma_f32_16x16x32_bf16 v[32:35], v[230:233], v[214:217], v[32:35]
	s_setprio 0
	s_mov_b32 m0, s66
	s_barrier
	ds_read_b128 v[186:189], v145 offset:49152
	ds_read_b128 v[190:193], v145 offset:50176
	ds_read_b128 v[194:197], v145 offset:51200
	ds_read_b128 v[198:201], v145 offset:52224
	ds_read_b128 v[202:205], v145 offset:53248
	ds_read_b128 v[206:209], v145 offset:54272
	ds_read_b128 v[210:213], v145 offset:55296
	ds_read_b128 v[214:217], v145 offset:56320
	s_add_u32 s100, s46, 0x80
	s_addc_u32 s101, s47, 0
	global_load_lds_dwordx4 v134, s[100:101]
	s_mov_b32 m0, s67
	s_nop 0
	global_load_lds_dwordx4 v130, s[100:101]
	s_barrier
	s_waitcnt lgkmcnt(0)
	s_setprio 1
	s_waitcnt lgkmcnt(0)
	v_mfma_f32_16x16x32_bf16 v[92:95], v[170:173], v[186:189], v[92:95]
	v_mfma_f32_16x16x32_bf16 v[88:91], v[178:181], v[186:189], v[88:91]
	v_mfma_f32_16x16x32_bf16 v[84:87], v[170:173], v[194:197], v[84:87]
	v_mfma_f32_16x16x32_bf16 v[80:83], v[178:181], v[194:197], v[80:83]
	v_mfma_f32_16x16x32_bf16 v[76:79], v[170:173], v[202:205], v[76:79]
	v_mfma_f32_16x16x32_bf16 v[72:75], v[178:181], v[202:205], v[72:75]
	v_mfma_f32_16x16x32_bf16 v[68:71], v[170:173], v[210:213], v[68:71]
	v_mfma_f32_16x16x32_bf16 v[64:67], v[178:181], v[210:213], v[64:67]
	v_mfma_f32_16x16x32_bf16 v[92:95], v[174:177], v[190:193], v[92:95]
	v_mfma_f32_16x16x32_bf16 v[88:91], v[182:185], v[190:193], v[88:91]
	v_mfma_f32_16x16x32_bf16 v[84:87], v[174:177], v[198:201], v[84:87]
	v_mfma_f32_16x16x32_bf16 v[80:83], v[182:185], v[198:201], v[80:83]
	v_mfma_f32_16x16x32_bf16 v[76:79], v[174:177], v[206:209], v[76:79]
	v_mfma_f32_16x16x32_bf16 v[72:75], v[182:185], v[206:209], v[72:75]
	v_mfma_f32_16x16x32_bf16 v[68:71], v[174:177], v[214:217], v[68:71]
	v_mfma_f32_16x16x32_bf16 v[64:67], v[182:185], v[214:217], v[64:67]
	s_setprio 0
	s_barrier
	s_add_u32 s40, s44, 0x44080
	s_addc_u32 s41, s45, 0
	s_mov_b32 m0, s68
	s_nop 0
	global_load_lds_dwordx4 v132, s[40:41]
	s_mov_b32 m0, s69
	s_nop 0
	global_load_lds_dwordx4 v128, s[40:41]
	s_waitcnt vmcnt(6)
	s_barrier
; #define PG8_STAMP() do { if (STAMP && wid == 0 && nts < 64) { const unsigned long long _c = 0ull; \
;         ts_lo = (lane == nts) ? (int)(unsigned)_c : ts_lo; ts_hi = (lane == nts) ? (int)(unsigned)(_c >> 32) : ts_hi; ++nts; } } while (0)
; #define PG8_MMA(ai, bj, At, Bt) do { __builtin_amdgcn_s_setprio(1); _Pragma("unroll") for (int m = 0; m < 4; ++m) _Pragma("unroll") for (int n = 0; n < 2; ++n) _Pragma("unroll") for (int k = 0; k < 2; ++k) \
;         acc[ai][bj][m][n] = __builtin_amdgcn_mfma_f32_16x16x32_bf16(Bt[n][k], At[m][k], acc[ai][bj][m][n], 0, 0, 0); __builtin_amdgcn_s_setprio(0); } while (0)
; #define PG8_WAIT_V(n) asm volatile("s_waitcnt vmcnt(" #n ")" ::: "memory")
; #define PG8_BAR __builtin_amdgcn_s_barrier()
;     DI void operator()(const f32x4 (&acc)[2][2][4][2], const Unit& u, int wr, int wc, int fr, int fq) const {
;         const int row0 = u.pm * BM + wr * 64 + fr, col0 = u.pn * BM + wc * 32 + 8 * fq;
; #pragma unroll
;         for (int ai = 0; ai < 2; ++ai)
; #pragma unroll
;             for (int m = 0; m < 4; ++m) { u16* rowp = O + (size_t)(row0 + ai * HALF + m * 16) * ldc + col0;
; #pragma unroll
;                 for (int bj = 0; bj < 2; ++bj) { const f32x4 v0 = acc[ai][bj][m][0], v1 = acc[ai][bj][m][1];
;                     uint4 w = {pack2(v0[0], v0[1]), pack2(v0[2], v0[3]), pack2(v1[0], v1[1]), pack2(v1[2], v1[3])}; *(uint4*)(rowp + bj * HALF) = w; } }
;         if (kmaxp) {
; #pragma unroll
;             for (int bj = 0; bj < 2; ++bj) {
;                 const int cb = u.pn * BM + bj * HALF + wc * 32;
;                 const bool isA = (cb >= 384 && cb < 768), isB = (cb >= 1408 && cb < 1664);
;                 if (isA || isB) {
; template <class Epi, class Sched, bool STAMP = false>
; __device__ __forceinline__ void gemm_phase(PG8_LAS unsigned char* lds, const Gemm g, const Sched& S, const Epi& E, unsigned long long* stamps) {
;     ...
;             PG8_WAIT_V(6); PG8_BAR; PG8_MMA(1, 1, At, B1); PG8_BAR;
;         }
;         PG8_STAMP();
;         if constexpr (!Epi::AFTER_DRAIN) { E(acc, cur, wr, wc, fr, fq); S.done(cur); }
;         PG8_STAMP();
;         if (!has_next) break;
	s_setprio 1
	v_mfma_f32_16x16x32_bf16 v[28:31], v[218:221], v[186:189], v[28:31]
	v_mfma_f32_16x16x32_bf16 v[24:27], v[226:229], v[186:189], v[24:27]
	v_mfma_f32_16x16x32_bf16 v[20:23], v[218:221], v[194:197], v[20:23]
	v_mfma_f32_16x16x32_bf16 v[16:19], v[226:229], v[194:197], v[16:19]
	v_mfma_f32_16x16x32_bf16 v[12:15], v[218:221], v[202:205], v[12:15]
	v_mfma_f32_16x16x32_bf16 v[8:11], v[226:229], v[202:205], v[8:11]
	v_mfma_f32_16x16x32_bf16 v[4:7], v[218:221], v[210:213], v[4:7]
	v_mfma_f32_16x16x32_bf16 v[0:3], v[226:229], v[210:213], v[0:3]
	v_mfma_f32_16x16x32_bf16 v[28:31], v[222:225], v[190:193], v[28:31]
	v_mfma_f32_16x16x32_bf16 v[24:27], v[230:233], v[190:193], v[24:27]
	v_mfma_f32_16x16x32_bf16 v[20:23], v[222:225], v[198:201], v[20:23]
	v_mfma_f32_16x16x32_bf16 v[16:19], v[230:233], v[198:201], v[16:19]
	v_mfma_f32_16x16x32_bf16 v[12:15], v[222:225], v[206:209], v[12:15]
	v_mfma_f32_16x16x32_bf16 v[8:11], v[230:233], v[206:209], v[8:11]
	v_mfma_f32_16x16x32_bf16 v[4:7], v[222:225], v[214:217], v[4:7]
	v_mfma_f32_16x16x32_bf16 v[0:3], v[230:233], v[214:217], v[0:3]
	s_setprio 0
	s_add_i32 s10, s10, 2
	s_add_u32 s81, s81, 0x100
	s_addc_u32 s82, s82, 0
	s_cmp_gt_u32 s10, 13
	s_mov_b64 s[40:41], s[42:43]
	s_barrier
	s_cbranch_scc0 .LBB0_514
	s_lshl_b32 s46, s79, 8
	v_or_b32_e32 v170, s46, v146
	v_lshl_add_u32 v180, s80, 8, v144
	v_ashrrev_i32_e32 v171, 31, v170
	v_mov_b64_e32 v[174:175], s[12:13]
	v_mad_i64_i32 v[172:173], s[40:41], v180, s76, v[174:175]
	v_lshlrev_b64 v[176:177], 1, v[170:171]
	v_lshl_add_u64 v[178:179], v[172:173], 0, v[176:177]
	v_cvt_pk_bf16_f32 v170, v124, v125
	v_cvt_pk_bf16_f32 v171, v126, v127
	v_cvt_pk_bf16_f32 v172, v120, v121
	v_cvt_pk_bf16_f32 v173, v122, v123
	global_store_dwordx4 v[178:179], v[170:173], off
	s_or_b32 s10, s46, s63
	s_nop 0
	v_cvt_pk_bf16_f32 v170, v60, v61
	v_cvt_pk_bf16_f32 v171, v62, v63
	v_cvt_pk_bf16_f32 v172, v56, v57
	v_cvt_pk_bf16_f32 v173, v58, v59
	global_store_dwordx4 v[178:179], v[170:173], off offset:256
	s_nop 1
	v_or_b32_e32 v170, 16, v180
	v_mad_i64_i32 v[170:171], s[40:41], v170, s76, v[174:175]
	v_lshl_add_u64 v[178:179], v[170:171], 0, v[176:177]
	v_cvt_pk_bf16_f32 v170, v116, v117
	v_cvt_pk_bf16_f32 v171, v118, v119
	v_cvt_pk_bf16_f32 v172, v112, v113
	v_cvt_pk_bf16_f32 v173, v114, v115
	global_store_dwordx4 v[178:179], v[170:173], off
	s_nop 1
	v_cvt_pk_bf16_f32 v170, v52, v53
	v_cvt_pk_bf16_f32 v171, v54, v55
	v_cvt_pk_bf16_f32 v172, v48, v49
	v_cvt_pk_bf16_f32 v173, v50, v51
	global_store_dwordx4 v[178:179], v[170:173], off offset:256
	s_nop 1
	v_or_b32_e32 v170, 32, v180
	v_mad_i64_i32 v[170:171], s[40:41], v170, s76, v[174:175]
	v_lshl_add_u64 v[178:179], v[170:171], 0, v[176:177]
	v_cvt_pk_bf16_f32 v170, v108, v109
	v_cvt_pk_bf16_f32 v171, v110, v111
	v_cvt_pk_bf16_f32 v172, v104, v105
	v_cvt_pk_bf16_f32 v173, v106, v107
	global_store_dwordx4 v[178:179], v[170:173], off
	s_nop 1
	v_cvt_pk_bf16_f32 v170, v44, v45
	v_cvt_pk_bf16_f32 v171, v46, v47
	v_cvt_pk_bf16_f32 v172, v40, v41
	v_cvt_pk_bf16_f32 v173, v42, v43
	global_store_dwordx4 v[178:179], v[170:173], off offset:256
	s_nop 1
	v_or_b32_e32 v170, 48, v180
	v_mad_i64_i32 v[170:171], s[40:41], v170, s76, v[174:175]
	v_lshl_add_u64 v[178:179], v[170:171], 0, v[176:177]
	v_cvt_pk_bf16_f32 v170, v100, v101
	v_cvt_pk_bf16_f32 v171, v102, v103
	v_cvt_pk_bf16_f32 v172, v96, v97
	v_cvt_pk_bf16_f32 v173, v98, v99
	global_store_dwordx4 v[178:179], v[170:173], off
	s_nop 1
	v_cvt_pk_bf16_f32 v170, v36, v37
	v_cvt_pk_bf16_f32 v171, v38, v39
	v_cvt_pk_bf16_f32 v172, v32, v33
	v_cvt_pk_bf16_f32 v173, v34, v35
	global_store_dwordx4 v[178:179], v[170:173], off offset:256
	s_nop 1
	v_add_u32_e32 v170, 0x80, v180
	v_mad_i64_i32 v[170:171], s[40:41], v170, s76, v[174:175]
	v_lshl_add_u64 v[178:179], v[170:171], 0, v[176:177]
	v_cvt_pk_bf16_f32 v170, v92, v93
	v_cvt_pk_bf16_f32 v171, v94, v95
	v_cvt_pk_bf16_f32 v172, v88, v89
	v_cvt_pk_bf16_f32 v173, v90, v91
	global_store_dwordx4 v[178:179], v[170:173], off
	s_nop 1
	v_cvt_pk_bf16_f32 v170, v28, v29
	v_cvt_pk_bf16_f32 v171, v30, v31
	v_cvt_pk_bf16_f32 v172, v24, v25
	v_cvt_pk_bf16_f32 v173, v26, v27
	global_store_dwordx4 v[178:179], v[170:173], off offset:256
	s_nop 1
	v_add_u32_e32 v170, 0x90, v180
	v_mad_i64_i32 v[170:171], s[40:41], v170, s76, v[174:175]
	v_lshl_add_u64 v[178:179], v[170:171], 0, v[176:177]
	v_cvt_pk_bf16_f32 v170, v84, v85
	v_cvt_pk_bf16_f32 v171, v86, v87
	v_cvt_pk_bf16_f32 v172, v80, v81
	v_cvt_pk_bf16_f32 v173, v82, v83
	global_store_dwordx4 v[178:179], v[170:173], off
	s_nop 1
	v_cvt_pk_bf16_f32 v170, v20, v21
	v_cvt_pk_bf16_f32 v171, v22, v23
	v_cvt_pk_bf16_f32 v172, v16, v17
	v_cvt_pk_bf16_f32 v173, v18, v19
	global_store_dwordx4 v[178:179], v[170:173], off offset:256
	s_nop 1
	v_add_u32_e32 v170, 0xa0, v180
	v_mad_i64_i32 v[170:171], s[40:41], v170, s76, v[174:175]
	v_lshl_add_u64 v[178:179], v[170:171], 0, v[176:177]
	v_cvt_pk_bf16_f32 v170, v76, v77
	v_cvt_pk_bf16_f32 v171, v78, v79
	v_cvt_pk_bf16_f32 v172, v72, v73
	v_cvt_pk_bf16_f32 v173, v74, v75
	global_store_dwordx4 v[178:179], v[170:173], off
	s_nop 1
	v_cvt_pk_bf16_f32 v170, v12, v13
	v_cvt_pk_bf16_f32 v171, v14, v15
	v_cvt_pk_bf16_f32 v172, v8, v9
	v_cvt_pk_bf16_f32 v173, v10, v11
	global_store_dwordx4 v[178:179], v[170:173], off offset:256
	s_nop 1
	v_add_u32_e32 v170, 0xb0, v180
	v_mad_i64_i32 v[170:171], s[40:41], v170, s76, v[174:175]
	s_add_i32 s40, s46, 0xfffffe80
	s_cmpk_gt_u32 s40, 0x17f
	s_cselect_b64 s[40:41], -1, 0
	s_add_i32 s42, s46, 0xfffffa80
	s_cmpk_gt_u32 s42, 0xff
	s_cselect_b64 s[42:43], -1, 0
	v_lshl_add_u64 v[174:175], v[170:171], 0, v[176:177]
	v_cvt_pk_bf16_f32 v170, v68, v69
	v_cvt_pk_bf16_f32 v171, v70, v71
	v_cvt_pk_bf16_f32 v172, v64, v65
	v_cvt_pk_bf16_f32 v173, v66, v67
	s_and_b64 s[42:43], s[40:41], s[42:43]
	global_store_dwordx4 v[174:175], v[170:173], off
	s_and_b64 vcc, exec, s[42:43]
	s_nop 0
	v_cvt_pk_bf16_f32 v170, v4, v5
	v_cvt_pk_bf16_f32 v171, v6, v7
	v_cvt_pk_bf16_f32 v172, v0, v1
	v_cvt_pk_bf16_f32 v173, v2, v3
	global_store_dwordx4 v[174:175], v[170:173], off offset:256
	s_cbranch_vccnz .LBB0_526
;     DI void operator()(const f32x4 (&acc)[2][2][4][2], const Unit& u, int wr, int wc, int fr, int fq) const {
;     ...
;                     float mx = 0.f;
; #pragma unroll
;                     for (int ai = 0; ai < 2; ++ai)
; #pragma unroll
;                         for (int m = 0; m < 4; ++m) {
;                             const f32x4 a = acc[ai][bj][m][0], b = acc[ai][bj][m][1];
;                             float s0 = a[0] * a[0] + a[1] * a[1] + a[2] * a[2] + a[3] * a[3] + b[0] * b[0] + b[1] * b[1] + b[2] * b[2] + b[3] * b[3];
;                             s0 += __shfl_xor(s0, 16);
;                             s0 += __shfl_xor(s0, 32);
;                             mx = fmaxf(mx, s0);
;                         }
; #pragma unroll
;                     for (int o = 1; o <= 8; o <<= 1) mx = fmaxf(mx, __shfl_xor(mx, o));
;                     if ((threadIdx.x & 63) == 0) atomicMax((unsigned*)kmaxp + (isA ? ((cb - 384) >> 5) : (12 + ((cb - 1408) >> 5))), __float_as_uint(mx));
;                 }
	v_mul_f32_e32 v125, v125, v125
	v_mul_f32_e32 v117, v117, v117
	v_fmac_f32_e32 v125, v124, v124
	v_fmac_f32_e32 v117, v116, v116
	v_mul_f32_e32 v109, v109, v109
	v_mul_f32_e32 v101, v101, v101
	v_fmac_f32_e32 v125, v126, v126
	v_fmac_f32_e32 v117, v118, v118
	v_fmac_f32_e32 v109, v108, v108
	v_fmac_f32_e32 v101, v100, v100
	v_fmac_f32_e32 v125, v127, v127
	v_fmac_f32_e32 v117, v119, v119
	v_fmac_f32_e32 v109, v110, v110
	v_fmac_f32_e32 v101, v102, v102
	v_fmac_f32_e32 v125, v120, v120
	v_fmac_f32_e32 v117, v112, v112
	v_fmac_f32_e32 v109, v111, v111
	v_fmac_f32_e32 v101, v103, v103
	v_fmac_f32_e32 v125, v121, v121
	v_fmac_f32_e32 v117, v113, v113
	v_fmac_f32_e32 v109, v104, v104
	v_fmac_f32_e32 v101, v96, v96
	v_fmac_f32_e32 v125, v122, v122
	v_fmac_f32_e32 v117, v114, v114
	v_fmac_f32_e32 v109, v105, v105
	v_fmac_f32_e32 v101, v97, v97
	v_fmac_f32_e32 v125, v123, v123
	v_fmac_f32_e32 v117, v115, v115
	v_fmac_f32_e32 v109, v106, v106
	v_fmac_f32_e32 v101, v98, v98
	v_mul_f32_e32 v93, v93, v93
	v_mul_f32_e32 v85, v85, v85
	ds_bpermute_b32 v120, v160, v125
	ds_bpermute_b32 v112, v160, v117
	v_fmac_f32_e32 v109, v107, v107
	v_fmac_f32_e32 v101, v99, v99
	v_fmac_f32_e32 v93, v92, v92
	v_fmac_f32_e32 v85, v84, v84
	v_mul_f32_e32 v77, v77, v77
	v_mul_f32_e32 v69, v69, v69
	ds_bpermute_b32 v104, v160, v109
	ds_bpermute_b32 v96, v160, v101
	v_fmac_f32_e32 v93, v94, v94
	v_fmac_f32_e32 v85, v86, v86
	v_fmac_f32_e32 v77, v76, v76
	v_fmac_f32_e32 v69, v68, v68
	v_fmac_f32_e32 v93, v95, v95
	v_fmac_f32_e32 v85, v87, v87
	v_fmac_f32_e32 v77, v78, v78
	v_fmac_f32_e32 v69, v70, v70
	v_fmac_f32_e32 v93, v88, v88
	v_fmac_f32_e32 v85, v80, v80
	v_fmac_f32_e32 v77, v79, v79
	v_fmac_f32_e32 v69, v71, v71
	v_fmac_f32_e32 v93, v89, v89
	v_fmac_f32_e32 v85, v81, v81
	v_fmac_f32_e32 v77, v72, v72
	v_fmac_f32_e32 v69, v64, v64
	s_waitcnt lgkmcnt(0)
	v_add_f32_e32 v113, v125, v120
	v_add_f32_e32 v112, v117, v112
	v_fmac_f32_e32 v93, v90, v90
	v_fmac_f32_e32 v85, v82, v82
	v_fmac_f32_e32 v77, v73, v73
	v_fmac_f32_e32 v69, v65, v65
	ds_bpermute_b32 v114, v159, v113
	ds_bpermute_b32 v115, v159, v112
	v_add_f32_e32 v99, v109, v104
	v_add_f32_e32 v96, v101, v96
	v_fmac_f32_e32 v93, v91, v91
	v_fmac_f32_e32 v85, v83, v83
	v_fmac_f32_e32 v77, v74, v74
	v_fmac_f32_e32 v69, v66, v66
	ds_bpermute_b32 v100, v159, v99
	ds_bpermute_b32 v101, v159, v96
	ds_bpermute_b32 v88, v160, v93
	ds_bpermute_b32 v80, v160, v85
	v_fmac_f32_e32 v77, v75, v75
	v_fmac_f32_e32 v69, v67, v67
	ds_bpermute_b32 v72, v160, v77
	ds_bpermute_b32 v64, v160, v69
	s_waitcnt lgkmcnt(0)
	v_add_f32_e32 v97, v113, v114
	v_add_f32_e32 v98, v112, v115
	v_max3_f32 v89, v97, 0, v98
	v_add_f32_e32 v90, v99, v100
	v_add_f32_e32 v91, v96, v101
	v_add_f32_e32 v88, v93, v88
	v_add_f32_e32 v65, v85, v80
	v_max3_f32 v89, v89, v90, v91
	ds_bpermute_b32 v90, v159, v88
	ds_bpermute_b32 v66, v159, v65
	v_add_f32_e32 v67, v77, v72
	v_add_f32_e32 v64, v69, v64
	ds_bpermute_b32 v68, v159, v67
	ds_bpermute_b32 v69, v159, v64
	s_waitcnt lgkmcnt(0)
	v_add_f32_e32 v70, v88, v90
	v_add_f32_e32 v65, v65, v66
	v_max3_f32 v65, v89, v70, v65
	v_add_f32_e32 v66, v67, v68
	v_add_f32_e32 v64, v64, v69
	v_max3_f32 v64, v65, v66, v64
	ds_bpermute_b32 v65, v164, v64
	s_waitcnt lgkmcnt(0)
	v_max_f32_e32 v65, v65, v65
	v_max_f32_e32 v64, v64, v65
	ds_bpermute_b32 v65, v163, v64
	s_waitcnt lgkmcnt(0)
	v_max_f32_e32 v65, v65, v65
	v_max_f32_e32 v64, v64, v65
	ds_bpermute_b32 v65, v162, v64
	s_waitcnt lgkmcnt(0)
	v_max_f32_e32 v65, v65, v65
	v_max_f32_e32 v64, v64, v65
	ds_bpermute_b32 v65, v161, v64
	s_and_saveexec_b64 s[42:43], s[2:3]
	s_cbranch_execz .LBB0_525
	s_mov_b64 s[44:45], -1
	s_and_b64 vcc, exec, s[40:41]
	s_cbranch_vccz .LBB0_519
	s_add_i32 s40, s10, 0xfffffa80
	s_ashr_i32 s40, s40, 5
	s_add_i32 s40, s40, 12
	s_mov_b64 s[44:45], 0

; #define PG8_STAGE(bufoff, gbase, voff) do { _Pragma("unroll") for (int _i = 0; _i < 2; ++_i) \
;         __builtin_amdgcn_global_load_lds((const unsigned*)((const char*)(gbase) + (voff)[_i]), (PG8_LAS unsigned*)(lds + (bufoff) + ldsw + _i * 8192), 16, 0, 0); } while (0)
; #define PG8_LDA(dst, b, h) do { _Pragma("unroll") for (int m = 0; m < 4; ++m) _Pragma("unroll") for (int k = 0; k < 2; ++k) dst[m][k] = *(const PG8_LAS bf16x8*)(lds + PG8_SA(b, h) + aoff + m * 2048 + k * 1024); } while (0)
; #define PG8_WAIT_V(n) asm volatile("s_waitcnt vmcnt(" #n ")" ::: "memory")
; #define PG8_WAIT_L(n) asm volatile("s_waitcnt lgkmcnt(" #n ")" ::: "memory")
; template <class Epi, class Sched, bool STAMP = false>
; __device__ __forceinline__ void gemm_phase(PG8_LAS unsigned char* lds, const Gemm g, const Sched& S, const Epi& E, unsigned long long* stamps) {
;     ...
;         const bool has_next = S.next(ui + 1, nxt);
;         const char* nA = has_next ? (const char*)g.A + (size_t)nxt.pm * tstep : cA; const char* nB = has_next ? (const char*)g.Bt + (size_t)nxt.pn * tstep : cB;
;         for (int t = 0; t < nt; t += 2) {
;             const bool last = (t == nt - 2);
;             const char* a1 = cA + (size_t)(t + 1) * kstep;
;             const char* a2 = last ? nA : cA + (size_t)(t + 2) * kstep; const char* b2 = last ? nB : cB + (size_t)(t + 2) * kstep;
;             const char* a3 = a2 + kstep; const char* b3 = b2 + kstep;
;             if (last && has_next) S.a_ready(nxt);
;             PG8_LDB(B0, 0, 0); PG8_SCHED; PG8_LDA(At, 0, 0); PG8_STAGE(PG8_SA(1, 1), a1 + hstep, voffA);
;             PG8_WAIT_L(8); PG8_BAR; PG8_WAIT_L(0); PG8_MMA(0, 0, At, B0); PG8_BAR; PG8_SCHED;
;             PG8_LDB(B1, 0, 1); PG8_STAGE(PG8_SB(0, 0), b2, voffB);
;             PG8_BAR; PG8_WAIT_L(0); PG8_MMA(0, 1, At, B1); PG8_BAR;
;             PG8_LDA(At, 0, 1); PG8_STAGE(PG8_SA(0, 0), a2, voffA);
;             PG8_BAR; PG8_WAIT_L(0); PG8_MMA(1, 0, At, B0); PG8_BAR; PG8_SCHED;
;             PG8_STAGE(PG8_SB(0, 1), b2 + hstep, voffB);
;             PG8_WAIT_V(6); PG8_BAR; PG8_MMA(1, 1, At, B1); PG8_BAR;
;     ...
; #pragma unroll
;         for (int a = 0; a < 2; ++a)
; #pragma unroll
;             for (int b = 0; b < 2; ++b)
; #pragma unroll
;                 for (int m = 0; m < 4; ++m)
; #pragma unroll
;                     for (int n = 0; n < 2; ++n) acc[a][b][m][n] = (f32x4){0.f, 0.f, 0.f, 0.f};
.LBB0_687:
	s_add_u32 s76, s36, 0x100
	s_addc_u32 s77, s37, 0
	s_mov_b32 s10, -2
	ds_read_b128 v[170:173], v147
	ds_read_b128 v[174:177], v148
	ds_read_b128 v[178:181], v149
	ds_read_b128 v[182:185], v150
	s_add_u32 s36, s34, 0x100
	s_addc_u32 s37, s35, 0
	s_cmp_eq_u32 s10, 12
	s_cselect_b32 s43, s5, s37
	s_cselect_b32 s42, s4, s36
	s_cselect_b32 s41, s1, s77
	s_cselect_b32 s40, s0, s76
	s_mov_b32 m0, s63
	ds_read_b128 v[186:189], v145
	ds_read_b128 v[190:193], v145 offset:1024
	ds_read_b128 v[194:197], v145 offset:2048
	ds_read_b128 v[198:201], v145 offset:3072
	ds_read_b128 v[202:205], v145 offset:4096
	ds_read_b128 v[206:209], v145 offset:5120
	ds_read_b128 v[210:213], v145 offset:6144
	ds_read_b128 v[214:217], v145 offset:7168
	global_load_lds_dwordx4 v136, s[34:35]
	s_mov_b32 m0, s64
	s_nop 0
	global_load_lds_dwordx4 v138, s[34:35]
	s_waitcnt lgkmcnt(8)
	s_barrier
	s_waitcnt lgkmcnt(0)
	s_setprio 1
	s_waitcnt lgkmcnt(0)
	v_mfma_f32_16x16x32_bf16 v[124:127], v[170:173], v[186:189], 0
	v_mfma_f32_16x16x32_bf16 v[120:123], v[178:181], v[186:189], 0
	v_mfma_f32_16x16x32_bf16 v[116:119], v[170:173], v[194:197], 0
	v_mfma_f32_16x16x32_bf16 v[112:115], v[178:181], v[194:197], 0
	v_mfma_f32_16x16x32_bf16 v[100:103], v[170:173], v[202:205], 0
	v_mfma_f32_16x16x32_bf16 v[96:99], v[178:181], v[202:205], 0
	v_mfma_f32_16x16x32_bf16 v[84:87], v[170:173], v[210:213], 0
	v_mfma_f32_16x16x32_bf16 v[80:83], v[178:181], v[210:213], 0
	v_mfma_f32_16x16x32_bf16 v[124:127], v[174:177], v[190:193], v[124:127]
	v_mfma_f32_16x16x32_bf16 v[120:123], v[182:185], v[190:193], v[120:123]
	v_mfma_f32_16x16x32_bf16 v[116:119], v[174:177], v[198:201], v[116:119]
	v_mfma_f32_16x16x32_bf16 v[112:115], v[182:185], v[198:201], v[112:115]
	v_mfma_f32_16x16x32_bf16 v[100:103], v[174:177], v[206:209], v[100:103]
	v_mfma_f32_16x16x32_bf16 v[96:99], v[182:185], v[206:209], v[96:99]
	v_mfma_f32_16x16x32_bf16 v[84:87], v[174:177], v[214:217], v[84:87]
	v_mfma_f32_16x16x32_bf16 v[80:83], v[182:185], v[214:217], v[80:83]
	s_setprio 0
	s_barrier
	s_mov_b32 m0, s48
	ds_read_b128 v[218:221], v151
	ds_read_b128 v[222:225], v152
	ds_read_b128 v[226:229], v153
	ds_read_b128 v[230:233], v154
	global_load_lds_dwordx4 v130, s[40:41]
	s_mov_b32 m0, s49
	s_nop 0
	global_load_lds_dwordx4 v134, s[40:41]
	s_barrier
	s_waitcnt lgkmcnt(0)
	s_setprio 1
	s_waitcnt lgkmcnt(0)
	v_mfma_f32_16x16x32_bf16 v[108:111], v[218:221], v[186:189], 0
	v_mfma_f32_16x16x32_bf16 v[104:107], v[226:229], v[186:189], 0
	v_mfma_f32_16x16x32_bf16 v[92:95], v[218:221], v[194:197], 0
	v_mfma_f32_16x16x32_bf16 v[88:91], v[226:229], v[194:197], 0
	v_mfma_f32_16x16x32_bf16 v[76:79], v[218:221], v[202:205], 0
	v_mfma_f32_16x16x32_bf16 v[72:75], v[226:229], v[202:205], 0
	v_mfma_f32_16x16x32_bf16 v[68:71], v[218:221], v[210:213], 0
	v_mfma_f32_16x16x32_bf16 v[64:67], v[226:229], v[210:213], 0
	v_mfma_f32_16x16x32_bf16 v[108:111], v[222:225], v[190:193], v[108:111]
	v_mfma_f32_16x16x32_bf16 v[104:107], v[230:233], v[190:193], v[104:107]
	v_mfma_f32_16x16x32_bf16 v[92:95], v[222:225], v[198:201], v[92:95]
	v_mfma_f32_16x16x32_bf16 v[88:91], v[230:233], v[198:201], v[88:91]
	v_mfma_f32_16x16x32_bf16 v[76:79], v[222:225], v[206:209], v[76:79]
	v_mfma_f32_16x16x32_bf16 v[72:75], v[230:233], v[206:209], v[72:75]
	v_mfma_f32_16x16x32_bf16 v[68:71], v[222:225], v[214:217], v[68:71]
	v_mfma_f32_16x16x32_bf16 v[64:67], v[230:233], v[214:217], v[64:67]
	s_setprio 0
	s_mov_b32 m0, s47
	s_barrier
	ds_read_b128 v[186:189], v145 offset:16384
	ds_read_b128 v[190:193], v145 offset:17408
	ds_read_b128 v[194:197], v145 offset:18432
	ds_read_b128 v[198:201], v145 offset:19456
	ds_read_b128 v[202:205], v145 offset:20480
	ds_read_b128 v[206:209], v145 offset:21504
	ds_read_b128 v[210:213], v145 offset:22528
	ds_read_b128 v[214:217], v145 offset:23552
	global_load_lds_dwordx4 v128, s[42:43]
	s_mov_b32 m0, s50
	s_nop 0
	global_load_lds_dwordx4 v132, s[42:43]
	s_barrier
	s_waitcnt lgkmcnt(0)
	s_setprio 1
	s_waitcnt lgkmcnt(0)
	v_mfma_f32_16x16x32_bf16 v[60:63], v[170:173], v[186:189], 0
	v_mfma_f32_16x16x32_bf16 v[56:59], v[178:181], v[186:189], 0
	v_mfma_f32_16x16x32_bf16 v[52:55], v[170:173], v[194:197], 0
	v_mfma_f32_16x16x32_bf16 v[48:51], v[178:181], v[194:197], 0
	v_mfma_f32_16x16x32_bf16 v[36:39], v[170:173], v[202:205], 0
	v_mfma_f32_16x16x32_bf16 v[32:35], v[178:181], v[202:205], 0
	v_mfma_f32_16x16x32_bf16 v[20:23], v[170:173], v[210:213], 0
	v_mfma_f32_16x16x32_bf16 v[16:19], v[178:181], v[210:213], 0
	v_mfma_f32_16x16x32_bf16 v[60:63], v[174:177], v[190:193], v[60:63]
	v_mfma_f32_16x16x32_bf16 v[56:59], v[182:185], v[190:193], v[56:59]
	v_mfma_f32_16x16x32_bf16 v[52:55], v[174:177], v[198:201], v[52:55]
	v_mfma_f32_16x16x32_bf16 v[48:51], v[182:185], v[198:201], v[48:51]
	v_mfma_f32_16x16x32_bf16 v[36:39], v[174:177], v[206:209], v[36:39]
	v_mfma_f32_16x16x32_bf16 v[32:35], v[182:185], v[206:209], v[32:35]
	v_mfma_f32_16x16x32_bf16 v[20:23], v[174:177], v[214:217], v[20:23]
	v_mfma_f32_16x16x32_bf16 v[16:19], v[182:185], v[214:217], v[16:19]
	s_setprio 0
	s_barrier
	s_add_u32 s34, s40, 0x44000
	s_addc_u32 s35, s41, 0
	s_mov_b32 m0, s51
	s_nop 0
	global_load_lds_dwordx4 v130, s[34:35]
	s_mov_b32 m0, s52
	s_nop 0
	global_load_lds_dwordx4 v134, s[34:35]
	s_waitcnt vmcnt(6)
	s_barrier
	s_setprio 1
	v_mfma_f32_16x16x32_bf16 v[44:47], v[218:221], v[186:189], 0
	v_mfma_f32_16x16x32_bf16 v[40:43], v[226:229], v[186:189], 0
	v_mfma_f32_16x16x32_bf16 v[28:31], v[218:221], v[194:197], 0
	v_mfma_f32_16x16x32_bf16 v[24:27], v[226:229], v[194:197], 0
	v_mfma_f32_16x16x32_bf16 v[12:15], v[218:221], v[202:205], 0
	v_mfma_f32_16x16x32_bf16 v[8:11], v[226:229], v[202:205], 0
	v_mfma_f32_16x16x32_bf16 v[4:7], v[218:221], v[210:213], 0
	v_mfma_f32_16x16x32_bf16 v[0:3], v[226:229], v[210:213], 0
	v_mfma_f32_16x16x32_bf16 v[44:47], v[222:225], v[190:193], v[44:47]
	v_mfma_f32_16x16x32_bf16 v[40:43], v[230:233], v[190:193], v[40:43]
	v_mfma_f32_16x16x32_bf16 v[28:31], v[222:225], v[198:201], v[28:31]
	v_mfma_f32_16x16x32_bf16 v[24:27], v[230:233], v[198:201], v[24:27]
	v_mfma_f32_16x16x32_bf16 v[12:15], v[222:225], v[206:209], v[12:15]
	v_mfma_f32_16x16x32_bf16 v[8:11], v[230:233], v[206:209], v[8:11]
	v_mfma_f32_16x16x32_bf16 v[4:7], v[222:225], v[214:217], v[4:7]
	v_mfma_f32_16x16x32_bf16 v[0:3], v[230:233], v[214:217], v[0:3]
	s_setprio 0
	s_barrier
	s_branch .Lzp10_mid

; #define PG8_STAGE(bufoff, gbase, voff) do { _Pragma("unroll") for (int _i = 0; _i < 2; ++_i) \
;         __builtin_amdgcn_global_load_lds((const unsigned*)((const char*)(gbase) + (voff)[_i]), (PG8_LAS unsigned*)(lds + (bufoff) + ldsw + _i * 8192), 16, 0, 0); } while (0)
; #define PG8_LDA(dst, b, h) do { _Pragma("unroll") for (int m = 0; m < 4; ++m) _Pragma("unroll") for (int k = 0; k < 2; ++k) dst[m][k] = *(const PG8_LAS bf16x8*)(lds + PG8_SA(b, h) + aoff + m * 2048 + k * 1024); } while (0)
; #define PG8_LDB(dst, b, h) do { _Pragma("unroll") for (int n = 0; n < 2; ++n) _Pragma("unroll") for (int k = 0; k < 2; ++k) dst[n][k] = *(const PG8_LAS bf16x8*)(lds + PG8_SB(b, h) + boff + n * 2048 + k * 1024); } while (0)
; #define PG8_MMA(ai, bj, At, Bt) do { __builtin_amdgcn_s_setprio(1); _Pragma("unroll") for (int m = 0; m < 4; ++m) _Pragma("unroll") for (int n = 0; n < 2; ++n) _Pragma("unroll") for (int k = 0; k < 2; ++k) \
;         acc[ai][bj][m][n] = __builtin_amdgcn_mfma_f32_16x16x32_bf16(Bt[n][k], At[m][k], acc[ai][bj][m][n], 0, 0, 0); __builtin_amdgcn_s_setprio(0); } while (0)
; #define PG8_WAIT_V(n) asm volatile("s_waitcnt vmcnt(" #n ")" ::: "memory")
; #define PG8_WAIT_L(n) asm volatile("s_waitcnt lgkmcnt(" #n ")" ::: "memory")
; #define PG8_BAR __builtin_amdgcn_s_barrier()
; #define PG8_SCHED __builtin_amdgcn_sched_barrier(0)
; template <class Epi, class Sched, bool STAMP = false>
; __device__ __forceinline__ void gemm_phase(PG8_LAS unsigned char* lds, const Gemm g, const Sched& S, const Epi& E, unsigned long long* stamps) {
;     ...
;             PG8_LDB(B0, 1, 0); PG8_SCHED; PG8_LDA(At, 1, 0); PG8_STAGE(PG8_SA(0, 1), a2 + hstep, voffA);
;             PG8_WAIT_L(8); PG8_BAR; PG8_WAIT_L(0); PG8_MMA(0, 0, At, B0); PG8_BAR; PG8_SCHED;
;             PG8_LDB(B1, 1, 1); PG8_STAGE(PG8_SB(1, 0), b3, voffB);
;             PG8_BAR; PG8_WAIT_L(0); PG8_MMA(0, 1, At, B1); PG8_BAR;
;             PG8_LDA(At, 1, 1); PG8_STAGE(PG8_SA(1, 0), a3, voffA);
;             PG8_BAR; PG8_WAIT_L(0); PG8_MMA(1, 0, At, B0); PG8_BAR; PG8_SCHED;
;             PG8_STAGE(PG8_SB(1, 1), b3 + hstep, voffB);
;             PG8_WAIT_V(6); PG8_BAR; PG8_MMA(1, 1, At, B1); PG8_BAR;
.Lzp10_mid:
	ds_read_b128 v[170:173], v155
	ds_read_b128 v[174:177], v156
	ds_read_b128 v[178:181], v157
	ds_read_b128 v[182:185], v165
	s_add_u32 s34, s42, 0x44000
	s_addc_u32 s35, s43, 0
	s_mov_b32 m0, s53
	ds_read_b128 v[186:189], v145 offset:32768
	ds_read_b128 v[190:193], v145 offset:33792
	ds_read_b128 v[194:197], v145 offset:34816
	ds_read_b128 v[198:201], v145 offset:35840
	ds_read_b128 v[202:205], v145 offset:36864
	ds_read_b128 v[206:209], v145 offset:37888
	ds_read_b128 v[210:213], v145 offset:38912
	ds_read_b128 v[214:217], v145 offset:39936
	global_load_lds_dwordx4 v128, s[34:35]
	s_mov_b32 m0, s54
	s_nop 0
	global_load_lds_dwordx4 v132, s[34:35]
	s_waitcnt lgkmcnt(8)
	s_barrier
	s_waitcnt lgkmcnt(0)
	s_setprio 1
	s_waitcnt lgkmcnt(0)
	v_mfma_f32_16x16x32_bf16 v[124:127], v[170:173], v[186:189], v[124:127]
	v_mfma_f32_16x16x32_bf16 v[120:123], v[178:181], v[186:189], v[120:123]
	v_mfma_f32_16x16x32_bf16 v[116:119], v[170:173], v[194:197], v[116:119]
	v_mfma_f32_16x16x32_bf16 v[112:115], v[178:181], v[194:197], v[112:115]
	v_mfma_f32_16x16x32_bf16 v[100:103], v[170:173], v[202:205], v[100:103]
	v_mfma_f32_16x16x32_bf16 v[96:99], v[178:181], v[202:205], v[96:99]
	v_mfma_f32_16x16x32_bf16 v[84:87], v[170:173], v[210:213], v[84:87]
	v_mfma_f32_16x16x32_bf16 v[80:83], v[178:181], v[210:213], v[80:83]
	v_mfma_f32_16x16x32_bf16 v[124:127], v[174:177], v[190:193], v[124:127]
	v_mfma_f32_16x16x32_bf16 v[120:123], v[182:185], v[190:193], v[120:123]
	v_mfma_f32_16x16x32_bf16 v[116:119], v[174:177], v[198:201], v[116:119]
	v_mfma_f32_16x16x32_bf16 v[112:115], v[182:185], v[198:201], v[112:115]
	v_mfma_f32_16x16x32_bf16 v[100:103], v[174:177], v[206:209], v[100:103]
	v_mfma_f32_16x16x32_bf16 v[96:99], v[182:185], v[206:209], v[96:99]
	v_mfma_f32_16x16x32_bf16 v[84:87], v[174:177], v[214:217], v[84:87]
	v_mfma_f32_16x16x32_bf16 v[80:83], v[182:185], v[214:217], v[80:83]
	s_setprio 0
	s_barrier
	s_mov_b32 m0, s55
	ds_read_b128 v[218:221], v166
	ds_read_b128 v[222:225], v167
	ds_read_b128 v[226:229], v168
	ds_read_b128 v[230:233], v169
	s_add_u32 s100, s40, 0x80
	s_addc_u32 s101, s41, 0
	global_load_lds_dwordx4 v130, s[100:101]
	s_mov_b32 m0, s56
	s_nop 0
	global_load_lds_dwordx4 v134, s[100:101]
	s_barrier
	s_waitcnt lgkmcnt(0)
	s_setprio 1
	s_waitcnt lgkmcnt(0)
	v_mfma_f32_16x16x32_bf16 v[108:111], v[218:221], v[186:189], v[108:111]
	v_mfma_f32_16x16x32_bf16 v[104:107], v[226:229], v[186:189], v[104:107]
	v_mfma_f32_16x16x32_bf16 v[92:95], v[218:221], v[194:197], v[92:95]
	v_mfma_f32_16x16x32_bf16 v[88:91], v[226:229], v[194:197], v[88:91]
	v_mfma_f32_16x16x32_bf16 v[76:79], v[218:221], v[202:205], v[76:79]
	v_mfma_f32_16x16x32_bf16 v[72:75], v[226:229], v[202:205], v[72:75]
	v_mfma_f32_16x16x32_bf16 v[68:71], v[218:221], v[210:213], v[68:71]
	v_mfma_f32_16x16x32_bf16 v[64:67], v[226:229], v[210:213], v[64:67]
	v_mfma_f32_16x16x32_bf16 v[108:111], v[222:225], v[190:193], v[108:111]
	v_mfma_f32_16x16x32_bf16 v[104:107], v[230:233], v[190:193], v[104:107]
	v_mfma_f32_16x16x32_bf16 v[92:95], v[222:225], v[198:201], v[92:95]
	v_mfma_f32_16x16x32_bf16 v[88:91], v[230:233], v[198:201], v[88:91]
	v_mfma_f32_16x16x32_bf16 v[76:79], v[222:225], v[206:209], v[76:79]
	v_mfma_f32_16x16x32_bf16 v[72:75], v[230:233], v[206:209], v[72:75]
	v_mfma_f32_16x16x32_bf16 v[68:71], v[222:225], v[214:217], v[68:71]
	v_mfma_f32_16x16x32_bf16 v[64:67], v[230:233], v[214:217], v[64:67]
	s_setprio 0
	s_mov_b32 m0, s57
	s_barrier
	ds_read_b128 v[186:189], v145 offset:49152
	ds_read_b128 v[190:193], v145 offset:50176
	ds_read_b128 v[194:197], v145 offset:51200
	ds_read_b128 v[198:201], v145 offset:52224
	ds_read_b128 v[202:205], v145 offset:53248
	ds_read_b128 v[206:209], v145 offset:54272
	ds_read_b128 v[210:213], v145 offset:55296
	ds_read_b128 v[214:217], v145 offset:56320
	s_add_u32 s100, s42, 0x80
	s_addc_u32 s101, s43, 0
	global_load_lds_dwordx4 v128, s[100:101]
	s_mov_b32 m0, s58
	s_nop 0
	global_load_lds_dwordx4 v132, s[100:101]
	s_barrier
	s_waitcnt lgkmcnt(0)
	s_setprio 1
	s_waitcnt lgkmcnt(0)
	v_mfma_f32_16x16x32_bf16 v[60:63], v[170:173], v[186:189], v[60:63]
	v_mfma_f32_16x16x32_bf16 v[56:59], v[178:181], v[186:189], v[56:59]
	v_mfma_f32_16x16x32_bf16 v[52:55], v[170:173], v[194:197], v[52:55]
	v_mfma_f32_16x16x32_bf16 v[48:51], v[178:181], v[194:197], v[48:51]
	v_mfma_f32_16x16x32_bf16 v[36:39], v[170:173], v[202:205], v[36:39]
	v_mfma_f32_16x16x32_bf16 v[32:35], v[178:181], v[202:205], v[32:35]
	v_mfma_f32_16x16x32_bf16 v[20:23], v[170:173], v[210:213], v[20:23]
	v_mfma_f32_16x16x32_bf16 v[16:19], v[178:181], v[210:213], v[16:19]
	v_mfma_f32_16x16x32_bf16 v[60:63], v[174:177], v[190:193], v[60:63]
	v_mfma_f32_16x16x32_bf16 v[56:59], v[182:185], v[190:193], v[56:59]
	v_mfma_f32_16x16x32_bf16 v[52:55], v[174:177], v[198:201], v[52:55]
	v_mfma_f32_16x16x32_bf16 v[48:51], v[182:185], v[198:201], v[48:51]
	v_mfma_f32_16x16x32_bf16 v[36:39], v[174:177], v[206:209], v[36:39]
	v_mfma_f32_16x16x32_bf16 v[32:35], v[182:185], v[206:209], v[32:35]
	v_mfma_f32_16x16x32_bf16 v[20:23], v[174:177], v[214:217], v[20:23]
	v_mfma_f32_16x16x32_bf16 v[16:19], v[182:185], v[214:217], v[16:19]
	s_setprio 0
	s_barrier
	s_add_u32 s34, s40, 0x44080
	s_addc_u32 s35, s41, 0
	s_mov_b32 m0, s59
	s_nop 0
	global_load_lds_dwordx4 v130, s[34:35]
	s_mov_b32 m0, s60
	s_nop 0
	global_load_lds_dwordx4 v134, s[34:35]
	s_waitcnt vmcnt(6)
	s_barrier
; #define PG8_STAMP() do { if (STAMP && wid == 0 && nts < 64) { const unsigned long long _c = 0ull; \
;         ts_lo = (lane == nts) ? (int)(unsigned)_c : ts_lo; ts_hi = (lane == nts) ? (int)(unsigned)(_c >> 32) : ts_hi; ++nts; } } while (0)
; #define PG8_MMA(ai, bj, At, Bt) do { __builtin_amdgcn_s_setprio(1); _Pragma("unroll") for (int m = 0; m < 4; ++m) _Pragma("unroll") for (int n = 0; n < 2; ++n) _Pragma("unroll") for (int k = 0; k < 2; ++k) \
;         acc[ai][bj][m][n] = __builtin_amdgcn_mfma_f32_16x16x32_bf16(Bt[n][k], At[m][k], acc[ai][bj][m][n], 0, 0, 0); __builtin_amdgcn_s_setprio(0); } while (0)
; #define PG8_WAIT_V(n) asm volatile("s_waitcnt vmcnt(" #n ")" ::: "memory")
; #define PG8_BAR __builtin_amdgcn_s_barrier()
;     DI void operator()(const f32x4 (&acc)[2][2][4][2], const Unit& u, int wr, int wc, int fr, int fq) const {
;         const int row0 = u.pm * BM + wr * 64 + fr, col0 = u.pn * BM + wc * 32 + 8 * fq;
; #pragma unroll
;         for (int ai = 0; ai < 2; ++ai)
; #pragma unroll
;             for (int m = 0; m < 4; ++m) { u16* rowp = O + (size_t)(row0 + ai * HALF + m * 16) * ldc + col0;
; #pragma unroll
;                 for (int bj = 0; bj < 2; ++bj) { const f32x4 v0 = acc[ai][bj][m][0], v1 = acc[ai][bj][m][1];
;                     uint4 w = {pack2(v0[0], v0[1]), pack2(v0[2], v0[3]), pack2(v1[0], v1[1]), pack2(v1[2], v1[3])}; *(uint4*)(rowp + bj * HALF) = w; } }
; template <class Epi, class Sched, bool STAMP = false>
; __device__ __forceinline__ void gemm_phase(PG8_LAS unsigned char* lds, const Gemm g, const Sched& S, const Epi& E, unsigned long long* stamps) {
;     ...
;             PG8_WAIT_V(6); PG8_BAR; PG8_MMA(1, 1, At, B1); PG8_BAR;
;         }
;         PG8_STAMP();
;         if constexpr (!Epi::AFTER_DRAIN) { E(acc, cur, wr, wc, fr, fq); S.done(cur); }
;         PG8_STAMP();
;         if (!has_next) break;
	s_setprio 1
	v_mfma_f32_16x16x32_bf16 v[44:47], v[218:221], v[186:189], v[44:47]
	v_mfma_f32_16x16x32_bf16 v[40:43], v[226:229], v[186:189], v[40:43]
	v_mfma_f32_16x16x32_bf16 v[28:31], v[218:221], v[194:197], v[28:31]
	v_mfma_f32_16x16x32_bf16 v[24:27], v[226:229], v[194:197], v[24:27]
	v_mfma_f32_16x16x32_bf16 v[12:15], v[218:221], v[202:205], v[12:15]
	v_mfma_f32_16x16x32_bf16 v[8:11], v[226:229], v[202:205], v[8:11]
	v_mfma_f32_16x16x32_bf16 v[4:7], v[218:221], v[210:213], v[4:7]
	v_mfma_f32_16x16x32_bf16 v[0:3], v[226:229], v[210:213], v[0:3]
	v_mfma_f32_16x16x32_bf16 v[44:47], v[222:225], v[190:193], v[44:47]
	v_mfma_f32_16x16x32_bf16 v[40:43], v[230:233], v[190:193], v[40:43]
	v_mfma_f32_16x16x32_bf16 v[28:31], v[222:225], v[198:201], v[28:31]
	v_mfma_f32_16x16x32_bf16 v[24:27], v[230:233], v[198:201], v[24:27]
	v_mfma_f32_16x16x32_bf16 v[12:15], v[222:225], v[206:209], v[12:15]
	v_mfma_f32_16x16x32_bf16 v[8:11], v[230:233], v[206:209], v[8:11]
	v_mfma_f32_16x16x32_bf16 v[4:7], v[222:225], v[214:217], v[4:7]
	v_mfma_f32_16x16x32_bf16 v[0:3], v[230:233], v[214:217], v[0:3]
	s_setprio 0
	s_add_i32 s10, s10, 2
	s_add_u32 s76, s76, 0x100
	s_addc_u32 s77, s77, 0
	s_cmp_gt_u32 s10, 13
	s_mov_b64 s[34:35], s[36:37]
	s_barrier
	s_cbranch_scc0 .LBB0_688
	v_lshl_add_u32 v170, s69, 8, v144
	v_lshl_or_b32 v172, s75, 8, v146
	v_ashrrev_i32_e32 v171, 31, v170
	v_ashrrev_i32_e32 v173, 31, v172
	v_lshlrev_b64 v[174:175], 11, v[170:171]
	v_lshl_add_u64 v[174:175], s[14:15], 0, v[174:175]
	v_lshlrev_b64 v[172:173], 1, v[172:173]
	v_lshl_add_u64 v[174:175], v[174:175], 0, v[172:173]
	v_cvt_pk_bf16_f32 v60, v60, v61
	v_cvt_pk_bf16_f32 v61, v62, v63
	v_cvt_pk_bf16_f32 v62, v56, v57
	v_add_co_u32_e32 v56, vcc, s65, v174
	v_cvt_pk_bf16_f32 v68, v68, v69
	v_cvt_pk_bf16_f32 v69, v70, v71
	v_cvt_pk_bf16_f32 v70, v64, v65
	v_lshl_add_u64 v[64:65], v[174:175], 0, s[16:17]
	v_addc_co_u32_e32 v57, vcc, 0, v175, vcc
	v_cvt_pk_bf16_f32 v44, v44, v45
	v_cvt_pk_bf16_f32 v45, v46, v47
	v_cvt_pk_bf16_f32 v46, v40, v41
	v_cvt_pk_bf16_f32 v47, v42, v43
	v_cvt_pk_bf16_f32 v108, v108, v109
	v_cvt_pk_bf16_f32 v109, v110, v111
	v_cvt_pk_bf16_f32 v110, v104, v105
	v_or_b32_e32 v104, 16, v170
	global_store_dwordx4 v[64:65], v[44:47], off offset:256
	v_ashrrev_i32_e32 v105, 31, v104
	v_cvt_pk_bf16_f32 v92, v92, v93
	v_add_co_u32_e32 v46, vcc, s66, v174
	v_cvt_pk_bf16_f32 v93, v94, v95
	v_cvt_pk_bf16_f32 v94, v88, v89
	v_or_b32_e32 v88, 32, v170
	v_lshl_add_u64 v[44:45], v[174:175], 0, s[18:19]
	v_addc_co_u32_e32 v47, vcc, 0, v175, vcc
	v_cvt_pk_bf16_f32 v28, v28, v29
	v_cvt_pk_bf16_f32 v29, v30, v31
	v_cvt_pk_bf16_f32 v30, v24, v25
	v_cvt_pk_bf16_f32 v31, v26, v27
	v_lshlrev_b64 v[104:105], 11, v[104:105]
	v_ashrrev_i32_e32 v89, 31, v88
	v_cvt_pk_bf16_f32 v76, v76, v77
	v_cvt_pk_bf16_f32 v77, v78, v79
	v_cvt_pk_bf16_f32 v78, v72, v73
	v_or_b32_e32 v72, 48, v170
	global_store_dwordx4 v[44:45], v[28:31], off offset:256
	v_cvt_pk_bf16_f32 v111, v106, v107
	v_lshl_add_u64 v[104:105], s[14:15], 0, v[104:105]
	v_add_co_u32_e32 v30, vcc, s67, v174
	v_lshlrev_b64 v[88:89], 11, v[88:89]
	v_ashrrev_i32_e32 v73, 31, v72
	v_lshl_add_u64 v[28:29], v[174:175], 0, s[20:21]
	v_addc_co_u32_e32 v31, vcc, 0, v175, vcc
	v_cvt_pk_bf16_f32 v12, v12, v13
	v_cvt_pk_bf16_f32 v13, v14, v15
	v_cvt_pk_bf16_f32 v14, v8, v9
	v_cvt_pk_bf16_f32 v15, v10, v11
	global_store_dwordx4 v[174:175], v[108:111], off offset:256
	v_cvt_pk_bf16_f32 v95, v90, v91
	v_lshl_add_u64 v[88:89], s[14:15], 0, v[88:89]
	v_lshl_add_u64 v[108:109], v[104:105], 0, v[172:173]
	v_lshlrev_b64 v[72:73], 11, v[72:73]
	global_store_dwordx4 v[28:29], v[12:15], off offset:256
	global_store_dwordx4 v[108:109], v[92:95], off offset:256
	v_cvt_pk_bf16_f32 v79, v74, v75
	v_add_co_u32_e32 v14, vcc, s68, v174
	v_lshl_add_u64 v[92:93], v[88:89], 0, v[172:173]
	v_lshl_add_u64 v[72:73], s[14:15], 0, v[72:73]
	v_addc_co_u32_e32 v15, vcc, 0, v175, vcc
	v_cvt_pk_bf16_f32 v124, v124, v125
	v_cvt_pk_bf16_f32 v125, v126, v127
	v_cvt_pk_bf16_f32 v126, v120, v121
	v_cvt_pk_bf16_f32 v127, v122, v123
	v_cvt_pk_bf16_f32 v104, v116, v117
	v_cvt_pk_bf16_f32 v105, v118, v119
	v_cvt_pk_bf16_f32 v106, v112, v113
	v_cvt_pk_bf16_f32 v107, v114, v115
	v_cvt_pk_bf16_f32 v88, v100, v101
	v_cvt_pk_bf16_f32 v89, v102, v103
	v_cvt_pk_bf16_f32 v90, v96, v97
	v_cvt_pk_bf16_f32 v91, v98, v99
	global_store_dwordx4 v[92:93], v[76:79], off offset:256
	v_cvt_pk_bf16_f32 v74, v80, v81
	v_cvt_pk_bf16_f32 v75, v82, v83
	v_lshl_add_u64 v[76:77], v[72:73], 0, v[172:173]
	v_cvt_pk_bf16_f32 v72, v84, v85
	v_cvt_pk_bf16_f32 v73, v86, v87
	v_cvt_pk_bf16_f32 v71, v66, v67
	v_cvt_pk_bf16_f32 v63, v58, v59
	v_cvt_pk_bf16_f32 v40, v52, v53
	v_cvt_pk_bf16_f32 v41, v54, v55
	v_cvt_pk_bf16_f32 v42, v48, v49
	v_cvt_pk_bf16_f32 v43, v50, v51
	v_cvt_pk_bf16_f32 v24, v36, v37
	v_cvt_pk_bf16_f32 v25, v38, v39
	v_cvt_pk_bf16_f32 v26, v32, v33
	v_cvt_pk_bf16_f32 v27, v34, v35
	v_lshl_add_u64 v[12:13], v[174:175], 0, s[28:29]
	v_cvt_pk_bf16_f32 v8, v20, v21
	v_cvt_pk_bf16_f32 v9, v22, v23
	v_cvt_pk_bf16_f32 v10, v16, v17
	v_cvt_pk_bf16_f32 v11, v18, v19
	v_cvt_pk_bf16_f32 v4, v4, v5
	v_cvt_pk_bf16_f32 v5, v6, v7
	v_cvt_pk_bf16_f32 v6, v0, v1
	v_cvt_pk_bf16_f32 v7, v2, v3
	s_and_b64 vcc, exec, s[2:3]
	s_mov_b32 s75, s70
	s_mov_b32 s69, s71
	s_mov_b64 s[36:37], s[0:1]
	s_mov_b64 s[34:35], s[4:5]
	global_store_dwordx4 v[174:175], v[124:127], off
	global_store_dwordx4 v[108:109], v[104:107], off
	global_store_dwordx4 v[92:93], v[88:91], off
	global_store_dwordx4 v[76:77], v[72:75], off
	global_store_dwordx4 v[76:77], v[68:71], off offset:256
	global_store_dwordx4 v[56:57], v[60:63], off
	global_store_dwordx4 v[46:47], v[40:43], off
	global_store_dwordx4 v[30:31], v[24:27], off
	global_store_dwordx4 v[14:15], v[8:11], off
	global_store_dwordx4 v[12:13], v[4:7], off offset:256
	s_cbranch_vccz .LBB0_677
	s_waitcnt vmcnt(0)
	s_cmpk_gt_u32 s45, 0xff
	s_cbranch_scc1 .LBB0_692
	s_barrier

; #define PG8_STAGE(bufoff, gbase, voff) do { _Pragma("unroll") for (int _i = 0; _i < 2; ++_i) \
;         __builtin_amdgcn_global_load_lds((const unsigned*)((const char*)(gbase) + (voff)[_i]), (PG8_LAS unsigned*)(lds + (bufoff) + ldsw + _i * 8192), 16, 0, 0); } while (0)
; #define PG8_LDA(dst, b, h) do { _Pragma("unroll") for (int m = 0; m < 4; ++m) _Pragma("unroll") for (int k = 0; k < 2; ++k) dst[m][k] = *(const PG8_LAS bf16x8*)(lds + PG8_SA(b, h) + aoff + m * 2048 + k * 1024); } while (0)
; #define PG8_WAIT_V(n) asm volatile("s_waitcnt vmcnt(" #n ")" ::: "memory")
; #define PG8_WAIT_L(n) asm volatile("s_waitcnt lgkmcnt(" #n ")" ::: "memory")
; template <class Epi, class Sched, bool STAMP = false>
; __device__ __forceinline__ void gemm_phase(PG8_LAS unsigned char* lds, const Gemm g, const Sched& S, const Epi& E, unsigned long long* stamps) {
;     ...
;         const bool has_next = S.next(ui + 1, nxt);
;         const char* nA = has_next ? (const char*)g.A + (size_t)nxt.pm * tstep : cA; const char* nB = has_next ? (const char*)g.Bt + (size_t)nxt.pn * tstep : cB;
;         for (int t = 0; t < nt; t += 2) {
;             const bool last = (t == nt - 2);
;             const char* a1 = cA + (size_t)(t + 1) * kstep;
;             const char* a2 = last ? nA : cA + (size_t)(t + 2) * kstep; const char* b2 = last ? nB : cB + (size_t)(t + 2) * kstep;
;             const char* a3 = a2 + kstep; const char* b3 = b2 + kstep;
;             if (last && has_next) S.a_ready(nxt);
;             PG8_LDB(B0, 0, 0); PG8_SCHED; PG8_LDA(At, 0, 0); PG8_STAGE(PG8_SA(1, 1), a1 + hstep, voffA);
;             PG8_WAIT_L(8); PG8_BAR; PG8_WAIT_L(0); PG8_MMA(0, 0, At, B0); PG8_BAR; PG8_SCHED;
;             PG8_LDB(B1, 0, 1); PG8_STAGE(PG8_SB(0, 0), b2, voffB);
;             PG8_BAR; PG8_WAIT_L(0); PG8_MMA(0, 1, At, B1); PG8_BAR;
;             PG8_LDA(At, 0, 1); PG8_STAGE(PG8_SA(0, 0), a2, voffA);
;             PG8_BAR; PG8_WAIT_L(0); PG8_MMA(1, 0, At, B0); PG8_BAR; PG8_SCHED;
;             PG8_STAGE(PG8_SB(0, 1), b2 + hstep, voffB);
;             PG8_WAIT_V(6); PG8_BAR; PG8_MMA(1, 1, At, B1); PG8_BAR;
;     ...
; #pragma unroll
;         for (int a = 0; a < 2; ++a)
; #pragma unroll
;             for (int b = 0; b < 2; ++b)
; #pragma unroll
;                 for (int m = 0; m < 4; ++m)
; #pragma unroll
;                     for (int n = 0; n < 2; ++n) acc[a][b][m][n] = (f32x4){0.f, 0.f, 0.f, 0.f};
.LBB0_726:
	s_add_u32 s62, s18, 0x100
	s_addc_u32 s63, s19, 0
	s_mov_b32 s10, -2
	s_cmp_eq_u32 s46, s99
	s_cbranch_scc1 .Lgu4_half_loop_z
	ds_read_b128 v[140:143], v147
	ds_read_b128 v[170:173], v148
	ds_read_b128 v[174:177], v149
	ds_read_b128 v[178:181], v150
	s_add_u32 s18, s16, 0x100
	s_addc_u32 s19, s17, 0
	s_cmp_eq_u32 s10, 12
	s_cselect_b32 s29, s5, s19
	s_cselect_b32 s28, s4, s18
	s_cselect_b32 s21, s1, s63
	s_cselect_b32 s20, s0, s62
	s_mov_b32 m0, s55
	ds_read_b128 v[182:185], v145
	ds_read_b128 v[186:189], v145 offset:1024
	ds_read_b128 v[190:193], v145 offset:2048
	ds_read_b128 v[194:197], v145 offset:3072
	ds_read_b128 v[198:201], v145 offset:4096
	ds_read_b128 v[202:205], v145 offset:5120
	ds_read_b128 v[206:209], v145 offset:6144
	ds_read_b128 v[210:213], v145 offset:7168
	global_load_lds_dwordx4 v132, s[16:17]
	s_mov_b32 m0, s56
	s_nop 0
	global_load_lds_dwordx4 v134, s[16:17]
	s_waitcnt lgkmcnt(8)
	s_barrier
	s_waitcnt lgkmcnt(0)
	s_setprio 1
	s_waitcnt lgkmcnt(0)
	v_mfma_f32_16x16x32_bf16 v[124:127], v[140:143], v[182:185], 0
	v_mfma_f32_16x16x32_bf16 v[120:123], v[174:177], v[182:185], 0
	v_mfma_f32_16x16x32_bf16 v[108:111], v[140:143], v[190:193], 0
	v_mfma_f32_16x16x32_bf16 v[104:107], v[174:177], v[190:193], 0
	v_mfma_f32_16x16x32_bf16 v[92:95], v[140:143], v[198:201], 0
	v_mfma_f32_16x16x32_bf16 v[88:91], v[174:177], v[198:201], 0
	v_mfma_f32_16x16x32_bf16 v[76:79], v[140:143], v[206:209], 0
	v_mfma_f32_16x16x32_bf16 v[72:75], v[174:177], v[206:209], 0
	v_mfma_f32_16x16x32_bf16 v[124:127], v[170:173], v[186:189], v[124:127]
	v_mfma_f32_16x16x32_bf16 v[120:123], v[178:181], v[186:189], v[120:123]
	v_mfma_f32_16x16x32_bf16 v[108:111], v[170:173], v[194:197], v[108:111]
	v_mfma_f32_16x16x32_bf16 v[104:107], v[178:181], v[194:197], v[104:107]
	v_mfma_f32_16x16x32_bf16 v[92:95], v[170:173], v[202:205], v[92:95]
	v_mfma_f32_16x16x32_bf16 v[88:91], v[178:181], v[202:205], v[88:91]
	v_mfma_f32_16x16x32_bf16 v[76:79], v[170:173], v[210:213], v[76:79]
	v_mfma_f32_16x16x32_bf16 v[72:75], v[178:181], v[210:213], v[72:75]
	s_setprio 0
	s_barrier
	s_mov_b32 m0, s37
	ds_read_b128 v[214:217], v151
	ds_read_b128 v[218:221], v152
	ds_read_b128 v[222:225], v153
	ds_read_b128 v[226:229], v154
	global_load_lds_dwordx4 v130, s[20:21]
	s_mov_b32 m0, s40
	s_nop 0
	global_load_lds_dwordx4 v128, s[20:21]
	s_barrier
	s_waitcnt lgkmcnt(0)
	s_setprio 1
	s_waitcnt lgkmcnt(0)
	v_mfma_f32_16x16x32_bf16 v[116:119], v[214:217], v[182:185], 0
	v_mfma_f32_16x16x32_bf16 v[112:115], v[222:225], v[182:185], 0
	v_mfma_f32_16x16x32_bf16 v[100:103], v[214:217], v[190:193], 0
	v_mfma_f32_16x16x32_bf16 v[96:99], v[222:225], v[190:193], 0
	v_mfma_f32_16x16x32_bf16 v[84:87], v[214:217], v[198:201], 0
	v_mfma_f32_16x16x32_bf16 v[80:83], v[222:225], v[198:201], 0
	v_mfma_f32_16x16x32_bf16 v[68:71], v[214:217], v[206:209], 0
	v_mfma_f32_16x16x32_bf16 v[64:67], v[222:225], v[206:209], 0
	v_mfma_f32_16x16x32_bf16 v[116:119], v[218:221], v[186:189], v[116:119]
	v_mfma_f32_16x16x32_bf16 v[112:115], v[226:229], v[186:189], v[112:115]
	v_mfma_f32_16x16x32_bf16 v[100:103], v[218:221], v[194:197], v[100:103]
	v_mfma_f32_16x16x32_bf16 v[96:99], v[226:229], v[194:197], v[96:99]
	v_mfma_f32_16x16x32_bf16 v[84:87], v[218:221], v[202:205], v[84:87]
	v_mfma_f32_16x16x32_bf16 v[80:83], v[226:229], v[202:205], v[80:83]
	v_mfma_f32_16x16x32_bf16 v[68:71], v[218:221], v[210:213], v[68:71]
	v_mfma_f32_16x16x32_bf16 v[64:67], v[226:229], v[210:213], v[64:67]
	s_setprio 0
	s_mov_b32 m0, s34
	s_barrier
	ds_read_b128 v[182:185], v145 offset:16384
	ds_read_b128 v[186:189], v145 offset:17408
	ds_read_b128 v[190:193], v145 offset:18432
	ds_read_b128 v[194:197], v145 offset:19456
	ds_read_b128 v[198:201], v145 offset:20480
	ds_read_b128 v[202:205], v145 offset:21504
	ds_read_b128 v[206:209], v145 offset:22528
	ds_read_b128 v[210:213], v145 offset:23552
	global_load_lds_dwordx4 v130, s[28:29]
	s_mov_b32 m0, s41
	s_nop 0
	global_load_lds_dwordx4 v128, s[28:29]
	s_barrier
	s_waitcnt lgkmcnt(0)
	s_setprio 1
	s_waitcnt lgkmcnt(0)
	v_mfma_f32_16x16x32_bf16 v[60:63], v[140:143], v[182:185], 0
	v_mfma_f32_16x16x32_bf16 v[56:59], v[174:177], v[182:185], 0
	v_mfma_f32_16x16x32_bf16 v[44:47], v[140:143], v[190:193], 0
	v_mfma_f32_16x16x32_bf16 v[40:43], v[174:177], v[190:193], 0
	v_mfma_f32_16x16x32_bf16 v[28:31], v[140:143], v[198:201], 0
	v_mfma_f32_16x16x32_bf16 v[24:27], v[174:177], v[198:201], 0
	v_mfma_f32_16x16x32_bf16 v[12:15], v[140:143], v[206:209], 0
	v_mfma_f32_16x16x32_bf16 v[8:11], v[174:177], v[206:209], 0
	v_mfma_f32_16x16x32_bf16 v[60:63], v[170:173], v[186:189], v[60:63]
	v_mfma_f32_16x16x32_bf16 v[56:59], v[178:181], v[186:189], v[56:59]
	v_mfma_f32_16x16x32_bf16 v[44:47], v[170:173], v[194:197], v[44:47]
	v_mfma_f32_16x16x32_bf16 v[40:43], v[178:181], v[194:197], v[40:43]
	v_mfma_f32_16x16x32_bf16 v[28:31], v[170:173], v[202:205], v[28:31]
	v_mfma_f32_16x16x32_bf16 v[24:27], v[178:181], v[202:205], v[24:27]
	v_mfma_f32_16x16x32_bf16 v[12:15], v[170:173], v[210:213], v[12:15]
	v_mfma_f32_16x16x32_bf16 v[8:11], v[178:181], v[210:213], v[8:11]
	s_setprio 0
	s_barrier
	s_add_u32 s16, s20, 0x44000
	s_addc_u32 s17, s21, 0
	s_mov_b32 m0, s42
	s_nop 0
	global_load_lds_dwordx4 v130, s[16:17]
	s_mov_b32 m0, s43
	s_nop 0
	global_load_lds_dwordx4 v128, s[16:17]
	s_waitcnt vmcnt(6)
	s_barrier
	s_setprio 1
	v_mfma_f32_16x16x32_bf16 v[52:55], v[214:217], v[182:185], 0
	v_mfma_f32_16x16x32_bf16 v[48:51], v[222:225], v[182:185], 0
	v_mfma_f32_16x16x32_bf16 v[36:39], v[214:217], v[190:193], 0
	v_mfma_f32_16x16x32_bf16 v[32:35], v[222:225], v[190:193], 0
	v_mfma_f32_16x16x32_bf16 v[20:23], v[214:217], v[198:201], 0
	v_mfma_f32_16x16x32_bf16 v[16:19], v[222:225], v[198:201], 0
	v_mfma_f32_16x16x32_bf16 v[4:7], v[214:217], v[206:209], 0
	v_mfma_f32_16x16x32_bf16 v[0:3], v[222:225], v[206:209], 0
	v_mfma_f32_16x16x32_bf16 v[52:55], v[218:221], v[186:189], v[52:55]
	v_mfma_f32_16x16x32_bf16 v[48:51], v[226:229], v[186:189], v[48:51]
	v_mfma_f32_16x16x32_bf16 v[36:39], v[218:221], v[194:197], v[36:39]
	v_mfma_f32_16x16x32_bf16 v[32:35], v[226:229], v[194:197], v[32:35]
	v_mfma_f32_16x16x32_bf16 v[20:23], v[218:221], v[202:205], v[20:23]
	v_mfma_f32_16x16x32_bf16 v[16:19], v[226:229], v[202:205], v[16:19]
	v_mfma_f32_16x16x32_bf16 v[4:7], v[218:221], v[210:213], v[4:7]
	v_mfma_f32_16x16x32_bf16 v[0:3], v[226:229], v[210:213], v[0:3]
	s_setprio 0
	s_barrier
	s_branch .Lzp11_mid

; #define PG8_STAGE(bufoff, gbase, voff) do { _Pragma("unroll") for (int _i = 0; _i < 2; ++_i) \
;         __builtin_amdgcn_global_load_lds((const unsigned*)((const char*)(gbase) + (voff)[_i]), (PG8_LAS unsigned*)(lds + (bufoff) + ldsw + _i * 8192), 16, 0, 0); } while (0)
; #define PG8_LDA(dst, b, h) do { _Pragma("unroll") for (int m = 0; m < 4; ++m) _Pragma("unroll") for (int k = 0; k < 2; ++k) dst[m][k] = *(const PG8_LAS bf16x8*)(lds + PG8_SA(b, h) + aoff + m * 2048 + k * 1024); } while (0)
; #define PG8_LDB(dst, b, h) do { _Pragma("unroll") for (int n = 0; n < 2; ++n) _Pragma("unroll") for (int k = 0; k < 2; ++k) dst[n][k] = *(const PG8_LAS bf16x8*)(lds + PG8_SB(b, h) + boff + n * 2048 + k * 1024); } while (0)
; #define PG8_MMA(ai, bj, At, Bt) do { __builtin_amdgcn_s_setprio(1); _Pragma("unroll") for (int m = 0; m < 4; ++m) _Pragma("unroll") for (int n = 0; n < 2; ++n) _Pragma("unroll") for (int k = 0; k < 2; ++k) \
;         acc[ai][bj][m][n] = __builtin_amdgcn_mfma_f32_16x16x32_bf16(Bt[n][k], At[m][k], acc[ai][bj][m][n], 0, 0, 0); __builtin_amdgcn_s_setprio(0); } while (0)
; #define PG8_WAIT_V(n) asm volatile("s_waitcnt vmcnt(" #n ")" ::: "memory")
; #define PG8_WAIT_L(n) asm volatile("s_waitcnt lgkmcnt(" #n ")" ::: "memory")
; #define PG8_BAR __builtin_amdgcn_s_barrier()
; #define PG8_SCHED __builtin_amdgcn_sched_barrier(0)
; template <class Epi, class Sched, bool STAMP = false>
; __device__ __forceinline__ void gemm_phase(PG8_LAS unsigned char* lds, const Gemm g, const Sched& S, const Epi& E, unsigned long long* stamps) {
;     ...
;             PG8_LDB(B0, 1, 0); PG8_SCHED; PG8_LDA(At, 1, 0); PG8_STAGE(PG8_SA(0, 1), a2 + hstep, voffA);
;             PG8_WAIT_L(8); PG8_BAR; PG8_WAIT_L(0); PG8_MMA(0, 0, At, B0); PG8_BAR; PG8_SCHED;
;             PG8_LDB(B1, 1, 1); PG8_STAGE(PG8_SB(1, 0), b3, voffB);
;             PG8_BAR; PG8_WAIT_L(0); PG8_MMA(0, 1, At, B1); PG8_BAR;
;             PG8_LDA(At, 1, 1); PG8_STAGE(PG8_SA(1, 0), a3, voffA);
;             PG8_BAR; PG8_WAIT_L(0); PG8_MMA(1, 0, At, B0); PG8_BAR; PG8_SCHED;
;             PG8_STAGE(PG8_SB(1, 1), b3 + hstep, voffB);
;             PG8_WAIT_V(6); PG8_BAR; PG8_MMA(1, 1, At, B1); PG8_BAR;
.Lzp11_mid:
	ds_read_b128 v[140:143], v155
	ds_read_b128 v[170:173], v156
	ds_read_b128 v[174:177], v157
	ds_read_b128 v[178:181], v165
	s_add_u32 s16, s28, 0x44000
	s_addc_u32 s17, s29, 0
	s_mov_b32 m0, s44
	ds_read_b128 v[182:185], v145 offset:32768
	ds_read_b128 v[186:189], v145 offset:33792
	ds_read_b128 v[190:193], v145 offset:34816
	ds_read_b128 v[194:197], v145 offset:35840
	ds_read_b128 v[198:201], v145 offset:36864
	ds_read_b128 v[202:205], v145 offset:37888
	ds_read_b128 v[206:209], v145 offset:38912
	ds_read_b128 v[210:213], v145 offset:39936
	global_load_lds_dwordx4 v130, s[16:17]
	s_mov_b32 m0, s45
	s_nop 0
	global_load_lds_dwordx4 v128, s[16:17]
	s_waitcnt lgkmcnt(8)
	s_barrier
	s_waitcnt lgkmcnt(0)
	s_setprio 1
	s_waitcnt lgkmcnt(0)
	v_mfma_f32_16x16x32_bf16 v[124:127], v[140:143], v[182:185], v[124:127]
	v_mfma_f32_16x16x32_bf16 v[120:123], v[174:177], v[182:185], v[120:123]
	v_mfma_f32_16x16x32_bf16 v[108:111], v[140:143], v[190:193], v[108:111]
	v_mfma_f32_16x16x32_bf16 v[104:107], v[174:177], v[190:193], v[104:107]
	v_mfma_f32_16x16x32_bf16 v[92:95], v[140:143], v[198:201], v[92:95]
	v_mfma_f32_16x16x32_bf16 v[88:91], v[174:177], v[198:201], v[88:91]
	v_mfma_f32_16x16x32_bf16 v[76:79], v[140:143], v[206:209], v[76:79]
	v_mfma_f32_16x16x32_bf16 v[72:75], v[174:177], v[206:209], v[72:75]
	v_mfma_f32_16x16x32_bf16 v[124:127], v[170:173], v[186:189], v[124:127]
	v_mfma_f32_16x16x32_bf16 v[120:123], v[178:181], v[186:189], v[120:123]
	v_mfma_f32_16x16x32_bf16 v[108:111], v[170:173], v[194:197], v[108:111]
	v_mfma_f32_16x16x32_bf16 v[104:107], v[178:181], v[194:197], v[104:107]
	v_mfma_f32_16x16x32_bf16 v[92:95], v[170:173], v[202:205], v[92:95]
	v_mfma_f32_16x16x32_bf16 v[88:91], v[178:181], v[202:205], v[88:91]
	v_mfma_f32_16x16x32_bf16 v[76:79], v[170:173], v[210:213], v[76:79]
	v_mfma_f32_16x16x32_bf16 v[72:75], v[178:181], v[210:213], v[72:75]
	s_setprio 0
	s_barrier
	s_mov_b32 m0, s48
	ds_read_b128 v[214:217], v166
	ds_read_b128 v[218:221], v167
	ds_read_b128 v[222:225], v168
	ds_read_b128 v[226:229], v169
	s_add_u32 s100, s20, 0x80
	s_addc_u32 s101, s21, 0
	global_load_lds_dwordx4 v130, s[100:101]
	s_mov_b32 m0, s49
	s_nop 0
	global_load_lds_dwordx4 v128, s[100:101]
	s_barrier
	s_waitcnt lgkmcnt(0)
	s_setprio 1
	s_waitcnt lgkmcnt(0)
	v_mfma_f32_16x16x32_bf16 v[116:119], v[214:217], v[182:185], v[116:119]
	v_mfma_f32_16x16x32_bf16 v[112:115], v[222:225], v[182:185], v[112:115]
	v_mfma_f32_16x16x32_bf16 v[100:103], v[214:217], v[190:193], v[100:103]
	v_mfma_f32_16x16x32_bf16 v[96:99], v[222:225], v[190:193], v[96:99]
	v_mfma_f32_16x16x32_bf16 v[84:87], v[214:217], v[198:201], v[84:87]
	v_mfma_f32_16x16x32_bf16 v[80:83], v[222:225], v[198:201], v[80:83]
	v_mfma_f32_16x16x32_bf16 v[68:71], v[214:217], v[206:209], v[68:71]
	v_mfma_f32_16x16x32_bf16 v[64:67], v[222:225], v[206:209], v[64:67]
	v_mfma_f32_16x16x32_bf16 v[116:119], v[218:221], v[186:189], v[116:119]
	v_mfma_f32_16x16x32_bf16 v[112:115], v[226:229], v[186:189], v[112:115]
	v_mfma_f32_16x16x32_bf16 v[100:103], v[218:221], v[194:197], v[100:103]
	v_mfma_f32_16x16x32_bf16 v[96:99], v[226:229], v[194:197], v[96:99]
	v_mfma_f32_16x16x32_bf16 v[84:87], v[218:221], v[202:205], v[84:87]
	v_mfma_f32_16x16x32_bf16 v[80:83], v[226:229], v[202:205], v[80:83]
	v_mfma_f32_16x16x32_bf16 v[68:71], v[218:221], v[210:213], v[68:71]
	v_mfma_f32_16x16x32_bf16 v[64:67], v[226:229], v[210:213], v[64:67]
	s_setprio 0
	s_mov_b32 m0, s50
	s_barrier
	ds_read_b128 v[182:185], v145 offset:49152
	ds_read_b128 v[186:189], v145 offset:50176
	ds_read_b128 v[190:193], v145 offset:51200
	ds_read_b128 v[194:197], v145 offset:52224
	ds_read_b128 v[198:201], v145 offset:53248
	ds_read_b128 v[202:205], v145 offset:54272
	ds_read_b128 v[206:209], v145 offset:55296
	ds_read_b128 v[210:213], v145 offset:56320
	s_add_u32 s100, s28, 0x80
	s_addc_u32 s101, s29, 0
	global_load_lds_dwordx4 v130, s[100:101]
	s_mov_b32 m0, s51
	s_nop 0
	global_load_lds_dwordx4 v128, s[100:101]
	s_barrier
	s_waitcnt lgkmcnt(0)
	s_setprio 1
	s_waitcnt lgkmcnt(0)
	v_mfma_f32_16x16x32_bf16 v[60:63], v[140:143], v[182:185], v[60:63]
	v_mfma_f32_16x16x32_bf16 v[56:59], v[174:177], v[182:185], v[56:59]
	v_mfma_f32_16x16x32_bf16 v[44:47], v[140:143], v[190:193], v[44:47]
	v_mfma_f32_16x16x32_bf16 v[40:43], v[174:177], v[190:193], v[40:43]
	v_mfma_f32_16x16x32_bf16 v[28:31], v[140:143], v[198:201], v[28:31]
	v_mfma_f32_16x16x32_bf16 v[24:27], v[174:177], v[198:201], v[24:27]
	v_mfma_f32_16x16x32_bf16 v[12:15], v[140:143], v[206:209], v[12:15]
	v_mfma_f32_16x16x32_bf16 v[8:11], v[174:177], v[206:209], v[8:11]
	v_mfma_f32_16x16x32_bf16 v[60:63], v[170:173], v[186:189], v[60:63]
	v_mfma_f32_16x16x32_bf16 v[56:59], v[178:181], v[186:189], v[56:59]
	v_mfma_f32_16x16x32_bf16 v[44:47], v[170:173], v[194:197], v[44:47]
	v_mfma_f32_16x16x32_bf16 v[40:43], v[178:181], v[194:197], v[40:43]
	v_mfma_f32_16x16x32_bf16 v[28:31], v[170:173], v[202:205], v[28:31]
	v_mfma_f32_16x16x32_bf16 v[24:27], v[178:181], v[202:205], v[24:27]
	v_mfma_f32_16x16x32_bf16 v[12:15], v[170:173], v[210:213], v[12:15]
	v_mfma_f32_16x16x32_bf16 v[8:11], v[178:181], v[210:213], v[8:11]
	s_setprio 0
	s_barrier
	s_add_u32 s16, s20, 0x44080
	s_addc_u32 s17, s21, 0
	s_mov_b32 m0, s52
	s_nop 0
	global_load_lds_dwordx4 v130, s[16:17]
	s_mov_b32 m0, s53
	s_nop 0
	global_load_lds_dwordx4 v128, s[16:17]
	s_waitcnt vmcnt(6)
	s_barrier
; DI float ex2(float x) { return __builtin_amdgcn_exp2f(x); }
; #define PG8_STAMP() do { if (STAMP && wid == 0 && nts < 64) { const unsigned long long _c = 0ull; \
;         ts_lo = (lane == nts) ? (int)(unsigned)_c : ts_lo; ts_hi = (lane == nts) ? (int)(unsigned)(_c >> 32) : ts_hi; ++nts; } } while (0)
; #define PG8_MMA(ai, bj, At, Bt) do { __builtin_amdgcn_s_setprio(1); _Pragma("unroll") for (int m = 0; m < 4; ++m) _Pragma("unroll") for (int n = 0; n < 2; ++n) _Pragma("unroll") for (int k = 0; k < 2; ++k) \
;         acc[ai][bj][m][n] = __builtin_amdgcn_mfma_f32_16x16x32_bf16(Bt[n][k], At[m][k], acc[ai][bj][m][n], 0, 0, 0); __builtin_amdgcn_s_setprio(0); } while (0)
; #define PG8_WAIT_V(n) asm volatile("s_waitcnt vmcnt(" #n ")" ::: "memory")
; #define PG8_BAR __builtin_amdgcn_s_barrier()
;     DI void operator()(const f32x4 (&acc)[2][2][4][2], const Unit& u, int wr, int wc, int fr, int fq) const {
;         const int row0 = u.pm * BM + wr * 64 + fr, hcol0 = ((u.pn * BM + wc * 32) >> 1) + 4 * fq;
; #pragma unroll
;         for (int ai = 0; ai < 2; ++ai)
; #pragma unroll
;             for (int m = 0; m < 4; ++m) { u16* rowp = O + (size_t)(row0 + ai * HALF + m * 16) * ldc + hcol0;
; #pragma unroll
;                 for (int bj = 0; bj < 2; ++bj) { const f32x4 g = acc[ai][bj][m][0], up = acc[ai][bj][m][1]; float r[4];
; #pragma unroll
;                     for (int j = 0; j < 4; ++j) r[j] = g[j] * up[j] * __builtin_amdgcn_rcpf(1.f + ex2(-LOG2E * g[j]));
;                     uint2 w = {pack2(r[0], r[1]), pack2(r[2], r[3])}; *(uint2*)(rowp + bj * (HALF / 2)) = w; } }
; template <class Epi, class Sched, bool STAMP = false>
; __device__ __forceinline__ void gemm_phase(PG8_LAS unsigned char* lds, const Gemm g, const Sched& S, const Epi& E, unsigned long long* stamps) {
;     ...
;             PG8_WAIT_V(6); PG8_BAR; PG8_MMA(1, 1, At, B1); PG8_BAR;
;         }
;         PG8_STAMP();
;         if constexpr (!Epi::AFTER_DRAIN) { E(acc, cur, wr, wc, fr, fq); S.done(cur); }
	s_setprio 1
	v_mfma_f32_16x16x32_bf16 v[52:55], v[214:217], v[182:185], v[52:55]
	v_mfma_f32_16x16x32_bf16 v[48:51], v[222:225], v[182:185], v[48:51]
	v_mfma_f32_16x16x32_bf16 v[36:39], v[214:217], v[190:193], v[36:39]
	v_mfma_f32_16x16x32_bf16 v[32:35], v[222:225], v[190:193], v[32:35]
	v_mfma_f32_16x16x32_bf16 v[20:23], v[214:217], v[198:201], v[20:23]
	v_mfma_f32_16x16x32_bf16 v[16:19], v[222:225], v[198:201], v[16:19]
	v_mfma_f32_16x16x32_bf16 v[4:7], v[214:217], v[206:209], v[4:7]
	v_mfma_f32_16x16x32_bf16 v[0:3], v[222:225], v[206:209], v[0:3]
	v_mfma_f32_16x16x32_bf16 v[52:55], v[218:221], v[186:189], v[52:55]
	v_mfma_f32_16x16x32_bf16 v[48:51], v[226:229], v[186:189], v[48:51]
	v_mfma_f32_16x16x32_bf16 v[36:39], v[218:221], v[194:197], v[36:39]
	v_mfma_f32_16x16x32_bf16 v[32:35], v[226:229], v[194:197], v[32:35]
	v_mfma_f32_16x16x32_bf16 v[20:23], v[218:221], v[202:205], v[20:23]
	v_mfma_f32_16x16x32_bf16 v[16:19], v[226:229], v[202:205], v[16:19]
	v_mfma_f32_16x16x32_bf16 v[4:7], v[218:221], v[210:213], v[4:7]
	v_mfma_f32_16x16x32_bf16 v[0:3], v[226:229], v[210:213], v[0:3]
	s_setprio 0
	s_add_i32 s10, s10, 2
	s_add_u32 s62, s62, 0x100
	s_addc_u32 s63, s63, 0
	s_cmp_gt_u32 s10, 13
	s_mov_b64 s[16:17], s[18:19]
	s_barrier
	s_cbranch_scc0 .LBB0_727
	v_mul_f32_e32 v171, 0xbfb8aa3b, v124
	v_exp_f32_e32 v171, v171
	v_mul_f32_e32 v174, 0xbfb8aa3b, v125
	v_exp_f32_e32 v175, v174
	s_lshl_b32 s10, s61, 8
	v_add_f32_e32 v171, 1.0, v171
	v_rcp_f32_e32 v174, v171
	v_add_f32_e32 v171, 1.0, v175
	v_mul_f32_e32 v175, 0xbfb8aa3b, v126
	v_exp_f32_e32 v176, v175
	v_mul_f32_e32 v175, 0xbfb8aa3b, v127
	v_exp_f32_e32 v177, v175
	v_rcp_f32_e32 v175, v171
	v_add_f32_e32 v171, 1.0, v176
	v_rcp_f32_e32 v176, v171
	v_add_f32_e32 v171, 1.0, v177
	v_rcp_f32_e32 v177, v171
	v_pk_mul_f32 v[122:123], v[126:127], v[122:123]
	v_pk_mul_f32 v[120:121], v[124:125], v[120:121]
	s_or_b32 s10, s10, s47
	v_pk_mul_f32 v[120:121], v[120:121], v[174:175]
	v_pk_mul_f32 v[122:123], v[122:123], v[176:177]
	s_ashr_i32 s10, s10, 1
	v_cvt_pk_bf16_f32 v120, v120, v121
	v_cvt_pk_bf16_f32 v121, v122, v123
	v_mul_f32_e32 v122, 0xbfb8aa3b, v116
	v_mul_f32_e32 v123, 0xbfb8aa3b, v117
	v_or_b32_e32 v140, s10, v146
	v_exp_f32_e32 v122, v122
	v_exp_f32_e32 v123, v123
	v_lshl_add_u32 v170, s60, 8, v144
	v_ashrrev_i32_e32 v141, 31, v140
	v_mov_b64_e32 v[142:143], s[12:13]
	v_mad_i64_i32 v[172:173], s[16:17], v170, s57, v[142:143]
	v_lshlrev_b64 v[140:141], 1, v[140:141]
	v_lshl_add_u64 v[172:173], v[172:173], 0, v[140:141]
	global_store_dwordx2 v[172:173], v[120:121], off
	v_add_f32_e32 v120, 1.0, v122
	v_add_f32_e32 v121, 1.0, v123
	v_mul_f32_e32 v122, 0xbfb8aa3b, v118
	v_mul_f32_e32 v123, 0xbfb8aa3b, v119
	v_exp_f32_e32 v122, v122
	v_exp_f32_e32 v123, v123
	v_rcp_f32_e32 v120, v120
	v_rcp_f32_e32 v121, v121
	v_add_f32_e32 v122, 1.0, v122
	v_add_f32_e32 v123, 1.0, v123
	v_rcp_f32_e32 v122, v122
	v_rcp_f32_e32 v123, v123
	v_pk_mul_f32 v[114:115], v[118:119], v[114:115]
	v_pk_mul_f32 v[112:113], v[116:117], v[112:113]
	v_mul_f32_e32 v116, 0xbfb8aa3b, v110
	v_pk_mul_f32 v[112:113], v[112:113], v[120:121]
	v_pk_mul_f32 v[114:115], v[114:115], v[122:123]
	v_cvt_pk_bf16_f32 v112, v112, v113
	v_cvt_pk_bf16_f32 v113, v114, v115
	v_mul_f32_e32 v114, 0xbfb8aa3b, v108
	v_mul_f32_e32 v115, 0xbfb8aa3b, v109
	v_mul_f32_e32 v117, 0xbfb8aa3b, v111
	v_exp_f32_e32 v114, v114
	v_exp_f32_e32 v115, v115
	v_exp_f32_e32 v116, v116
	v_exp_f32_e32 v117, v117
	v_add_f32_e32 v114, 1.0, v114
	v_add_f32_e32 v115, 1.0, v115
	v_add_f32_e32 v116, 1.0, v116
	v_add_f32_e32 v117, 1.0, v117
	v_rcp_f32_e32 v114, v114
	v_rcp_f32_e32 v115, v115
	v_rcp_f32_e32 v116, v116
	v_rcp_f32_e32 v117, v117
	v_pk_mul_f32 v[106:107], v[110:111], v[106:107]
	v_pk_mul_f32 v[104:105], v[108:109], v[104:105]
	global_store_dwordx2 v[172:173], v[112:113], off offset:128
	v_pk_mul_f32 v[104:105], v[104:105], v[114:115]
	v_pk_mul_f32 v[106:107], v[106:107], v[116:117]
	v_cvt_pk_bf16_f32 v104, v104, v105
	v_cvt_pk_bf16_f32 v105, v106, v107
	v_mul_f32_e32 v106, 0xbfb8aa3b, v100
	v_mul_f32_e32 v107, 0xbfb8aa3b, v101
	v_exp_f32_e32 v106, v106
	v_exp_f32_e32 v107, v107
	v_or_b32_e32 v112, 16, v170
	v_mad_i64_i32 v[112:113], s[16:17], v112, s57, v[142:143]
	v_lshl_add_u64 v[112:113], v[112:113], 0, v[140:141]
	global_store_dwordx2 v[112:113], v[104:105], off
	v_add_f32_e32 v104, 1.0, v106
	v_add_f32_e32 v105, 1.0, v107
	v_mul_f32_e32 v106, 0xbfb8aa3b, v102
	v_mul_f32_e32 v107, 0xbfb8aa3b, v103
	v_exp_f32_e32 v106, v106
	v_exp_f32_e32 v107, v107
	v_rcp_f32_e32 v104, v104
	v_rcp_f32_e32 v105, v105
	v_add_f32_e32 v106, 1.0, v106
	v_add_f32_e32 v107, 1.0, v107
	v_rcp_f32_e32 v106, v106
	v_rcp_f32_e32 v107, v107
	v_pk_mul_f32 v[98:99], v[102:103], v[98:99]
	v_pk_mul_f32 v[96:97], v[100:101], v[96:97]
	v_mul_f32_e32 v100, 0xbfb8aa3b, v94
	v_pk_mul_f32 v[96:97], v[96:97], v[104:105]
	v_pk_mul_f32 v[98:99], v[98:99], v[106:107]
	v_cvt_pk_bf16_f32 v96, v96, v97
	v_cvt_pk_bf16_f32 v97, v98, v99
	v_mul_f32_e32 v98, 0xbfb8aa3b, v92
	v_mul_f32_e32 v99, 0xbfb8aa3b, v93
	v_mul_f32_e32 v101, 0xbfb8aa3b, v95
	v_exp_f32_e32 v98, v98
	v_exp_f32_e32 v99, v99
	v_exp_f32_e32 v100, v100
	v_exp_f32_e32 v101, v101
	v_add_f32_e32 v98, 1.0, v98
	v_add_f32_e32 v99, 1.0, v99
	v_add_f32_e32 v100, 1.0, v100
	v_add_f32_e32 v101, 1.0, v101
	v_rcp_f32_e32 v98, v98
	v_rcp_f32_e32 v99, v99
	v_rcp_f32_e32 v100, v100
	v_rcp_f32_e32 v101, v101
	v_pk_mul_f32 v[90:91], v[94:95], v[90:91]
	v_pk_mul_f32 v[88:89], v[92:93], v[88:89]
	global_store_dwordx2 v[112:113], v[96:97], off offset:128
	v_pk_mul_f32 v[88:89], v[88:89], v[98:99]
	v_pk_mul_f32 v[90:91], v[90:91], v[100:101]
; DI float ex2(float x) { return __builtin_amdgcn_exp2f(x); }
;     DI void operator()(const f32x4 (&acc)[2][2][4][2], const Unit& u, int wr, int wc, int fr, int fq) const {
;     ...
;             for (int m = 0; m < 4; ++m) { u16* rowp = O + (size_t)(row0 + ai * HALF + m * 16) * ldc + hcol0;
; #pragma unroll
;                 for (int bj = 0; bj < 2; ++bj) { const f32x4 g = acc[ai][bj][m][0], up = acc[ai][bj][m][1]; float r[4];
; #pragma unroll
;                     for (int j = 0; j < 4; ++j) r[j] = g[j] * up[j] * __builtin_amdgcn_rcpf(1.f + ex2(-LOG2E * g[j]));
;                     uint2 w = {pack2(r[0], r[1]), pack2(r[2], r[3])}; *(uint2*)(rowp + bj * (HALF / 2)) = w; } }
	v_cvt_pk_bf16_f32 v88, v88, v89
	v_cvt_pk_bf16_f32 v89, v90, v91
	v_mul_f32_e32 v90, 0xbfb8aa3b, v84
	v_mul_f32_e32 v91, 0xbfb8aa3b, v85
	v_exp_f32_e32 v90, v90
	v_exp_f32_e32 v91, v91
	v_or_b32_e32 v96, 32, v170
	v_mad_i64_i32 v[96:97], s[16:17], v96, s57, v[142:143]
	v_lshl_add_u64 v[96:97], v[96:97], 0, v[140:141]
	global_store_dwordx2 v[96:97], v[88:89], off
	v_add_f32_e32 v88, 1.0, v90
	v_add_f32_e32 v89, 1.0, v91
	v_mul_f32_e32 v90, 0xbfb8aa3b, v86
	v_mul_f32_e32 v91, 0xbfb8aa3b, v87
	v_exp_f32_e32 v90, v90
	v_exp_f32_e32 v91, v91
	v_rcp_f32_e32 v88, v88
	v_rcp_f32_e32 v89, v89
	v_add_f32_e32 v90, 1.0, v90
	v_add_f32_e32 v91, 1.0, v91
	v_rcp_f32_e32 v90, v90
	v_rcp_f32_e32 v91, v91
	v_pk_mul_f32 v[82:83], v[86:87], v[82:83]
	v_pk_mul_f32 v[80:81], v[84:85], v[80:81]
	v_mul_f32_e32 v84, 0xbfb8aa3b, v78
	v_pk_mul_f32 v[80:81], v[80:81], v[88:89]
	v_pk_mul_f32 v[82:83], v[82:83], v[90:91]
	v_cvt_pk_bf16_f32 v80, v80, v81
	v_cvt_pk_bf16_f32 v81, v82, v83
	v_mul_f32_e32 v82, 0xbfb8aa3b, v76
	v_mul_f32_e32 v83, 0xbfb8aa3b, v77
	v_mul_f32_e32 v85, 0xbfb8aa3b, v79
	v_exp_f32_e32 v82, v82
	v_exp_f32_e32 v83, v83
	v_exp_f32_e32 v84, v84
	v_exp_f32_e32 v85, v85
	v_add_f32_e32 v82, 1.0, v82
	v_add_f32_e32 v83, 1.0, v83
	v_add_f32_e32 v84, 1.0, v84
	v_add_f32_e32 v85, 1.0, v85
	v_rcp_f32_e32 v82, v82
	v_rcp_f32_e32 v83, v83
	v_rcp_f32_e32 v84, v84
	v_rcp_f32_e32 v85, v85
	v_pk_mul_f32 v[74:75], v[78:79], v[74:75]
	v_pk_mul_f32 v[72:73], v[76:77], v[72:73]
	global_store_dwordx2 v[96:97], v[80:81], off offset:128
	v_pk_mul_f32 v[72:73], v[72:73], v[82:83]
	v_pk_mul_f32 v[74:75], v[74:75], v[84:85]
	v_cvt_pk_bf16_f32 v72, v72, v73
	v_cvt_pk_bf16_f32 v73, v74, v75
	v_mul_f32_e32 v74, 0xbfb8aa3b, v68
	v_mul_f32_e32 v75, 0xbfb8aa3b, v69
	v_exp_f32_e32 v74, v74
	v_exp_f32_e32 v75, v75
	v_or_b32_e32 v80, 48, v170
	v_mad_i64_i32 v[80:81], s[16:17], v80, s57, v[142:143]
	v_lshl_add_u64 v[80:81], v[80:81], 0, v[140:141]
	global_store_dwordx2 v[80:81], v[72:73], off
	v_add_f32_e32 v72, 1.0, v74
	v_add_f32_e32 v73, 1.0, v75
	v_mul_f32_e32 v74, 0xbfb8aa3b, v70
	v_mul_f32_e32 v75, 0xbfb8aa3b, v71
	v_exp_f32_e32 v74, v74
	v_exp_f32_e32 v75, v75
	v_rcp_f32_e32 v72, v72
	v_rcp_f32_e32 v73, v73
	v_add_f32_e32 v74, 1.0, v74
	v_add_f32_e32 v75, 1.0, v75
	v_rcp_f32_e32 v74, v74
	v_rcp_f32_e32 v75, v75
	v_pk_mul_f32 v[66:67], v[70:71], v[66:67]
	v_pk_mul_f32 v[64:65], v[68:69], v[64:65]
	v_mul_f32_e32 v68, 0xbfb8aa3b, v62
	v_pk_mul_f32 v[64:65], v[64:65], v[72:73]
	v_pk_mul_f32 v[66:67], v[66:67], v[74:75]
	v_cvt_pk_bf16_f32 v64, v64, v65
	v_cvt_pk_bf16_f32 v65, v66, v67
	v_mul_f32_e32 v66, 0xbfb8aa3b, v60
	v_mul_f32_e32 v67, 0xbfb8aa3b, v61
	v_mul_f32_e32 v69, 0xbfb8aa3b, v63
	v_exp_f32_e32 v66, v66
	v_exp_f32_e32 v67, v67
	v_exp_f32_e32 v68, v68
	v_exp_f32_e32 v69, v69
	v_add_f32_e32 v66, 1.0, v66
	v_add_f32_e32 v67, 1.0, v67
	v_add_f32_e32 v68, 1.0, v68
	v_add_f32_e32 v69, 1.0, v69
	v_rcp_f32_e32 v66, v66
	v_rcp_f32_e32 v67, v67
	v_rcp_f32_e32 v68, v68
	v_rcp_f32_e32 v69, v69
	v_pk_mul_f32 v[58:59], v[62:63], v[58:59]
	v_pk_mul_f32 v[56:57], v[60:61], v[56:57]
	global_store_dwordx2 v[80:81], v[64:65], off offset:128
	v_pk_mul_f32 v[56:57], v[56:57], v[66:67]
	v_pk_mul_f32 v[58:59], v[58:59], v[68:69]
	v_cvt_pk_bf16_f32 v56, v56, v57
	v_cvt_pk_bf16_f32 v57, v58, v59
	v_mul_f32_e32 v58, 0xbfb8aa3b, v52
	v_mul_f32_e32 v59, 0xbfb8aa3b, v53
	v_exp_f32_e32 v58, v58
	v_exp_f32_e32 v59, v59
	v_add_u32_e32 v64, 0x80, v170
	v_mad_i64_i32 v[64:65], s[16:17], v64, s57, v[142:143]
	v_lshl_add_u64 v[64:65], v[64:65], 0, v[140:141]
	global_store_dwordx2 v[64:65], v[56:57], off
	v_add_f32_e32 v56, 1.0, v58
	v_add_f32_e32 v57, 1.0, v59
	v_mul_f32_e32 v58, 0xbfb8aa3b, v54
	v_mul_f32_e32 v59, 0xbfb8aa3b, v55
	v_exp_f32_e32 v58, v58
	v_exp_f32_e32 v59, v59
	v_rcp_f32_e32 v56, v56
	v_rcp_f32_e32 v57, v57
	v_add_f32_e32 v58, 1.0, v58
	v_add_f32_e32 v59, 1.0, v59
	v_rcp_f32_e32 v58, v58
	v_rcp_f32_e32 v59, v59
	v_pk_mul_f32 v[50:51], v[54:55], v[50:51]
	v_pk_mul_f32 v[48:49], v[52:53], v[48:49]
	v_mul_f32_e32 v52, 0xbfb8aa3b, v46
	v_pk_mul_f32 v[48:49], v[48:49], v[56:57]
	v_pk_mul_f32 v[50:51], v[50:51], v[58:59]
	v_cvt_pk_bf16_f32 v48, v48, v49
	v_cvt_pk_bf16_f32 v49, v50, v51
	v_mul_f32_e32 v50, 0xbfb8aa3b, v44
	v_mul_f32_e32 v51, 0xbfb8aa3b, v45
	v_mul_f32_e32 v53, 0xbfb8aa3b, v47
	v_exp_f32_e32 v50, v50
	v_exp_f32_e32 v51, v51
	v_exp_f32_e32 v52, v52
	v_exp_f32_e32 v53, v53
	v_add_f32_e32 v50, 1.0, v50
	v_add_f32_e32 v51, 1.0, v51
	v_add_f32_e32 v52, 1.0, v52
	v_add_f32_e32 v53, 1.0, v53
	v_rcp_f32_e32 v50, v50
	v_rcp_f32_e32 v51, v51
	v_rcp_f32_e32 v52, v52
; DI float ex2(float x) { return __builtin_amdgcn_exp2f(x); }
;     DI void operator()(const f32x4 (&acc)[2][2][4][2], const Unit& u, int wr, int wc, int fr, int fq) const {
;     ...
;             for (int m = 0; m < 4; ++m) { u16* rowp = O + (size_t)(row0 + ai * HALF + m * 16) * ldc + hcol0;
; #pragma unroll
;                 for (int bj = 0; bj < 2; ++bj) { const f32x4 g = acc[ai][bj][m][0], up = acc[ai][bj][m][1]; float r[4];
; #pragma unroll
;                     for (int j = 0; j < 4; ++j) r[j] = g[j] * up[j] * __builtin_amdgcn_rcpf(1.f + ex2(-LOG2E * g[j]));
;                     uint2 w = {pack2(r[0], r[1]), pack2(r[2], r[3])}; *(uint2*)(rowp + bj * (HALF / 2)) = w; } }
	v_rcp_f32_e32 v53, v53
	v_pk_mul_f32 v[42:43], v[46:47], v[42:43]
	v_pk_mul_f32 v[40:41], v[44:45], v[40:41]
	global_store_dwordx2 v[64:65], v[48:49], off offset:128
	v_pk_mul_f32 v[40:41], v[40:41], v[50:51]
	v_pk_mul_f32 v[42:43], v[42:43], v[52:53]
	v_cvt_pk_bf16_f32 v40, v40, v41
	v_cvt_pk_bf16_f32 v41, v42, v43
	v_mul_f32_e32 v42, 0xbfb8aa3b, v36
	v_mul_f32_e32 v43, 0xbfb8aa3b, v37
	v_exp_f32_e32 v42, v42
	v_exp_f32_e32 v43, v43
	v_add_u32_e32 v48, 0x90, v170
	v_mad_i64_i32 v[48:49], s[16:17], v48, s57, v[142:143]
	v_lshl_add_u64 v[48:49], v[48:49], 0, v[140:141]
	global_store_dwordx2 v[48:49], v[40:41], off
	v_add_f32_e32 v40, 1.0, v42
	v_add_f32_e32 v41, 1.0, v43
	v_mul_f32_e32 v42, 0xbfb8aa3b, v38
	v_mul_f32_e32 v43, 0xbfb8aa3b, v39
	v_exp_f32_e32 v42, v42
	v_exp_f32_e32 v43, v43
	v_rcp_f32_e32 v40, v40
	v_rcp_f32_e32 v41, v41
	v_add_f32_e32 v42, 1.0, v42
	v_add_f32_e32 v43, 1.0, v43
	v_rcp_f32_e32 v42, v42
	v_rcp_f32_e32 v43, v43
	v_pk_mul_f32 v[34:35], v[38:39], v[34:35]
	v_pk_mul_f32 v[32:33], v[36:37], v[32:33]
	v_mul_f32_e32 v36, 0xbfb8aa3b, v30
	v_pk_mul_f32 v[32:33], v[32:33], v[40:41]
	v_pk_mul_f32 v[34:35], v[34:35], v[42:43]
	v_cvt_pk_bf16_f32 v32, v32, v33
	v_cvt_pk_bf16_f32 v33, v34, v35
	v_mul_f32_e32 v34, 0xbfb8aa3b, v28
	v_mul_f32_e32 v35, 0xbfb8aa3b, v29
	v_mul_f32_e32 v37, 0xbfb8aa3b, v31
	v_exp_f32_e32 v34, v34
	v_exp_f32_e32 v35, v35
	v_exp_f32_e32 v36, v36
	v_exp_f32_e32 v37, v37
	v_add_f32_e32 v34, 1.0, v34
	v_add_f32_e32 v35, 1.0, v35
	v_add_f32_e32 v36, 1.0, v36
	v_add_f32_e32 v37, 1.0, v37
	v_rcp_f32_e32 v34, v34
	v_rcp_f32_e32 v35, v35
	v_rcp_f32_e32 v36, v36
	v_rcp_f32_e32 v37, v37
	v_pk_mul_f32 v[26:27], v[30:31], v[26:27]
	v_pk_mul_f32 v[24:25], v[28:29], v[24:25]
	global_store_dwordx2 v[48:49], v[32:33], off offset:128
	v_pk_mul_f32 v[24:25], v[24:25], v[34:35]
	v_pk_mul_f32 v[26:27], v[26:27], v[36:37]
	v_cvt_pk_bf16_f32 v24, v24, v25
	v_cvt_pk_bf16_f32 v25, v26, v27
	v_mul_f32_e32 v26, 0xbfb8aa3b, v20
	v_mul_f32_e32 v27, 0xbfb8aa3b, v21
	v_exp_f32_e32 v26, v26
	v_exp_f32_e32 v27, v27
	v_add_u32_e32 v32, 0xa0, v170
	v_mad_i64_i32 v[32:33], s[16:17], v32, s57, v[142:143]
	v_lshl_add_u64 v[32:33], v[32:33], 0, v[140:141]
	global_store_dwordx2 v[32:33], v[24:25], off
	v_add_f32_e32 v24, 1.0, v26
	v_add_f32_e32 v25, 1.0, v27
	v_mul_f32_e32 v26, 0xbfb8aa3b, v22
	v_mul_f32_e32 v27, 0xbfb8aa3b, v23
	v_exp_f32_e32 v26, v26
	v_exp_f32_e32 v27, v27
	v_rcp_f32_e32 v24, v24
	v_rcp_f32_e32 v25, v25
	v_add_f32_e32 v26, 1.0, v26
	v_add_f32_e32 v27, 1.0, v27
	v_rcp_f32_e32 v26, v26
	v_rcp_f32_e32 v27, v27
	v_pk_mul_f32 v[18:19], v[22:23], v[18:19]
	v_pk_mul_f32 v[16:17], v[20:21], v[16:17]
	v_mul_f32_e32 v20, 0xbfb8aa3b, v14
	v_pk_mul_f32 v[16:17], v[16:17], v[24:25]
	v_pk_mul_f32 v[18:19], v[18:19], v[26:27]
	v_cvt_pk_bf16_f32 v16, v16, v17
	v_cvt_pk_bf16_f32 v17, v18, v19
	v_mul_f32_e32 v18, 0xbfb8aa3b, v12
	v_mul_f32_e32 v19, 0xbfb8aa3b, v13
	v_mul_f32_e32 v21, 0xbfb8aa3b, v15
	v_exp_f32_e32 v18, v18
	v_exp_f32_e32 v19, v19
	v_exp_f32_e32 v20, v20
	v_exp_f32_e32 v21, v21
	v_add_f32_e32 v18, 1.0, v18
	v_add_f32_e32 v19, 1.0, v19
	v_add_f32_e32 v20, 1.0, v20
	v_add_f32_e32 v21, 1.0, v21
	v_rcp_f32_e32 v18, v18
	v_rcp_f32_e32 v19, v19
	v_rcp_f32_e32 v20, v20
	v_rcp_f32_e32 v21, v21
	v_pk_mul_f32 v[10:11], v[14:15], v[10:11]
	v_pk_mul_f32 v[8:9], v[12:13], v[8:9]
	global_store_dwordx2 v[32:33], v[16:17], off offset:128
	v_pk_mul_f32 v[8:9], v[8:9], v[18:19]
	v_pk_mul_f32 v[10:11], v[10:11], v[20:21]
	v_cvt_pk_bf16_f32 v8, v8, v9
	v_cvt_pk_bf16_f32 v9, v10, v11
	v_mul_f32_e32 v10, 0xbfb8aa3b, v4
	v_mul_f32_e32 v11, 0xbfb8aa3b, v5
	v_exp_f32_e32 v10, v10
	v_exp_f32_e32 v11, v11
	v_add_u32_e32 v16, 0xb0, v170
	v_mad_i64_i32 v[16:17], s[16:17], v16, s57, v[142:143]
	v_lshl_add_u64 v[16:17], v[16:17], 0, v[140:141]
	global_store_dwordx2 v[16:17], v[8:9], off
	v_add_f32_e32 v8, 1.0, v10
	v_add_f32_e32 v9, 1.0, v11
	v_mul_f32_e32 v10, 0xbfb8aa3b, v6
	v_mul_f32_e32 v11, 0xbfb8aa3b, v7
	v_exp_f32_e32 v10, v10
	v_exp_f32_e32 v11, v11
	v_rcp_f32_e32 v8, v8
	v_rcp_f32_e32 v9, v9
	v_add_f32_e32 v10, 1.0, v10
	v_add_f32_e32 v11, 1.0, v11
	v_rcp_f32_e32 v10, v10
	v_rcp_f32_e32 v11, v11
	v_pk_mul_f32 v[2:3], v[6:7], v[2:3]
	v_pk_mul_f32 v[0:1], v[4:5], v[0:1]
	s_and_b64 vcc, exec, s[2:3]
	v_pk_mul_f32 v[0:1], v[0:1], v[8:9]
	v_pk_mul_f32 v[2:3], v[2:3], v[10:11]
	v_cvt_pk_bf16_f32 v0, v0, v1
	v_cvt_pk_bf16_f32 v1, v2, v3
	s_mov_b32 s61, s58
	s_mov_b32 s60, s59
	s_mov_b64 s[18:19], s[0:1]
	s_mov_b64 s[16:17], s[4:5]
	global_store_dwordx2 v[16:17], v[0:1], off offset:128
	s_cbranch_vccz .LBB0_720
	s_branch .Lgu4_done

; #define PG8_STAGE(bufoff, gbase, voff) do { _Pragma("unroll") for (int _i = 0; _i < 2; ++_i) \
;         __builtin_amdgcn_global_load_lds((const unsigned*)((const char*)(gbase) + (voff)[_i]), (PG8_LAS unsigned*)(lds + (bufoff) + ldsw + _i * 8192), 16, 0, 0); } while (0)
; #define PG8_LDA(dst, b, h) do { _Pragma("unroll") for (int m = 0; m < 4; ++m) _Pragma("unroll") for (int k = 0; k < 2; ++k) dst[m][k] = *(const PG8_LAS bf16x8*)(lds + PG8_SA(b, h) + aoff + m * 2048 + k * 1024); } while (0)
; #define PG8_LDB(dst, b, h) do { _Pragma("unroll") for (int n = 0; n < 2; ++n) _Pragma("unroll") for (int k = 0; k < 2; ++k) dst[n][k] = *(const PG8_LAS bf16x8*)(lds + PG8_SB(b, h) + boff + n * 2048 + k * 1024); } while (0)
; #define PG8_MMA(ai, bj, At, Bt) do { __builtin_amdgcn_s_setprio(1); _Pragma("unroll") for (int m = 0; m < 4; ++m) _Pragma("unroll") for (int n = 0; n < 2; ++n) _Pragma("unroll") for (int k = 0; k < 2; ++k) \
;         acc[ai][bj][m][n] = __builtin_amdgcn_mfma_f32_16x16x32_bf16(Bt[n][k], At[m][k], acc[ai][bj][m][n], 0, 0, 0); __builtin_amdgcn_s_setprio(0); } while (0)
; #define PG8_BAR __builtin_amdgcn_s_barrier()
; template <class Epi, class Sched, bool STAMP = false>
; __device__ __forceinline__ void gemm_phase(PG8_LAS unsigned char* lds, const Gemm g, const Sched& S, const Epi& E, unsigned long long* stamps) {
;     ...
;         for (int t = 0; t < nt; t += 2) {
;             const bool last = (t == nt - 2);
;             const char* a1 = cA + (size_t)(t + 1) * kstep;
;             const char* a2 = last ? nA : cA + (size_t)(t + 2) * kstep; const char* b2 = last ? nB : cB + (size_t)(t + 2) * kstep;
;             const char* a3 = a2 + kstep; const char* b3 = b2 + kstep;
;             if (last && has_next) S.a_ready(nxt);
;             PG8_LDB(B0, 0, 0); PG8_SCHED; PG8_LDA(At, 0, 0); PG8_STAGE(PG8_SA(1, 1), a1 + hstep, voffA);
;             PG8_WAIT_L(8); PG8_BAR; PG8_WAIT_L(0); PG8_MMA(0, 0, At, B0); PG8_BAR; PG8_SCHED;
;             PG8_LDB(B1, 0, 1); PG8_STAGE(PG8_SB(0, 0), b2, voffB);
;             PG8_BAR; PG8_WAIT_L(0); PG8_MMA(0, 1, At, B1); PG8_BAR;
;             PG8_LDA(At, 0, 1); PG8_STAGE(PG8_SA(0, 0), a2, voffA);
;             PG8_BAR; PG8_WAIT_L(0); PG8_MMA(1, 0, At, B0); PG8_BAR; PG8_SCHED;
;             PG8_STAGE(PG8_SB(0, 1), b2 + hstep, voffB);
;             PG8_WAIT_V(6); PG8_BAR; PG8_MMA(1, 1, At, B1); PG8_BAR;
.LBB0_760:
	s_add_u32 s68, s30, 0x100
	s_addc_u32 s69, s31, 0
	s_mov_b32 s10, -2
	ds_read_b128 v[170:173], v147
	ds_read_b128 v[174:177], v148
	ds_read_b128 v[178:181], v149
	ds_read_b128 v[182:185], v150
	s_add_u32 s30, s28, 0x100
	s_addc_u32 s31, s29, 0
	s_cmp_eq_u32 s10, 40
	s_cselect_b32 s37, s5, s31
	s_cselect_b32 s36, s4, s30
	s_cselect_b32 s35, s1, s69
	s_cselect_b32 s34, s0, s68
	s_mov_b32 m0, s58
	ds_read_b128 v[186:189], v145
	ds_read_b128 v[190:193], v145 offset:1024
	ds_read_b128 v[194:197], v145 offset:2048
	ds_read_b128 v[198:201], v145 offset:3072
	ds_read_b128 v[202:205], v145 offset:4096
	ds_read_b128 v[206:209], v145 offset:5120
	ds_read_b128 v[210:213], v145 offset:6144
	ds_read_b128 v[214:217], v145 offset:7168
	global_load_lds_dwordx4 v136, s[28:29]
	s_mov_b32 m0, s59
	s_nop 0
	global_load_lds_dwordx4 v138, s[28:29]
	s_waitcnt lgkmcnt(8)
	s_barrier
	s_waitcnt lgkmcnt(0)
	s_setprio 1
	s_waitcnt lgkmcnt(0)
	v_mfma_f32_16x16x32_bf16 v[124:127], v[170:173], v[186:189], 0
	v_mfma_f32_16x16x32_bf16 v[120:123], v[178:181], v[186:189], 0
	v_mfma_f32_16x16x32_bf16 v[116:119], v[170:173], v[194:197], 0
	v_mfma_f32_16x16x32_bf16 v[112:115], v[178:181], v[194:197], 0
	v_mfma_f32_16x16x32_bf16 v[100:103], v[170:173], v[202:205], 0
	v_mfma_f32_16x16x32_bf16 v[96:99], v[178:181], v[202:205], 0
	v_mfma_f32_16x16x32_bf16 v[84:87], v[170:173], v[210:213], 0
	v_mfma_f32_16x16x32_bf16 v[80:83], v[178:181], v[210:213], 0
	v_mfma_f32_16x16x32_bf16 v[124:127], v[174:177], v[190:193], v[124:127]
	v_mfma_f32_16x16x32_bf16 v[120:123], v[182:185], v[190:193], v[120:123]
	v_mfma_f32_16x16x32_bf16 v[116:119], v[174:177], v[198:201], v[116:119]
	v_mfma_f32_16x16x32_bf16 v[112:115], v[182:185], v[198:201], v[112:115]
	v_mfma_f32_16x16x32_bf16 v[100:103], v[174:177], v[206:209], v[100:103]
	v_mfma_f32_16x16x32_bf16 v[96:99], v[182:185], v[206:209], v[96:99]
	v_mfma_f32_16x16x32_bf16 v[84:87], v[174:177], v[214:217], v[84:87]
	v_mfma_f32_16x16x32_bf16 v[80:83], v[182:185], v[214:217], v[80:83]
	s_setprio 0
	s_barrier
	s_mov_b32 m0, s43
	ds_read_b128 v[218:221], v151
	ds_read_b128 v[222:225], v152
	ds_read_b128 v[226:229], v153
	ds_read_b128 v[230:233], v154
	global_load_lds_dwordx4 v130, s[34:35]
	s_mov_b32 m0, s44
	s_nop 0
	global_load_lds_dwordx4 v134, s[34:35]
	s_barrier
	s_waitcnt lgkmcnt(0)
	s_setprio 1
	s_waitcnt lgkmcnt(0)
	v_mfma_f32_16x16x32_bf16 v[108:111], v[218:221], v[186:189], 0
	v_mfma_f32_16x16x32_bf16 v[104:107], v[226:229], v[186:189], 0
	v_mfma_f32_16x16x32_bf16 v[92:95], v[218:221], v[194:197], 0
	v_mfma_f32_16x16x32_bf16 v[88:91], v[226:229], v[194:197], 0
	v_mfma_f32_16x16x32_bf16 v[76:79], v[218:221], v[202:205], 0
	v_mfma_f32_16x16x32_bf16 v[72:75], v[226:229], v[202:205], 0
	v_mfma_f32_16x16x32_bf16 v[68:71], v[218:221], v[210:213], 0
	v_mfma_f32_16x16x32_bf16 v[64:67], v[226:229], v[210:213], 0
	v_mfma_f32_16x16x32_bf16 v[108:111], v[222:225], v[190:193], v[108:111]
	v_mfma_f32_16x16x32_bf16 v[104:107], v[230:233], v[190:193], v[104:107]
	v_mfma_f32_16x16x32_bf16 v[92:95], v[222:225], v[198:201], v[92:95]
	v_mfma_f32_16x16x32_bf16 v[88:91], v[230:233], v[198:201], v[88:91]
	v_mfma_f32_16x16x32_bf16 v[76:79], v[222:225], v[206:209], v[76:79]
	v_mfma_f32_16x16x32_bf16 v[72:75], v[230:233], v[206:209], v[72:75]
	v_mfma_f32_16x16x32_bf16 v[68:71], v[222:225], v[214:217], v[68:71]
	v_mfma_f32_16x16x32_bf16 v[64:67], v[230:233], v[214:217], v[64:67]
	s_setprio 0
	s_mov_b32 m0, s42
	s_barrier
	ds_read_b128 v[186:189], v145 offset:16384
	ds_read_b128 v[190:193], v145 offset:17408
	ds_read_b128 v[194:197], v145 offset:18432
	ds_read_b128 v[198:201], v145 offset:19456
	ds_read_b128 v[202:205], v145 offset:20480
	ds_read_b128 v[206:209], v145 offset:21504
	ds_read_b128 v[210:213], v145 offset:22528
	ds_read_b128 v[214:217], v145 offset:23552
	global_load_lds_dwordx4 v128, s[36:37]
	s_mov_b32 m0, s45
	s_nop 0
	global_load_lds_dwordx4 v132, s[36:37]
	s_barrier
	s_waitcnt lgkmcnt(0)
	s_setprio 1
	s_waitcnt lgkmcnt(0)
	v_mfma_f32_16x16x32_bf16 v[60:63], v[170:173], v[186:189], 0
	v_mfma_f32_16x16x32_bf16 v[56:59], v[178:181], v[186:189], 0
	v_mfma_f32_16x16x32_bf16 v[52:55], v[170:173], v[194:197], 0
	v_mfma_f32_16x16x32_bf16 v[48:51], v[178:181], v[194:197], 0
	v_mfma_f32_16x16x32_bf16 v[36:39], v[170:173], v[202:205], 0
	v_mfma_f32_16x16x32_bf16 v[32:35], v[178:181], v[202:205], 0
	v_mfma_f32_16x16x32_bf16 v[20:23], v[170:173], v[210:213], 0
	v_mfma_f32_16x16x32_bf16 v[16:19], v[178:181], v[210:213], 0
	v_mfma_f32_16x16x32_bf16 v[60:63], v[174:177], v[190:193], v[60:63]
	v_mfma_f32_16x16x32_bf16 v[56:59], v[182:185], v[190:193], v[56:59]
	v_mfma_f32_16x16x32_bf16 v[52:55], v[174:177], v[198:201], v[52:55]
	v_mfma_f32_16x16x32_bf16 v[48:51], v[182:185], v[198:201], v[48:51]
	v_mfma_f32_16x16x32_bf16 v[36:39], v[174:177], v[206:209], v[36:39]
	v_mfma_f32_16x16x32_bf16 v[32:35], v[182:185], v[206:209], v[32:35]
	v_mfma_f32_16x16x32_bf16 v[20:23], v[174:177], v[214:217], v[20:23]
	v_mfma_f32_16x16x32_bf16 v[16:19], v[182:185], v[214:217], v[16:19]
	s_setprio 0
	s_barrier
	s_add_u32 s28, s34, 0xb4000
	s_addc_u32 s29, s35, 0
	s_mov_b32 m0, s46
	s_nop 0
	global_load_lds_dwordx4 v130, s[28:29]
	s_mov_b32 m0, s47
	s_nop 0
	global_load_lds_dwordx4 v134, s[28:29]
	s_waitcnt vmcnt(6)
	s_barrier
	s_setprio 1
	v_mfma_f32_16x16x32_bf16 v[44:47], v[218:221], v[186:189], 0
	v_mfma_f32_16x16x32_bf16 v[40:43], v[226:229], v[186:189], 0
	v_mfma_f32_16x16x32_bf16 v[28:31], v[218:221], v[194:197], 0
	v_mfma_f32_16x16x32_bf16 v[24:27], v[226:229], v[194:197], 0
	v_mfma_f32_16x16x32_bf16 v[12:15], v[218:221], v[202:205], 0
	v_mfma_f32_16x16x32_bf16 v[8:11], v[226:229], v[202:205], 0
	v_mfma_f32_16x16x32_bf16 v[4:7], v[218:221], v[210:213], 0
	v_mfma_f32_16x16x32_bf16 v[0:3], v[226:229], v[210:213], 0
	v_mfma_f32_16x16x32_bf16 v[44:47], v[222:225], v[190:193], v[44:47]
	v_mfma_f32_16x16x32_bf16 v[40:43], v[230:233], v[190:193], v[40:43]
	v_mfma_f32_16x16x32_bf16 v[28:31], v[222:225], v[198:201], v[28:31]
	v_mfma_f32_16x16x32_bf16 v[24:27], v[230:233], v[198:201], v[24:27]
	v_mfma_f32_16x16x32_bf16 v[12:15], v[222:225], v[206:209], v[12:15]
	v_mfma_f32_16x16x32_bf16 v[8:11], v[230:233], v[206:209], v[8:11]
	v_mfma_f32_16x16x32_bf16 v[4:7], v[222:225], v[214:217], v[4:7]
	v_mfma_f32_16x16x32_bf16 v[0:3], v[230:233], v[214:217], v[0:3]
	s_setprio 0
	s_barrier
	s_branch .Lzp12_mid

; #define PG8_STAGE(bufoff, gbase, voff) do { _Pragma("unroll") for (int _i = 0; _i < 2; ++_i) \
;         __builtin_amdgcn_global_load_lds((const unsigned*)((const char*)(gbase) + (voff)[_i]), (PG8_LAS unsigned*)(lds + (bufoff) + ldsw + _i * 8192), 16, 0, 0); } while (0)
; #define PG8_LDA(dst, b, h) do { _Pragma("unroll") for (int m = 0; m < 4; ++m) _Pragma("unroll") for (int k = 0; k < 2; ++k) dst[m][k] = *(const PG8_LAS bf16x8*)(lds + PG8_SA(b, h) + aoff + m * 2048 + k * 1024); } while (0)
; #define PG8_LDB(dst, b, h) do { _Pragma("unroll") for (int n = 0; n < 2; ++n) _Pragma("unroll") for (int k = 0; k < 2; ++k) dst[n][k] = *(const PG8_LAS bf16x8*)(lds + PG8_SB(b, h) + boff + n * 2048 + k * 1024); } while (0)
; #define PG8_MMA(ai, bj, At, Bt) do { __builtin_amdgcn_s_setprio(1); _Pragma("unroll") for (int m = 0; m < 4; ++m) _Pragma("unroll") for (int n = 0; n < 2; ++n) _Pragma("unroll") for (int k = 0; k < 2; ++k) \
;         acc[ai][bj][m][n] = __builtin_amdgcn_mfma_f32_16x16x32_bf16(Bt[n][k], At[m][k], acc[ai][bj][m][n], 0, 0, 0); __builtin_amdgcn_s_setprio(0); } while (0)
; #define PG8_WAIT_V(n) asm volatile("s_waitcnt vmcnt(" #n ")" ::: "memory")
; #define PG8_WAIT_L(n) asm volatile("s_waitcnt lgkmcnt(" #n ")" ::: "memory")
; #define PG8_BAR __builtin_amdgcn_s_barrier()
; #define PG8_SCHED __builtin_amdgcn_sched_barrier(0)
; template <class Epi, class Sched, bool STAMP = false>
; __device__ __forceinline__ void gemm_phase(PG8_LAS unsigned char* lds, const Gemm g, const Sched& S, const Epi& E, unsigned long long* stamps) {
;     ...
;             PG8_LDB(B0, 1, 0); PG8_SCHED; PG8_LDA(At, 1, 0); PG8_STAGE(PG8_SA(0, 1), a2 + hstep, voffA);
;             PG8_WAIT_L(8); PG8_BAR; PG8_WAIT_L(0); PG8_MMA(0, 0, At, B0); PG8_BAR; PG8_SCHED;
;             PG8_LDB(B1, 1, 1); PG8_STAGE(PG8_SB(1, 0), b3, voffB);
;             PG8_BAR; PG8_WAIT_L(0); PG8_MMA(0, 1, At, B1); PG8_BAR;
;             PG8_LDA(At, 1, 1); PG8_STAGE(PG8_SA(1, 0), a3, voffA);
;             PG8_BAR; PG8_WAIT_L(0); PG8_MMA(1, 0, At, B0); PG8_BAR; PG8_SCHED;
;             PG8_STAGE(PG8_SB(1, 1), b3 + hstep, voffB);
;             PG8_WAIT_V(6); PG8_BAR; PG8_MMA(1, 1, At, B1); PG8_BAR;
.Lzp12_mid:
	ds_read_b128 v[170:173], v155
	ds_read_b128 v[174:177], v156
	ds_read_b128 v[178:181], v157
	ds_read_b128 v[182:185], v165
	s_add_u32 s28, s36, 0xb4000
	s_addc_u32 s29, s37, 0
	s_mov_b32 m0, s48
	ds_read_b128 v[186:189], v145 offset:32768
	ds_read_b128 v[190:193], v145 offset:33792
	ds_read_b128 v[194:197], v145 offset:34816
	ds_read_b128 v[198:201], v145 offset:35840
	ds_read_b128 v[202:205], v145 offset:36864
	ds_read_b128 v[206:209], v145 offset:37888
	ds_read_b128 v[210:213], v145 offset:38912
	ds_read_b128 v[214:217], v145 offset:39936
	global_load_lds_dwordx4 v128, s[28:29]
	s_mov_b32 m0, s49
	s_nop 0
	global_load_lds_dwordx4 v132, s[28:29]
	s_waitcnt lgkmcnt(8)
	s_barrier
	s_waitcnt lgkmcnt(0)
	s_setprio 1
	s_waitcnt lgkmcnt(0)
	v_mfma_f32_16x16x32_bf16 v[124:127], v[170:173], v[186:189], v[124:127]
	v_mfma_f32_16x16x32_bf16 v[120:123], v[178:181], v[186:189], v[120:123]
	v_mfma_f32_16x16x32_bf16 v[116:119], v[170:173], v[194:197], v[116:119]
	v_mfma_f32_16x16x32_bf16 v[112:115], v[178:181], v[194:197], v[112:115]
	v_mfma_f32_16x16x32_bf16 v[100:103], v[170:173], v[202:205], v[100:103]
	v_mfma_f32_16x16x32_bf16 v[96:99], v[178:181], v[202:205], v[96:99]
	v_mfma_f32_16x16x32_bf16 v[84:87], v[170:173], v[210:213], v[84:87]
	v_mfma_f32_16x16x32_bf16 v[80:83], v[178:181], v[210:213], v[80:83]
	v_mfma_f32_16x16x32_bf16 v[124:127], v[174:177], v[190:193], v[124:127]
	v_mfma_f32_16x16x32_bf16 v[120:123], v[182:185], v[190:193], v[120:123]
	v_mfma_f32_16x16x32_bf16 v[116:119], v[174:177], v[198:201], v[116:119]
	v_mfma_f32_16x16x32_bf16 v[112:115], v[182:185], v[198:201], v[112:115]
	v_mfma_f32_16x16x32_bf16 v[100:103], v[174:177], v[206:209], v[100:103]
	v_mfma_f32_16x16x32_bf16 v[96:99], v[182:185], v[206:209], v[96:99]
	v_mfma_f32_16x16x32_bf16 v[84:87], v[174:177], v[214:217], v[84:87]
	v_mfma_f32_16x16x32_bf16 v[80:83], v[182:185], v[214:217], v[80:83]
	s_setprio 0
	s_barrier
	s_mov_b32 m0, s50
	ds_read_b128 v[218:221], v166
	ds_read_b128 v[222:225], v167
	ds_read_b128 v[226:229], v168
	ds_read_b128 v[230:233], v169
	s_add_u32 s100, s34, 0x80
	s_addc_u32 s101, s35, 0
	global_load_lds_dwordx4 v130, s[100:101]
	s_mov_b32 m0, s51
	s_nop 0
	global_load_lds_dwordx4 v134, s[100:101]
	s_barrier
	s_waitcnt lgkmcnt(0)
	s_setprio 1
	s_waitcnt lgkmcnt(0)
	v_mfma_f32_16x16x32_bf16 v[108:111], v[218:221], v[186:189], v[108:111]
	v_mfma_f32_16x16x32_bf16 v[104:107], v[226:229], v[186:189], v[104:107]
	v_mfma_f32_16x16x32_bf16 v[92:95], v[218:221], v[194:197], v[92:95]
	v_mfma_f32_16x16x32_bf16 v[88:91], v[226:229], v[194:197], v[88:91]
	v_mfma_f32_16x16x32_bf16 v[76:79], v[218:221], v[202:205], v[76:79]
	v_mfma_f32_16x16x32_bf16 v[72:75], v[226:229], v[202:205], v[72:75]
	v_mfma_f32_16x16x32_bf16 v[68:71], v[218:221], v[210:213], v[68:71]
	v_mfma_f32_16x16x32_bf16 v[64:67], v[226:229], v[210:213], v[64:67]
	v_mfma_f32_16x16x32_bf16 v[108:111], v[222:225], v[190:193], v[108:111]
	v_mfma_f32_16x16x32_bf16 v[104:107], v[230:233], v[190:193], v[104:107]
	v_mfma_f32_16x16x32_bf16 v[92:95], v[222:225], v[198:201], v[92:95]
	v_mfma_f32_16x16x32_bf16 v[88:91], v[230:233], v[198:201], v[88:91]
	v_mfma_f32_16x16x32_bf16 v[76:79], v[222:225], v[206:209], v[76:79]
	v_mfma_f32_16x16x32_bf16 v[72:75], v[230:233], v[206:209], v[72:75]
	v_mfma_f32_16x16x32_bf16 v[68:71], v[222:225], v[214:217], v[68:71]
	v_mfma_f32_16x16x32_bf16 v[64:67], v[230:233], v[214:217], v[64:67]
	s_setprio 0
	s_mov_b32 m0, s52
	s_barrier
	ds_read_b128 v[186:189], v145 offset:49152
	ds_read_b128 v[190:193], v145 offset:50176
	ds_read_b128 v[194:197], v145 offset:51200
	ds_read_b128 v[198:201], v145 offset:52224
	ds_read_b128 v[202:205], v145 offset:53248
	ds_read_b128 v[206:209], v145 offset:54272
	ds_read_b128 v[210:213], v145 offset:55296
	ds_read_b128 v[214:217], v145 offset:56320
	s_add_u32 s100, s36, 0x80
	s_addc_u32 s101, s37, 0
	global_load_lds_dwordx4 v128, s[100:101]
	s_mov_b32 m0, s53
	s_nop 0
	global_load_lds_dwordx4 v132, s[100:101]
	s_barrier
	s_waitcnt lgkmcnt(0)
	s_setprio 1
	s_waitcnt lgkmcnt(0)
	v_mfma_f32_16x16x32_bf16 v[60:63], v[170:173], v[186:189], v[60:63]
	v_mfma_f32_16x16x32_bf16 v[56:59], v[178:181], v[186:189], v[56:59]
	v_mfma_f32_16x16x32_bf16 v[52:55], v[170:173], v[194:197], v[52:55]
	v_mfma_f32_16x16x32_bf16 v[48:51], v[178:181], v[194:197], v[48:51]
	v_mfma_f32_16x16x32_bf16 v[36:39], v[170:173], v[202:205], v[36:39]
	v_mfma_f32_16x16x32_bf16 v[32:35], v[178:181], v[202:205], v[32:35]
	v_mfma_f32_16x16x32_bf16 v[20:23], v[170:173], v[210:213], v[20:23]
	v_mfma_f32_16x16x32_bf16 v[16:19], v[178:181], v[210:213], v[16:19]
	v_mfma_f32_16x16x32_bf16 v[60:63], v[174:177], v[190:193], v[60:63]
	v_mfma_f32_16x16x32_bf16 v[56:59], v[182:185], v[190:193], v[56:59]
	v_mfma_f32_16x16x32_bf16 v[52:55], v[174:177], v[198:201], v[52:55]
	v_mfma_f32_16x16x32_bf16 v[48:51], v[182:185], v[198:201], v[48:51]
	v_mfma_f32_16x16x32_bf16 v[36:39], v[174:177], v[206:209], v[36:39]
	v_mfma_f32_16x16x32_bf16 v[32:35], v[182:185], v[206:209], v[32:35]
	v_mfma_f32_16x16x32_bf16 v[20:23], v[174:177], v[214:217], v[20:23]
	v_mfma_f32_16x16x32_bf16 v[16:19], v[182:185], v[214:217], v[16:19]
	s_setprio 0
	s_barrier
	s_add_u32 s28, s34, 0xb4080
	s_addc_u32 s29, s35, 0
	s_mov_b32 m0, s54
	s_nop 0
	global_load_lds_dwordx4 v130, s[28:29]
	s_mov_b32 m0, s55
	s_nop 0
	global_load_lds_dwordx4 v134, s[28:29]
	s_waitcnt vmcnt(6)
	s_barrier
; #define PG8_STAMP() do { if (STAMP && wid == 0 && nts < 64) { const unsigned long long _c = 0ull; \
;         ts_lo = (lane == nts) ? (int)(unsigned)_c : ts_lo; ts_hi = (lane == nts) ? (int)(unsigned)(_c >> 32) : ts_hi; ++nts; } } while (0)
; #define PG8_MMA(ai, bj, At, Bt) do { __builtin_amdgcn_s_setprio(1); _Pragma("unroll") for (int m = 0; m < 4; ++m) _Pragma("unroll") for (int n = 0; n < 2; ++n) _Pragma("unroll") for (int k = 0; k < 2; ++k) \
;         acc[ai][bj][m][n] = __builtin_amdgcn_mfma_f32_16x16x32_bf16(Bt[n][k], At[m][k], acc[ai][bj][m][n], 0, 0, 0); __builtin_amdgcn_s_setprio(0); } while (0)
; #define PG8_WAIT_V(n) asm volatile("s_waitcnt vmcnt(" #n ")" ::: "memory")
; #define PG8_BAR __builtin_amdgcn_s_barrier()
;     DI void operator()(const f32x4 (&acc)[2][2][4][2], const Unit& u, int wr, int wc, int fr, int fq) const {
;         const int row0 = u.pm * BM + wr * 64 + fr, col0 = u.pn * BM + wc * 32 + 8 * fq;
; #pragma unroll
;         for (int ai = 0; ai < 2; ++ai)
; #pragma unroll
;             for (int m = 0; m < 4; ++m) { u16* rowp = O + (size_t)(row0 + ai * HALF + m * 16) * ldc + col0;
; #pragma unroll
;                 for (int bj = 0; bj < 2; ++bj) { const f32x4 v0 = acc[ai][bj][m][0], v1 = acc[ai][bj][m][1];
;                     uint4 w = {pack2(v0[0], v0[1]), pack2(v0[2], v0[3]), pack2(v1[0], v1[1]), pack2(v1[2], v1[3])}; *(uint4*)(rowp + bj * HALF) = w; } }
; template <class Epi, class Sched, bool STAMP = false>
; __device__ __forceinline__ void gemm_phase(PG8_LAS unsigned char* lds, const Gemm g, const Sched& S, const Epi& E, unsigned long long* stamps) {
;     ...
;             PG8_WAIT_V(6); PG8_BAR; PG8_MMA(1, 1, At, B1); PG8_BAR;
;         }
;         PG8_STAMP();
;         if constexpr (!Epi::AFTER_DRAIN) { E(acc, cur, wr, wc, fr, fq); S.done(cur); }
	s_setprio 1
	v_mfma_f32_16x16x32_bf16 v[44:47], v[218:221], v[186:189], v[44:47]
	v_mfma_f32_16x16x32_bf16 v[40:43], v[226:229], v[186:189], v[40:43]
	v_mfma_f32_16x16x32_bf16 v[28:31], v[218:221], v[194:197], v[28:31]
	v_mfma_f32_16x16x32_bf16 v[24:27], v[226:229], v[194:197], v[24:27]
	v_mfma_f32_16x16x32_bf16 v[12:15], v[218:221], v[202:205], v[12:15]
	v_mfma_f32_16x16x32_bf16 v[8:11], v[226:229], v[202:205], v[8:11]
	v_mfma_f32_16x16x32_bf16 v[4:7], v[218:221], v[210:213], v[4:7]
	v_mfma_f32_16x16x32_bf16 v[0:3], v[226:229], v[210:213], v[0:3]
	v_mfma_f32_16x16x32_bf16 v[44:47], v[222:225], v[190:193], v[44:47]
	v_mfma_f32_16x16x32_bf16 v[40:43], v[230:233], v[190:193], v[40:43]
	v_mfma_f32_16x16x32_bf16 v[28:31], v[222:225], v[198:201], v[28:31]
	v_mfma_f32_16x16x32_bf16 v[24:27], v[230:233], v[198:201], v[24:27]
	v_mfma_f32_16x16x32_bf16 v[12:15], v[222:225], v[206:209], v[12:15]
	v_mfma_f32_16x16x32_bf16 v[8:11], v[230:233], v[206:209], v[8:11]
	v_mfma_f32_16x16x32_bf16 v[4:7], v[222:225], v[214:217], v[4:7]
	v_mfma_f32_16x16x32_bf16 v[0:3], v[230:233], v[214:217], v[0:3]
	s_setprio 0
	s_add_i32 s10, s10, 2
	s_add_u32 s68, s68, 0x100
	s_addc_u32 s69, s69, 0
	s_cmp_gt_u32 s10, 41
	s_mov_b64 s[28:29], s[30:31]
	s_barrier
	s_cbranch_scc0 .LBB0_761
	v_lshl_add_u32 v170, s64, 8, v144
	v_lshl_or_b32 v172, s67, 8, v146
	v_ashrrev_i32_e32 v171, 31, v170
	v_ashrrev_i32_e32 v173, 31, v172
	v_lshlrev_b64 v[174:175], 11, v[170:171]
	v_lshl_add_u64 v[174:175], s[14:15], 0, v[174:175]
	v_lshlrev_b64 v[172:173], 1, v[172:173]
	v_lshl_add_u64 v[174:175], v[174:175], 0, v[172:173]
	v_cvt_pk_bf16_f32 v60, v60, v61
	v_cvt_pk_bf16_f32 v61, v62, v63
	v_cvt_pk_bf16_f32 v62, v56, v57
	v_add_co_u32_e32 v56, vcc, s60, v174
	v_cvt_pk_bf16_f32 v68, v68, v69
	v_cvt_pk_bf16_f32 v69, v70, v71
	v_cvt_pk_bf16_f32 v70, v64, v65
	v_lshl_add_u64 v[64:65], v[174:175], 0, s[16:17]
	v_addc_co_u32_e32 v57, vcc, 0, v175, vcc
	v_cvt_pk_bf16_f32 v44, v44, v45
	v_cvt_pk_bf16_f32 v45, v46, v47
	v_cvt_pk_bf16_f32 v46, v40, v41
	v_cvt_pk_bf16_f32 v47, v42, v43
	v_cvt_pk_bf16_f32 v108, v108, v109
	v_cvt_pk_bf16_f32 v109, v110, v111
	v_cvt_pk_bf16_f32 v110, v104, v105
	v_or_b32_e32 v104, 16, v170
	global_store_dwordx4 v[64:65], v[44:47], off offset:256
	v_ashrrev_i32_e32 v105, 31, v104
	v_cvt_pk_bf16_f32 v92, v92, v93
	v_add_co_u32_e32 v46, vcc, s61, v174
	v_cvt_pk_bf16_f32 v93, v94, v95
	v_cvt_pk_bf16_f32 v94, v88, v89
	v_or_b32_e32 v88, 32, v170
	v_lshl_add_u64 v[44:45], v[174:175], 0, s[18:19]
	v_addc_co_u32_e32 v47, vcc, 0, v175, vcc
	v_cvt_pk_bf16_f32 v28, v28, v29
	v_cvt_pk_bf16_f32 v29, v30, v31
	v_cvt_pk_bf16_f32 v30, v24, v25
	v_cvt_pk_bf16_f32 v31, v26, v27
	v_lshlrev_b64 v[104:105], 11, v[104:105]
	v_ashrrev_i32_e32 v89, 31, v88
	v_cvt_pk_bf16_f32 v76, v76, v77
	v_cvt_pk_bf16_f32 v77, v78, v79
	v_cvt_pk_bf16_f32 v78, v72, v73
	v_or_b32_e32 v72, 48, v170
	global_store_dwordx4 v[44:45], v[28:31], off offset:256
	v_cvt_pk_bf16_f32 v111, v106, v107
	v_lshl_add_u64 v[104:105], s[14:15], 0, v[104:105]
	v_add_co_u32_e32 v30, vcc, s62, v174
	v_lshlrev_b64 v[88:89], 11, v[88:89]
	v_ashrrev_i32_e32 v73, 31, v72
	v_lshl_add_u64 v[28:29], v[174:175], 0, s[20:21]
	v_addc_co_u32_e32 v31, vcc, 0, v175, vcc
	v_cvt_pk_bf16_f32 v12, v12, v13
	v_cvt_pk_bf16_f32 v13, v14, v15
	v_cvt_pk_bf16_f32 v14, v8, v9
	v_cvt_pk_bf16_f32 v15, v10, v11
	global_store_dwordx4 v[174:175], v[108:111], off offset:256
	v_cvt_pk_bf16_f32 v95, v90, v91
	v_lshl_add_u64 v[88:89], s[14:15], 0, v[88:89]
	v_lshl_add_u64 v[108:109], v[104:105], 0, v[172:173]
	v_lshlrev_b64 v[72:73], 11, v[72:73]
	global_store_dwordx4 v[28:29], v[12:15], off offset:256
	global_store_dwordx4 v[108:109], v[92:95], off offset:256
	v_cvt_pk_bf16_f32 v79, v74, v75
	v_add_co_u32_e32 v14, vcc, s63, v174
	v_lshl_add_u64 v[92:93], v[88:89], 0, v[172:173]
	v_lshl_add_u64 v[72:73], s[14:15], 0, v[72:73]
	v_addc_co_u32_e32 v15, vcc, 0, v175, vcc
	v_cvt_pk_bf16_f32 v124, v124, v125
	v_cvt_pk_bf16_f32 v125, v126, v127
	v_cvt_pk_bf16_f32 v126, v120, v121
	v_cvt_pk_bf16_f32 v127, v122, v123
	v_cvt_pk_bf16_f32 v104, v116, v117
	v_cvt_pk_bf16_f32 v105, v118, v119
	v_cvt_pk_bf16_f32 v106, v112, v113
	v_cvt_pk_bf16_f32 v107, v114, v115
	v_cvt_pk_bf16_f32 v88, v100, v101
	v_cvt_pk_bf16_f32 v89, v102, v103
	v_cvt_pk_bf16_f32 v90, v96, v97
	v_cvt_pk_bf16_f32 v91, v98, v99
	global_store_dwordx4 v[92:93], v[76:79], off offset:256
	v_cvt_pk_bf16_f32 v74, v80, v81
	v_cvt_pk_bf16_f32 v75, v82, v83
	v_lshl_add_u64 v[76:77], v[72:73], 0, v[172:173]
	v_cvt_pk_bf16_f32 v72, v84, v85
	v_cvt_pk_bf16_f32 v73, v86, v87
	v_cvt_pk_bf16_f32 v71, v66, v67
	v_cvt_pk_bf16_f32 v63, v58, v59
	v_cvt_pk_bf16_f32 v40, v52, v53
	v_cvt_pk_bf16_f32 v41, v54, v55
	v_cvt_pk_bf16_f32 v42, v48, v49
	v_cvt_pk_bf16_f32 v43, v50, v51
	v_cvt_pk_bf16_f32 v24, v36, v37
	v_cvt_pk_bf16_f32 v25, v38, v39
	v_cvt_pk_bf16_f32 v26, v32, v33
	v_cvt_pk_bf16_f32 v27, v34, v35
	v_lshl_add_u64 v[12:13], v[174:175], 0, s[26:27]
	v_cvt_pk_bf16_f32 v8, v20, v21
	v_cvt_pk_bf16_f32 v9, v22, v23
	v_cvt_pk_bf16_f32 v10, v16, v17
	v_cvt_pk_bf16_f32 v11, v18, v19
	v_cvt_pk_bf16_f32 v4, v4, v5
	v_cvt_pk_bf16_f32 v5, v6, v7
	v_cvt_pk_bf16_f32 v6, v0, v1
	v_cvt_pk_bf16_f32 v7, v2, v3
	s_and_b64 vcc, exec, s[2:3]
	s_mov_b32 s67, s65
	s_mov_b32 s64, s66
	s_mov_b64 s[30:31], s[0:1]
	s_mov_b64 s[28:29], s[4:5]
	global_store_dwordx4 v[174:175], v[124:127], off
	global_store_dwordx4 v[108:109], v[104:107], off
	global_store_dwordx4 v[92:93], v[88:91], off
	global_store_dwordx4 v[76:77], v[72:75], off
	global_store_dwordx4 v[76:77], v[68:71], off offset:256
	global_store_dwordx4 v[56:57], v[60:63], off
	global_store_dwordx4 v[46:47], v[40:43], off
	global_store_dwordx4 v[30:31], v[24:27], off
	global_store_dwordx4 v[14:15], v[8:11], off
	global_store_dwordx4 v[12:13], v[4:7], off offset:256
	s_cbranch_vccz .LBB0_750
	s_waitcnt vmcnt(0)
	s_cmpk_gt_u32 s40, 0xff
	s_cbranch_scc1 .LBB0_765
	s_barrier
